# bit-trick bf16 rounding -> v_cvt_pk_bf16_f32 also in prologue, mixer items, UP tail, DOWN fixup
# speedup vs baseline: 1.0226x; 1.0019x over previous
.LBB0_18:
	s_or_b64 exec, exec, s[14:15]
	v_lshlrev_b32_e32 v2, 2, v5
	v_mul_lo_u32 v3, v6, s27
	v_add3_u32 v2, s20, v2, v3
	s_waitcnt vmcnt(0)
	ds_write2_b32 v2, v0, v7 offset1:66
	ds_write2_b32 v2, v10, v9 offset0:132 offset1:198
	v_add_u32_e32 v0, 0x400, v2
	ds_write2_b32 v0, v12, v11 offset0:8 offset1:74
	ds_write2_b32 v0, v14, v13 offset0:140 offset1:206
	v_add_u32_e32 v0, 0x800, v2
	ds_write2_b32 v0, v16, v15 offset0:16 offset1:82
	ds_write2_b32 v0, v18, v17 offset0:148 offset1:214
	v_add_u32_e32 v0, 0xc00, v2
	ds_write2_b32 v0, v20, v19 offset0:24 offset1:90
	ds_write2_b32 v0, v22, v21 offset0:156 offset1:222
	v_add_u32_e32 v0, 0x1000, v2
	ds_write2_b32 v0, v24, v23 offset0:32 offset1:98
	ds_write2_b32 v0, v26, v25 offset0:164 offset1:230
	v_add_u32_e32 v0, 0x1400, v2
	ds_write2_b32 v0, v28, v27 offset0:40 offset1:106
	ds_write2_b32 v0, v30, v29 offset0:172 offset1:238
	v_add_u32_e32 v0, 0x1800, v2
	ds_write2_b32 v0, v32, v31 offset0:48 offset1:114
	ds_write2_b32 v0, v34, v33 offset0:180 offset1:246
	v_add_u32_e32 v0, 0x1c00, v2
	ds_write2_b32 v0, v36, v35 offset0:56 offset1:122
	ds_write2_b32 v0, v38, v37 offset0:188 offset1:254
	v_lshlrev_b32_e32 v0, 3, v4
	v_ashrrev_i32_e32 v24, 3, v4
	v_and_b32_e32 v0, 56, v0
	s_waitcnt lgkmcnt(0)
	v_mul_u32_u24_e32 v2, 0x84, v0
	v_lshlrev_b32_e32 v3, 2, v24
	s_mul_hi_i32 s13, s34, 0x580000
	s_mul_i32 s34, s34, 0x580000
	v_add3_u32 v28, s20, v2, v3
	s_add_u32 s14, s10, s34
	ds_read2_b32 v[6:7], v28 offset1:8
	s_addc_u32 s15, s11, s13
	s_ashr_i32 s13, s12, 31
	ds_read2_b32 v[10:11], v28 offset0:33 offset1:41
	s_lshl_b64 s[10:11], s[12:13], 1
	s_add_u32 s10, s14, s10
	ds_read2_b32 v[12:13], v28 offset0:66 offset1:74
	s_addc_u32 s11, s15, s11
	v_lshlrev_b32_e32 v0, 1, v0
	ds_read2_b32 v[14:15], v28 offset0:99 offset1:107
	v_lshl_add_u64 v[2:3], s[10:11], 0, v[0:1]
	s_waitcnt lgkmcnt(3)
	v_lshl_add_u64 v[8:9], v[2:3], 0, s[2:3]
	s_waitcnt lgkmcnt(2)
	ds_read2_b32 v[16:17], v28 offset0:132 offset1:140
	ds_read2_b32 v[18:19], v28 offset0:165 offset1:173
	v_cvt_pk_bf16_f32 v2, v6, v10
	s_waitcnt lgkmcnt(3)
	s_waitcnt lgkmcnt(2)
	ds_read2_b32 v[20:21], v28 offset0:198 offset1:206
	ds_read2_b32 v[22:23], v28 offset0:231 offset1:239
	v_cvt_pk_bf16_f32 v3, v12, v14
	s_waitcnt lgkmcnt(3)
	s_waitcnt lgkmcnt(2)
	v_cvt_pk_bf16_f32 v4, v16, v18
	s_waitcnt lgkmcnt(1)
	v_add_u32_e32 v24, s31, v24
	s_waitcnt lgkmcnt(0)
	v_ashrrev_i32_e32 v25, 31, v24
	v_lshlrev_b64 v[26:27], 11, v[24:25]
	v_cvt_pk_bf16_f32 v5, v20, v22
	v_lshl_add_u64 v[26:27], v[8:9], 0, v[26:27]
	global_store_dwordx4 v[26:27], v[2:5], off
	s_nop 1
	v_cvt_pk_bf16_f32 v2, v7, v11
	v_cvt_pk_bf16_f32 v3, v13, v15
	v_cvt_pk_bf16_f32 v4, v17, v19
	v_add_u32_e32 v6, 8, v24
	v_ashrrev_i32_e32 v7, 31, v6
	v_lshlrev_b64 v[6:7], 11, v[6:7]
	v_cvt_pk_bf16_f32 v5, v21, v23
	ds_read2_b32 v[10:11], v28 offset0:16 offset1:24
	v_lshl_add_u64 v[6:7], v[8:9], 0, v[6:7]
	global_store_dwordx4 v[6:7], v[2:5], off
	ds_read2_b32 v[6:7], v28 offset0:49 offset1:57
	ds_read2_b32 v[12:13], v28 offset0:82 offset1:90
	ds_read2_b32 v[14:15], v28 offset0:115 offset1:123
	s_waitcnt lgkmcnt(3)
	s_waitcnt lgkmcnt(2)
	ds_read2_b32 v[16:17], v28 offset0:148 offset1:156
	ds_read2_b32 v[18:19], v28 offset0:181 offset1:189
	v_cvt_pk_bf16_f32 v2, v10, v6
	s_waitcnt lgkmcnt(3)
	s_waitcnt lgkmcnt(2)
	ds_read2_b32 v[20:21], v28 offset0:214 offset1:222
	ds_read2_b32 v[22:23], v28 offset0:247 offset1:255
	v_cvt_pk_bf16_f32 v3, v12, v14
	s_waitcnt lgkmcnt(3)
	s_waitcnt lgkmcnt(2)
	v_cvt_pk_bf16_f32 v4, v16, v18
	s_waitcnt lgkmcnt(1)
	v_add_u32_e32 v26, 16, v24
	s_waitcnt lgkmcnt(0)
	v_ashrrev_i32_e32 v27, 31, v26
	v_lshlrev_b64 v[26:27], 11, v[26:27]
	v_cvt_pk_bf16_f32 v5, v20, v22
	v_lshl_add_u64 v[26:27], v[8:9], 0, v[26:27]
	global_store_dwordx4 v[26:27], v[2:5], off
	s_nop 1
	v_cvt_pk_bf16_f32 v2, v11, v7
	v_cvt_pk_bf16_f32 v3, v13, v15
	v_cvt_pk_bf16_f32 v4, v17, v19
	v_add_u32_e32 v6, 24, v24
	v_ashrrev_i32_e32 v7, 31, v6
	v_lshlrev_b64 v[6:7], 11, v[6:7]
	v_cvt_pk_bf16_f32 v5, v21, v23
	v_lshl_add_u64 v[6:7], v[8:9], 0, v[6:7]
	global_store_dwordx4 v[6:7], v[2:5], off
	s_waitcnt lgkmcnt(0)
	s_add_i32 s30, s30, s33
	s_cmpk_gt_i32 s30, 0x57f
	s_cbranch_scc1 .LBB0_97

.LBB0_404:
	v_readlane_b32 vcc_lo, v255, 28
	s_waitcnt lgkmcnt(0)
	s_barrier
	v_readlane_b32 vcc_hi, v255, 29
	s_load_dwordx2 s[20:21], vcc, 0x100
	s_movk_i32 s6, 0x1600
	v_mov_b32_e32 v71, v1
	v_lshlrev_b32_e32 v34, 2, v46
	v_mov_b32_e32 v69, v1
	s_waitcnt lgkmcnt(0)
	s_add_u32 s4, s20, 0xb600000
	s_addc_u32 s5, s21, 0
	s_lshl_b32 s0, s35, 5
	s_and_b32 s0, s0, 0xffffff80
	s_and_b32 s1, s35, 3
	v_add_u32_e32 v0, s0, v76
	v_mov_b64_e32 v[2:3], s[4:5]
	v_mad_i64_i32 v[4:5], s[4:5], v0, s6, v[2:3]
	s_lshl_b32 s22, s1, 7
	v_lshl_add_u64 v[4:5], v[4:5], 0, s[22:23]
	v_lshlrev_b32_e32 v0, 1, v46
	v_lshl_add_u64 v[4:5], v[4:5], 0, v[0:1]
	v_add_u32_e32 v0, s0, v49
	global_load_dwordx4 v[38:41], v[4:5], off offset:2064
	global_load_dwordx4 v[42:45], v[4:5], off offset:2048
	v_mad_i64_i32 v[4:5], s[4:5], v0, s6, v[2:3]
	v_lshl_add_u64 v[4:5], v[4:5], 0, v[70:71]
	v_lshl_add_u64 v[4:5], v[4:5], 0, s[22:23]
	global_load_ushort v106, v[4:5], off offset:1536
	global_load_ushort v105, v[4:5], off offset:1568
	global_load_ushort v103, v[4:5], off offset:1600
	global_load_ushort v100, v[4:5], off offset:1632
	v_or_b32_e32 v4, 1, v0
	v_mad_i64_i32 v[4:5], s[4:5], v4, s6, v[2:3]
	v_lshl_add_u64 v[4:5], v[4:5], 0, v[70:71]
	v_lshl_add_u64 v[4:5], v[4:5], 0, s[22:23]
	global_load_ushort v104, v[4:5], off offset:1536
	global_load_ushort v102, v[4:5], off offset:1568
	global_load_ushort v99, v[4:5], off offset:1600
	global_load_ushort v96, v[4:5], off offset:1632
	v_or_b32_e32 v4, 2, v0
	v_or_b32_e32 v0, 3, v0
	v_mad_i64_i32 v[4:5], s[4:5], v4, s6, v[2:3]
	v_mad_i64_i32 v[2:3], s[4:5], v0, s6, v[2:3]
	v_lshl_add_u64 v[4:5], v[4:5], 0, v[70:71]
	v_lshl_add_u64 v[2:3], v[2:3], 0, v[70:71]
	v_lshl_add_u64 v[4:5], v[4:5], 0, s[22:23]
	v_lshl_add_u64 v[2:3], v[2:3], 0, s[22:23]
	global_load_ushort v101, v[4:5], off offset:1536
	global_load_ushort v97, v[4:5], off offset:1568
	global_load_ushort v94, v[4:5], off offset:1600
	global_load_ushort v92, v[4:5], off offset:1632
	global_load_ushort v98, v[2:3], off offset:1536
	global_load_ushort v95, v[2:3], off offset:1568
	global_load_ushort v93, v[2:3], off offset:1600
	global_load_ushort v0, v[2:3], off offset:1632
	s_load_dwordx8 s[4:11], vcc, 0x68
	s_or_b32 s22, s22, s19
	s_lshl_b64 vcc, s[22:23], 2
	v_lshlrev_b32_e32 v2, 2, v48
	s_waitcnt lgkmcnt(0)
	s_add_u32 s22, s10, vcc_lo
	s_addc_u32 vcc_lo, s11, vcc_hi
	s_lshl_b64 s[10:11], s[24:25], 2
	s_add_u32 s10, s22, s10
	s_addc_u32 s11, vcc_lo, s11
	global_load_dwordx4 v[2:5], v2, s[10:11]
	s_lshl_b64 s[10:11], s[16:17], 2
	s_add_u32 s4, s4, s10
	s_addc_u32 s5, s5, s11
	s_lshl_b32 s22, s1, 8
	s_add_u32 s4, s4, s22
	s_addc_u32 s5, s5, 0
	s_add_u32 s6, s6, s10
	s_addc_u32 s7, s7, s11
	s_add_u32 s6, s6, s22
	s_addc_u32 s7, s7, 0
	global_load_dwordx4 v[6:9], v34, s[4:5] offset:48
	global_load_dwordx4 v[14:17], v34, s[4:5] offset:32
	global_load_dwordx4 v[22:25], v34, s[4:5] offset:16
	global_load_dwordx4 v[30:33], v34, s[4:5]
	global_load_dwordx4 v[10:13], v34, s[6:7] offset:48
	global_load_dwordx4 v[18:21], v34, s[6:7] offset:32
	global_load_dwordx4 v[26:29], v34, s[6:7] offset:16
	s_nop 0
	global_load_dwordx4 v[34:37], v34, s[6:7]
	s_lshl_b32 s4, s1, 14
	s_or_b32 s22, s4, s15
	s_lshl_b64 s[4:5], s[22:23], 2
	s_add_u32 s4, s8, s4
	s_addc_u32 s5, s9, s5
	v_lshl_add_u64 v[136:137], s[4:5], 0, v[68:69]
	v_lshl_add_u64 v[108:109], v[60:61], 2, v[136:137]
	global_load_dwordx4 v[108:111], v[108:109], off
	v_lshl_add_u64 v[112:113], v[50:51], 2, v[136:137]
	global_load_dwordx4 v[112:115], v[112:113], off
	v_lshl_add_u64 v[116:117], v[52:53], 2, v[136:137]
	global_load_dwordx4 v[116:119], v[116:117], off
	v_lshl_add_u64 v[120:121], v[54:55], 2, v[136:137]
	global_load_dwordx4 v[120:123], v[120:121], off
	v_lshl_add_u64 v[124:125], v[56:57], 2, v[136:137]
	global_load_dwordx4 v[124:127], v[124:125], off
	v_lshl_add_u64 v[128:129], v[62:63], 2, v[136:137]
	global_load_dwordx4 v[128:131], v[128:129], off
	v_lshl_add_u64 v[132:133], v[64:65], 2, v[136:137]
	global_load_dwordx4 v[132:135], v[132:133], off
	v_lshl_add_u64 v[136:137], v[66:67], 2, v[136:137]
	global_load_dwordx4 v[136:139], v[136:137], off
	s_mov_b32 s4, 0xf800000
	s_waitcnt vmcnt(7)
	v_cndmask_b32_e64 v69, v108, 0, s[36:37]
	v_cndmask_b32_e64 v71, 0, v109, s[38:39]
	v_cvt_pk_bf16_f32 v108, v69, v71
	v_cndmask_b32_e64 v69, v110, 0, s[40:41]
	v_cndmask_b32_e64 v71, v111, 0, s[42:43]
	v_cvt_pk_bf16_f32 v109, v69, v71
	s_waitcnt vmcnt(6)
	v_cndmask_b32_e64 v69, v112, 0, s[44:45]
	v_cndmask_b32_e64 v71, 0, v113, s[46:47]
	ds_write_b64 v82, v[108:109]
	v_cvt_pk_bf16_f32 v108, v69, v71
	v_cndmask_b32_e64 v69, v114, 0, s[48:49]
	v_cndmask_b32_e64 v71, v115, 0, s[50:51]
	v_cvt_pk_bf16_f32 v109, v69, v71
	s_waitcnt vmcnt(5)
	v_cndmask_b32_e64 v69, v116, 0, s[52:53]
	v_cndmask_b32_e64 v71, 0, v117, s[54:55]
	ds_write_b64 v83, v[108:109]
	v_cvt_pk_bf16_f32 v108, v69, v71
	v_cndmask_b32_e64 v69, v118, 0, s[56:57]
	v_cndmask_b32_e64 v71, v119, 0, s[58:59]
	v_cvt_pk_bf16_f32 v109, v69, v71
	s_waitcnt vmcnt(4)
	v_cndmask_b32_e64 v69, v120, 0, s[60:61]
	v_cndmask_b32_e64 v71, 0, v121, s[62:63]
	ds_write_b64 v85, v[108:109]
	v_cvt_pk_bf16_f32 v108, v69, v71
	v_cndmask_b32_e64 v69, v122, 0, s[64:65]
	v_cndmask_b32_e64 v71, v123, 0, s[66:67]
	v_cvt_pk_bf16_f32 v109, v69, v71
	s_waitcnt vmcnt(3)
	v_cndmask_b32_e64 v69, v124, 0, s[68:69]
	v_cndmask_b32_e64 v71, 0, v125, s[70:71]
	ds_write_b64 v86, v[108:109]
	v_cvt_pk_bf16_f32 v108, v69, v71
	v_cndmask_b32_e64 v69, v126, 0, s[72:73]
	v_cndmask_b32_e64 v71, v127, 0, s[74:75]
	v_cvt_pk_bf16_f32 v109, v69, v71
	s_waitcnt vmcnt(2)
	v_cndmask_b32_e64 v69, v128, 0, s[12:13]
	v_cndmask_b32_e64 v71, 0, v129, s[78:79]
	ds_write_b64 v87, v[108:109]
	v_cvt_pk_bf16_f32 v108, v69, v71
	v_cndmask_b32_e64 v69, v130, 0, s[80:81]
	v_cndmask_b32_e64 v71, v131, 0, s[82:83]
	v_cvt_pk_bf16_f32 v109, v69, v71
	s_waitcnt vmcnt(1)
	v_cndmask_b32_e64 v69, v132, 0, s[84:85]
	v_cndmask_b32_e64 v71, 0, v133, s[86:87]
	ds_write_b64 v88, v[108:109]
	v_cvt_pk_bf16_f32 v108, v69, v71
	v_cndmask_b32_e64 v69, v134, 0, s[88:89]
	v_cndmask_b32_e64 v71, v135, 0, s[90:91]
	v_cvt_pk_bf16_f32 v109, v69, v71
	s_waitcnt vmcnt(0)
	v_cndmask_b32_e64 v69, v136, 0, s[92:93]
	v_cndmask_b32_e64 v71, 0, v137, s[94:95]
	ds_write_b64 v89, v[108:109]
	v_cvt_pk_bf16_f32 v108, v69, v71
	v_cndmask_b32_e64 v69, v138, 0, s[96:97]
	v_cndmask_b32_e64 v71, v139, 0, s[2:3]
	v_cvt_pk_bf16_f32 v109, v69, v71
	v_lshlrev_b32_e32 v69, 16, v42
	v_and_b32_e32 v42, 0xffff0000, v42
	v_add_f32_e32 v114, 0, v69
	v_lshlrev_b32_e32 v71, 16, v43
	v_add_f32_e32 v114, v114, v42
	v_and_b32_e32 v43, 0xffff0000, v43
	v_add_f32_e32 v114, v114, v71
	v_lshlrev_b32_e32 v107, 16, v44
	v_add_f32_e32 v114, v114, v43
	v_and_b32_e32 v44, 0xffff0000, v44
	v_add_f32_e32 v114, v114, v107
	ds_write_b64 v90, v[108:109]
	v_lshlrev_b32_e32 v108, 16, v45
	v_add_f32_e32 v114, v114, v44
	v_and_b32_e32 v45, 0xffff0000, v45
	v_add_f32_e32 v114, v114, v108
	v_lshlrev_b32_e32 v109, 16, v38
	v_add_f32_e32 v114, v114, v45
	v_and_b32_e32 v38, 0xffff0000, v38
	v_add_f32_e32 v114, v114, v109
	v_lshlrev_b32_e32 v110, 16, v39
	v_add_f32_e32 v114, v114, v38
	v_and_b32_e32 v111, 0xffff0000, v39
	v_add_f32_e32 v114, v114, v110
	v_lshlrev_b32_e32 v112, 16, v40
	v_add_f32_e32 v114, v114, v111
	v_and_b32_e32 v40, 0xffff0000, v40
	v_add_f32_e32 v114, v114, v112
	v_lshlrev_b32_e32 v113, 16, v41
	v_add_f32_e32 v114, v114, v40
	v_and_b32_e32 v41, 0xffff0000, v41
	v_add_f32_e32 v114, v114, v113
	v_add_f32_e32 v114, v114, v41
	v_mov_b32_e32 v39, 0
	s_nop 0
	v_add_f32_dpp v114, v114, v114 quad_perm:[1,0,3,2] row_mask:0xf bank_mask:0xf bound_ctrl:1
	s_nop 1
	v_add_f32_dpp v114, v114, v114 quad_perm:[2,3,0,1] row_mask:0xf bank_mask:0xf bound_ctrl:1
	v_fmac_f32_e32 v42, 0xbc800000, v114
	v_fmac_f32_e32 v69, 0xbc800000, v114
	v_mul_f32_e32 v115, v42, v42
	v_fmac_f32_e32 v115, v69, v69
	v_fmac_f32_e32 v71, 0xbc800000, v114
	v_fmac_f32_e32 v115, v71, v71
	v_fmac_f32_e32 v43, 0xbc800000, v114
	v_fmac_f32_e32 v115, v43, v43
	v_fmac_f32_e32 v107, 0xbc800000, v114
	v_fmac_f32_e32 v115, v107, v107
	v_fmac_f32_e32 v44, 0xbc800000, v114
	v_fmac_f32_e32 v115, v44, v44
	v_fmac_f32_e32 v108, 0xbc800000, v114
	v_fmac_f32_e32 v115, v108, v108
	v_fmac_f32_e32 v45, 0xbc800000, v114
	v_fmac_f32_e32 v115, v45, v45
	v_fmac_f32_e32 v109, 0xbc800000, v114
	v_fmac_f32_e32 v115, v109, v109
	v_fmac_f32_e32 v38, 0xbc800000, v114
	v_fmac_f32_e32 v115, v38, v38
	v_fmac_f32_e32 v110, 0xbc800000, v114
	v_fmac_f32_e32 v115, v110, v110
	v_fmac_f32_e32 v111, 0xbc800000, v114
	v_fmac_f32_e32 v115, v111, v111
	v_fmac_f32_e32 v112, 0xbc800000, v114
	v_fmac_f32_e32 v115, v112, v112
	v_fmac_f32_e32 v40, 0xbc800000, v114
	v_fmac_f32_e32 v115, v40, v40
	v_fmac_f32_e32 v113, 0xbc800000, v114
	v_fmac_f32_e32 v115, v113, v113
	v_fmac_f32_e32 v41, 0xbc800000, v114
	v_fmac_f32_e32 v115, v41, v41
	s_nop 1
	v_add_f32_dpp v114, v115, v115 quad_perm:[1,0,3,2] row_mask:0xf bank_mask:0xf bound_ctrl:1
	s_nop 1
	v_add_f32_dpp v114, v114, v114 quad_perm:[2,3,0,1] row_mask:0xf bank_mask:0xf bound_ctrl:1
	v_fmamk_f32 v114, v114, 0x3c800000, v216
	v_cmp_gt_f32_e64 s[4:5], s4, v114
	v_mul_f32_e32 v115, 0x4f800000, v114
	s_nop 0
	v_cndmask_b32_e64 v114, v114, v115, s[4:5]
	v_sqrt_f32_e32 v115, v114
	s_nop 0
	v_add_u32_e32 v116, -1, v115
	v_fma_f32 v117, -v116, v115, v114
	v_cmp_ge_f32_e32 vcc, 0, v117
	v_add_u32_e32 v117, 1, v115
	s_nop 0
	v_cndmask_b32_e32 v116, v115, v116, vcc
	v_fma_f32 v115, -v117, v115, v114
	v_cmp_lt_f32_e32 vcc, 0, v115
	s_nop 1
	v_cndmask_b32_e32 v115, v116, v117, vcc
	v_mul_f32_e32 v116, 0x37800000, v115
	v_cndmask_b32_e64 v115, v115, v116, s[4:5]
	v_cmp_class_f32_e32 vcc, v114, v217
	s_nop 1
	v_cndmask_b32_e32 v114, v115, v114, vcc
	v_div_scale_f32 v115, s[4:5], v114, v114, 1.0
	v_rcp_f32_e32 v116, v115
	s_nop 0
	v_fma_f32 v117, -v115, v116, 1.0
	v_fmac_f32_e32 v116, v117, v116
	v_div_scale_f32 v117, vcc, 1.0, v114, 1.0
	v_mul_f32_e32 v118, v117, v116
	v_fma_f32 v119, -v115, v118, v117
	v_fmac_f32_e32 v118, v119, v116
	v_fma_f32 v115, -v115, v118, v117
	v_div_fmas_f32 v115, v115, v116, v118
	v_div_fixup_f32 v114, v115, v114, 1.0
	v_mul_f32_e32 v69, v69, v114
	v_fma_f32 v30, v30, v69, v34
	v_bfe_u32 v34, v30, 16, 1
	v_add3_u32 v30, v30, v34, s33
	ds_write_b16_d16_hi v91, v30 offset:34816
	v_mul_f32_e32 v30, v42, v114
	v_fma_f32 v30, v31, v30, v35
	v_bfe_u32 v31, v30, 16, 1
	v_add3_u32 v30, v30, v31, s33
	ds_write_b16_d16_hi v91, v30 offset:35088
	v_mul_f32_e32 v30, v71, v114
	v_fma_f32 v30, v32, v30, v36
	v_bfe_u32 v31, v30, 16, 1
	v_add3_u32 v30, v30, v31, s33
	ds_write_b16_d16_hi v91, v30 offset:35360
	v_mul_f32_e32 v30, v43, v114
	v_fmac_f32_e32 v37, v33, v30
	v_bfe_u32 v30, v37, 16, 1
	v_add3_u32 v30, v37, v30, s33
	ds_write_b16_d16_hi v91, v30 offset:35632
	v_mul_f32_e32 v30, v107, v114
	v_fma_f32 v22, v22, v30, v26
	v_bfe_u32 v26, v22, 16, 1
	v_add3_u32 v22, v22, v26, s33
	ds_write_b16_d16_hi v91, v22 offset:35904
	v_mul_f32_e32 v22, v44, v114
	v_fma_f32 v22, v23, v22, v27
	v_bfe_u32 v23, v22, 16, 1
	v_add3_u32 v22, v22, v23, s33
	ds_write_b16_d16_hi v91, v22 offset:36176
	v_mul_f32_e32 v22, v108, v114
	v_fma_f32 v22, v24, v22, v28
	v_bfe_u32 v23, v22, 16, 1
	v_add3_u32 v22, v22, v23, s33
	ds_write_b16_d16_hi v91, v22 offset:36448
	v_mul_f32_e32 v22, v45, v114
	v_fmac_f32_e32 v29, v25, v22
	v_bfe_u32 v22, v29, 16, 1
	v_add3_u32 v22, v29, v22, s33
	ds_write_b16_d16_hi v91, v22 offset:36720
	v_mul_f32_e32 v22, v109, v114
	v_fma_f32 v14, v14, v22, v18
	v_bfe_u32 v18, v14, 16, 1
	v_add3_u32 v14, v14, v18, s33
	ds_write_b16_d16_hi v91, v14 offset:36992
	v_mul_f32_e32 v14, v38, v114
	v_fma_f32 v14, v15, v14, v19
	v_bfe_u32 v15, v14, 16, 1
	v_add3_u32 v14, v14, v15, s33
	ds_write_b16_d16_hi v91, v14 offset:37264
	v_mul_f32_e32 v14, v110, v114
	v_fma_f32 v14, v16, v14, v20
	v_bfe_u32 v15, v14, 16, 1
	v_add3_u32 v14, v14, v15, s33
	ds_write_b16_d16_hi v91, v14 offset:37536
	v_mul_f32_e32 v14, v111, v114
	v_fmac_f32_e32 v21, v17, v14
	v_bfe_u32 v14, v21, 16, 1
	v_add3_u32 v14, v21, v14, s33
	ds_write_b16_d16_hi v91, v14 offset:37808
	v_mul_f32_e32 v14, v112, v114
	v_fma_f32 v6, v6, v14, v10
	v_bfe_u32 v10, v6, 16, 1
	v_add3_u32 v6, v6, v10, s33
	ds_write_b16_d16_hi v91, v6 offset:38080
	v_mul_f32_e32 v6, v40, v114
	v_fma_f32 v6, v7, v6, v11
	v_bfe_u32 v7, v6, 16, 1
	v_add3_u32 v6, v6, v7, s33
	ds_write_b16_d16_hi v91, v6 offset:38352
	v_mul_f32_e32 v6, v113, v114
	v_fma_f32 v6, v8, v6, v12
	v_bfe_u32 v7, v6, 16, 1
	v_add3_u32 v6, v6, v7, s33
	ds_write_b16_d16_hi v91, v6 offset:38624
	v_mul_f32_e32 v6, v41, v114
	v_fmac_f32_e32 v13, v9, v6
	v_bfe_u32 v6, v13, 16, 1
	v_add3_u32 v6, v13, v6, s33
	ds_write_b16_d16_hi v91, v6 offset:38896
	s_waitcnt lgkmcnt(0)
	s_barrier
	s_andn2_b64 vcc, exec, s[28:29]
	v_mov_b32_e32 v38, v39
	v_mov_b32_e32 v37, v39
	v_mov_b32_e32 v36, v39
	v_mov_b32_e32 v17, v39
	v_mov_b32_e32 v16, v39
	v_mov_b32_e32 v15, v39
	v_mov_b32_e32 v14, v39
	v_mov_b32_e32 v13, v39
	v_mov_b32_e32 v12, v39
	v_mov_b32_e32 v11, v39
	v_mov_b32_e32 v10, v39
	v_mov_b32_e32 v9, v39
	v_mov_b32_e32 v8, v39
	v_mov_b32_e32 v7, v39
	v_mov_b32_e32 v6, v39
	s_cbranch_vccnz .LBB0_403
	v_mov_b32_e32 v6, 0
	v_mov_b32_e32 v18, v73
	v_mov_b32_e32 v19, v72
	v_readlane_b32 s4, v255, 32
	v_mov_b32_e32 v7, v6
	v_mov_b32_e32 v8, v6
	v_mov_b32_e32 v9, v6
	v_mov_b32_e32 v10, v6
	v_mov_b32_e32 v11, v6
	v_mov_b32_e32 v12, v6
	v_mov_b32_e32 v13, v6
	v_mov_b32_e32 v14, v6
	v_mov_b32_e32 v15, v6
	v_mov_b32_e32 v16, v6
	v_mov_b32_e32 v17, v6
	v_mov_b32_e32 v36, v6
	v_mov_b32_e32 v37, v6
	v_mov_b32_e32 v38, v6
	v_mov_b32_e32 v39, v6

.LBB0_410:
	s_or_b64 exec, exec, s[16:17]
	s_waitcnt lgkmcnt(0)
	s_barrier
	ds_read2st64_b32 v[120:121], v89 offset1:4
	ds_read2st64_b32 v[122:123], v89 offset0:8 offset1:12
	ds_read2st64_b32 v[72:73], v89 offset0:16 offset1:20
	ds_read2st64_b32 v[70:71], v89 offset0:24 offset1:28
	ds_read2st64_b32 v[68:69], v89 offset0:32 offset1:36
	ds_read2st64_b32 v[66:67], v89 offset0:40 offset1:44
	ds_read2st64_b32 v[64:65], v89 offset0:48 offset1:52
	ds_read2st64_b32 v[40:41], v89 offset0:56 offset1:60
	ds_read2st64_b32 v[38:39], v89 offset0:64 offset1:68
	ds_read2st64_b32 v[36:37], v89 offset0:72 offset1:76
	ds_read2st64_b32 v[34:35], v89 offset0:80 offset1:84
	s_waitcnt vmcnt(38)
	ds_read2st64_b32 v[32:33], v89 offset0:88 offset1:92
	ds_read2st64_b32 v[30:31], v89 offset0:96 offset1:100
	ds_read2st64_b32 v[28:29], v89 offset0:104 offset1:108
	ds_read2st64_b32 v[26:27], v89 offset0:112 offset1:116
	s_waitcnt vmcnt(36)
	ds_read2st64_b32 v[24:25], v89 offset0:120 offset1:124
	ds_read2st64_b32 v[22:23], v89 offset0:128 offset1:132
	ds_read2st64_b32 v[20:21], v89 offset0:136 offset1:140
	ds_read2st64_b32 v[18:19], v89 offset0:144 offset1:148
	s_waitcnt vmcnt(34)
	ds_read2st64_b32 v[16:17], v89 offset0:152 offset1:156
	ds_read2st64_b32 v[14:15], v89 offset0:160 offset1:164
	ds_read2st64_b32 v[12:13], v89 offset0:168 offset1:172
	ds_read2st64_b32 v[10:11], v89 offset0:176 offset1:180
	s_waitcnt vmcnt(2) lgkmcnt(14)
	v_fma_f32 v0, v55, v120, v117
	v_fma_f32 v57, v55, v121, v117
	v_fmac_f32_e32 v0, v53, v121
	v_fmac_f32_e32 v57, v53, v122
	v_fmac_f32_e32 v0, v51, v122
	v_fmac_f32_e32 v57, v51, v123
	v_fmac_f32_e32 v0, v49, v123
	v_fmac_f32_e32 v57, v49, v72
	v_fmac_f32_e32 v0, v94, v72
	v_fmac_f32_e32 v57, v94, v73
	v_fmac_f32_e32 v0, v93, v73
	v_fmac_f32_e32 v57, v93, v70
	v_fmac_f32_e32 v0, v92, v70
	v_fmac_f32_e32 v57, v92, v71
	v_fmac_f32_e32 v0, v63, v71
	v_fmac_f32_e32 v57, v63, v68
	v_fmac_f32_e32 v0, v98, v68
	v_fmac_f32_e32 v57, v98, v69
	v_fmac_f32_e32 v0, v97, v69
	v_fmac_f32_e32 v57, v97, v66
	v_fmac_f32_e32 v0, v96, v66
	v_fmac_f32_e32 v57, v96, v67
	v_fmac_f32_e32 v0, v95, v67
	v_fmac_f32_e32 v57, v95, v64
	v_fmac_f32_e32 v0, v106, v64
	v_fmac_f32_e32 v57, v106, v65
	v_fmac_f32_e32 v0, v105, v65
	v_fmac_f32_e32 v57, v105, v40
	v_fmac_f32_e32 v0, v104, v40
	v_fmac_f32_e32 v57, v104, v41
	v_fmac_f32_e32 v0, v103, v41
	v_fmac_f32_e32 v57, v103, v38
	v_fmac_f32_e32 v0, v102, v38
	v_fmac_f32_e32 v57, v102, v39
	v_fmac_f32_e32 v0, v101, v39
	s_waitcnt lgkmcnt(13)
	v_fmac_f32_e32 v57, v101, v36
	v_fmac_f32_e32 v0, v100, v36
	v_fmac_f32_e32 v57, v100, v37
	v_fmac_f32_e32 v0, v99, v37
	s_waitcnt lgkmcnt(12)
	v_fmac_f32_e32 v57, v99, v34
	v_fmac_f32_e32 v0, v107, v34
	v_fmac_f32_e32 v57, v107, v35
	v_fmac_f32_e32 v0, v110, v35
	s_waitcnt lgkmcnt(11)
	v_fmac_f32_e32 v57, v110, v32
	v_fmac_f32_e32 v0, v109, v32
	v_fmac_f32_e32 v57, v109, v33
	v_fmac_f32_e32 v0, v108, v33
	s_waitcnt lgkmcnt(10)
	v_fmac_f32_e32 v57, v108, v30
	v_fmac_f32_e32 v0, v114, v30
	v_fmac_f32_e32 v57, v114, v31
	v_fmac_f32_e32 v0, v113, v31
	s_waitcnt lgkmcnt(9)
	v_fmac_f32_e32 v57, v113, v28
	v_fmac_f32_e32 v0, v112, v28
	v_fmac_f32_e32 v57, v112, v29
	v_fmac_f32_e32 v0, v111, v29
	s_waitcnt lgkmcnt(8)
	v_fmac_f32_e32 v57, v111, v26
	v_fmac_f32_e32 v0, v118, v26
	v_fmac_f32_e32 v57, v118, v27
	v_fmac_f32_e32 v0, v116, v27
	s_waitcnt lgkmcnt(7)
	v_fmac_f32_e32 v57, v116, v24
	v_fmac_f32_e32 v0, v115, v24
	v_fmac_f32_e32 v57, v115, v25
	ds_write2st64_b32 v89, v0, v57 offset0:248 offset1:252
	v_fma_f32 v0, v55, v122, v117
	v_fma_f32 v57, v55, v123, v117
	v_fmac_f32_e32 v0, v53, v123
	v_fmac_f32_e32 v57, v53, v72
	v_fmac_f32_e32 v0, v51, v72
	v_fmac_f32_e32 v57, v51, v73
	v_fmac_f32_e32 v0, v49, v73
	v_fmac_f32_e32 v57, v49, v70
	v_fmac_f32_e32 v0, v94, v70
	v_fmac_f32_e32 v57, v94, v71
	v_fmac_f32_e32 v0, v93, v71
	v_fmac_f32_e32 v57, v93, v68
	v_fmac_f32_e32 v0, v92, v68
	v_fmac_f32_e32 v57, v92, v69
	v_fmac_f32_e32 v0, v63, v69
	v_fmac_f32_e32 v57, v63, v66
	v_fmac_f32_e32 v0, v98, v66
	v_fmac_f32_e32 v57, v98, v67
	v_fmac_f32_e32 v0, v97, v67
	v_fmac_f32_e32 v57, v97, v64
	v_fmac_f32_e32 v0, v96, v64
	v_fmac_f32_e32 v57, v96, v65
	v_fmac_f32_e32 v0, v95, v65
	v_fmac_f32_e32 v57, v95, v40
	v_fmac_f32_e32 v0, v106, v40
	v_fmac_f32_e32 v57, v106, v41
	v_fmac_f32_e32 v0, v105, v41
	v_fmac_f32_e32 v57, v105, v38
	v_fmac_f32_e32 v0, v104, v38
	v_fmac_f32_e32 v57, v104, v39
	v_fmac_f32_e32 v0, v103, v39
	v_fmac_f32_e32 v57, v103, v36
	v_fmac_f32_e32 v0, v102, v36
	v_fmac_f32_e32 v57, v102, v37
	v_fmac_f32_e32 v0, v101, v37
	v_fmac_f32_e32 v57, v101, v34
	v_fmac_f32_e32 v0, v100, v34
	v_fmac_f32_e32 v57, v100, v35
	v_fmac_f32_e32 v0, v99, v35
	v_fmac_f32_e32 v57, v99, v32
	v_fmac_f32_e32 v0, v107, v32
	v_fmac_f32_e32 v57, v107, v33
	v_fmac_f32_e32 v0, v110, v33
	v_fmac_f32_e32 v57, v110, v30
	v_fmac_f32_e32 v0, v109, v30
	v_fmac_f32_e32 v57, v109, v31
	v_fmac_f32_e32 v0, v108, v31
	v_fmac_f32_e32 v57, v108, v28
	v_fmac_f32_e32 v0, v114, v28
	v_fmac_f32_e32 v57, v114, v29
	v_fmac_f32_e32 v0, v113, v29
	v_fmac_f32_e32 v57, v113, v26
	v_fmac_f32_e32 v0, v112, v26
	v_fmac_f32_e32 v57, v112, v27
	v_fmac_f32_e32 v0, v111, v27
	v_fmac_f32_e32 v57, v111, v24
	v_fmac_f32_e32 v0, v118, v24
	v_fmac_f32_e32 v57, v118, v25
	v_fmac_f32_e32 v0, v116, v25
	s_waitcnt lgkmcnt(7)
	v_fmac_f32_e32 v57, v116, v22
	v_fmac_f32_e32 v0, v115, v22
	v_fmac_f32_e32 v57, v115, v23
	ds_write2st64_b32 v90, v0, v57 offset0:8 offset1:12
	v_fma_f32 v0, v55, v72, v117
	v_fma_f32 v57, v55, v73, v117
	v_fmac_f32_e32 v0, v53, v73
	v_fmac_f32_e32 v57, v53, v70
	v_fmac_f32_e32 v0, v51, v70
	v_fmac_f32_e32 v57, v51, v71
	v_fmac_f32_e32 v0, v49, v71
	v_fmac_f32_e32 v57, v49, v68
	v_fmac_f32_e32 v0, v94, v68
	v_fmac_f32_e32 v57, v94, v69
	v_fmac_f32_e32 v0, v93, v69
	v_fmac_f32_e32 v57, v93, v66
	v_fmac_f32_e32 v0, v92, v66
	v_fmac_f32_e32 v57, v92, v67
	v_fmac_f32_e32 v0, v63, v67
	v_fmac_f32_e32 v57, v63, v64
	v_fmac_f32_e32 v0, v98, v64
	v_fmac_f32_e32 v57, v98, v65
	v_fmac_f32_e32 v0, v97, v65
	v_fmac_f32_e32 v57, v97, v40
	v_fmac_f32_e32 v0, v96, v40
	v_fmac_f32_e32 v57, v96, v41
	v_fmac_f32_e32 v0, v95, v41
	v_fmac_f32_e32 v57, v95, v38
	v_fmac_f32_e32 v0, v106, v38
	v_fmac_f32_e32 v57, v106, v39
	v_fmac_f32_e32 v0, v105, v39
	v_fmac_f32_e32 v57, v105, v36
	v_fmac_f32_e32 v0, v104, v36
	v_fmac_f32_e32 v57, v104, v37
	v_fmac_f32_e32 v0, v103, v37
	v_fmac_f32_e32 v57, v103, v34
	v_fmac_f32_e32 v0, v102, v34
	v_fmac_f32_e32 v57, v102, v35
	v_fmac_f32_e32 v0, v101, v35
	v_fmac_f32_e32 v57, v101, v32
	v_fmac_f32_e32 v0, v100, v32
	v_fmac_f32_e32 v57, v100, v33
	v_fmac_f32_e32 v0, v99, v33
	v_fmac_f32_e32 v57, v99, v30
	v_fmac_f32_e32 v0, v107, v30
	v_fmac_f32_e32 v57, v107, v31
	v_fmac_f32_e32 v0, v110, v31
	v_fmac_f32_e32 v57, v110, v28
	v_fmac_f32_e32 v0, v109, v28
	v_fmac_f32_e32 v57, v109, v29
	v_fmac_f32_e32 v0, v108, v29
	v_fmac_f32_e32 v57, v108, v26
	v_fmac_f32_e32 v0, v114, v26
	v_fmac_f32_e32 v57, v114, v27
	v_fmac_f32_e32 v0, v113, v27
	v_fmac_f32_e32 v57, v113, v24
	v_fmac_f32_e32 v0, v112, v24
	v_fmac_f32_e32 v57, v112, v25
	v_fmac_f32_e32 v0, v111, v25
	v_fmac_f32_e32 v57, v111, v22
	v_fmac_f32_e32 v0, v118, v22
	v_fmac_f32_e32 v57, v118, v23
	v_fmac_f32_e32 v0, v116, v23
	s_waitcnt lgkmcnt(7)
	v_fmac_f32_e32 v57, v116, v20
	v_fmac_f32_e32 v0, v115, v20
	v_fmac_f32_e32 v57, v115, v21
	ds_write2st64_b32 v90, v0, v57 offset0:16 offset1:20
	v_fma_f32 v0, v55, v70, v117
	v_fma_f32 v57, v55, v71, v117
	v_fmac_f32_e32 v0, v53, v71
	v_fmac_f32_e32 v57, v53, v68
	v_fmac_f32_e32 v0, v51, v68
	v_fmac_f32_e32 v57, v51, v69
	v_fmac_f32_e32 v0, v49, v69
	v_fmac_f32_e32 v57, v49, v66
	v_fmac_f32_e32 v0, v94, v66
	v_fmac_f32_e32 v57, v94, v67
	v_fmac_f32_e32 v0, v93, v67
	v_fmac_f32_e32 v57, v93, v64
	v_fmac_f32_e32 v0, v92, v64
	v_fmac_f32_e32 v57, v92, v65
	v_fmac_f32_e32 v0, v63, v65
	v_fmac_f32_e32 v57, v63, v40
	v_fmac_f32_e32 v0, v98, v40
	v_fmac_f32_e32 v57, v98, v41
	v_fmac_f32_e32 v0, v97, v41
	v_fmac_f32_e32 v57, v97, v38
	v_fmac_f32_e32 v0, v96, v38
	v_fmac_f32_e32 v57, v96, v39
	v_fmac_f32_e32 v0, v95, v39
	v_fmac_f32_e32 v57, v95, v36
	v_fmac_f32_e32 v0, v106, v36
	v_fmac_f32_e32 v57, v106, v37
	v_fmac_f32_e32 v0, v105, v37
	v_fmac_f32_e32 v57, v105, v34
	v_fmac_f32_e32 v0, v104, v34
	v_fmac_f32_e32 v57, v104, v35
	v_fmac_f32_e32 v0, v103, v35
	v_fmac_f32_e32 v57, v103, v32
	v_fmac_f32_e32 v0, v102, v32
	v_fmac_f32_e32 v57, v102, v33
	v_fmac_f32_e32 v0, v101, v33
	v_fmac_f32_e32 v57, v101, v30
	v_fmac_f32_e32 v0, v100, v30
	v_fmac_f32_e32 v57, v100, v31
	v_fmac_f32_e32 v0, v99, v31
	v_fmac_f32_e32 v57, v99, v28
	v_fmac_f32_e32 v0, v107, v28
	v_fmac_f32_e32 v57, v107, v29
	v_fmac_f32_e32 v0, v110, v29
	v_fmac_f32_e32 v57, v110, v26
	v_fmac_f32_e32 v0, v109, v26
	v_fmac_f32_e32 v57, v109, v27
	v_fmac_f32_e32 v0, v108, v27
	v_fmac_f32_e32 v57, v108, v24
	v_fmac_f32_e32 v0, v114, v24
	v_fmac_f32_e32 v57, v114, v25
	v_fmac_f32_e32 v0, v113, v25
	v_fmac_f32_e32 v57, v113, v22
	v_fmac_f32_e32 v0, v112, v22
	v_fmac_f32_e32 v57, v112, v23
	v_fmac_f32_e32 v0, v111, v23
	v_fmac_f32_e32 v57, v111, v20
	v_fmac_f32_e32 v0, v118, v20
	v_fmac_f32_e32 v57, v118, v21
	v_fmac_f32_e32 v0, v116, v21
	s_waitcnt lgkmcnt(7)
	v_fmac_f32_e32 v57, v116, v18
	v_fmac_f32_e32 v0, v115, v18
	v_fmac_f32_e32 v57, v115, v19
	ds_write2st64_b32 v90, v0, v57 offset0:24 offset1:28
	v_fma_f32 v0, v55, v68, v117
	v_fma_f32 v57, v55, v69, v117
	v_fmac_f32_e32 v0, v53, v69
	v_fmac_f32_e32 v57, v53, v66
	v_fmac_f32_e32 v0, v51, v66
	v_fmac_f32_e32 v57, v51, v67
	v_fmac_f32_e32 v0, v49, v67
	v_fmac_f32_e32 v57, v49, v64
	v_fmac_f32_e32 v0, v94, v64
	v_fmac_f32_e32 v57, v94, v65
	v_fmac_f32_e32 v0, v93, v65
	v_fmac_f32_e32 v57, v93, v40
	v_fmac_f32_e32 v0, v92, v40
	v_fmac_f32_e32 v57, v92, v41
	v_fmac_f32_e32 v0, v63, v41
	v_fmac_f32_e32 v57, v63, v38
	v_fmac_f32_e32 v0, v98, v38
	v_fmac_f32_e32 v57, v98, v39
	v_fmac_f32_e32 v0, v97, v39
	v_fmac_f32_e32 v57, v97, v36
	v_fmac_f32_e32 v0, v96, v36
	v_fmac_f32_e32 v57, v96, v37
	v_fmac_f32_e32 v0, v95, v37
	v_fmac_f32_e32 v57, v95, v34
	v_fmac_f32_e32 v0, v106, v34
	v_fmac_f32_e32 v57, v106, v35
	v_fmac_f32_e32 v0, v105, v35
	v_fmac_f32_e32 v57, v105, v32
	v_fmac_f32_e32 v0, v104, v32
	v_fmac_f32_e32 v57, v104, v33
	v_fmac_f32_e32 v0, v103, v33
	v_fmac_f32_e32 v57, v103, v30
	v_fmac_f32_e32 v0, v102, v30
	v_fmac_f32_e32 v57, v102, v31
	v_fmac_f32_e32 v0, v101, v31
	v_fmac_f32_e32 v57, v101, v28
	v_fmac_f32_e32 v0, v100, v28
	v_fmac_f32_e32 v57, v100, v29
	v_fmac_f32_e32 v0, v99, v29
	v_fmac_f32_e32 v57, v99, v26
	v_fmac_f32_e32 v0, v107, v26
	v_fmac_f32_e32 v57, v107, v27
	v_fmac_f32_e32 v0, v110, v27
	v_fmac_f32_e32 v57, v110, v24
	v_fmac_f32_e32 v0, v109, v24
	v_fmac_f32_e32 v57, v109, v25
	v_fmac_f32_e32 v0, v108, v25
	v_fmac_f32_e32 v57, v108, v22
	v_fmac_f32_e32 v0, v114, v22
	v_fmac_f32_e32 v57, v114, v23
	v_fmac_f32_e32 v0, v113, v23
	v_fmac_f32_e32 v57, v113, v20
	v_fmac_f32_e32 v0, v112, v20
	v_fmac_f32_e32 v57, v112, v21
	v_fmac_f32_e32 v0, v111, v21
	v_fmac_f32_e32 v57, v111, v18
	v_fmac_f32_e32 v0, v118, v18
	v_fmac_f32_e32 v57, v118, v19
	v_fmac_f32_e32 v0, v116, v19
	s_waitcnt lgkmcnt(7)
	v_fmac_f32_e32 v57, v116, v16
	v_fmac_f32_e32 v0, v115, v16
	v_fmac_f32_e32 v57, v115, v17
	ds_write2st64_b32 v90, v0, v57 offset0:32 offset1:36
	v_fma_f32 v0, v55, v66, v117
	v_fma_f32 v57, v55, v67, v117
	v_fmac_f32_e32 v0, v53, v67
	v_fmac_f32_e32 v57, v53, v64
	v_fmac_f32_e32 v0, v51, v64
	v_fmac_f32_e32 v57, v51, v65
	v_fmac_f32_e32 v0, v49, v65
	v_fmac_f32_e32 v57, v49, v40
	v_fmac_f32_e32 v0, v94, v40
	v_fmac_f32_e32 v57, v94, v41
	v_fmac_f32_e32 v0, v93, v41
	v_fmac_f32_e32 v57, v93, v38
	v_fmac_f32_e32 v0, v92, v38
	v_fmac_f32_e32 v57, v92, v39
	v_fmac_f32_e32 v0, v63, v39
	v_fmac_f32_e32 v57, v63, v36
	v_fmac_f32_e32 v0, v98, v36
	v_fmac_f32_e32 v57, v98, v37
	v_fmac_f32_e32 v0, v97, v37
	v_fmac_f32_e32 v57, v97, v34
	v_fmac_f32_e32 v0, v96, v34
	v_fmac_f32_e32 v57, v96, v35
	v_fmac_f32_e32 v0, v95, v35
	v_fmac_f32_e32 v57, v95, v32
	v_fmac_f32_e32 v0, v106, v32
	v_fmac_f32_e32 v57, v106, v33
	v_fmac_f32_e32 v0, v105, v33
	v_fmac_f32_e32 v57, v105, v30
	v_fmac_f32_e32 v0, v104, v30
	v_fmac_f32_e32 v57, v104, v31
	v_fmac_f32_e32 v0, v103, v31
	v_fmac_f32_e32 v57, v103, v28
	v_fmac_f32_e32 v0, v102, v28
	v_fmac_f32_e32 v57, v102, v29
	v_fmac_f32_e32 v0, v101, v29
	v_fmac_f32_e32 v57, v101, v26
	v_fmac_f32_e32 v0, v100, v26
	v_fmac_f32_e32 v57, v100, v27
	v_fmac_f32_e32 v0, v99, v27
	v_fmac_f32_e32 v57, v99, v24
	v_fmac_f32_e32 v0, v107, v24
	v_fmac_f32_e32 v57, v107, v25
	v_fmac_f32_e32 v0, v110, v25
	v_fmac_f32_e32 v57, v110, v22
	v_fmac_f32_e32 v0, v109, v22
	v_fmac_f32_e32 v57, v109, v23
	v_fmac_f32_e32 v0, v108, v23
	v_fmac_f32_e32 v57, v108, v20
	v_fmac_f32_e32 v0, v114, v20
	v_fmac_f32_e32 v57, v114, v21
	v_fmac_f32_e32 v0, v113, v21
	v_fmac_f32_e32 v57, v113, v18
	v_fmac_f32_e32 v0, v112, v18
	v_fmac_f32_e32 v57, v112, v19
	v_fmac_f32_e32 v0, v111, v19
	v_fmac_f32_e32 v57, v111, v16
	v_fmac_f32_e32 v0, v118, v16
	v_fmac_f32_e32 v57, v118, v17
	v_fmac_f32_e32 v0, v116, v17
	s_waitcnt lgkmcnt(7)
	v_fmac_f32_e32 v57, v116, v14
	v_fmac_f32_e32 v0, v115, v14
	v_fmac_f32_e32 v57, v115, v15
	ds_write2st64_b32 v90, v0, v57 offset0:40 offset1:44
	v_fma_f32 v0, v55, v64, v117
	v_fma_f32 v57, v55, v65, v117
	v_fmac_f32_e32 v0, v53, v65
	v_fmac_f32_e32 v57, v53, v40
	v_fmac_f32_e32 v0, v51, v40
	v_fmac_f32_e32 v57, v51, v41
	v_fmac_f32_e32 v0, v49, v41
	v_fmac_f32_e32 v57, v49, v38
	v_fmac_f32_e32 v0, v94, v38
	v_fmac_f32_e32 v57, v94, v39
	v_fmac_f32_e32 v0, v93, v39
	v_fmac_f32_e32 v57, v93, v36
	v_fmac_f32_e32 v0, v92, v36
	v_fmac_f32_e32 v57, v92, v37
	v_fmac_f32_e32 v0, v63, v37
	v_fmac_f32_e32 v57, v63, v34
	v_fmac_f32_e32 v0, v98, v34
	v_fmac_f32_e32 v57, v98, v35
	v_fmac_f32_e32 v0, v97, v35
	v_fmac_f32_e32 v57, v97, v32
	v_fmac_f32_e32 v0, v96, v32
	v_fmac_f32_e32 v57, v96, v33
	v_fmac_f32_e32 v0, v95, v33
	v_fmac_f32_e32 v57, v95, v30
	v_fmac_f32_e32 v0, v106, v30
	v_fmac_f32_e32 v57, v106, v31
	v_fmac_f32_e32 v0, v105, v31
	v_fmac_f32_e32 v57, v105, v28
	v_fmac_f32_e32 v0, v104, v28
	v_fmac_f32_e32 v57, v104, v29
	v_fmac_f32_e32 v0, v103, v29
	v_fmac_f32_e32 v57, v103, v26
	v_fmac_f32_e32 v0, v102, v26
	v_fmac_f32_e32 v57, v102, v27
	v_fmac_f32_e32 v0, v101, v27
	v_fmac_f32_e32 v57, v101, v24
	v_fmac_f32_e32 v0, v100, v24
	v_fmac_f32_e32 v57, v100, v25
	v_fmac_f32_e32 v0, v99, v25
	v_fmac_f32_e32 v57, v99, v22
	v_fmac_f32_e32 v0, v107, v22
	v_fmac_f32_e32 v57, v107, v23
	v_fmac_f32_e32 v0, v110, v23
	v_fmac_f32_e32 v57, v110, v20
	v_fmac_f32_e32 v0, v109, v20
	v_fmac_f32_e32 v57, v109, v21
	v_fmac_f32_e32 v0, v108, v21
	v_fmac_f32_e32 v57, v108, v18
	v_fmac_f32_e32 v0, v114, v18
	v_fmac_f32_e32 v57, v114, v19
	v_fmac_f32_e32 v0, v113, v19
	v_fmac_f32_e32 v57, v113, v16
	v_fmac_f32_e32 v0, v112, v16
	v_fmac_f32_e32 v57, v112, v17
	v_fmac_f32_e32 v0, v111, v17
	v_fmac_f32_e32 v57, v111, v14
	v_fmac_f32_e32 v0, v118, v14
	v_fmac_f32_e32 v57, v118, v15
	v_fmac_f32_e32 v0, v116, v15
	s_waitcnt lgkmcnt(7)
	v_fmac_f32_e32 v57, v116, v12
	v_fmac_f32_e32 v0, v115, v12
	v_fmac_f32_e32 v57, v115, v13
	ds_write2st64_b32 v90, v0, v57 offset0:48 offset1:52
	v_fma_f32 v0, v55, v40, v117
	v_fmac_f32_e32 v117, v55, v41
	v_fmac_f32_e32 v0, v53, v41
	v_fmac_f32_e32 v117, v53, v38
	v_fmac_f32_e32 v0, v51, v38
	v_fmac_f32_e32 v117, v51, v39
	v_fmac_f32_e32 v0, v49, v39
	v_fmac_f32_e32 v117, v49, v36
	v_fmac_f32_e32 v0, v94, v36
	v_fmac_f32_e32 v117, v94, v37
	v_fmac_f32_e32 v0, v93, v37
	v_fmac_f32_e32 v117, v93, v34
	v_fmac_f32_e32 v0, v92, v34
	v_fmac_f32_e32 v117, v92, v35
	v_fmac_f32_e32 v0, v63, v35
	v_fmac_f32_e32 v117, v63, v32
	v_fmac_f32_e32 v0, v98, v32
	v_fmac_f32_e32 v117, v98, v33
	v_fmac_f32_e32 v0, v97, v33
	v_fmac_f32_e32 v117, v97, v30
	v_fmac_f32_e32 v0, v96, v30
	v_fmac_f32_e32 v117, v96, v31
	v_fmac_f32_e32 v0, v95, v31
	v_fmac_f32_e32 v117, v95, v28
	v_fmac_f32_e32 v0, v106, v28
	v_fmac_f32_e32 v117, v106, v29
	v_fmac_f32_e32 v0, v105, v29
	v_fmac_f32_e32 v117, v105, v26
	v_fmac_f32_e32 v0, v104, v26
	v_fmac_f32_e32 v117, v104, v27
	v_fmac_f32_e32 v0, v103, v27
	v_fmac_f32_e32 v117, v103, v24
	v_fmac_f32_e32 v0, v102, v24
	v_fmac_f32_e32 v117, v102, v25
	v_fmac_f32_e32 v0, v101, v25
	v_fmac_f32_e32 v117, v101, v22
	v_fmac_f32_e32 v0, v100, v22
	v_fmac_f32_e32 v117, v100, v23
	v_fmac_f32_e32 v0, v99, v23
	v_fmac_f32_e32 v117, v99, v20
	v_fmac_f32_e32 v0, v107, v20
	v_fmac_f32_e32 v117, v107, v21
	v_fmac_f32_e32 v0, v110, v21
	v_fmac_f32_e32 v117, v110, v18
	v_fmac_f32_e32 v0, v109, v18
	v_fmac_f32_e32 v117, v109, v19
	v_fmac_f32_e32 v0, v108, v19
	v_fmac_f32_e32 v117, v108, v16
	v_fmac_f32_e32 v0, v114, v16
	v_fmac_f32_e32 v117, v114, v17
	v_fmac_f32_e32 v0, v113, v17
	v_fmac_f32_e32 v117, v113, v14
	v_fmac_f32_e32 v0, v112, v14
	v_fmac_f32_e32 v117, v112, v15
	v_fmac_f32_e32 v0, v111, v15
	v_fmac_f32_e32 v117, v111, v12
	v_fmac_f32_e32 v0, v118, v12
	v_fmac_f32_e32 v117, v118, v13
	v_fmac_f32_e32 v0, v116, v13
	s_waitcnt lgkmcnt(7)
	v_fmac_f32_e32 v117, v116, v10
	v_fmac_f32_e32 v0, v115, v10
	v_fmac_f32_e32 v117, v115, v11
	ds_write2st64_b32 v90, v0, v117 offset0:56 offset1:60
	s_waitcnt lgkmcnt(0)
	s_barrier
	v_add_u32_e32 v0, s53, v91
	ds_read_b128 v[10:13], v0 offset:63488
	s_mov_b32 s16, 0xf800000
	s_lshl_b32 s0, s2, 11
	s_or_b32 s8, s0, s62
	s_mov_b32 s9, 0x42ce8ed0
	s_waitcnt lgkmcnt(0)
	v_mov_b32_e32 v14, v11
	v_mov_b32_e32 v15, v12
	v_mov_b32_e32 v16, v10
	v_mov_b32_e32 v17, v13
	v_pk_add_f32 v[14:15], v[14:15], v[16:17]
	s_mov_b32 s15, 0xc2b17218
	v_add_f32_e32 v0, v14, v15
	v_mov_b32_e32 v63, v1
	s_mov_b32 s17, 0x10f60000
	v_add_f32_dpp v0, v0, v0 quad_perm:[1,0,3,2] row_mask:0xf bank_mask:0xf bound_ctrl:1
	s_nop 1
	v_add_f32_dpp v0, v0, v0 quad_perm:[2,3,0,1] row_mask:0xf bank_mask:0xf bound_ctrl:1
	s_nop 1
	v_add_f32_dpp v0, v0, v0 row_half_mirror row_mask:0xf bank_mask:0xf bound_ctrl:1
	s_nop 1
	v_add_f32_dpp v0, v0, v0 row_mirror row_mask:0xf bank_mask:0xf bound_ctrl:1
	v_fmamk_f32 v11, v0, 0xbc800000, v11
	v_fmamk_f32 v10, v0, 0xbc800000, v10
	v_fmamk_f32 v13, v0, 0xbc800000, v13
	v_fmac_f32_e32 v12, 0xbc800000, v0
	v_pk_mul_f32 v[14:15], v[12:13], v[12:13]
	v_pk_mul_f32 v[16:17], v[10:11], v[10:11]
	s_nop 0
	v_pk_mov_b32 v[18:19], v[16:17], v[14:15] op_sel:[1,0]
	v_mov_b32_e32 v17, v15
	v_pk_add_f32 v[14:15], v[18:19], v[16:17]
	s_nop 0
	v_add_f32_e32 v0, v14, v15
	s_nop 1
	v_add_f32_dpp v0, v0, v0 quad_perm:[1,0,3,2] row_mask:0xf bank_mask:0xf bound_ctrl:1
	s_nop 1
	v_add_f32_dpp v0, v0, v0 quad_perm:[2,3,0,1] row_mask:0xf bank_mask:0xf bound_ctrl:1
	s_nop 1
	v_add_f32_dpp v0, v0, v0 row_half_mirror row_mask:0xf bank_mask:0xf bound_ctrl:1
	s_nop 1
	v_add_f32_dpp v0, v0, v0 row_mirror row_mask:0xf bank_mask:0xf bound_ctrl:1
	v_fmamk_f32 v0, v0, 0x3c800000, v216
	v_cmp_gt_f32_e32 vcc, s16, v0
	v_mul_f32_e32 v14, 0x4f800000, v0
	s_nop 0
	v_cndmask_b32_e32 v0, v0, v14, vcc
	v_sqrt_f32_e32 v14, v0
	s_nop 0
	v_add_u32_e32 v15, -1, v14
	v_fma_f32 v16, -v15, v14, v0
	v_cmp_ge_f32_e64 s[2:3], 0, v16
	v_add_u32_e32 v16, 1, v14
	s_nop 0
	v_cndmask_b32_e64 v15, v14, v15, s[2:3]
	v_fma_f32 v14, -v16, v14, v0
	v_cmp_lt_f32_e64 s[2:3], 0, v14
	s_nop 1
	v_cndmask_b32_e64 v14, v15, v16, s[2:3]
	v_mul_f32_e32 v15, 0x37800000, v14
	v_cndmask_b32_e32 v14, v14, v15, vcc
	v_cmp_class_f32_e32 vcc, v0, v217
	s_nop 1
	v_cndmask_b32_e32 v0, v14, v0, vcc
	v_div_scale_f32 v14, s[0:1], v0, v0, 1.0
	v_rcp_f32_e32 v15, v14
	s_nop 0
	v_fma_f32 v16, -v14, v15, 1.0
	v_fmac_f32_e32 v15, v16, v15
	v_div_scale_f32 v16, vcc, 1.0, v0, 1.0
	v_mul_f32_e32 v17, v16, v15
	v_fma_f32 v18, -v14, v17, v16
	v_fmac_f32_e32 v17, v18, v15
	v_fma_f32 v14, -v14, v17, v16
	v_div_fmas_f32 v14, v14, v15, v17
	v_div_fixup_f32 v0, v14, v0, 1.0
	v_pk_mul_f32 v[10:11], v[10:11], v[0:1] op_sel_hi:[1,0]
	v_pk_mul_f32 v[12:13], v[12:13], v[0:1] op_sel_hi:[1,0]
	s_waitcnt vmcnt(0)
	v_pk_fma_f32 v[10:11], v[2:3], v[10:11], v[6:7]
	v_pk_fma_f32 v[12:13], v[4:5], v[12:13], v[8:9]
	v_mul_f32_e32 v0, 0xbfb8aa3b, v10
	v_fma_f32 v14, v10, s34, -v0
	v_rndne_f32_e32 v15, v0
	v_fmac_f32_e32 v14, 0xb2a5705f, v10
	v_sub_f32_e32 v0, v0, v15
	v_add_f32_e32 v0, v0, v14
	v_exp_f32_e32 v0, v0
	v_cvt_i32_f32_e32 v14, v15
	v_cmp_nlt_f32_e32 vcc, s9, v10
	v_ldexp_f32 v0, v0, v14
	s_nop 0
	v_cndmask_b32_e32 v0, 0, v0, vcc
	v_cmp_ngt_f32_e32 vcc, s15, v10
	s_nop 1
	v_cndmask_b32_e32 v0, v219, v0, vcc
	v_add_f32_e32 v0, 1.0, v0
	v_div_scale_f32 v14, s[0:1], v0, v0, v10
	v_rcp_f32_e32 v15, v14
	s_nop 0
	v_fma_f32 v16, -v14, v15, 1.0
	v_fmac_f32_e32 v15, v16, v15
	v_div_scale_f32 v16, vcc, v10, v0, v10
	v_mul_f32_e32 v17, v16, v15
	v_fma_f32 v18, -v14, v17, v16
	v_fmac_f32_e32 v17, v18, v15
	v_fma_f32 v14, -v14, v17, v16
	v_div_fmas_f32 v14, v14, v15, v17
	v_div_fixup_f32 v0, v14, v0, v10
	v_mul_f32_e32 v10, 0xbfb8aa3b, v11
	v_fma_f32 v14, v11, s34, -v10
	v_rndne_f32_e32 v15, v10
	v_fmac_f32_e32 v14, 0xb2a5705f, v11
	v_sub_f32_e32 v10, v10, v15
	v_add_f32_e32 v10, v10, v14
	v_exp_f32_e32 v10, v10
	v_cvt_i32_f32_e32 v14, v15
	v_cmp_nlt_f32_e32 vcc, s9, v11
	v_ldexp_f32 v10, v10, v14
	s_nop 0
	v_cndmask_b32_e32 v10, 0, v10, vcc
	v_cmp_ngt_f32_e32 vcc, s15, v11
	s_nop 1
	v_cndmask_b32_e32 v10, v219, v10, vcc
	v_add_f32_e32 v10, 1.0, v10
	v_div_scale_f32 v14, s[0:1], v10, v10, v11
	v_rcp_f32_e32 v15, v14
	s_nop 0
	v_fma_f32 v16, -v14, v15, 1.0
	v_fmac_f32_e32 v15, v16, v15
	v_div_scale_f32 v16, vcc, v11, v10, v11
	v_mul_f32_e32 v17, v16, v15
	v_fma_f32 v18, -v14, v17, v16
	v_fmac_f32_e32 v17, v18, v15
	v_fma_f32 v14, -v14, v17, v16
	v_div_fmas_f32 v14, v14, v15, v17
	v_div_fixup_f32 v10, v14, v10, v11
	v_cvt_pk_bf16_f32 v10, v0, v10
	v_mul_f32_e32 v0, 0xbfb8aa3b, v12
	v_fma_f32 v11, v12, s34, -v0
	v_rndne_f32_e32 v14, v0
	v_fmac_f32_e32 v11, 0xb2a5705f, v12
	v_sub_f32_e32 v0, v0, v14
	v_add_f32_e32 v0, v0, v11
	v_exp_f32_e32 v0, v0
	v_cvt_i32_f32_e32 v11, v14
	v_cmp_nlt_f32_e32 vcc, s9, v12
	v_ldexp_f32 v0, v0, v11
	s_nop 0
	v_cndmask_b32_e32 v0, 0, v0, vcc
	v_cmp_ngt_f32_e32 vcc, s15, v12
	s_nop 1
	v_cndmask_b32_e32 v0, v219, v0, vcc
	v_add_f32_e32 v0, 1.0, v0
	v_div_scale_f32 v11, s[0:1], v0, v0, v12
	v_rcp_f32_e32 v14, v11
	s_nop 0
	v_fma_f32 v15, -v11, v14, 1.0
	v_fmac_f32_e32 v14, v15, v14
	v_div_scale_f32 v15, vcc, v12, v0, v12
	v_mul_f32_e32 v16, v15, v14
	v_fma_f32 v17, -v11, v16, v15
	v_fmac_f32_e32 v16, v17, v14
	v_fma_f32 v11, -v11, v16, v15
	v_div_fmas_f32 v11, v11, v14, v16
	v_div_fixup_f32 v0, v11, v0, v12
	v_mul_f32_e32 v11, 0xbfb8aa3b, v13
	v_fma_f32 v12, v13, s34, -v11
	v_rndne_f32_e32 v14, v11
	v_fmac_f32_e32 v12, 0xb2a5705f, v13
	v_sub_f32_e32 v11, v11, v14
	v_add_f32_e32 v11, v11, v12
	v_exp_f32_e32 v11, v11
	v_cvt_i32_f32_e32 v12, v14
	v_cmp_nlt_f32_e32 vcc, s9, v13
	v_ldexp_f32 v11, v11, v12
	s_nop 0
	v_cndmask_b32_e32 v11, 0, v11, vcc
	v_cmp_ngt_f32_e32 vcc, s15, v13
	s_nop 1
	v_cndmask_b32_e32 v11, v219, v11, vcc
	v_add_f32_e32 v11, 1.0, v11
	v_div_scale_f32 v12, s[0:1], v11, v11, v13
	v_rcp_f32_e32 v14, v12
	s_add_i32 s0, s8, s52
	s_ashr_i32 s1, s0, 31
	s_lshl_b64 s[0:1], s[0:1], 11
	v_fma_f32 v15, -v12, v14, 1.0
	v_fmac_f32_e32 v14, v15, v14
	v_div_scale_f32 v15, vcc, v13, v11, v13
	v_mul_f32_e32 v16, v15, v14
	v_fma_f32 v17, -v12, v16, v15
	v_fmac_f32_e32 v16, v17, v14
	v_fma_f32 v12, -v12, v16, v15
	v_div_fmas_f32 v12, v12, v14, v16
	v_div_fixup_f32 v11, v12, v11, v13
	s_add_u32 s0, s6, s0
	s_addc_u32 s1, s7, s1
	v_lshl_add_u64 v[12:13], s[0:1], 0, v[62:63]
	v_add_co_u32_e32 v12, vcc, s17, v12
	v_cvt_pk_bf16_f32 v11, v0, v11
	s_nop 0
	v_addc_co_u32_e32 v13, vcc, 0, v13, vcc
	v_add_u32_e32 v0, s55, v91
	global_store_dwordx2 v[12:13], v[10:11], off offset:1536
	ds_read_b128 v[10:13], v0 offset:63488
	s_waitcnt lgkmcnt(0)
	v_mov_b32_e32 v14, v11
	v_mov_b32_e32 v15, v12
	v_mov_b32_e32 v16, v10
	v_mov_b32_e32 v17, v13
	v_pk_add_f32 v[14:15], v[14:15], v[16:17]
	s_nop 0
	v_add_f32_e32 v0, v14, v15
	s_nop 1
	v_add_f32_dpp v0, v0, v0 quad_perm:[1,0,3,2] row_mask:0xf bank_mask:0xf bound_ctrl:1
	s_nop 1
	v_add_f32_dpp v0, v0, v0 quad_perm:[2,3,0,1] row_mask:0xf bank_mask:0xf bound_ctrl:1
	s_nop 1
	v_add_f32_dpp v0, v0, v0 row_half_mirror row_mask:0xf bank_mask:0xf bound_ctrl:1
	s_nop 1
	v_add_f32_dpp v0, v0, v0 row_mirror row_mask:0xf bank_mask:0xf bound_ctrl:1
	v_fmamk_f32 v11, v0, 0xbc800000, v11
	v_fmamk_f32 v10, v0, 0xbc800000, v10
	v_fmamk_f32 v13, v0, 0xbc800000, v13
	v_fmac_f32_e32 v12, 0xbc800000, v0
	v_pk_mul_f32 v[14:15], v[12:13], v[12:13]
	v_pk_mul_f32 v[16:17], v[10:11], v[10:11]
	s_nop 0
	v_pk_mov_b32 v[18:19], v[16:17], v[14:15] op_sel:[1,0]
	v_mov_b32_e32 v17, v15
	v_pk_add_f32 v[14:15], v[18:19], v[16:17]
	s_nop 0
	v_add_f32_e32 v0, v14, v15
	s_nop 1
	v_add_f32_dpp v0, v0, v0 quad_perm:[1,0,3,2] row_mask:0xf bank_mask:0xf bound_ctrl:1
	s_nop 1
	v_add_f32_dpp v0, v0, v0 quad_perm:[2,3,0,1] row_mask:0xf bank_mask:0xf bound_ctrl:1
	s_nop 1
	v_add_f32_dpp v0, v0, v0 row_half_mirror row_mask:0xf bank_mask:0xf bound_ctrl:1
	s_nop 1
	v_add_f32_dpp v0, v0, v0 row_mirror row_mask:0xf bank_mask:0xf bound_ctrl:1
	v_fmamk_f32 v0, v0, 0x3c800000, v216
	v_cmp_gt_f32_e32 vcc, s16, v0
	v_mul_f32_e32 v14, 0x4f800000, v0
	s_nop 0
	v_cndmask_b32_e32 v0, v0, v14, vcc
	v_sqrt_f32_e32 v14, v0
	s_nop 0
	v_add_u32_e32 v15, -1, v14
	v_fma_f32 v16, -v15, v14, v0
	v_cmp_ge_f32_e64 s[2:3], 0, v16
	v_add_u32_e32 v16, 1, v14
	s_nop 0
	v_cndmask_b32_e64 v15, v14, v15, s[2:3]
	v_fma_f32 v14, -v16, v14, v0
	v_cmp_lt_f32_e64 s[2:3], 0, v14
	s_nop 1
	v_cndmask_b32_e64 v14, v15, v16, s[2:3]
	v_mul_f32_e32 v15, 0x37800000, v14
	v_cndmask_b32_e32 v14, v14, v15, vcc
	v_cmp_class_f32_e32 vcc, v0, v217
	s_nop 1
	v_cndmask_b32_e32 v0, v14, v0, vcc
	v_div_scale_f32 v14, s[0:1], v0, v0, 1.0
	v_rcp_f32_e32 v15, v14
	s_nop 0
	v_fma_f32 v16, -v14, v15, 1.0
	v_fmac_f32_e32 v15, v16, v15
	v_div_scale_f32 v16, vcc, 1.0, v0, 1.0
	v_mul_f32_e32 v17, v16, v15
	v_fma_f32 v18, -v14, v17, v16
	v_fmac_f32_e32 v17, v18, v15
	v_fma_f32 v14, -v14, v17, v16
	v_div_fmas_f32 v14, v14, v15, v17
	v_div_fixup_f32 v0, v14, v0, 1.0
	v_pk_mul_f32 v[14:15], v[10:11], v[0:1] op_sel_hi:[1,0]
	v_pk_mul_f32 v[10:11], v[12:13], v[0:1] op_sel_hi:[1,0]
	v_pk_fma_f32 v[12:13], v[2:3], v[14:15], v[6:7]
	v_pk_fma_f32 v[10:11], v[4:5], v[10:11], v[8:9]
	v_mul_f32_e32 v0, 0xbfb8aa3b, v12
	v_fma_f32 v14, v12, s34, -v0
	v_rndne_f32_e32 v15, v0
	v_fmac_f32_e32 v14, 0xb2a5705f, v12
	v_sub_f32_e32 v0, v0, v15
	v_add_f32_e32 v0, v0, v14
	v_exp_f32_e32 v0, v0
	v_cvt_i32_f32_e32 v14, v15
	v_cmp_nlt_f32_e32 vcc, s9, v12
	v_ldexp_f32 v0, v0, v14
	s_nop 0
	v_cndmask_b32_e32 v0, 0, v0, vcc
	v_cmp_ngt_f32_e32 vcc, s15, v12
	s_nop 1
	v_cndmask_b32_e32 v0, v219, v0, vcc
	v_add_f32_e32 v0, 1.0, v0
	v_div_scale_f32 v14, s[0:1], v0, v0, v12
	v_rcp_f32_e32 v15, v14
	s_nop 0
	v_fma_f32 v16, -v14, v15, 1.0
	v_fmac_f32_e32 v15, v16, v15
	v_div_scale_f32 v16, vcc, v12, v0, v12
	v_mul_f32_e32 v17, v16, v15
	v_fma_f32 v18, -v14, v17, v16
	v_fmac_f32_e32 v17, v18, v15
	v_fma_f32 v14, -v14, v17, v16
	v_div_fmas_f32 v14, v14, v15, v17
	v_div_fixup_f32 v0, v14, v0, v12
	v_mul_f32_e32 v12, 0xbfb8aa3b, v13
	v_fma_f32 v14, v13, s34, -v12
	v_rndne_f32_e32 v15, v12
	v_fmac_f32_e32 v14, 0xb2a5705f, v13
	v_sub_f32_e32 v12, v12, v15
	v_add_f32_e32 v12, v12, v14
	v_exp_f32_e32 v12, v12
	v_cvt_i32_f32_e32 v14, v15
	v_cmp_nlt_f32_e32 vcc, s9, v13
	v_ldexp_f32 v12, v12, v14
	s_nop 0
	v_cndmask_b32_e32 v12, 0, v12, vcc
	v_cmp_ngt_f32_e32 vcc, s15, v13
	s_nop 1
	v_cndmask_b32_e32 v12, v219, v12, vcc
	v_add_f32_e32 v12, 1.0, v12
	v_div_scale_f32 v14, s[0:1], v12, v12, v13
	v_rcp_f32_e32 v15, v14
	s_nop 0
	v_fma_f32 v16, -v14, v15, 1.0
	v_fmac_f32_e32 v15, v16, v15
	v_div_scale_f32 v16, vcc, v13, v12, v13
	v_mul_f32_e32 v17, v16, v15
	v_fma_f32 v18, -v14, v17, v16
	v_fmac_f32_e32 v17, v18, v15
	v_fma_f32 v14, -v14, v17, v16
	v_div_fmas_f32 v14, v14, v15, v17
	v_div_fixup_f32 v12, v14, v12, v13
	v_cvt_pk_bf16_f32 v12, v0, v12
	v_mul_f32_e32 v0, 0xbfb8aa3b, v10
	v_fma_f32 v13, v10, s34, -v0
	v_rndne_f32_e32 v14, v0
	v_fmac_f32_e32 v13, 0xb2a5705f, v10
	v_sub_f32_e32 v0, v0, v14
	v_add_f32_e32 v0, v0, v13
	v_exp_f32_e32 v0, v0
	v_cvt_i32_f32_e32 v13, v14
	v_cmp_nlt_f32_e32 vcc, s9, v10
	v_ldexp_f32 v0, v0, v13
	s_nop 0
	v_cndmask_b32_e32 v0, 0, v0, vcc
	v_cmp_ngt_f32_e32 vcc, s15, v10
	s_nop 1
	v_cndmask_b32_e32 v0, v219, v0, vcc
	v_add_f32_e32 v0, 1.0, v0
	v_div_scale_f32 v13, s[0:1], v0, v0, v10
	v_rcp_f32_e32 v14, v13
	s_nop 0
	v_fma_f32 v15, -v13, v14, 1.0
	v_fmac_f32_e32 v14, v15, v14
	v_div_scale_f32 v15, vcc, v10, v0, v10
	v_mul_f32_e32 v16, v15, v14
	v_fma_f32 v17, -v13, v16, v15
	v_fmac_f32_e32 v16, v17, v14
	v_fma_f32 v13, -v13, v16, v15
	v_div_fmas_f32 v13, v13, v14, v16
	v_div_fixup_f32 v0, v13, v0, v10
	v_mul_f32_e32 v10, 0xbfb8aa3b, v11
	v_fma_f32 v13, v11, s34, -v10
	v_rndne_f32_e32 v14, v10
	v_fmac_f32_e32 v13, 0xb2a5705f, v11
	v_sub_f32_e32 v10, v10, v14
	v_add_f32_e32 v10, v10, v13
	v_exp_f32_e32 v10, v10
	v_cvt_i32_f32_e32 v13, v14
	v_cmp_nlt_f32_e32 vcc, s9, v11
	v_ldexp_f32 v10, v10, v13
	s_nop 0
	v_cndmask_b32_e32 v10, 0, v10, vcc
	v_cmp_ngt_f32_e32 vcc, s15, v11
	s_nop 1
	v_cndmask_b32_e32 v10, v219, v10, vcc
	v_add_f32_e32 v10, 1.0, v10
	v_div_scale_f32 v13, s[0:1], v10, v10, v11
	v_rcp_f32_e32 v14, v13
	s_add_i32 s0, s8, s54
	s_ashr_i32 s1, s0, 31
	s_lshl_b64 s[0:1], s[0:1], 11
	v_fma_f32 v15, -v13, v14, 1.0
	v_fmac_f32_e32 v14, v15, v14
	v_div_scale_f32 v15, vcc, v11, v10, v11
	v_mul_f32_e32 v16, v15, v14
	v_fma_f32 v17, -v13, v16, v15
	v_fmac_f32_e32 v16, v17, v14
	v_fma_f32 v13, -v13, v16, v15
	v_div_fmas_f32 v13, v13, v14, v16
	v_div_fixup_f32 v10, v13, v10, v11
	s_add_u32 s0, s6, s0
	s_addc_u32 s1, s7, s1
	v_cvt_pk_bf16_f32 v13, v0, v10
	v_lshl_add_u64 v[10:11], s[0:1], 0, v[62:63]
	v_add_co_u32_e32 v10, vcc, s17, v10
	v_add_u32_e32 v0, s57, v91
	s_nop 0
	v_addc_co_u32_e32 v11, vcc, 0, v11, vcc
	global_store_dwordx2 v[10:11], v[12:13], off offset:1536
	ds_read_b128 v[10:13], v0 offset:63488
	s_waitcnt lgkmcnt(0)
	v_mov_b32_e32 v14, v11
	v_mov_b32_e32 v15, v12
	v_mov_b32_e32 v16, v10
	v_mov_b32_e32 v17, v13
	v_pk_add_f32 v[14:15], v[14:15], v[16:17]
	s_nop 0
	v_add_f32_e32 v0, v14, v15
	s_nop 1
	v_add_f32_dpp v0, v0, v0 quad_perm:[1,0,3,2] row_mask:0xf bank_mask:0xf bound_ctrl:1
	s_nop 1
	v_add_f32_dpp v0, v0, v0 quad_perm:[2,3,0,1] row_mask:0xf bank_mask:0xf bound_ctrl:1
	s_nop 1
	v_add_f32_dpp v0, v0, v0 row_half_mirror row_mask:0xf bank_mask:0xf bound_ctrl:1
	s_nop 1
	v_add_f32_dpp v0, v0, v0 row_mirror row_mask:0xf bank_mask:0xf bound_ctrl:1
	v_fmamk_f32 v11, v0, 0xbc800000, v11
	v_fmamk_f32 v10, v0, 0xbc800000, v10
	v_fmamk_f32 v13, v0, 0xbc800000, v13
	v_fmac_f32_e32 v12, 0xbc800000, v0
	v_pk_mul_f32 v[14:15], v[12:13], v[12:13]
	v_pk_mul_f32 v[16:17], v[10:11], v[10:11]
	s_nop 0
	v_pk_mov_b32 v[18:19], v[16:17], v[14:15] op_sel:[1,0]
	v_mov_b32_e32 v17, v15
	v_pk_add_f32 v[14:15], v[18:19], v[16:17]
	s_nop 0
	v_add_f32_e32 v0, v14, v15
	s_nop 1
	v_add_f32_dpp v0, v0, v0 quad_perm:[1,0,3,2] row_mask:0xf bank_mask:0xf bound_ctrl:1
	s_nop 1
	v_add_f32_dpp v0, v0, v0 quad_perm:[2,3,0,1] row_mask:0xf bank_mask:0xf bound_ctrl:1
	s_nop 1
	v_add_f32_dpp v0, v0, v0 row_half_mirror row_mask:0xf bank_mask:0xf bound_ctrl:1
	s_nop 1
	v_add_f32_dpp v0, v0, v0 row_mirror row_mask:0xf bank_mask:0xf bound_ctrl:1
	v_fmamk_f32 v0, v0, 0x3c800000, v216
	v_cmp_gt_f32_e32 vcc, s16, v0
	v_mul_f32_e32 v14, 0x4f800000, v0
	s_nop 0
	v_cndmask_b32_e32 v0, v0, v14, vcc
	v_sqrt_f32_e32 v14, v0
	s_nop 0
	v_add_u32_e32 v15, -1, v14
	v_fma_f32 v16, -v15, v14, v0
	v_cmp_ge_f32_e64 s[2:3], 0, v16
	v_add_u32_e32 v16, 1, v14
	s_nop 0
	v_cndmask_b32_e64 v15, v14, v15, s[2:3]
	v_fma_f32 v14, -v16, v14, v0
	v_cmp_lt_f32_e64 s[2:3], 0, v14
	s_nop 1
	v_cndmask_b32_e64 v14, v15, v16, s[2:3]
	v_mul_f32_e32 v15, 0x37800000, v14
	v_cndmask_b32_e32 v14, v14, v15, vcc
	v_cmp_class_f32_e32 vcc, v0, v217
	s_nop 1
	v_cndmask_b32_e32 v0, v14, v0, vcc
	v_div_scale_f32 v14, s[0:1], v0, v0, 1.0
	v_rcp_f32_e32 v15, v14
	s_nop 0
	v_fma_f32 v16, -v14, v15, 1.0
	v_fmac_f32_e32 v15, v16, v15
	v_div_scale_f32 v16, vcc, 1.0, v0, 1.0
	v_mul_f32_e32 v17, v16, v15
	v_fma_f32 v18, -v14, v17, v16
	v_fmac_f32_e32 v17, v18, v15
	v_fma_f32 v14, -v14, v17, v16
	v_div_fmas_f32 v14, v14, v15, v17
	v_div_fixup_f32 v0, v14, v0, 1.0
	v_pk_mul_f32 v[10:11], v[10:11], v[0:1] op_sel_hi:[1,0]
	v_pk_mul_f32 v[12:13], v[12:13], v[0:1] op_sel_hi:[1,0]
	v_pk_fma_f32 v[10:11], v[2:3], v[10:11], v[6:7]
	v_pk_fma_f32 v[12:13], v[4:5], v[12:13], v[8:9]
	v_mul_f32_e32 v0, 0xbfb8aa3b, v10
	v_fma_f32 v14, v10, s34, -v0
	v_rndne_f32_e32 v15, v0
	v_fmac_f32_e32 v14, 0xb2a5705f, v10
	v_sub_f32_e32 v0, v0, v15
	v_add_f32_e32 v0, v0, v14
	v_exp_f32_e32 v0, v0
	v_cvt_i32_f32_e32 v14, v15
	v_cmp_nlt_f32_e32 vcc, s9, v10
	v_ldexp_f32 v0, v0, v14
	s_nop 0
	v_cndmask_b32_e32 v0, 0, v0, vcc
	v_cmp_ngt_f32_e32 vcc, s15, v10
	s_nop 1
	v_cndmask_b32_e32 v0, v219, v0, vcc
	v_add_f32_e32 v0, 1.0, v0
	v_div_scale_f32 v14, s[0:1], v0, v0, v10
	v_rcp_f32_e32 v15, v14
	s_nop 0
	v_fma_f32 v16, -v14, v15, 1.0
	v_fmac_f32_e32 v15, v16, v15
	v_div_scale_f32 v16, vcc, v10, v0, v10
	v_mul_f32_e32 v17, v16, v15
	v_fma_f32 v18, -v14, v17, v16
	v_fmac_f32_e32 v17, v18, v15
	v_fma_f32 v14, -v14, v17, v16
	v_div_fmas_f32 v14, v14, v15, v17
	v_div_fixup_f32 v0, v14, v0, v10
	v_mul_f32_e32 v10, 0xbfb8aa3b, v11
	v_fma_f32 v14, v11, s34, -v10
	v_rndne_f32_e32 v15, v10
	v_fmac_f32_e32 v14, 0xb2a5705f, v11
	v_sub_f32_e32 v10, v10, v15
	v_add_f32_e32 v10, v10, v14
	v_exp_f32_e32 v10, v10
	v_cvt_i32_f32_e32 v14, v15
	v_cmp_nlt_f32_e32 vcc, s9, v11
	v_ldexp_f32 v10, v10, v14
	s_nop 0
	v_cndmask_b32_e32 v10, 0, v10, vcc
	v_cmp_ngt_f32_e32 vcc, s15, v11
	s_nop 1
	v_cndmask_b32_e32 v10, v219, v10, vcc
	v_add_f32_e32 v10, 1.0, v10
	v_div_scale_f32 v14, s[0:1], v10, v10, v11
	v_rcp_f32_e32 v15, v14
	s_nop 0
	v_fma_f32 v16, -v14, v15, 1.0
	v_fmac_f32_e32 v15, v16, v15
	v_div_scale_f32 v16, vcc, v11, v10, v11
	v_mul_f32_e32 v17, v16, v15
	v_fma_f32 v18, -v14, v17, v16
	v_fmac_f32_e32 v17, v18, v15
	v_fma_f32 v14, -v14, v17, v16
	v_div_fmas_f32 v14, v14, v15, v17
	v_div_fixup_f32 v10, v14, v10, v11
	v_cvt_pk_bf16_f32 v10, v0, v10
	v_mul_f32_e32 v0, 0xbfb8aa3b, v12
	v_fma_f32 v11, v12, s34, -v0
	v_rndne_f32_e32 v14, v0
	v_fmac_f32_e32 v11, 0xb2a5705f, v12
	v_sub_f32_e32 v0, v0, v14
	v_add_f32_e32 v0, v0, v11
	v_exp_f32_e32 v0, v0
	v_cvt_i32_f32_e32 v11, v14
	v_cmp_nlt_f32_e32 vcc, s9, v12
	v_ldexp_f32 v0, v0, v11
	s_nop 0
	v_cndmask_b32_e32 v0, 0, v0, vcc
	v_cmp_ngt_f32_e32 vcc, s15, v12
	s_nop 1
	v_cndmask_b32_e32 v0, v219, v0, vcc
	v_add_f32_e32 v0, 1.0, v0
	v_div_scale_f32 v11, s[0:1], v0, v0, v12
	v_rcp_f32_e32 v14, v11
	s_nop 0
	v_fma_f32 v15, -v11, v14, 1.0
	v_fmac_f32_e32 v14, v15, v14
	v_div_scale_f32 v15, vcc, v12, v0, v12
	v_mul_f32_e32 v16, v15, v14
	v_fma_f32 v17, -v11, v16, v15
	v_fmac_f32_e32 v16, v17, v14
	v_fma_f32 v11, -v11, v16, v15
	v_div_fmas_f32 v11, v11, v14, v16
	v_div_fixup_f32 v0, v11, v0, v12
	v_mul_f32_e32 v11, 0xbfb8aa3b, v13
	v_fma_f32 v12, v13, s34, -v11
	v_rndne_f32_e32 v14, v11
	v_fmac_f32_e32 v12, 0xb2a5705f, v13
	v_sub_f32_e32 v11, v11, v14
	v_add_f32_e32 v11, v11, v12
	v_exp_f32_e32 v11, v11
	v_cvt_i32_f32_e32 v12, v14
	v_cmp_nlt_f32_e32 vcc, s9, v13
	v_ldexp_f32 v11, v11, v12
	s_nop 0
	v_cndmask_b32_e32 v11, 0, v11, vcc
	v_cmp_ngt_f32_e32 vcc, s15, v13
	s_nop 1
	v_cndmask_b32_e32 v11, v219, v11, vcc
	v_add_f32_e32 v11, 1.0, v11
	v_div_scale_f32 v12, s[0:1], v11, v11, v13
	v_rcp_f32_e32 v14, v12
	s_add_i32 s0, s8, s56
	s_ashr_i32 s1, s0, 31
	s_lshl_b64 s[0:1], s[0:1], 11
	v_fma_f32 v15, -v12, v14, 1.0
	v_fmac_f32_e32 v14, v15, v14
	v_div_scale_f32 v15, vcc, v13, v11, v13
	v_mul_f32_e32 v16, v15, v14
	v_fma_f32 v17, -v12, v16, v15
	v_fmac_f32_e32 v16, v17, v14
	v_fma_f32 v12, -v12, v16, v15
	v_div_fmas_f32 v12, v12, v14, v16
	v_div_fixup_f32 v11, v12, v11, v13
	s_add_u32 s0, s6, s0
	s_addc_u32 s1, s7, s1
	v_lshl_add_u64 v[12:13], s[0:1], 0, v[62:63]
	v_add_co_u32_e32 v12, vcc, s17, v12
	v_cvt_pk_bf16_f32 v11, v0, v11
	s_nop 0
	v_addc_co_u32_e32 v13, vcc, 0, v13, vcc
	v_add_u32_e32 v0, s59, v91
	global_store_dwordx2 v[12:13], v[10:11], off offset:1536
	ds_read_b128 v[10:13], v0 offset:63488
	s_waitcnt lgkmcnt(0)
	v_mov_b32_e32 v14, v11
	v_mov_b32_e32 v15, v12
	v_mov_b32_e32 v16, v10
	v_mov_b32_e32 v17, v13
	v_pk_add_f32 v[14:15], v[14:15], v[16:17]
	s_nop 0
	v_add_f32_e32 v0, v14, v15
	s_nop 1
	v_add_f32_dpp v0, v0, v0 quad_perm:[1,0,3,2] row_mask:0xf bank_mask:0xf bound_ctrl:1
	s_nop 1
	v_add_f32_dpp v0, v0, v0 quad_perm:[2,3,0,1] row_mask:0xf bank_mask:0xf bound_ctrl:1
	s_nop 1
	v_add_f32_dpp v0, v0, v0 row_half_mirror row_mask:0xf bank_mask:0xf bound_ctrl:1
	s_nop 1
	v_add_f32_dpp v0, v0, v0 row_mirror row_mask:0xf bank_mask:0xf bound_ctrl:1
	v_fmamk_f32 v11, v0, 0xbc800000, v11
	v_fmamk_f32 v10, v0, 0xbc800000, v10
	v_fmamk_f32 v13, v0, 0xbc800000, v13
	v_fmac_f32_e32 v12, 0xbc800000, v0
	v_pk_mul_f32 v[14:15], v[12:13], v[12:13]
	v_pk_mul_f32 v[16:17], v[10:11], v[10:11]
	s_nop 0
	v_pk_mov_b32 v[18:19], v[16:17], v[14:15] op_sel:[1,0]
	v_mov_b32_e32 v17, v15
	v_pk_add_f32 v[14:15], v[18:19], v[16:17]
	s_nop 0
	v_add_f32_e32 v0, v14, v15
	s_nop 1
	v_add_f32_dpp v0, v0, v0 quad_perm:[1,0,3,2] row_mask:0xf bank_mask:0xf bound_ctrl:1
	s_nop 1
	v_add_f32_dpp v0, v0, v0 quad_perm:[2,3,0,1] row_mask:0xf bank_mask:0xf bound_ctrl:1
	s_nop 1
	v_add_f32_dpp v0, v0, v0 row_half_mirror row_mask:0xf bank_mask:0xf bound_ctrl:1
	s_nop 1
	v_add_f32_dpp v0, v0, v0 row_mirror row_mask:0xf bank_mask:0xf bound_ctrl:1
	v_fmamk_f32 v0, v0, 0x3c800000, v216
	v_cmp_gt_f32_e32 vcc, s16, v0
	v_mul_f32_e32 v14, 0x4f800000, v0
	s_nop 0
	v_cndmask_b32_e32 v0, v0, v14, vcc
	v_sqrt_f32_e32 v14, v0
	s_nop 0
	v_add_u32_e32 v15, -1, v14
	v_fma_f32 v16, -v15, v14, v0
	v_cmp_ge_f32_e64 s[2:3], 0, v16
	v_add_u32_e32 v16, 1, v14
	s_nop 0
	v_cndmask_b32_e64 v15, v14, v15, s[2:3]
	v_fma_f32 v14, -v16, v14, v0
	v_cmp_lt_f32_e64 s[2:3], 0, v14
	s_nop 1
	v_cndmask_b32_e64 v14, v15, v16, s[2:3]
	v_mul_f32_e32 v15, 0x37800000, v14
	v_cndmask_b32_e32 v14, v14, v15, vcc
	v_cmp_class_f32_e32 vcc, v0, v217
	s_nop 1
	v_cndmask_b32_e32 v0, v14, v0, vcc
	v_div_scale_f32 v14, s[0:1], v0, v0, 1.0
	v_rcp_f32_e32 v15, v14
	s_nop 0
	v_fma_f32 v16, -v14, v15, 1.0
	v_fmac_f32_e32 v15, v16, v15
	v_div_scale_f32 v16, vcc, 1.0, v0, 1.0
	v_mul_f32_e32 v17, v16, v15
	v_fma_f32 v18, -v14, v17, v16
	v_fmac_f32_e32 v17, v18, v15
	v_fma_f32 v14, -v14, v17, v16
	v_div_fmas_f32 v14, v14, v15, v17
	v_div_fixup_f32 v0, v14, v0, 1.0
	v_pk_mul_f32 v[10:11], v[10:11], v[0:1] op_sel_hi:[1,0]
	v_pk_mul_f32 v[12:13], v[12:13], v[0:1] op_sel_hi:[1,0]
	v_pk_fma_f32 v[2:3], v[2:3], v[10:11], v[6:7]
	v_pk_fma_f32 v[4:5], v[4:5], v[12:13], v[8:9]
	v_mul_f32_e32 v0, 0xbfb8aa3b, v2
	v_fma_f32 v6, v2, s34, -v0
	v_rndne_f32_e32 v7, v0
	v_fmac_f32_e32 v6, 0xb2a5705f, v2
	v_sub_f32_e32 v0, v0, v7
	v_add_f32_e32 v0, v0, v6
	v_exp_f32_e32 v0, v0
	v_cvt_i32_f32_e32 v6, v7
	v_cmp_nlt_f32_e32 vcc, s9, v2
	v_ldexp_f32 v0, v0, v6
	s_nop 0
	v_cndmask_b32_e32 v0, 0, v0, vcc
	v_cmp_ngt_f32_e32 vcc, s15, v2
	s_nop 1
	v_cndmask_b32_e32 v0, v219, v0, vcc
	v_add_f32_e32 v0, 1.0, v0
	v_div_scale_f32 v6, s[0:1], v0, v0, v2
	v_rcp_f32_e32 v7, v6
	s_nop 0
	v_fma_f32 v8, -v6, v7, 1.0
	v_fmac_f32_e32 v7, v8, v7
	v_div_scale_f32 v8, vcc, v2, v0, v2
	v_mul_f32_e32 v9, v8, v7
	v_fma_f32 v10, -v6, v9, v8
	v_fmac_f32_e32 v9, v10, v7
	v_fma_f32 v6, -v6, v9, v8
	v_div_fmas_f32 v6, v6, v7, v9
	v_div_fixup_f32 v0, v6, v0, v2
	v_mul_f32_e32 v2, 0xbfb8aa3b, v3
	v_fma_f32 v6, v3, s34, -v2
	v_rndne_f32_e32 v7, v2
	v_fmac_f32_e32 v6, 0xb2a5705f, v3
	v_sub_f32_e32 v2, v2, v7
	v_add_f32_e32 v2, v2, v6
	v_exp_f32_e32 v2, v2
	v_cvt_i32_f32_e32 v6, v7
	v_cmp_nlt_f32_e32 vcc, s9, v3
	v_ldexp_f32 v2, v2, v6
	s_nop 0
	v_cndmask_b32_e32 v2, 0, v2, vcc
	v_cmp_ngt_f32_e32 vcc, s15, v3
	s_nop 1
	v_cndmask_b32_e32 v2, v219, v2, vcc
	v_add_f32_e32 v2, 1.0, v2
	v_div_scale_f32 v6, s[0:1], v2, v2, v3
	v_rcp_f32_e32 v7, v6
	s_nop 0
	v_fma_f32 v8, -v6, v7, 1.0
	v_fmac_f32_e32 v7, v8, v7
	v_div_scale_f32 v8, vcc, v3, v2, v3
	v_mul_f32_e32 v9, v8, v7
	v_fma_f32 v10, -v6, v9, v8
	v_fmac_f32_e32 v9, v10, v7
	v_fma_f32 v6, -v6, v9, v8
	v_div_fmas_f32 v6, v6, v7, v9
	v_div_fixup_f32 v2, v6, v2, v3
	v_cvt_pk_bf16_f32 v2, v0, v2
	v_mul_f32_e32 v0, 0xbfb8aa3b, v4
	v_fma_f32 v3, v4, s34, -v0
	v_rndne_f32_e32 v6, v0
	v_fmac_f32_e32 v3, 0xb2a5705f, v4
	v_sub_f32_e32 v0, v0, v6
	v_add_f32_e32 v0, v0, v3
	v_exp_f32_e32 v0, v0
	v_cvt_i32_f32_e32 v3, v6
	v_cmp_nlt_f32_e32 vcc, s9, v4
	v_ldexp_f32 v0, v0, v3
	s_nop 0
	v_cndmask_b32_e32 v0, 0, v0, vcc
	v_cmp_ngt_f32_e32 vcc, s15, v4
	s_nop 1
	v_cndmask_b32_e32 v0, v219, v0, vcc
	v_add_f32_e32 v0, 1.0, v0
	v_div_scale_f32 v3, s[0:1], v0, v0, v4
	v_rcp_f32_e32 v6, v3
	s_nop 0
	v_fma_f32 v7, -v3, v6, 1.0
	v_fmac_f32_e32 v6, v7, v6
	v_div_scale_f32 v7, vcc, v4, v0, v4
	v_mul_f32_e32 v8, v7, v6
	v_fma_f32 v9, -v3, v8, v7
	v_fmac_f32_e32 v8, v9, v6
	v_fma_f32 v3, -v3, v8, v7
	v_div_fmas_f32 v3, v3, v6, v8
	v_div_fixup_f32 v0, v3, v0, v4
	v_mul_f32_e32 v3, 0xbfb8aa3b, v5
	v_fma_f32 v4, v5, s34, -v3
	v_rndne_f32_e32 v6, v3
	v_fmac_f32_e32 v4, 0xb2a5705f, v5
	v_sub_f32_e32 v3, v3, v6
	v_add_f32_e32 v3, v3, v4
	v_exp_f32_e32 v3, v3
	v_cvt_i32_f32_e32 v4, v6
	v_cmp_nlt_f32_e32 vcc, s9, v5
	v_ldexp_f32 v3, v3, v4
	s_nop 0
	v_cndmask_b32_e32 v3, 0, v3, vcc
	v_cmp_ngt_f32_e32 vcc, s15, v5
	s_nop 1
	v_cndmask_b32_e32 v3, v219, v3, vcc
	v_add_f32_e32 v3, 1.0, v3
	v_div_scale_f32 v4, s[0:1], v3, v3, v5
	v_rcp_f32_e32 v6, v4
	s_add_i32 s0, s8, s58
	s_ashr_i32 s1, s0, 31
	s_lshl_b64 s[0:1], s[0:1], 11
	v_fma_f32 v7, -v4, v6, 1.0
	v_fmac_f32_e32 v6, v7, v6
	v_div_scale_f32 v7, vcc, v5, v3, v5
	v_mul_f32_e32 v8, v7, v6
	v_fma_f32 v9, -v4, v8, v7
	v_fmac_f32_e32 v8, v9, v6
	v_fma_f32 v4, -v4, v8, v7
	v_div_fmas_f32 v4, v4, v6, v8
	v_div_fixup_f32 v3, v4, v3, v5
	s_add_u32 s0, s6, s0
	s_addc_u32 s1, s7, s1
	v_lshl_add_u64 v[4:5], s[0:1], 0, v[62:63]
	v_readlane_b32 s0, v255, 27
	v_add_co_u32_e32 v4, vcc, 0x10f60000, v4
	s_add_i32 s22, s22, s0
	s_add_i32 s60, s60, s61
	v_cvt_pk_bf16_f32 v3, v0, v3
	v_addc_co_u32_e32 v5, vcc, 0, v5, vcc
	s_cmpk_lt_i32 s22, 0x200
	global_store_dwordx2 v[4:5], v[2:3], off offset:1536
	s_cbranch_scc0 .LBB0_433

.LBB0_434:
	s_andn2_b64 vcc, exec, s[2:3]
	s_cbranch_vccnz .LBB0_490
	s_waitcnt lgkmcnt(0)
	s_barrier
	s_load_dwordx2 s[16:17], s[12:13], 0x100
	v_lshlrev_b32_e32 v0, 4, v80
	v_and_b32_e32 v99, 48, v0
	v_and_b32_e32 v96, 12, v78
	v_lshlrev_b32_e32 v62, 1, v58
	s_waitcnt lgkmcnt(0)
	s_add_u32 s2, s16, 0xb600000
	s_addc_u32 s3, s17, 0
	s_lshl_b32 s15, s64, 5
	s_and_b32 s4, s15, 0xffffff80
	s_and_b32 s19, s64, 3
	v_add_u32_e32 v0, s4, v76
	v_mov_b64_e32 v[2:3], s[2:3]
	s_lshl_b32 s20, s35, 4
	v_mad_i64_i32 v[4:5], s[2:3], v0, s63, v[2:3]
	s_lshl_b32 s22, s19, 7
	v_or_b32_e32 v6, s20, v96
	v_lshl_add_u64 v[4:5], v[4:5], 0, s[22:23]
	v_lshlrev_b32_e32 v0, 1, v99
	v_lshl_add_u64 v[4:5], v[4:5], 0, v[0:1]
	v_add_u32_e32 v7, s4, v6
	global_load_dwordx4 v[46:49], v[4:5], off offset:2064
	global_load_dwordx4 v[50:53], v[4:5], off offset:2048
	v_mad_i64_i32 v[4:5], s[2:3], v7, s63, v[2:3]
	v_mov_b32_e32 v63, v1
	v_lshl_add_u64 v[4:5], v[4:5], 0, v[62:63]
	v_lshl_add_u64 v[4:5], v[4:5], 0, s[22:23]
	global_load_ushort v103, v[4:5], off offset:1536
	global_load_ushort v102, v[4:5], off offset:1568
	global_load_ushort v100, v[4:5], off offset:1600
	global_load_ushort v95, v[4:5], off offset:1632
	v_or_b32_e32 v4, 1, v7
	v_mad_i64_i32 v[4:5], s[2:3], v4, s63, v[2:3]
	v_lshl_add_u64 v[4:5], v[4:5], 0, v[62:63]
	v_lshl_add_u64 v[4:5], v[4:5], 0, s[22:23]
	global_load_ushort v101, v[4:5], off offset:1536
	global_load_ushort v98, v[4:5], off offset:1568
	global_load_ushort v94, v[4:5], off offset:1600
	global_load_ushort v91, v[4:5], off offset:1632
	v_or_b32_e32 v4, 2, v7
	v_mad_i64_i32 v[4:5], s[2:3], v4, s63, v[2:3]
	v_lshl_add_u64 v[4:5], v[4:5], 0, v[62:63]
	v_lshl_add_u64 v[4:5], v[4:5], 0, s[22:23]
	global_load_ushort v97, v[4:5], off offset:1536
	global_load_ushort v93, v[4:5], off offset:1568
	global_load_ushort v90, v[4:5], off offset:1600
	global_load_ushort v88, v[4:5], off offset:1632
	v_or_b32_e32 v4, 3, v7
	s_and_b32 s0, s15, 0xfffff800
	v_mad_i64_i32 v[4:5], s[2:3], v4, s63, v[2:3]
	s_and_b32 s1, s15, 0x780
	v_lshl_add_u64 v[4:5], v[4:5], 0, v[62:63]
	s_add_i32 s24, s0, 0x2000
	v_lshl_add_u64 v[4:5], v[4:5], 0, s[22:23]
	s_or_b32 s4, s24, s1
	global_load_ushort v92, v[4:5], off offset:1536
	global_load_ushort v89, v[4:5], off offset:1568
	global_load_ushort v87, v[4:5], off offset:1600
	global_load_ushort v86, v[4:5], off offset:1632
	v_add_u32_e32 v4, s4, v76
	v_mad_i64_i32 v[4:5], s[2:3], v4, s63, v[2:3]
	v_lshl_add_u64 v[4:5], v[4:5], 0, s[22:23]
	v_lshl_add_u64 v[4:5], v[4:5], 0, v[0:1]
	v_add_u32_e32 v0, s4, v6
	global_load_dwordx4 v[30:33], v[4:5], off offset:2064
	global_load_dwordx4 v[34:37], v[4:5], off offset:2048
	v_mad_i64_i32 v[4:5], s[2:3], v0, s63, v[2:3]
	v_lshl_add_u64 v[4:5], v[4:5], 0, v[62:63]
	v_lshl_add_u64 v[4:5], v[4:5], 0, s[22:23]
	global_load_ushort v83, v[4:5], off offset:1536
	global_load_ushort v82, v[4:5], off offset:1568
	global_load_ushort v79, v[4:5], off offset:1600
	global_load_ushort v73, v[4:5], off offset:1632
	v_or_b32_e32 v4, 1, v0
	v_mad_i64_i32 v[4:5], s[2:3], v4, s63, v[2:3]
	v_lshl_add_u64 v[4:5], v[4:5], 0, v[62:63]
	v_lshl_add_u64 v[4:5], v[4:5], 0, s[22:23]
	global_load_ushort v81, v[4:5], off offset:1536
	global_load_ushort v78, v[4:5], off offset:1568
	global_load_ushort v72, v[4:5], off offset:1600
	global_load_ushort v69, v[4:5], off offset:1632
	v_or_b32_e32 v4, 2, v0
	v_or_b32_e32 v0, 3, v0
	v_mad_i64_i32 v[4:5], s[2:3], v4, s63, v[2:3]
	v_mad_i64_i32 v[2:3], s[2:3], v0, s63, v[2:3]
	v_lshl_add_u64 v[4:5], v[4:5], 0, v[62:63]
	v_lshl_add_u64 v[2:3], v[2:3], 0, v[62:63]
	v_lshl_add_u64 v[4:5], v[4:5], 0, s[22:23]
	v_lshl_add_u64 v[2:3], v[2:3], 0, s[22:23]
	global_load_ushort v75, v[4:5], off offset:1536
	global_load_ushort v71, v[4:5], off offset:1568
	global_load_ushort v68, v[4:5], off offset:1600
	global_load_ushort v66, v[4:5], off offset:1632
	global_load_ushort v70, v[2:3], off offset:1536
	global_load_ushort v67, v[2:3], off offset:1568
	global_load_ushort v65, v[2:3], off offset:1600
	global_load_ushort v64, v[2:3], off offset:1632
	s_load_dwordx8 s[4:11], s[12:13], 0x68
	s_lshl_b32 s2, s74, 9
	s_or_b32 s22, s22, s2
	s_ashr_i32 s21, s20, 31
	s_lshl_b64 s[2:3], s[22:23], 2
	s_waitcnt lgkmcnt(0)
	s_add_u32 s10, s10, s2
	s_addc_u32 s11, s11, s3
	s_lshl_b64 s[2:3], s[20:21], 2
	s_add_u32 s2, s10, s2
	s_addc_u32 s3, s11, s3
	s_lshl_b32 s22, s74, 8
	v_lshlrev_b32_e32 v0, 2, v96
	s_lshl_b64 s[10:11], s[22:23], 2
	global_load_dwordx4 v[2:5], v0, s[2:3]
	s_add_u32 s2, s4, s10
	s_addc_u32 s3, s5, s11
	s_lshl_b32 s4, s19, 8
	s_add_u32 s2, s2, s4
	s_addc_u32 s3, s3, 0
	s_add_u32 s5, s6, s10
	s_addc_u32 s6, s7, s11
	v_lshlrev_b32_e32 v0, 2, v99
	s_add_u32 s4, s5, s4
	s_addc_u32 s5, s6, 0
	global_load_dwordx4 v[6:9], v0, s[2:3] offset:48
	global_load_dwordx4 v[14:17], v0, s[2:3] offset:32
	global_load_dwordx4 v[22:25], v0, s[2:3] offset:16
	global_load_dwordx4 v[38:41], v0, s[2:3]
	global_load_dwordx4 v[10:13], v0, s[4:5] offset:48
	global_load_dwordx4 v[18:21], v0, s[4:5] offset:32
	global_load_dwordx4 v[26:29], v0, s[4:5] offset:16
	global_load_dwordx4 v[42:45], v0, s[4:5]
	s_lshl_b32 s2, s74, 16
	s_lshl_b32 s3, s19, 14
	s_or_b32 s2, s3, s2
	s_mov_b32 s3, s23
	s_lshl_b64 s[2:3], s[2:3], 2
	s_add_u32 s2, s8, s2
	v_and_b32_e32 v63, 0x7c, v77
	s_addc_u32 s3, s9, s3
	v_lshlrev_b32_e32 v0, 2, v63
	v_lshl_add_u64 v[116:117], s[2:3], 0, v[0:1]
	v_ashrrev_i32_e32 v61, 31, v60
	v_lshl_add_u64 v[54:55], v[60:61], 2, v[116:117]
	global_load_dwordx4 v[54:57], v[54:55], off
	v_add_u32_e32 v104, 0x800, v60
	v_ashrrev_i32_e32 v105, 31, v104
	v_lshl_add_u64 v[104:105], v[104:105], 2, v[116:117]
	global_load_dwordx4 v[104:107], v[104:105], off
	v_add_u32_e32 v108, 0x1000, v60
	v_ashrrev_i32_e32 v109, 31, v108
	v_lshl_add_u64 v[108:109], v[108:109], 2, v[116:117]
	global_load_dwordx4 v[108:111], v[108:109], off
	v_add_u32_e32 v112, 0x1800, v60
	v_ashrrev_i32_e32 v113, 31, v112
	v_lshl_add_u64 v[112:113], v[112:113], 2, v[116:117]
	global_load_dwordx4 v[112:115], v[112:113], off
	v_add_u32_e32 v118, 0x2000, v60
	v_ashrrev_i32_e32 v119, 31, v118
	v_lshl_add_u64 v[118:119], v[118:119], 2, v[116:117]
	global_load_dwordx4 v[122:125], v[118:119], off
	v_add_u32_e32 v118, 0x2800, v60
	v_ashrrev_i32_e32 v119, 31, v118
	v_lshl_add_u64 v[118:119], v[118:119], 2, v[116:117]
	global_load_dwordx4 v[126:129], v[118:119], off
	v_add_u32_e32 v118, 0x3000, v60
	v_ashrrev_i32_e32 v119, 31, v118
	v_lshl_add_u64 v[118:119], v[118:119], 2, v[116:117]
	global_load_dwordx4 v[130:133], v[118:119], off
	v_add_u32_e32 v60, 0x3800, v60
	v_ashrrev_i32_e32 v61, 31, v60
	v_ashrrev_i32_e32 v121, 5, v74
	v_lshl_add_u64 v[60:61], v[60:61], 2, v[116:117]
	v_cmp_le_i32_e32 vcc, v63, v121
	global_load_dwordx4 v[134:137], v[60:61], off
	v_or_b32_e32 v60, 2, v63
	v_or_b32_e32 v61, 3, v63
	v_lshl_add_u32 v0, v63, 1, 0
	s_mul_i32 s7, s35, 0x1100
	s_waitcnt vmcnt(7)
	v_cndmask_b32_e32 v54, 0, v54, vcc
	v_cmp_lt_i32_e32 vcc, v63, v121
	s_nop 1
	v_cndmask_b32_e32 v55, 0, v55, vcc
	v_cmp_le_i32_e32 vcc, v60, v121
	v_cvt_pk_bf16_f32 v54, v54, v55
	s_nop 0
	v_cndmask_b32_e32 v55, 0, v56, vcc
	v_cmp_le_i32_e32 vcc, v61, v121
	s_nop 1
	v_cndmask_b32_e32 v56, 0, v57, vcc
	v_cvt_pk_bf16_f32 v55, v55, v56
	v_mad_u64_u32 v[56:57], s[2:3], v121, s95, v[0:1]
	ds_write_b64 v56, v[54:55]
	v_add_u32_e32 v54, 0x200, v74
	v_ashrrev_i32_e32 v119, 5, v54
	v_cmp_le_i32_e32 vcc, v63, v119
	s_waitcnt vmcnt(6)
	s_nop 0
	v_cndmask_b32_e32 v54, 0, v104, vcc
	v_cmp_lt_i32_e32 vcc, v63, v119
	s_nop 1
	v_cndmask_b32_e32 v55, 0, v105, vcc
	v_cmp_le_i32_e32 vcc, v60, v119
	v_cvt_pk_bf16_f32 v54, v54, v55
	s_nop 0
	v_cndmask_b32_e32 v55, 0, v106, vcc
	v_cmp_le_i32_e32 vcc, v61, v119
	s_nop 1
	v_cndmask_b32_e32 v56, 0, v107, vcc
	v_cvt_pk_bf16_f32 v55, v55, v56
	v_mad_u64_u32 v[56:57], s[2:3], v119, s95, v[0:1]
	ds_write_b64 v56, v[54:55]
	v_add_u32_e32 v54, 0x400, v74
	v_ashrrev_i32_e32 v118, 5, v54
	v_cmp_le_i32_e32 vcc, v63, v118
	s_waitcnt vmcnt(5)
	s_nop 0
	v_cndmask_b32_e32 v54, 0, v108, vcc
	v_cmp_lt_i32_e32 vcc, v63, v118
	s_nop 1
	v_cndmask_b32_e32 v55, 0, v109, vcc
	v_cmp_le_i32_e32 vcc, v60, v118
	v_cvt_pk_bf16_f32 v54, v54, v55
	s_nop 0
	v_cndmask_b32_e32 v55, 0, v110, vcc
	v_cmp_le_i32_e32 vcc, v61, v118
	s_nop 1
	v_cndmask_b32_e32 v56, 0, v111, vcc
	v_cvt_pk_bf16_f32 v55, v55, v56
	v_mad_u64_u32 v[56:57], s[2:3], v118, s95, v[0:1]
	ds_write_b64 v56, v[54:55]
	v_add_u32_e32 v54, 0x600, v74
	v_ashrrev_i32_e32 v85, 5, v54
	v_cmp_le_i32_e32 vcc, v63, v85
	s_waitcnt vmcnt(4)
	s_nop 0
	v_cndmask_b32_e32 v54, 0, v112, vcc
	v_cmp_lt_i32_e32 vcc, v63, v85
	s_nop 1
	v_cndmask_b32_e32 v55, 0, v113, vcc
	v_cmp_le_i32_e32 vcc, v60, v85
	v_cvt_pk_bf16_f32 v54, v54, v55
	s_nop 0
	v_cndmask_b32_e32 v55, 0, v114, vcc
	v_cmp_le_i32_e32 vcc, v61, v85
	s_nop 1
	v_cndmask_b32_e32 v56, 0, v115, vcc
	v_cvt_pk_bf16_f32 v55, v55, v56
	v_mad_u64_u32 v[56:57], s[2:3], v85, s95, v[0:1]
	ds_write_b64 v56, v[54:55]
	v_add_u32_e32 v54, 0x800, v74
	v_ashrrev_i32_e32 v56, 5, v54
	v_cmp_le_i32_e32 vcc, v63, v56
	s_waitcnt vmcnt(3)
	s_nop 0
	v_cndmask_b32_e32 v54, 0, v122, vcc
	v_cmp_lt_i32_e32 vcc, v63, v56
	s_nop 1
	v_cndmask_b32_e32 v55, 0, v123, vcc
	v_cmp_le_i32_e32 vcc, v60, v56
	v_cvt_pk_bf16_f32 v54, v54, v55
	s_nop 0
	v_cndmask_b32_e32 v55, 0, v124, vcc
	v_cmp_le_i32_e32 vcc, v61, v56
	s_nop 1
	v_cndmask_b32_e32 v57, 0, v125, vcc
	v_cvt_pk_bf16_f32 v55, v55, v57
	v_mad_u64_u32 v[56:57], s[2:3], v56, s95, v[0:1]
	ds_write_b64 v56, v[54:55]
	v_add_u32_e32 v54, 0xa00, v74
	v_ashrrev_i32_e32 v56, 5, v54
	v_cmp_le_i32_e32 vcc, v63, v56
	s_waitcnt vmcnt(2)
	s_nop 0
	v_cndmask_b32_e32 v54, 0, v126, vcc
	v_cmp_lt_i32_e32 vcc, v63, v56
	s_nop 1
	v_cndmask_b32_e32 v55, 0, v127, vcc
	v_cmp_le_i32_e32 vcc, v60, v56
	v_cvt_pk_bf16_f32 v54, v54, v55
	s_nop 0
	v_cndmask_b32_e32 v55, 0, v128, vcc
	v_cmp_le_i32_e32 vcc, v61, v56
	s_nop 1
	v_cndmask_b32_e32 v57, 0, v129, vcc
	v_cvt_pk_bf16_f32 v55, v55, v57
	v_mad_u64_u32 v[56:57], s[2:3], v56, s95, v[0:1]
	ds_write_b64 v56, v[54:55]
	v_add_u32_e32 v54, 0xc00, v74
	v_ashrrev_i32_e32 v56, 5, v54
	v_cmp_le_i32_e32 vcc, v63, v56
	s_waitcnt vmcnt(1)
	s_nop 0
	v_cndmask_b32_e32 v54, 0, v130, vcc
	v_cmp_lt_i32_e32 vcc, v63, v56
	s_nop 1
	v_cndmask_b32_e32 v55, 0, v131, vcc
	v_cmp_le_i32_e32 vcc, v60, v56
	v_cvt_pk_bf16_f32 v54, v54, v55
	s_nop 0
	v_cndmask_b32_e32 v55, 0, v132, vcc
	v_cmp_le_i32_e32 vcc, v61, v56
	s_nop 1
	v_cndmask_b32_e32 v57, 0, v133, vcc
	v_cvt_pk_bf16_f32 v55, v55, v57
	v_mad_u64_u32 v[56:57], s[2:3], v56, s95, v[0:1]
	ds_write_b64 v56, v[54:55]
	v_add_u32_e32 v54, 0xe00, v74
	v_ashrrev_i32_e32 v56, 5, v54
	v_cmp_le_i32_e32 vcc, v63, v56
	v_and_b32_e32 v77, 0xffff0000, v49
	s_waitcnt vmcnt(0)
	v_cndmask_b32_e32 v54, 0, v134, vcc
	v_cmp_lt_i32_e32 vcc, v63, v56
	s_nop 1
	v_cndmask_b32_e32 v55, 0, v135, vcc
	v_cmp_le_i32_e32 vcc, v60, v56
	v_cvt_pk_bf16_f32 v54, v54, v55
	v_lshlrev_b32_e32 v63, 16, v48
	v_cndmask_b32_e32 v55, 0, v136, vcc
	v_cmp_le_i32_e32 vcc, v61, v56
	s_nop 1
	v_cndmask_b32_e32 v57, 0, v137, vcc
	v_cvt_pk_bf16_f32 v55, v55, v57
	v_mad_u64_u32 v[56:57], s[2:3], v56, s95, v[0:1]
	ds_write_b64 v56, v[54:55]
	v_lshlrev_b32_e32 v54, 16, v50
	v_and_b32_e32 v50, 0xffff0000, v50
	v_add_f32_e32 v104, 0, v54
	v_lshlrev_b32_e32 v55, 16, v51
	v_add_f32_e32 v104, v104, v50
	v_and_b32_e32 v51, 0xffff0000, v51
	v_add_f32_e32 v104, v104, v55
	v_lshlrev_b32_e32 v56, 16, v52
	v_add_f32_e32 v104, v104, v51
	v_and_b32_e32 v52, 0xffff0000, v52
	v_add_f32_e32 v104, v104, v56
	v_lshlrev_b32_e32 v57, 16, v53
	v_add_f32_e32 v104, v104, v52
	v_and_b32_e32 v53, 0xffff0000, v53
	v_add_f32_e32 v104, v104, v57
	v_lshlrev_b32_e32 v60, 16, v46
	v_add_f32_e32 v104, v104, v53
	v_and_b32_e32 v46, 0xffff0000, v46
	v_add_f32_e32 v104, v104, v60
	v_lshlrev_b32_e32 v61, 16, v47
	v_add_f32_e32 v104, v104, v46
	v_and_b32_e32 v47, 0xffff0000, v47
	v_add_f32_e32 v104, v104, v61
	v_add_f32_e32 v104, v104, v47
	v_and_b32_e32 v48, 0xffff0000, v48
	v_add_f32_e32 v104, v104, v63
	v_lshl_add_u32 v0, v76, 1, 0
	v_lshlrev_b32_e32 v76, 16, v49
	v_add_f32_e32 v104, v104, v48
	v_add_f32_e32 v104, v104, v76
	v_add_f32_e32 v104, v104, v77
	s_add_i32 s2, s20, 47
	s_ashr_i32 s6, s2, 5
	v_add_f32_dpp v104, v104, v104 quad_perm:[1,0,3,2] row_mask:0xf bank_mask:0xf bound_ctrl:1
	s_cmp_gt_i32 s6, 0
	v_mov_b32_e32 v49, 0
	v_add_f32_dpp v104, v104, v104 quad_perm:[2,3,0,1] row_mask:0xf bank_mask:0xf bound_ctrl:1
	v_fmac_f32_e32 v50, 0xbc800000, v104
	v_fmac_f32_e32 v54, 0xbc800000, v104
	v_mul_f32_e32 v105, v50, v50
	v_fmac_f32_e32 v105, v54, v54
	v_fmac_f32_e32 v55, 0xbc800000, v104
	v_fmac_f32_e32 v105, v55, v55
	v_fmac_f32_e32 v51, 0xbc800000, v104
	v_fmac_f32_e32 v105, v51, v51
	v_fmac_f32_e32 v56, 0xbc800000, v104
	v_fmac_f32_e32 v105, v56, v56
	v_fmac_f32_e32 v52, 0xbc800000, v104
	v_fmac_f32_e32 v105, v52, v52
	v_fmac_f32_e32 v57, 0xbc800000, v104
	v_fmac_f32_e32 v105, v57, v57
	v_fmac_f32_e32 v53, 0xbc800000, v104
	v_fmac_f32_e32 v105, v53, v53
	v_fmac_f32_e32 v60, 0xbc800000, v104
	v_fmac_f32_e32 v105, v60, v60
	v_fmac_f32_e32 v46, 0xbc800000, v104
	v_fmac_f32_e32 v105, v46, v46
	v_fmac_f32_e32 v61, 0xbc800000, v104
	v_fmac_f32_e32 v105, v61, v61
	v_fmac_f32_e32 v47, 0xbc800000, v104
	v_fmac_f32_e32 v105, v47, v47
	v_fmac_f32_e32 v63, 0xbc800000, v104
	v_fmac_f32_e32 v105, v63, v63
	v_fmac_f32_e32 v48, 0xbc800000, v104
	v_fmac_f32_e32 v105, v48, v48
	v_fmac_f32_e32 v76, 0xbc800000, v104
	v_fmac_f32_e32 v105, v76, v76
	v_fmac_f32_e32 v77, 0xbc800000, v104
	v_fmac_f32_e32 v105, v77, v77
	s_cselect_b64 s[4:5], -1, 0
	s_cmp_lt_i32 s6, 1
	v_add_f32_dpp v104, v105, v105 quad_perm:[1,0,3,2] row_mask:0xf bank_mask:0xf bound_ctrl:1
	s_nop 1
	v_add_f32_dpp v104, v104, v104 quad_perm:[2,3,0,1] row_mask:0xf bank_mask:0xf bound_ctrl:1
	v_fmamk_f32 v104, v104, 0x3c800000, v216
	v_cmp_gt_f32_e32 vcc, s60, v104
	v_mul_f32_e32 v105, 0x4f800000, v104
	s_nop 0
	v_cndmask_b32_e32 v104, v104, v105, vcc
	v_sqrt_f32_e32 v105, v104
	s_nop 0
	v_add_u32_e32 v106, -1, v105
	v_fma_f32 v107, -v106, v105, v104
	v_cmp_ge_f32_e64 s[2:3], 0, v107
	v_add_u32_e32 v107, 1, v105
	s_nop 0
	v_cndmask_b32_e64 v106, v105, v106, s[2:3]
	v_fma_f32 v105, -v107, v105, v104
	v_cmp_lt_f32_e64 s[2:3], 0, v105
	s_nop 1
	v_cndmask_b32_e64 v105, v106, v107, s[2:3]
	v_mul_f32_e32 v106, 0x37800000, v105
	v_cndmask_b32_e32 v105, v105, v106, vcc
	v_cmp_class_f32_e32 vcc, v104, v217
	s_nop 1
	v_cndmask_b32_e32 v104, v105, v104, vcc
	v_div_scale_f32 v105, s[2:3], v104, v104, 1.0
	v_rcp_f32_e32 v106, v105
	s_nop 0
	v_fma_f32 v107, -v105, v106, 1.0
	v_fmac_f32_e32 v106, v107, v106
	v_div_scale_f32 v107, vcc, 1.0, v104, 1.0
	v_mul_f32_e32 v108, v107, v106
	v_fma_f32 v109, -v105, v108, v107
	v_fmac_f32_e32 v108, v109, v106
	v_fma_f32 v105, -v105, v108, v107
	v_div_fmas_f32 v105, v105, v106, v108
	v_div_fixup_f32 v104, v105, v104, 1.0
	v_mul_f32_e32 v54, v54, v104
	v_fma_f32 v54, v38, v54, v42
	v_bfe_u32 v105, v54, 16, 1
	v_mul_f32_e32 v50, v50, v104
	v_add3_u32 v54, v54, v105, s33
	v_mad_u32_u24 v105, v99, s95, v0
	v_fma_f32 v50, v39, v50, v43
	ds_write_b16_d16_hi v105, v54 offset:34816
	v_bfe_u32 v54, v50, 16, 1
	v_add3_u32 v50, v50, v54, s33
	ds_write_b16_d16_hi v105, v50 offset:35088
	v_mul_f32_e32 v50, v55, v104
	v_fma_f32 v50, v40, v50, v44
	v_bfe_u32 v54, v50, 16, 1
	v_add3_u32 v50, v50, v54, s33
	ds_write_b16_d16_hi v105, v50 offset:35360
	v_mul_f32_e32 v50, v51, v104
	v_fma_f32 v50, v41, v50, v45
	v_bfe_u32 v51, v50, 16, 1
	v_add3_u32 v50, v50, v51, s33
	ds_write_b16_d16_hi v105, v50 offset:35632
	v_mul_f32_e32 v50, v56, v104
	v_fma_f32 v50, v22, v50, v26
	v_bfe_u32 v51, v50, 16, 1
	v_add3_u32 v50, v50, v51, s33
	ds_write_b16_d16_hi v105, v50 offset:35904
	v_mul_f32_e32 v50, v52, v104
	v_fma_f32 v50, v23, v50, v27
	v_bfe_u32 v51, v50, 16, 1
	v_add3_u32 v50, v50, v51, s33
	ds_write_b16_d16_hi v105, v50 offset:36176
	v_mul_f32_e32 v50, v57, v104
	v_fma_f32 v50, v24, v50, v28
	v_bfe_u32 v51, v50, 16, 1
	v_add3_u32 v50, v50, v51, s33
	ds_write_b16_d16_hi v105, v50 offset:36448
	v_mul_f32_e32 v50, v53, v104
	v_fma_f32 v50, v25, v50, v29
	v_bfe_u32 v51, v50, 16, 1
	v_add3_u32 v50, v50, v51, s33
	ds_write_b16_d16_hi v105, v50 offset:36720
	v_mul_f32_e32 v50, v60, v104
	v_fma_f32 v50, v14, v50, v18
	v_bfe_u32 v51, v50, 16, 1
	v_mul_f32_e32 v46, v46, v104
	v_add3_u32 v50, v50, v51, s33
	v_fma_f32 v46, v15, v46, v19
	ds_write_b16_d16_hi v105, v50 offset:36992
	v_bfe_u32 v50, v46, 16, 1
	v_add3_u32 v46, v46, v50, s33
	ds_write_b16_d16_hi v105, v46 offset:37264
	v_mul_f32_e32 v46, v61, v104
	v_fma_f32 v46, v16, v46, v20
	v_bfe_u32 v50, v46, 16, 1
	v_add3_u32 v46, v46, v50, s33
	ds_write_b16_d16_hi v105, v46 offset:37536
	v_mul_f32_e32 v46, v47, v104
	v_fma_f32 v46, v17, v46, v21
	v_bfe_u32 v47, v46, 16, 1
	v_add3_u32 v46, v46, v47, s33
	ds_write_b16_d16_hi v105, v46 offset:37808
	v_mul_f32_e32 v46, v63, v104
	v_fma_f32 v46, v6, v46, v10
	v_bfe_u32 v47, v46, 16, 1
	v_add3_u32 v46, v46, v47, s33
	ds_write_b16_d16_hi v105, v46 offset:38080
	v_mul_f32_e32 v46, v48, v104
	v_fma_f32 v46, v7, v46, v11
	v_bfe_u32 v47, v46, 16, 1
	v_add3_u32 v46, v46, v47, s33
	ds_write_b16_d16_hi v105, v46 offset:38352
	v_mul_f32_e32 v46, v76, v104
	v_fma_f32 v46, v8, v46, v12
	v_bfe_u32 v47, v46, 16, 1
	v_add3_u32 v46, v46, v47, s33
	ds_write_b16_d16_hi v105, v46 offset:38624
	v_mul_f32_e32 v46, v77, v104
	v_fma_f32 v46, v9, v46, v13
	v_bfe_u32 v47, v46, 16, 1
	v_add3_u32 v46, v46, v47, s33
	ds_write_b16_d16_hi v105, v46 offset:38896
	s_waitcnt lgkmcnt(0)
	s_barrier
	v_mad_u32_u24 v77, v58, s95, v59
	v_add_u32_e32 v76, s96, v77
	v_mov_b32_e32 v48, v49
	v_mov_b32_e32 v47, v49
	v_mov_b32_e32 v46, v49
	v_mov_b32_e32 v61, v49
	v_mov_b32_e32 v60, v49
	v_mov_b32_e32 v59, v49
	v_mov_b32_e32 v58, v49
	v_mov_b32_e32 v57, v49
	v_mov_b32_e32 v56, v49
	v_mov_b32_e32 v55, v49
	v_mov_b32_e32 v54, v49
	v_mov_b32_e32 v53, v49
	v_mov_b32_e32 v52, v49
	v_mov_b32_e32 v51, v49
	v_mov_b32_e32 v50, v49
	s_cbranch_scc1 .LBB0_438
	s_add_i32 s2, s7, 0
	v_mov_b32_e32 v50, 0
	v_add_u32_e32 v63, s96, v77
	v_add_u32_e32 v104, s2, v77
	s_mov_b32 s2, s6
	v_mov_b32_e32 v51, v50
	v_mov_b32_e32 v52, v50
	v_mov_b32_e32 v53, v50
	v_mov_b32_e32 v54, v50
	v_mov_b32_e32 v55, v50
	v_mov_b32_e32 v56, v50
	v_mov_b32_e32 v57, v50
	v_mov_b32_e32 v58, v50
	v_mov_b32_e32 v59, v50
	v_mov_b32_e32 v60, v50
	v_mov_b32_e32 v61, v50
	v_mov_b32_e32 v46, v50
	v_mov_b32_e32 v47, v50
	v_mov_b32_e32 v48, v50
	v_mov_b32_e32 v49, v50

.LBB0_465:
	s_or_b64 exec, exec, s[10:11]
	v_lshlrev_b32_e32 v0, 6, v74
	v_and_b32_e32 v0, 0xffffc000, v0
	v_add3_u32 v127, 0, v76, v0
	s_waitcnt lgkmcnt(0)
	s_barrier
	ds_read2st64_b32 v[130:131], v127 offset1:4
	ds_read2st64_b32 v[132:133], v127 offset0:8 offset1:12
	ds_read2st64_b32 v[82:83], v127 offset0:16 offset1:20
	ds_read2st64_b32 v[80:81], v127 offset0:24 offset1:28
	ds_read2st64_b32 v[78:79], v127 offset0:32 offset1:36
	ds_read2st64_b32 v[76:77], v127 offset0:40 offset1:44
	ds_read2st64_b32 v[74:75], v127 offset0:48 offset1:52
	ds_read2st64_b32 v[72:73], v127 offset0:56 offset1:60
	ds_read2st64_b32 v[70:71], v127 offset0:64 offset1:68
	ds_read2st64_b32 v[68:69], v127 offset0:72 offset1:76
	ds_read2st64_b32 v[66:67], v127 offset0:80 offset1:84
	s_waitcnt vmcnt(46)
	ds_read2st64_b32 v[64:65], v127 offset0:88 offset1:92
	ds_read2st64_b32 v[62:63], v127 offset0:96 offset1:100
	ds_read2st64_b32 v[60:61], v127 offset0:104 offset1:108
	ds_read2st64_b32 v[58:59], v127 offset0:112 offset1:116
	s_waitcnt vmcnt(44)
	ds_read2st64_b32 v[56:57], v127 offset0:120 offset1:124
	ds_read2st64_b32 v[54:55], v127 offset0:128 offset1:132
	ds_read2st64_b32 v[52:53], v127 offset0:136 offset1:140
	ds_read2st64_b32 v[50:51], v127 offset0:144 offset1:148
	s_waitcnt vmcnt(42)
	ds_read2st64_b32 v[48:49], v127 offset0:152 offset1:156
	ds_read2st64_b32 v[46:47], v127 offset0:160 offset1:164
	ds_read2st64_b32 v[44:45], v127 offset0:168 offset1:172
	ds_read2st64_b32 v[42:43], v127 offset0:176 offset1:180
	s_waitcnt vmcnt(2) lgkmcnt(14)
	v_fma_f32 v0, v89, v130, v117
	v_fma_f32 v129, v89, v131, v117
	v_fmac_f32_e32 v0, v88, v131
	v_fmac_f32_e32 v129, v88, v132
	v_fmac_f32_e32 v0, v87, v132
	v_fmac_f32_e32 v129, v87, v133
	v_fmac_f32_e32 v0, v86, v133
	v_fmac_f32_e32 v129, v86, v82
	v_fmac_f32_e32 v0, v93, v82
	v_fmac_f32_e32 v129, v93, v83
	v_fmac_f32_e32 v0, v92, v83
	v_fmac_f32_e32 v129, v92, v80
	v_fmac_f32_e32 v0, v91, v80
	v_fmac_f32_e32 v129, v91, v81
	v_fmac_f32_e32 v0, v90, v81
	v_fmac_f32_e32 v129, v90, v78
	v_fmac_f32_e32 v0, v97, v78
	v_fmac_f32_e32 v129, v97, v79
	v_fmac_f32_e32 v0, v96, v79
	v_fmac_f32_e32 v129, v96, v76
	v_fmac_f32_e32 v0, v95, v76
	v_fmac_f32_e32 v129, v95, v77
	v_fmac_f32_e32 v0, v94, v77
	v_fmac_f32_e32 v129, v94, v74
	v_fmac_f32_e32 v0, v105, v74
	v_fmac_f32_e32 v129, v105, v75
	v_fmac_f32_e32 v0, v104, v75
	v_fmac_f32_e32 v129, v104, v72
	v_fmac_f32_e32 v0, v103, v72
	v_fmac_f32_e32 v129, v103, v73
	v_fmac_f32_e32 v0, v102, v73
	v_fmac_f32_e32 v129, v102, v70
	v_fmac_f32_e32 v0, v101, v70
	v_fmac_f32_e32 v129, v101, v71
	v_fmac_f32_e32 v0, v100, v71
	s_waitcnt lgkmcnt(13)
	v_fmac_f32_e32 v129, v100, v68
	v_fmac_f32_e32 v0, v99, v68
	v_fmac_f32_e32 v129, v99, v69
	v_fmac_f32_e32 v0, v98, v69
	s_waitcnt lgkmcnt(12)
	v_fmac_f32_e32 v129, v98, v66
	v_fmac_f32_e32 v0, v106, v66
	v_fmac_f32_e32 v129, v106, v67
	v_fmac_f32_e32 v0, v109, v67
	s_waitcnt lgkmcnt(11)
	v_fmac_f32_e32 v129, v109, v64
	v_fmac_f32_e32 v0, v108, v64
	v_fmac_f32_e32 v129, v108, v65
	v_fmac_f32_e32 v0, v107, v65
	s_waitcnt lgkmcnt(10)
	v_fmac_f32_e32 v129, v107, v62
	v_fmac_f32_e32 v0, v113, v62
	v_fmac_f32_e32 v129, v113, v63
	v_fmac_f32_e32 v0, v112, v63
	s_waitcnt lgkmcnt(9)
	v_fmac_f32_e32 v129, v112, v60
	v_fmac_f32_e32 v0, v111, v60
	v_fmac_f32_e32 v129, v111, v61
	v_fmac_f32_e32 v0, v110, v61
	s_waitcnt lgkmcnt(8)
	v_fmac_f32_e32 v129, v110, v58
	v_fmac_f32_e32 v0, v116, v58
	v_fmac_f32_e32 v129, v116, v59
	v_fmac_f32_e32 v0, v115, v59
	s_waitcnt lgkmcnt(7)
	v_fmac_f32_e32 v129, v115, v56
	v_fmac_f32_e32 v0, v114, v56
	v_fmac_f32_e32 v129, v114, v57
	ds_write2st64_b32 v127, v0, v129 offset0:248 offset1:252
	v_fma_f32 v0, v89, v132, v117
	v_fma_f32 v129, v89, v133, v117
	v_fmac_f32_e32 v0, v88, v133
	v_fmac_f32_e32 v129, v88, v82
	v_fmac_f32_e32 v0, v87, v82
	v_fmac_f32_e32 v129, v87, v83
	v_fmac_f32_e32 v0, v86, v83
	v_fmac_f32_e32 v129, v86, v80
	v_fmac_f32_e32 v0, v93, v80
	v_fmac_f32_e32 v129, v93, v81
	v_fmac_f32_e32 v0, v92, v81
	v_fmac_f32_e32 v129, v92, v78
	v_fmac_f32_e32 v0, v91, v78
	v_fmac_f32_e32 v129, v91, v79
	v_fmac_f32_e32 v0, v90, v79
	v_fmac_f32_e32 v129, v90, v76
	v_fmac_f32_e32 v0, v97, v76
	v_fmac_f32_e32 v129, v97, v77
	v_fmac_f32_e32 v0, v96, v77
	v_fmac_f32_e32 v129, v96, v74
	v_fmac_f32_e32 v0, v95, v74
	v_fmac_f32_e32 v129, v95, v75
	v_fmac_f32_e32 v0, v94, v75
	v_fmac_f32_e32 v129, v94, v72
	v_fmac_f32_e32 v0, v105, v72
	v_fmac_f32_e32 v129, v105, v73
	v_fmac_f32_e32 v0, v104, v73
	v_fmac_f32_e32 v129, v104, v70
	v_fmac_f32_e32 v0, v103, v70
	v_fmac_f32_e32 v129, v103, v71
	v_fmac_f32_e32 v0, v102, v71
	v_fmac_f32_e32 v129, v102, v68
	v_fmac_f32_e32 v0, v101, v68
	v_fmac_f32_e32 v129, v101, v69
	v_fmac_f32_e32 v0, v100, v69
	v_fmac_f32_e32 v129, v100, v66
	v_fmac_f32_e32 v0, v99, v66
	v_fmac_f32_e32 v129, v99, v67
	v_fmac_f32_e32 v0, v98, v67
	v_fmac_f32_e32 v129, v98, v64
	v_fmac_f32_e32 v0, v106, v64
	v_fmac_f32_e32 v129, v106, v65
	v_fmac_f32_e32 v0, v109, v65
	v_fmac_f32_e32 v129, v109, v62
	v_fmac_f32_e32 v0, v108, v62
	v_fmac_f32_e32 v129, v108, v63
	v_fmac_f32_e32 v0, v107, v63
	v_fmac_f32_e32 v129, v107, v60
	v_fmac_f32_e32 v0, v113, v60
	v_fmac_f32_e32 v129, v113, v61
	v_fmac_f32_e32 v0, v112, v61
	v_fmac_f32_e32 v129, v112, v58
	v_fmac_f32_e32 v0, v111, v58
	v_fmac_f32_e32 v129, v111, v59
	v_fmac_f32_e32 v0, v110, v59
	v_fmac_f32_e32 v129, v110, v56
	v_fmac_f32_e32 v0, v116, v56
	v_fmac_f32_e32 v129, v116, v57
	v_fmac_f32_e32 v0, v115, v57
	s_waitcnt lgkmcnt(7)
	v_fmac_f32_e32 v129, v115, v54
	v_add_u32_e32 v123, 0xf800, v127
	v_fmac_f32_e32 v0, v114, v54
	v_fmac_f32_e32 v129, v114, v55
	ds_write2st64_b32 v123, v0, v129 offset0:8 offset1:12
	v_fma_f32 v0, v89, v82, v117
	v_fma_f32 v82, v89, v83, v117
	v_fmac_f32_e32 v0, v88, v83
	v_fmac_f32_e32 v82, v88, v80
	v_fmac_f32_e32 v0, v87, v80
	v_fmac_f32_e32 v82, v87, v81
	v_fmac_f32_e32 v0, v86, v81
	v_fmac_f32_e32 v82, v86, v78
	v_fmac_f32_e32 v0, v93, v78
	v_fmac_f32_e32 v82, v93, v79
	v_fmac_f32_e32 v0, v92, v79
	v_fmac_f32_e32 v82, v92, v76
	v_fmac_f32_e32 v0, v91, v76
	v_fmac_f32_e32 v82, v91, v77
	v_fmac_f32_e32 v0, v90, v77
	v_fmac_f32_e32 v82, v90, v74
	v_fmac_f32_e32 v0, v97, v74
	v_fmac_f32_e32 v82, v97, v75
	v_fmac_f32_e32 v0, v96, v75
	v_fmac_f32_e32 v82, v96, v72
	v_fmac_f32_e32 v0, v95, v72
	v_fmac_f32_e32 v82, v95, v73
	v_fmac_f32_e32 v0, v94, v73
	v_fmac_f32_e32 v82, v94, v70
	v_fmac_f32_e32 v0, v105, v70
	v_fmac_f32_e32 v82, v105, v71
	v_fmac_f32_e32 v0, v104, v71
	v_fmac_f32_e32 v82, v104, v68
	v_fmac_f32_e32 v0, v103, v68
	v_fmac_f32_e32 v82, v103, v69
	v_fmac_f32_e32 v0, v102, v69
	v_fmac_f32_e32 v82, v102, v66
	v_fmac_f32_e32 v0, v101, v66
	v_fmac_f32_e32 v82, v101, v67
	v_fmac_f32_e32 v0, v100, v67
	v_fmac_f32_e32 v82, v100, v64
	v_fmac_f32_e32 v0, v99, v64
	v_fmac_f32_e32 v82, v99, v65
	v_fmac_f32_e32 v0, v98, v65
	v_fmac_f32_e32 v82, v98, v62
	v_fmac_f32_e32 v0, v106, v62
	v_fmac_f32_e32 v82, v106, v63
	v_fmac_f32_e32 v0, v109, v63
	v_fmac_f32_e32 v82, v109, v60
	v_fmac_f32_e32 v0, v108, v60
	v_fmac_f32_e32 v82, v108, v61
	v_fmac_f32_e32 v0, v107, v61
	v_fmac_f32_e32 v82, v107, v58
	v_fmac_f32_e32 v0, v113, v58
	v_fmac_f32_e32 v82, v113, v59
	v_fmac_f32_e32 v0, v112, v59
	v_fmac_f32_e32 v82, v112, v56
	v_fmac_f32_e32 v0, v111, v56
	v_fmac_f32_e32 v82, v111, v57
	v_fmac_f32_e32 v0, v110, v57
	v_fmac_f32_e32 v82, v110, v54
	v_fmac_f32_e32 v0, v116, v54
	v_fmac_f32_e32 v82, v116, v55
	v_fmac_f32_e32 v0, v115, v55
	s_waitcnt lgkmcnt(7)
	v_fmac_f32_e32 v82, v115, v52
	v_fmac_f32_e32 v0, v114, v52
	v_fmac_f32_e32 v82, v114, v53
	ds_write2st64_b32 v123, v0, v82 offset0:16 offset1:20
	v_fma_f32 v0, v89, v80, v117
	v_fma_f32 v80, v89, v81, v117
	v_fmac_f32_e32 v0, v88, v81
	v_fmac_f32_e32 v80, v88, v78
	v_fmac_f32_e32 v0, v87, v78
	v_fmac_f32_e32 v80, v87, v79
	v_fmac_f32_e32 v0, v86, v79
	v_fmac_f32_e32 v80, v86, v76
	v_fmac_f32_e32 v0, v93, v76
	v_fmac_f32_e32 v80, v93, v77
	v_fmac_f32_e32 v0, v92, v77
	v_fmac_f32_e32 v80, v92, v74
	v_fmac_f32_e32 v0, v91, v74
	v_fmac_f32_e32 v80, v91, v75
	v_fmac_f32_e32 v0, v90, v75
	v_fmac_f32_e32 v80, v90, v72
	v_fmac_f32_e32 v0, v97, v72
	v_fmac_f32_e32 v80, v97, v73
	v_fmac_f32_e32 v0, v96, v73
	v_fmac_f32_e32 v80, v96, v70
	v_fmac_f32_e32 v0, v95, v70
	v_fmac_f32_e32 v80, v95, v71
	v_fmac_f32_e32 v0, v94, v71
	v_fmac_f32_e32 v80, v94, v68
	v_fmac_f32_e32 v0, v105, v68
	v_fmac_f32_e32 v80, v105, v69
	v_fmac_f32_e32 v0, v104, v69
	v_fmac_f32_e32 v80, v104, v66
	v_fmac_f32_e32 v0, v103, v66
	v_fmac_f32_e32 v80, v103, v67
	v_fmac_f32_e32 v0, v102, v67
	v_fmac_f32_e32 v80, v102, v64
	v_fmac_f32_e32 v0, v101, v64
	v_fmac_f32_e32 v80, v101, v65
	v_fmac_f32_e32 v0, v100, v65
	v_fmac_f32_e32 v80, v100, v62
	v_fmac_f32_e32 v0, v99, v62
	v_fmac_f32_e32 v80, v99, v63
	v_fmac_f32_e32 v0, v98, v63
	v_fmac_f32_e32 v80, v98, v60
	v_fmac_f32_e32 v0, v106, v60
	v_fmac_f32_e32 v80, v106, v61
	v_fmac_f32_e32 v0, v109, v61
	v_fmac_f32_e32 v80, v109, v58
	v_fmac_f32_e32 v0, v108, v58
	v_fmac_f32_e32 v80, v108, v59
	v_fmac_f32_e32 v0, v107, v59
	v_fmac_f32_e32 v80, v107, v56
	v_fmac_f32_e32 v0, v113, v56
	v_fmac_f32_e32 v80, v113, v57
	v_fmac_f32_e32 v0, v112, v57
	v_fmac_f32_e32 v80, v112, v54
	v_fmac_f32_e32 v0, v111, v54
	v_fmac_f32_e32 v80, v111, v55
	v_fmac_f32_e32 v0, v110, v55
	v_fmac_f32_e32 v80, v110, v52
	v_fmac_f32_e32 v0, v116, v52
	v_fmac_f32_e32 v80, v116, v53
	v_fmac_f32_e32 v0, v115, v53
	s_waitcnt lgkmcnt(7)
	v_fmac_f32_e32 v80, v115, v50
	v_fmac_f32_e32 v0, v114, v50
	v_fmac_f32_e32 v80, v114, v51
	ds_write2st64_b32 v123, v0, v80 offset0:24 offset1:28
	v_fma_f32 v0, v89, v78, v117
	v_fma_f32 v78, v89, v79, v117
	v_fmac_f32_e32 v0, v88, v79
	v_fmac_f32_e32 v78, v88, v76
	v_fmac_f32_e32 v0, v87, v76
	v_fmac_f32_e32 v78, v87, v77
	v_fmac_f32_e32 v0, v86, v77
	v_fmac_f32_e32 v78, v86, v74
	v_fmac_f32_e32 v0, v93, v74
	v_fmac_f32_e32 v78, v93, v75
	v_fmac_f32_e32 v0, v92, v75
	v_fmac_f32_e32 v78, v92, v72
	v_fmac_f32_e32 v0, v91, v72
	v_fmac_f32_e32 v78, v91, v73
	v_fmac_f32_e32 v0, v90, v73
	v_fmac_f32_e32 v78, v90, v70
	v_fmac_f32_e32 v0, v97, v70
	v_fmac_f32_e32 v78, v97, v71
	v_fmac_f32_e32 v0, v96, v71
	v_fmac_f32_e32 v78, v96, v68
	v_fmac_f32_e32 v0, v95, v68
	v_fmac_f32_e32 v78, v95, v69
	v_fmac_f32_e32 v0, v94, v69
	v_fmac_f32_e32 v78, v94, v66
	v_fmac_f32_e32 v0, v105, v66
	v_fmac_f32_e32 v78, v105, v67
	v_fmac_f32_e32 v0, v104, v67
	v_fmac_f32_e32 v78, v104, v64
	v_fmac_f32_e32 v0, v103, v64
	v_fmac_f32_e32 v78, v103, v65
	v_fmac_f32_e32 v0, v102, v65
	v_fmac_f32_e32 v78, v102, v62
	v_fmac_f32_e32 v0, v101, v62
	v_fmac_f32_e32 v78, v101, v63
	v_fmac_f32_e32 v0, v100, v63
	v_fmac_f32_e32 v78, v100, v60
	v_fmac_f32_e32 v0, v99, v60
	v_fmac_f32_e32 v78, v99, v61
	v_fmac_f32_e32 v0, v98, v61
	v_fmac_f32_e32 v78, v98, v58
	v_fmac_f32_e32 v0, v106, v58
	v_fmac_f32_e32 v78, v106, v59
	v_fmac_f32_e32 v0, v109, v59
	v_fmac_f32_e32 v78, v109, v56
	v_fmac_f32_e32 v0, v108, v56
	v_fmac_f32_e32 v78, v108, v57
	v_fmac_f32_e32 v0, v107, v57
	v_fmac_f32_e32 v78, v107, v54
	v_fmac_f32_e32 v0, v113, v54
	v_fmac_f32_e32 v78, v113, v55
	v_fmac_f32_e32 v0, v112, v55
	v_fmac_f32_e32 v78, v112, v52
	v_fmac_f32_e32 v0, v111, v52
	v_fmac_f32_e32 v78, v111, v53
	v_fmac_f32_e32 v0, v110, v53
	v_fmac_f32_e32 v78, v110, v50
	v_fmac_f32_e32 v0, v116, v50
	v_fmac_f32_e32 v78, v116, v51
	v_fmac_f32_e32 v0, v115, v51
	s_waitcnt lgkmcnt(7)
	v_fmac_f32_e32 v78, v115, v48
	v_fmac_f32_e32 v0, v114, v48
	v_fmac_f32_e32 v78, v114, v49
	ds_write2st64_b32 v123, v0, v78 offset0:32 offset1:36
	v_fma_f32 v0, v89, v76, v117
	v_fma_f32 v76, v89, v77, v117
	v_fmac_f32_e32 v0, v88, v77
	v_fmac_f32_e32 v76, v88, v74
	v_fmac_f32_e32 v0, v87, v74
	v_fmac_f32_e32 v76, v87, v75
	v_fmac_f32_e32 v0, v86, v75
	v_fmac_f32_e32 v76, v86, v72
	v_fmac_f32_e32 v0, v93, v72
	v_fmac_f32_e32 v76, v93, v73
	v_fmac_f32_e32 v0, v92, v73
	v_fmac_f32_e32 v76, v92, v70
	v_fmac_f32_e32 v0, v91, v70
	v_fmac_f32_e32 v76, v91, v71
	v_fmac_f32_e32 v0, v90, v71
	v_fmac_f32_e32 v76, v90, v68
	v_fmac_f32_e32 v0, v97, v68
	v_fmac_f32_e32 v76, v97, v69
	v_fmac_f32_e32 v0, v96, v69
	v_fmac_f32_e32 v76, v96, v66
	v_fmac_f32_e32 v0, v95, v66
	v_fmac_f32_e32 v76, v95, v67
	v_fmac_f32_e32 v0, v94, v67
	v_fmac_f32_e32 v76, v94, v64
	v_fmac_f32_e32 v0, v105, v64
	v_fmac_f32_e32 v76, v105, v65
	v_fmac_f32_e32 v0, v104, v65
	v_fmac_f32_e32 v76, v104, v62
	v_fmac_f32_e32 v0, v103, v62
	v_fmac_f32_e32 v76, v103, v63
	v_fmac_f32_e32 v0, v102, v63
	v_fmac_f32_e32 v76, v102, v60
	v_fmac_f32_e32 v0, v101, v60
	v_fmac_f32_e32 v76, v101, v61
	v_fmac_f32_e32 v0, v100, v61
	v_fmac_f32_e32 v76, v100, v58
	v_fmac_f32_e32 v0, v99, v58
	v_fmac_f32_e32 v76, v99, v59
	v_fmac_f32_e32 v0, v98, v59
	v_fmac_f32_e32 v76, v98, v56
	v_fmac_f32_e32 v0, v106, v56
	v_fmac_f32_e32 v76, v106, v57
	v_fmac_f32_e32 v0, v109, v57
	v_fmac_f32_e32 v76, v109, v54
	v_fmac_f32_e32 v0, v108, v54
	v_fmac_f32_e32 v76, v108, v55
	v_fmac_f32_e32 v0, v107, v55
	v_fmac_f32_e32 v76, v107, v52
	v_fmac_f32_e32 v0, v113, v52
	v_fmac_f32_e32 v76, v113, v53
	v_fmac_f32_e32 v0, v112, v53
	v_fmac_f32_e32 v76, v112, v50
	v_fmac_f32_e32 v0, v111, v50
	v_fmac_f32_e32 v76, v111, v51
	v_fmac_f32_e32 v0, v110, v51
	v_fmac_f32_e32 v76, v110, v48
	v_fmac_f32_e32 v0, v116, v48
	v_fmac_f32_e32 v76, v116, v49
	v_fmac_f32_e32 v0, v115, v49
	s_waitcnt lgkmcnt(7)
	v_fmac_f32_e32 v76, v115, v46
	v_fmac_f32_e32 v0, v114, v46
	v_fmac_f32_e32 v76, v114, v47
	ds_write2st64_b32 v123, v0, v76 offset0:40 offset1:44
	v_fma_f32 v0, v89, v74, v117
	v_fma_f32 v74, v89, v75, v117
	v_fmac_f32_e32 v0, v88, v75
	v_fmac_f32_e32 v74, v88, v72
	v_fmac_f32_e32 v0, v87, v72
	v_fmac_f32_e32 v74, v87, v73
	v_fmac_f32_e32 v0, v86, v73
	v_fmac_f32_e32 v74, v86, v70
	v_fmac_f32_e32 v0, v93, v70
	v_fmac_f32_e32 v74, v93, v71
	v_fmac_f32_e32 v0, v92, v71
	v_fmac_f32_e32 v74, v92, v68
	v_fmac_f32_e32 v0, v91, v68
	v_fmac_f32_e32 v74, v91, v69
	v_fmac_f32_e32 v0, v90, v69
	v_fmac_f32_e32 v74, v90, v66
	v_fmac_f32_e32 v0, v97, v66
	v_fmac_f32_e32 v74, v97, v67
	v_fmac_f32_e32 v0, v96, v67
	v_fmac_f32_e32 v74, v96, v64
	v_fmac_f32_e32 v0, v95, v64
	v_fmac_f32_e32 v74, v95, v65
	v_fmac_f32_e32 v0, v94, v65
	v_fmac_f32_e32 v74, v94, v62
	v_fmac_f32_e32 v0, v105, v62
	v_fmac_f32_e32 v74, v105, v63
	v_fmac_f32_e32 v0, v104, v63
	v_fmac_f32_e32 v74, v104, v60
	v_fmac_f32_e32 v0, v103, v60
	v_fmac_f32_e32 v74, v103, v61
	v_fmac_f32_e32 v0, v102, v61
	v_fmac_f32_e32 v74, v102, v58
	v_fmac_f32_e32 v0, v101, v58
	v_fmac_f32_e32 v74, v101, v59
	v_fmac_f32_e32 v0, v100, v59
	v_fmac_f32_e32 v74, v100, v56
	v_fmac_f32_e32 v0, v99, v56
	v_fmac_f32_e32 v74, v99, v57
	v_fmac_f32_e32 v0, v98, v57
	v_fmac_f32_e32 v74, v98, v54
	v_fmac_f32_e32 v0, v106, v54
	v_fmac_f32_e32 v74, v106, v55
	v_fmac_f32_e32 v0, v109, v55
	v_fmac_f32_e32 v74, v109, v52
	v_fmac_f32_e32 v0, v108, v52
	v_fmac_f32_e32 v74, v108, v53
	v_fmac_f32_e32 v0, v107, v53
	v_fmac_f32_e32 v74, v107, v50
	v_fmac_f32_e32 v0, v113, v50
	v_fmac_f32_e32 v74, v113, v51
	v_fmac_f32_e32 v0, v112, v51
	v_fmac_f32_e32 v74, v112, v48
	v_fmac_f32_e32 v0, v111, v48
	v_fmac_f32_e32 v74, v111, v49
	v_fmac_f32_e32 v0, v110, v49
	v_fmac_f32_e32 v74, v110, v46
	v_fmac_f32_e32 v0, v116, v46
	v_fmac_f32_e32 v74, v116, v47
	v_fmac_f32_e32 v0, v115, v47
	s_waitcnt lgkmcnt(7)
	v_fmac_f32_e32 v74, v115, v44
	v_fmac_f32_e32 v0, v114, v44
	v_fmac_f32_e32 v74, v114, v45
	ds_write2st64_b32 v123, v0, v74 offset0:48 offset1:52
	v_fma_f32 v0, v89, v72, v117
	v_fma_f32 v72, v89, v73, v117
	v_fmac_f32_e32 v0, v88, v73
	v_fmac_f32_e32 v72, v88, v70
	v_fmac_f32_e32 v0, v87, v70
	v_fmac_f32_e32 v72, v87, v71
	v_fmac_f32_e32 v0, v86, v71
	v_fmac_f32_e32 v72, v86, v68
	v_fmac_f32_e32 v0, v93, v68
	v_fmac_f32_e32 v72, v93, v69
	v_fmac_f32_e32 v0, v92, v69
	v_fmac_f32_e32 v72, v92, v66
	v_fmac_f32_e32 v0, v91, v66
	v_fmac_f32_e32 v72, v91, v67
	v_fmac_f32_e32 v0, v90, v67
	v_fmac_f32_e32 v72, v90, v64
	v_fmac_f32_e32 v0, v97, v64
	v_fmac_f32_e32 v72, v97, v65
	v_fmac_f32_e32 v0, v96, v65
	v_fmac_f32_e32 v72, v96, v62
	v_fmac_f32_e32 v0, v95, v62
	v_fmac_f32_e32 v72, v95, v63
	v_fmac_f32_e32 v0, v94, v63
	v_fmac_f32_e32 v72, v94, v60
	v_fmac_f32_e32 v0, v105, v60
	v_fmac_f32_e32 v72, v105, v61
	v_fmac_f32_e32 v0, v104, v61
	v_fmac_f32_e32 v72, v104, v58
	v_fmac_f32_e32 v0, v103, v58
	v_fmac_f32_e32 v72, v103, v59
	v_fmac_f32_e32 v0, v102, v59
	v_fmac_f32_e32 v72, v102, v56
	v_fmac_f32_e32 v0, v101, v56
	v_fmac_f32_e32 v72, v101, v57
	v_fmac_f32_e32 v0, v100, v57
	v_fmac_f32_e32 v72, v100, v54
	v_fmac_f32_e32 v0, v99, v54
	v_fmac_f32_e32 v72, v99, v55
	v_fmac_f32_e32 v0, v98, v55
	v_fmac_f32_e32 v72, v98, v52
	v_fmac_f32_e32 v0, v106, v52
	v_fmac_f32_e32 v72, v106, v53
	v_fmac_f32_e32 v0, v109, v53
	v_fmac_f32_e32 v72, v109, v50
	v_fmac_f32_e32 v0, v108, v50
	v_fmac_f32_e32 v72, v108, v51
	v_fmac_f32_e32 v0, v107, v51
	v_fmac_f32_e32 v72, v107, v48
	v_fmac_f32_e32 v0, v113, v48
	v_fmac_f32_e32 v72, v113, v49
	v_fmac_f32_e32 v0, v112, v49
	v_fmac_f32_e32 v72, v112, v46
	v_fmac_f32_e32 v0, v111, v46
	v_fmac_f32_e32 v72, v111, v47
	v_fmac_f32_e32 v0, v110, v47
	v_fmac_f32_e32 v72, v110, v44
	v_fmac_f32_e32 v0, v116, v44
	v_fmac_f32_e32 v72, v116, v45
	v_fmac_f32_e32 v0, v115, v45
	s_waitcnt lgkmcnt(7)
	v_fmac_f32_e32 v72, v115, v42
	v_fmac_f32_e32 v0, v114, v42
	v_fmac_f32_e32 v72, v114, v43
	s_lshl_b32 s0, s2, 11
	ds_write2st64_b32 v123, v0, v72 offset0:56 offset1:60
	v_lshl_add_u32 v46, v84, 4, 0
	s_or_b32 s8, s0, s15
	s_lshl_b32 s0, s35, 12
	s_waitcnt lgkmcnt(0)
	s_barrier
	v_add_u32_e32 v55, s0, v46
	ds_read_b128 v[42:45], v55 offset:63488
	s_lshl_b32 s21, s35, 2
	s_mov_b32 s7, 0x10f60000
	s_waitcnt lgkmcnt(0)
	v_mov_b32_e32 v48, v43
	v_mov_b32_e32 v49, v44
	v_mov_b32_e32 v50, v42
	v_mov_b32_e32 v51, v45
	v_pk_add_f32 v[48:49], v[48:49], v[50:51]
	s_nop 0
	v_add_f32_e32 v0, v48, v49
	s_nop 1
	v_add_f32_dpp v0, v0, v0 quad_perm:[1,0,3,2] row_mask:0xf bank_mask:0xf bound_ctrl:1
	s_nop 1
	v_add_f32_dpp v0, v0, v0 quad_perm:[2,3,0,1] row_mask:0xf bank_mask:0xf bound_ctrl:1
	s_nop 1
	v_add_f32_dpp v0, v0, v0 row_half_mirror row_mask:0xf bank_mask:0xf bound_ctrl:1
	s_nop 1
	v_add_f32_dpp v0, v0, v0 row_mirror row_mask:0xf bank_mask:0xf bound_ctrl:1
	v_fmamk_f32 v43, v0, 0xbc800000, v43
	v_fmamk_f32 v42, v0, 0xbc800000, v42
	v_fmamk_f32 v45, v0, 0xbc800000, v45
	v_fmac_f32_e32 v44, 0xbc800000, v0
	v_pk_mul_f32 v[48:49], v[44:45], v[44:45]
	v_pk_mul_f32 v[50:51], v[42:43], v[42:43]
	s_nop 0
	v_pk_mov_b32 v[52:53], v[50:51], v[48:49] op_sel:[1,0]
	v_mov_b32_e32 v51, v49
	v_pk_add_f32 v[48:49], v[52:53], v[50:51]
	s_nop 0
	v_add_f32_e32 v0, v48, v49
	s_nop 1
	v_add_f32_dpp v0, v0, v0 quad_perm:[1,0,3,2] row_mask:0xf bank_mask:0xf bound_ctrl:1
	s_nop 1
	v_add_f32_dpp v0, v0, v0 quad_perm:[2,3,0,1] row_mask:0xf bank_mask:0xf bound_ctrl:1
	s_nop 1
	v_add_f32_dpp v0, v0, v0 row_half_mirror row_mask:0xf bank_mask:0xf bound_ctrl:1
	s_nop 1
	v_add_f32_dpp v0, v0, v0 row_mirror row_mask:0xf bank_mask:0xf bound_ctrl:1
	v_fmamk_f32 v0, v0, 0x3c800000, v216
	v_cmp_gt_f32_e32 vcc, s60, v0
	v_mul_f32_e32 v47, 0x4f800000, v0
	s_nop 0
	v_cndmask_b32_e32 v0, v0, v47, vcc
	v_sqrt_f32_e32 v47, v0
	s_nop 0
	v_add_u32_e32 v48, -1, v47
	v_fma_f32 v49, -v48, v47, v0
	v_cmp_ge_f32_e64 s[2:3], 0, v49
	v_add_u32_e32 v49, 1, v47
	s_nop 0
	v_cndmask_b32_e64 v48, v47, v48, s[2:3]
	v_fma_f32 v47, -v49, v47, v0
	v_cmp_lt_f32_e64 s[2:3], 0, v47
	s_nop 1
	v_cndmask_b32_e64 v47, v48, v49, s[2:3]
	v_mul_f32_e32 v48, 0x37800000, v47
	v_cndmask_b32_e32 v47, v47, v48, vcc
	v_cmp_class_f32_e32 vcc, v0, v217
	s_nop 1
	v_cndmask_b32_e32 v0, v47, v0, vcc
	v_div_scale_f32 v47, s[0:1], v0, v0, 1.0
	v_rcp_f32_e32 v48, v47
	s_nop 0
	v_fma_f32 v49, -v47, v48, 1.0
	v_fmac_f32_e32 v48, v49, v48
	v_div_scale_f32 v49, vcc, 1.0, v0, 1.0
	v_mul_f32_e32 v50, v49, v48
	v_fma_f32 v51, -v47, v50, v49
	v_fmac_f32_e32 v50, v51, v48
	v_fma_f32 v47, -v47, v50, v49
	v_div_fmas_f32 v47, v47, v48, v50
	v_div_fixup_f32 v0, v47, v0, 1.0
	v_pk_mul_f32 v[42:43], v[42:43], v[0:1] op_sel_hi:[1,0]
	v_pk_mul_f32 v[44:45], v[44:45], v[0:1] op_sel_hi:[1,0]
	s_waitcnt vmcnt(0)
	v_pk_fma_f32 v[42:43], v[2:3], v[42:43], v[6:7]
	v_pk_fma_f32 v[44:45], v[4:5], v[44:45], v[8:9]
	v_mul_f32_e32 v0, 0xbfb8aa3b, v42
	v_fma_f32 v47, v42, s34, -v0
	v_rndne_f32_e32 v48, v0
	v_fmac_f32_e32 v47, 0xb2a5705f, v42
	v_sub_f32_e32 v0, v0, v48
	v_add_f32_e32 v0, v0, v47
	v_exp_f32_e32 v0, v0
	v_cvt_i32_f32_e32 v47, v48
	v_cmp_nlt_f32_e32 vcc, s55, v42
	v_ldexp_f32 v0, v0, v47
	s_nop 0
	v_cndmask_b32_e32 v0, 0, v0, vcc
	v_cmp_ngt_f32_e32 vcc, s56, v42
	s_nop 1
	v_cndmask_b32_e32 v0, v219, v0, vcc
	v_add_f32_e32 v0, 1.0, v0
	v_div_scale_f32 v47, s[0:1], v0, v0, v42
	v_rcp_f32_e32 v48, v47
	s_nop 0
	v_fma_f32 v49, -v47, v48, 1.0
	v_fmac_f32_e32 v48, v49, v48
	v_div_scale_f32 v49, vcc, v42, v0, v42
	v_mul_f32_e32 v50, v49, v48
	v_fma_f32 v51, -v47, v50, v49
	v_fmac_f32_e32 v50, v51, v48
	v_fma_f32 v47, -v47, v50, v49
	v_div_fmas_f32 v47, v47, v48, v50
	v_div_fixup_f32 v0, v47, v0, v42
	v_mul_f32_e32 v42, 0xbfb8aa3b, v43
	v_fma_f32 v47, v43, s34, -v42
	v_rndne_f32_e32 v48, v42
	v_fmac_f32_e32 v47, 0xb2a5705f, v43
	v_sub_f32_e32 v42, v42, v48
	v_add_f32_e32 v42, v42, v47
	v_exp_f32_e32 v42, v42
	v_cvt_i32_f32_e32 v47, v48
	v_cmp_nlt_f32_e32 vcc, s55, v43
	v_ldexp_f32 v42, v42, v47
	s_nop 0
	v_cndmask_b32_e32 v42, 0, v42, vcc
	v_cmp_ngt_f32_e32 vcc, s56, v43
	s_nop 1
	v_cndmask_b32_e32 v42, v219, v42, vcc
	v_add_f32_e32 v42, 1.0, v42
	v_div_scale_f32 v47, s[0:1], v42, v42, v43
	v_rcp_f32_e32 v48, v47
	s_nop 0
	v_fma_f32 v49, -v47, v48, 1.0
	v_fmac_f32_e32 v48, v49, v48
	v_div_scale_f32 v49, vcc, v43, v42, v43
	v_mul_f32_e32 v50, v49, v48
	v_fma_f32 v51, -v47, v50, v49
	v_fmac_f32_e32 v50, v51, v48
	v_fma_f32 v47, -v47, v50, v49
	v_div_fmas_f32 v47, v47, v48, v50
	v_div_fixup_f32 v42, v47, v42, v43
	v_cvt_pk_bf16_f32 v42, v0, v42
	v_mul_f32_e32 v0, 0xbfb8aa3b, v44
	v_fma_f32 v43, v44, s34, -v0
	v_rndne_f32_e32 v47, v0
	v_fmac_f32_e32 v43, 0xb2a5705f, v44
	v_sub_f32_e32 v0, v0, v47
	v_add_f32_e32 v0, v0, v43
	v_exp_f32_e32 v0, v0
	v_cvt_i32_f32_e32 v43, v47
	v_cmp_nlt_f32_e32 vcc, s55, v44
	v_ldexp_f32 v0, v0, v43
	s_nop 0
	v_cndmask_b32_e32 v0, 0, v0, vcc
	v_cmp_ngt_f32_e32 vcc, s56, v44
	s_nop 1
	v_cndmask_b32_e32 v0, v219, v0, vcc
	v_add_f32_e32 v0, 1.0, v0
	v_div_scale_f32 v43, s[0:1], v0, v0, v44
	v_rcp_f32_e32 v47, v43
	s_nop 0
	v_fma_f32 v48, -v43, v47, 1.0
	v_fmac_f32_e32 v47, v48, v47
	v_div_scale_f32 v48, vcc, v44, v0, v44
	v_mul_f32_e32 v49, v48, v47
	v_fma_f32 v50, -v43, v49, v48
	v_fmac_f32_e32 v49, v50, v47
	v_fma_f32 v43, -v43, v49, v48
	v_div_fmas_f32 v43, v43, v47, v49
	v_div_fixup_f32 v0, v43, v0, v44
	v_mul_f32_e32 v43, 0xbfb8aa3b, v45
	v_fma_f32 v44, v45, s34, -v43
	v_rndne_f32_e32 v47, v43
	v_fmac_f32_e32 v44, 0xb2a5705f, v45
	v_sub_f32_e32 v43, v43, v47
	v_add_f32_e32 v43, v43, v44
	v_exp_f32_e32 v43, v43
	v_cvt_i32_f32_e32 v44, v47
	v_cmp_nlt_f32_e32 vcc, s55, v45
	v_ldexp_f32 v43, v43, v44
	s_nop 0
	v_cndmask_b32_e32 v43, 0, v43, vcc
	v_cmp_ngt_f32_e32 vcc, s56, v45
	s_nop 1
	v_cndmask_b32_e32 v43, v219, v43, vcc
	v_add_f32_e32 v43, 1.0, v43
	v_div_scale_f32 v44, s[0:1], v43, v43, v45
	v_rcp_f32_e32 v47, v44
	s_add_i32 s0, s8, s21
	s_ashr_i32 s1, s0, 31
	s_lshl_b64 s[0:1], s[0:1], 11
	v_fma_f32 v48, -v44, v47, 1.0
	v_fmac_f32_e32 v47, v48, v47
	v_div_scale_f32 v48, vcc, v45, v43, v45
	v_mul_f32_e32 v49, v48, v47
	v_fma_f32 v50, -v44, v49, v48
	v_fmac_f32_e32 v49, v50, v47
	v_fma_f32 v44, -v44, v49, v48
	v_div_fmas_f32 v44, v44, v47, v49
	v_div_fixup_f32 v43, v44, v43, v45
	s_add_u32 s0, s4, s0
	v_cvt_pk_bf16_f32 v43, v0, v43
	s_addc_u32 s1, s5, s1
	v_lshlrev_b32_e32 v0, 1, v128
	v_lshl_add_u64 v[44:45], s[0:1], 0, v[0:1]
	s_or_b32 s19, s21, 1
	v_add_co_u32_e32 v44, vcc, s7, v44
	s_lshl_b32 s0, s19, 10
	s_nop 0
	v_addc_co_u32_e32 v45, vcc, 0, v45, vcc
	v_add_u32_e32 v54, s0, v46
	global_store_dwordx2 v[44:45], v[42:43], off offset:1536
	ds_read_b128 v[42:45], v54 offset:63488
	s_waitcnt lgkmcnt(0)
	v_mov_b32_e32 v48, v43
	v_mov_b32_e32 v49, v44
	v_mov_b32_e32 v50, v42
	v_mov_b32_e32 v51, v45
	v_pk_add_f32 v[48:49], v[48:49], v[50:51]
	s_nop 0
	v_add_f32_e32 v47, v48, v49
	s_nop 1
	v_add_f32_dpp v47, v47, v47 quad_perm:[1,0,3,2] row_mask:0xf bank_mask:0xf bound_ctrl:1
	s_nop 1
	v_add_f32_dpp v47, v47, v47 quad_perm:[2,3,0,1] row_mask:0xf bank_mask:0xf bound_ctrl:1
	s_nop 1
	v_add_f32_dpp v47, v47, v47 row_half_mirror row_mask:0xf bank_mask:0xf bound_ctrl:1
	s_nop 1
	v_add_f32_dpp v47, v47, v47 row_mirror row_mask:0xf bank_mask:0xf bound_ctrl:1
	v_fmamk_f32 v43, v47, 0xbc800000, v43
	v_fmamk_f32 v42, v47, 0xbc800000, v42
	v_fmamk_f32 v45, v47, 0xbc800000, v45
	v_fmac_f32_e32 v44, 0xbc800000, v47
	v_pk_mul_f32 v[48:49], v[44:45], v[44:45]
	v_pk_mul_f32 v[50:51], v[42:43], v[42:43]
	s_nop 0
	v_pk_mov_b32 v[52:53], v[50:51], v[48:49] op_sel:[1,0]
	v_mov_b32_e32 v51, v49
	v_pk_add_f32 v[48:49], v[52:53], v[50:51]
	s_nop 0
	v_add_f32_e32 v47, v48, v49
	s_nop 1
	v_add_f32_dpp v47, v47, v47 quad_perm:[1,0,3,2] row_mask:0xf bank_mask:0xf bound_ctrl:1
	s_nop 1
	v_add_f32_dpp v47, v47, v47 quad_perm:[2,3,0,1] row_mask:0xf bank_mask:0xf bound_ctrl:1
	s_nop 1
	v_add_f32_dpp v47, v47, v47 row_half_mirror row_mask:0xf bank_mask:0xf bound_ctrl:1
	s_nop 1
	v_add_f32_dpp v47, v47, v47 row_mirror row_mask:0xf bank_mask:0xf bound_ctrl:1
	v_fmamk_f32 v47, v47, 0x3c800000, v216
	v_cmp_gt_f32_e32 vcc, s60, v47
	v_mul_f32_e32 v48, 0x4f800000, v47
	s_nop 0
	v_cndmask_b32_e32 v47, v47, v48, vcc
	v_sqrt_f32_e32 v48, v47
	s_nop 0
	v_add_u32_e32 v49, -1, v48
	v_fma_f32 v50, -v49, v48, v47
	v_cmp_ge_f32_e64 s[2:3], 0, v50
	v_add_u32_e32 v50, 1, v48
	s_nop 0
	v_cndmask_b32_e64 v49, v48, v49, s[2:3]
	v_fma_f32 v48, -v50, v48, v47
	v_cmp_lt_f32_e64 s[2:3], 0, v48
	s_nop 1
	v_cndmask_b32_e64 v48, v49, v50, s[2:3]
	v_mul_f32_e32 v49, 0x37800000, v48
	v_cndmask_b32_e32 v48, v48, v49, vcc
	v_cmp_class_f32_e32 vcc, v47, v217
	s_nop 1
	v_cndmask_b32_e32 v47, v48, v47, vcc
	v_div_scale_f32 v48, s[0:1], v47, v47, 1.0
	v_rcp_f32_e32 v49, v48
	s_nop 0
	v_fma_f32 v50, -v48, v49, 1.0
	v_fmac_f32_e32 v49, v50, v49
	v_div_scale_f32 v50, vcc, 1.0, v47, 1.0
	v_mul_f32_e32 v51, v50, v49
	v_fma_f32 v52, -v48, v51, v50
	v_fmac_f32_e32 v51, v52, v49
	v_fma_f32 v48, -v48, v51, v50
	v_div_fmas_f32 v48, v48, v49, v51
	v_div_fixup_f32 v48, v48, v47, 1.0
	v_pk_mul_f32 v[50:51], v[42:43], v[48:49] op_sel_hi:[1,0]
	v_pk_mul_f32 v[42:43], v[44:45], v[48:49] op_sel_hi:[1,0]
	v_pk_fma_f32 v[44:45], v[2:3], v[50:51], v[6:7]
	v_pk_fma_f32 v[42:43], v[4:5], v[42:43], v[8:9]
	v_mul_f32_e32 v47, 0xbfb8aa3b, v44
	v_fma_f32 v48, v44, s34, -v47
	v_rndne_f32_e32 v49, v47
	v_fmac_f32_e32 v48, 0xb2a5705f, v44
	v_sub_f32_e32 v47, v47, v49
	v_add_f32_e32 v47, v47, v48
	v_exp_f32_e32 v47, v47
	v_cvt_i32_f32_e32 v48, v49
	v_cmp_nlt_f32_e32 vcc, s55, v44
	v_ldexp_f32 v47, v47, v48
	s_nop 0
	v_cndmask_b32_e32 v47, 0, v47, vcc
	v_cmp_ngt_f32_e32 vcc, s56, v44
	s_nop 1
	v_cndmask_b32_e32 v47, v219, v47, vcc
	v_add_f32_e32 v47, 1.0, v47
	v_div_scale_f32 v48, s[0:1], v47, v47, v44
	v_rcp_f32_e32 v49, v48
	s_nop 0
	v_fma_f32 v50, -v48, v49, 1.0
	v_fmac_f32_e32 v49, v50, v49
	v_div_scale_f32 v50, vcc, v44, v47, v44
	v_mul_f32_e32 v51, v50, v49
	v_fma_f32 v52, -v48, v51, v50
	v_fmac_f32_e32 v51, v52, v49
	v_fma_f32 v48, -v48, v51, v50
	v_div_fmas_f32 v48, v48, v49, v51
	v_div_fixup_f32 v44, v48, v47, v44
	v_mul_f32_e32 v47, 0xbfb8aa3b, v45
	v_fma_f32 v48, v45, s34, -v47
	v_rndne_f32_e32 v49, v47
	v_fmac_f32_e32 v48, 0xb2a5705f, v45
	v_sub_f32_e32 v47, v47, v49
	v_add_f32_e32 v47, v47, v48
	v_exp_f32_e32 v47, v47
	v_cvt_i32_f32_e32 v48, v49
	v_cmp_nlt_f32_e32 vcc, s55, v45
	v_ldexp_f32 v47, v47, v48
	s_nop 0
	v_cndmask_b32_e32 v47, 0, v47, vcc
	v_cmp_ngt_f32_e32 vcc, s56, v45
	s_nop 1
	v_cndmask_b32_e32 v47, v219, v47, vcc
	v_add_f32_e32 v47, 1.0, v47
	v_div_scale_f32 v48, s[0:1], v47, v47, v45
	v_rcp_f32_e32 v49, v48
	s_nop 0
	v_fma_f32 v50, -v48, v49, 1.0
	v_fmac_f32_e32 v49, v50, v49
	v_div_scale_f32 v50, vcc, v45, v47, v45
	v_mul_f32_e32 v51, v50, v49
	v_fma_f32 v52, -v48, v51, v50
	v_fmac_f32_e32 v51, v52, v49
	v_fma_f32 v48, -v48, v51, v50
	v_div_fmas_f32 v48, v48, v49, v51
	v_div_fixup_f32 v45, v48, v47, v45
	v_cvt_pk_bf16_f32 v44, v44, v45
	v_mul_f32_e32 v45, 0xbfb8aa3b, v42
	v_fma_f32 v47, v42, s34, -v45
	v_rndne_f32_e32 v48, v45
	v_fmac_f32_e32 v47, 0xb2a5705f, v42
	v_sub_f32_e32 v45, v45, v48
	v_add_f32_e32 v45, v45, v47
	v_exp_f32_e32 v45, v45
	v_cvt_i32_f32_e32 v47, v48
	v_cmp_nlt_f32_e32 vcc, s55, v42
	v_ldexp_f32 v45, v45, v47
	s_nop 0
	v_cndmask_b32_e32 v45, 0, v45, vcc
	v_cmp_ngt_f32_e32 vcc, s56, v42
	s_nop 1
	v_cndmask_b32_e32 v45, v219, v45, vcc
	v_add_f32_e32 v45, 1.0, v45
	v_div_scale_f32 v47, s[0:1], v45, v45, v42
	v_rcp_f32_e32 v48, v47
	s_nop 0
	v_fma_f32 v49, -v47, v48, 1.0
	v_fmac_f32_e32 v48, v49, v48
	v_div_scale_f32 v49, vcc, v42, v45, v42
	v_mul_f32_e32 v50, v49, v48
	v_fma_f32 v51, -v47, v50, v49
	v_fmac_f32_e32 v50, v51, v48
	v_fma_f32 v47, -v47, v50, v49
	v_div_fmas_f32 v47, v47, v48, v50
	v_div_fixup_f32 v42, v47, v45, v42
	v_mul_f32_e32 v45, 0xbfb8aa3b, v43
	v_fma_f32 v47, v43, s34, -v45
	v_rndne_f32_e32 v48, v45
	v_fmac_f32_e32 v47, 0xb2a5705f, v43
	v_sub_f32_e32 v45, v45, v48
	v_add_f32_e32 v45, v45, v47
	v_exp_f32_e32 v45, v45
	v_cvt_i32_f32_e32 v47, v48
	v_cmp_nlt_f32_e32 vcc, s55, v43
	v_ldexp_f32 v45, v45, v47
	s_nop 0
	v_cndmask_b32_e32 v45, 0, v45, vcc
	v_cmp_ngt_f32_e32 vcc, s56, v43
	s_nop 1
	v_cndmask_b32_e32 v45, v219, v45, vcc
	v_add_f32_e32 v45, 1.0, v45
	v_div_scale_f32 v47, s[0:1], v45, v45, v43
	v_rcp_f32_e32 v48, v47
	s_add_i32 s0, s8, s19
	s_ashr_i32 s1, s0, 31
	s_lshl_b64 s[0:1], s[0:1], 11
	v_fma_f32 v49, -v47, v48, 1.0
	v_fmac_f32_e32 v48, v49, v48
	v_div_scale_f32 v49, vcc, v43, v45, v43
	v_mul_f32_e32 v50, v49, v48
	v_fma_f32 v51, -v47, v50, v49
	v_fmac_f32_e32 v50, v51, v48
	v_fma_f32 v47, -v47, v50, v49
	v_div_fmas_f32 v47, v47, v48, v50
	v_div_fixup_f32 v43, v47, v45, v43
	s_add_u32 s0, s4, s0
	s_addc_u32 s1, s5, s1
	v_cvt_pk_bf16_f32 v45, v42, v43
	v_lshl_add_u64 v[42:43], s[0:1], 0, v[0:1]
	s_or_b32 s20, s21, 2
	v_add_co_u32_e32 v42, vcc, s7, v42
	s_lshl_b32 s0, s20, 10
	s_nop 0
	v_addc_co_u32_e32 v43, vcc, 0, v43, vcc
	v_add_u32_e32 v53, s0, v46
	global_store_dwordx2 v[42:43], v[44:45], off offset:1536
	ds_read_b128 v[42:45], v53 offset:63488
	s_waitcnt lgkmcnt(0)
	v_mov_b32_e32 v48, v43
	v_mov_b32_e32 v49, v44
	v_mov_b32_e32 v50, v42
	v_mov_b32_e32 v51, v45
	v_pk_add_f32 v[48:49], v[48:49], v[50:51]
	s_nop 0
	v_add_f32_e32 v47, v48, v49
	s_nop 1
	v_add_f32_dpp v47, v47, v47 quad_perm:[1,0,3,2] row_mask:0xf bank_mask:0xf bound_ctrl:1
	s_nop 1
	v_add_f32_dpp v47, v47, v47 quad_perm:[2,3,0,1] row_mask:0xf bank_mask:0xf bound_ctrl:1
	s_nop 1
	v_add_f32_dpp v47, v47, v47 row_half_mirror row_mask:0xf bank_mask:0xf bound_ctrl:1
	s_nop 1
	v_add_f32_dpp v47, v47, v47 row_mirror row_mask:0xf bank_mask:0xf bound_ctrl:1
	v_fmamk_f32 v43, v47, 0xbc800000, v43
	v_fmamk_f32 v42, v47, 0xbc800000, v42
	v_fmamk_f32 v45, v47, 0xbc800000, v45
	v_fmac_f32_e32 v44, 0xbc800000, v47
	v_pk_mul_f32 v[48:49], v[44:45], v[44:45]
	v_pk_mul_f32 v[50:51], v[42:43], v[42:43]
	s_nop 0
	v_pk_mov_b32 v[56:57], v[50:51], v[48:49] op_sel:[1,0]
	v_mov_b32_e32 v51, v49
	v_pk_add_f32 v[48:49], v[56:57], v[50:51]
	s_nop 0
	v_add_f32_e32 v47, v48, v49
	s_nop 1
	v_add_f32_dpp v47, v47, v47 quad_perm:[1,0,3,2] row_mask:0xf bank_mask:0xf bound_ctrl:1
	s_nop 1
	v_add_f32_dpp v47, v47, v47 quad_perm:[2,3,0,1] row_mask:0xf bank_mask:0xf bound_ctrl:1
	s_nop 1
	v_add_f32_dpp v47, v47, v47 row_half_mirror row_mask:0xf bank_mask:0xf bound_ctrl:1
	s_nop 1
	v_add_f32_dpp v47, v47, v47 row_mirror row_mask:0xf bank_mask:0xf bound_ctrl:1
	v_fmamk_f32 v47, v47, 0x3c800000, v216
	v_cmp_gt_f32_e32 vcc, s60, v47
	v_mul_f32_e32 v48, 0x4f800000, v47
	s_nop 0
	v_cndmask_b32_e32 v47, v47, v48, vcc
	v_sqrt_f32_e32 v48, v47
	s_nop 0
	v_add_u32_e32 v49, -1, v48
	v_fma_f32 v50, -v49, v48, v47
	v_cmp_ge_f32_e64 s[2:3], 0, v50
	v_add_u32_e32 v50, 1, v48
	s_nop 0
	v_cndmask_b32_e64 v49, v48, v49, s[2:3]
	v_fma_f32 v48, -v50, v48, v47
	v_cmp_lt_f32_e64 s[2:3], 0, v48
	s_nop 1
	v_cndmask_b32_e64 v48, v49, v50, s[2:3]
	v_mul_f32_e32 v49, 0x37800000, v48
	v_cndmask_b32_e32 v48, v48, v49, vcc
	v_cmp_class_f32_e32 vcc, v47, v217
	s_nop 1
	v_cndmask_b32_e32 v47, v48, v47, vcc
	v_div_scale_f32 v48, s[0:1], v47, v47, 1.0
	v_rcp_f32_e32 v49, v48
	s_nop 0
	v_fma_f32 v50, -v48, v49, 1.0
	v_fmac_f32_e32 v49, v50, v49
	v_div_scale_f32 v50, vcc, 1.0, v47, 1.0
	v_mul_f32_e32 v51, v50, v49
	v_fma_f32 v52, -v48, v51, v50
	v_fmac_f32_e32 v51, v52, v49
	v_fma_f32 v48, -v48, v51, v50
	v_div_fmas_f32 v48, v48, v49, v51
	v_div_fixup_f32 v48, v48, v47, 1.0
	v_pk_mul_f32 v[42:43], v[42:43], v[48:49] op_sel_hi:[1,0]
	v_pk_mul_f32 v[44:45], v[44:45], v[48:49] op_sel_hi:[1,0]
	v_pk_fma_f32 v[42:43], v[2:3], v[42:43], v[6:7]
	v_pk_fma_f32 v[44:45], v[4:5], v[44:45], v[8:9]
	v_mul_f32_e32 v47, 0xbfb8aa3b, v42
	v_fma_f32 v48, v42, s34, -v47
	v_rndne_f32_e32 v49, v47
	v_fmac_f32_e32 v48, 0xb2a5705f, v42
	v_sub_f32_e32 v47, v47, v49
	v_add_f32_e32 v47, v47, v48
	v_exp_f32_e32 v47, v47
	v_cvt_i32_f32_e32 v48, v49
	v_cmp_nlt_f32_e32 vcc, s55, v42
	v_ldexp_f32 v47, v47, v48
	s_nop 0
	v_cndmask_b32_e32 v47, 0, v47, vcc
	v_cmp_ngt_f32_e32 vcc, s56, v42
	s_nop 1
	v_cndmask_b32_e32 v47, v219, v47, vcc
	v_add_f32_e32 v47, 1.0, v47
	v_div_scale_f32 v48, s[0:1], v47, v47, v42
	v_rcp_f32_e32 v49, v48
	s_nop 0
	v_fma_f32 v50, -v48, v49, 1.0
	v_fmac_f32_e32 v49, v50, v49
	v_div_scale_f32 v50, vcc, v42, v47, v42
	v_mul_f32_e32 v51, v50, v49
	v_fma_f32 v52, -v48, v51, v50
	v_fmac_f32_e32 v51, v52, v49
	v_fma_f32 v48, -v48, v51, v50
	v_div_fmas_f32 v48, v48, v49, v51
	v_div_fixup_f32 v42, v48, v47, v42
	v_mul_f32_e32 v47, 0xbfb8aa3b, v43
	v_fma_f32 v48, v43, s34, -v47
	v_rndne_f32_e32 v49, v47
	v_fmac_f32_e32 v48, 0xb2a5705f, v43
	v_sub_f32_e32 v47, v47, v49
	v_add_f32_e32 v47, v47, v48
	v_exp_f32_e32 v47, v47
	v_cvt_i32_f32_e32 v48, v49
	v_cmp_nlt_f32_e32 vcc, s55, v43
	v_ldexp_f32 v47, v47, v48
	s_nop 0
	v_cndmask_b32_e32 v47, 0, v47, vcc
	v_cmp_ngt_f32_e32 vcc, s56, v43
	s_nop 1
	v_cndmask_b32_e32 v47, v219, v47, vcc
	v_add_f32_e32 v47, 1.0, v47
	v_div_scale_f32 v48, s[0:1], v47, v47, v43
	v_rcp_f32_e32 v49, v48
	s_nop 0
	v_fma_f32 v50, -v48, v49, 1.0
	v_fmac_f32_e32 v49, v50, v49
	v_div_scale_f32 v50, vcc, v43, v47, v43
	v_mul_f32_e32 v51, v50, v49
	v_fma_f32 v52, -v48, v51, v50
	v_fmac_f32_e32 v51, v52, v49
	v_fma_f32 v48, -v48, v51, v50
	v_div_fmas_f32 v48, v48, v49, v51
	v_div_fixup_f32 v43, v48, v47, v43
	v_cvt_pk_bf16_f32 v42, v42, v43
	v_mul_f32_e32 v43, 0xbfb8aa3b, v44
	v_fma_f32 v47, v44, s34, -v43
	v_rndne_f32_e32 v48, v43
	v_fmac_f32_e32 v47, 0xb2a5705f, v44
	v_sub_f32_e32 v43, v43, v48
	v_add_f32_e32 v43, v43, v47
	v_exp_f32_e32 v43, v43
	v_cvt_i32_f32_e32 v47, v48
	v_cmp_nlt_f32_e32 vcc, s55, v44
	v_ldexp_f32 v43, v43, v47
	s_nop 0
	v_cndmask_b32_e32 v43, 0, v43, vcc
	v_cmp_ngt_f32_e32 vcc, s56, v44
	s_nop 1
	v_cndmask_b32_e32 v43, v219, v43, vcc
	v_add_f32_e32 v43, 1.0, v43
	v_div_scale_f32 v47, s[0:1], v43, v43, v44
	v_rcp_f32_e32 v48, v47
	s_nop 0
	v_fma_f32 v49, -v47, v48, 1.0
	v_fmac_f32_e32 v48, v49, v48
	v_div_scale_f32 v49, vcc, v44, v43, v44
	v_mul_f32_e32 v50, v49, v48
	v_fma_f32 v51, -v47, v50, v49
	v_fmac_f32_e32 v50, v51, v48
	v_fma_f32 v47, -v47, v50, v49
	v_div_fmas_f32 v47, v47, v48, v50
	v_div_fixup_f32 v43, v47, v43, v44
	v_mul_f32_e32 v44, 0xbfb8aa3b, v45
	v_fma_f32 v47, v45, s34, -v44
	v_rndne_f32_e32 v48, v44
	v_fmac_f32_e32 v47, 0xb2a5705f, v45
	v_sub_f32_e32 v44, v44, v48
	v_add_f32_e32 v44, v44, v47
	v_exp_f32_e32 v44, v44
	v_cvt_i32_f32_e32 v47, v48
	v_cmp_nlt_f32_e32 vcc, s55, v45
	v_ldexp_f32 v44, v44, v47
	s_nop 0
	v_cndmask_b32_e32 v44, 0, v44, vcc
	v_cmp_ngt_f32_e32 vcc, s56, v45
	s_nop 1
	v_cndmask_b32_e32 v44, v219, v44, vcc
	v_add_f32_e32 v44, 1.0, v44
	v_div_scale_f32 v47, s[0:1], v44, v44, v45
	v_rcp_f32_e32 v48, v47
	s_add_i32 s0, s8, s20
	s_ashr_i32 s1, s0, 31
	s_lshl_b64 s[0:1], s[0:1], 11
	v_fma_f32 v49, -v47, v48, 1.0
	v_fmac_f32_e32 v48, v49, v48
	v_div_scale_f32 v49, vcc, v45, v44, v45
	v_mul_f32_e32 v50, v49, v48
	v_fma_f32 v51, -v47, v50, v49
	v_fmac_f32_e32 v50, v51, v48
	v_fma_f32 v47, -v47, v50, v49
	v_div_fmas_f32 v47, v47, v48, v50
	v_div_fixup_f32 v44, v47, v44, v45
	s_add_u32 s0, s4, s0
	s_addc_u32 s1, s5, s1
	v_cvt_pk_bf16_f32 v43, v43, v44
	v_lshl_add_u64 v[44:45], s[0:1], 0, v[0:1]
	v_add_co_u32_e32 v44, vcc, s7, v44
	s_or_b32 s7, s21, 3
	s_lshl_b32 s0, s7, 10
	v_addc_co_u32_e32 v45, vcc, 0, v45, vcc
	v_add_u32_e32 v52, s0, v46
	global_store_dwordx2 v[44:45], v[42:43], off offset:1536
	ds_read_b128 v[42:45], v52 offset:63488
	s_waitcnt lgkmcnt(0)
	v_mov_b32_e32 v46, v43
	v_mov_b32_e32 v47, v44
	v_mov_b32_e32 v48, v42
	v_mov_b32_e32 v49, v45
	v_pk_add_f32 v[46:47], v[46:47], v[48:49]
	s_nop 0
	v_add_f32_e32 v46, v46, v47
	s_nop 1
	v_add_f32_dpp v46, v46, v46 quad_perm:[1,0,3,2] row_mask:0xf bank_mask:0xf bound_ctrl:1
	s_nop 1
	v_add_f32_dpp v46, v46, v46 quad_perm:[2,3,0,1] row_mask:0xf bank_mask:0xf bound_ctrl:1
	s_nop 1
	v_add_f32_dpp v46, v46, v46 row_half_mirror row_mask:0xf bank_mask:0xf bound_ctrl:1
	s_nop 1
	v_add_f32_dpp v46, v46, v46 row_mirror row_mask:0xf bank_mask:0xf bound_ctrl:1
	v_fmamk_f32 v43, v46, 0xbc800000, v43
	v_fmamk_f32 v42, v46, 0xbc800000, v42
	v_fmamk_f32 v45, v46, 0xbc800000, v45
	v_fmac_f32_e32 v44, 0xbc800000, v46
	v_pk_mul_f32 v[46:47], v[44:45], v[44:45]
	v_pk_mul_f32 v[48:49], v[42:43], v[42:43]
	s_nop 0
	v_pk_mov_b32 v[50:51], v[48:49], v[46:47] op_sel:[1,0]
	v_mov_b32_e32 v49, v47
	v_pk_add_f32 v[46:47], v[50:51], v[48:49]
	s_nop 0
	v_add_f32_e32 v46, v46, v47
	s_nop 1
	v_add_f32_dpp v46, v46, v46 quad_perm:[1,0,3,2] row_mask:0xf bank_mask:0xf bound_ctrl:1
	s_nop 1
	v_add_f32_dpp v46, v46, v46 quad_perm:[2,3,0,1] row_mask:0xf bank_mask:0xf bound_ctrl:1
	s_nop 1
	v_add_f32_dpp v46, v46, v46 row_half_mirror row_mask:0xf bank_mask:0xf bound_ctrl:1
	s_nop 1
	v_add_f32_dpp v46, v46, v46 row_mirror row_mask:0xf bank_mask:0xf bound_ctrl:1
	v_fmamk_f32 v46, v46, 0x3c800000, v216
	v_cmp_gt_f32_e32 vcc, s60, v46
	v_mul_f32_e32 v47, 0x4f800000, v46
	s_nop 0
	v_cndmask_b32_e32 v46, v46, v47, vcc
	v_sqrt_f32_e32 v47, v46
	s_nop 0
	v_add_u32_e32 v48, -1, v47
	v_fma_f32 v49, -v48, v47, v46
	v_cmp_ge_f32_e64 s[2:3], 0, v49
	v_add_u32_e32 v49, 1, v47
	s_nop 0
	v_cndmask_b32_e64 v48, v47, v48, s[2:3]
	v_fma_f32 v47, -v49, v47, v46
	v_cmp_lt_f32_e64 s[2:3], 0, v47
	s_nop 1
	v_cndmask_b32_e64 v47, v48, v49, s[2:3]
	v_mul_f32_e32 v48, 0x37800000, v47
	v_cndmask_b32_e32 v47, v47, v48, vcc
	v_cmp_class_f32_e32 vcc, v46, v217
	s_nop 1
	v_cndmask_b32_e32 v46, v47, v46, vcc
	v_div_scale_f32 v47, s[0:1], v46, v46, 1.0
	v_rcp_f32_e32 v48, v47
	s_nop 0
	v_fma_f32 v49, -v47, v48, 1.0
	v_fmac_f32_e32 v48, v49, v48
	v_div_scale_f32 v49, vcc, 1.0, v46, 1.0
	v_mul_f32_e32 v50, v49, v48
	v_fma_f32 v51, -v47, v50, v49
	v_fmac_f32_e32 v50, v51, v48
	v_fma_f32 v47, -v47, v50, v49
	v_div_fmas_f32 v47, v47, v48, v50
	v_div_fixup_f32 v46, v47, v46, 1.0
	v_pk_mul_f32 v[48:49], v[42:43], v[46:47] op_sel_hi:[1,0]
	v_pk_mul_f32 v[42:43], v[44:45], v[46:47] op_sel_hi:[1,0]
	v_pk_fma_f32 v[44:45], v[2:3], v[48:49], v[6:7]
	v_pk_fma_f32 v[42:43], v[4:5], v[42:43], v[8:9]
	v_mul_f32_e32 v46, 0xbfb8aa3b, v44
	v_fma_f32 v47, v44, s34, -v46
	v_rndne_f32_e32 v48, v46
	v_fmac_f32_e32 v47, 0xb2a5705f, v44
	v_sub_f32_e32 v46, v46, v48
	v_add_f32_e32 v46, v46, v47
	v_exp_f32_e32 v46, v46
	v_cvt_i32_f32_e32 v47, v48
	v_cmp_nlt_f32_e32 vcc, s55, v44
	v_ldexp_f32 v46, v46, v47
	s_nop 0
	v_cndmask_b32_e32 v46, 0, v46, vcc
	v_cmp_ngt_f32_e32 vcc, s56, v44
	s_nop 1
	v_cndmask_b32_e32 v46, v219, v46, vcc
	v_add_f32_e32 v46, 1.0, v46
	v_div_scale_f32 v47, s[0:1], v46, v46, v44
	v_rcp_f32_e32 v48, v47
	s_nop 0
	v_fma_f32 v49, -v47, v48, 1.0
	v_fmac_f32_e32 v48, v49, v48
	v_div_scale_f32 v49, vcc, v44, v46, v44
	v_mul_f32_e32 v50, v49, v48
	v_fma_f32 v51, -v47, v50, v49
	v_fmac_f32_e32 v50, v51, v48
	v_fma_f32 v47, -v47, v50, v49
	v_div_fmas_f32 v47, v47, v48, v50
	v_div_fixup_f32 v44, v47, v46, v44
	v_mul_f32_e32 v46, 0xbfb8aa3b, v45
	v_fma_f32 v47, v45, s34, -v46
	v_rndne_f32_e32 v48, v46
	v_fmac_f32_e32 v47, 0xb2a5705f, v45
	v_sub_f32_e32 v46, v46, v48
	v_add_f32_e32 v46, v46, v47
	v_exp_f32_e32 v46, v46
	v_cvt_i32_f32_e32 v47, v48
	v_cmp_nlt_f32_e32 vcc, s55, v45
	v_ldexp_f32 v46, v46, v47
	s_nop 0
	v_cndmask_b32_e32 v46, 0, v46, vcc
	v_cmp_ngt_f32_e32 vcc, s56, v45
	s_nop 1
	v_cndmask_b32_e32 v46, v219, v46, vcc
	v_add_f32_e32 v46, 1.0, v46
	v_div_scale_f32 v47, s[0:1], v46, v46, v45
	v_rcp_f32_e32 v48, v47
	s_nop 0
	v_fma_f32 v49, -v47, v48, 1.0
	v_fmac_f32_e32 v48, v49, v48
	v_div_scale_f32 v49, vcc, v45, v46, v45
	v_mul_f32_e32 v50, v49, v48
	v_fma_f32 v51, -v47, v50, v49
	v_fmac_f32_e32 v50, v51, v48
	v_fma_f32 v47, -v47, v50, v49
	v_div_fmas_f32 v47, v47, v48, v50
	v_div_fixup_f32 v45, v47, v46, v45
	v_cvt_pk_bf16_f32 v44, v44, v45
	v_mul_f32_e32 v45, 0xbfb8aa3b, v42
	v_fma_f32 v46, v42, s34, -v45
	v_rndne_f32_e32 v47, v45
	v_fmac_f32_e32 v46, 0xb2a5705f, v42
	v_sub_f32_e32 v45, v45, v47
	v_add_f32_e32 v45, v45, v46
	v_exp_f32_e32 v45, v45
	v_cvt_i32_f32_e32 v46, v47
	v_cmp_nlt_f32_e32 vcc, s55, v42
	v_ldexp_f32 v45, v45, v46
	s_nop 0
	v_cndmask_b32_e32 v45, 0, v45, vcc
	v_cmp_ngt_f32_e32 vcc, s56, v42
	s_nop 1
	v_cndmask_b32_e32 v45, v219, v45, vcc
	v_add_f32_e32 v45, 1.0, v45
	v_div_scale_f32 v46, s[0:1], v45, v45, v42
	v_rcp_f32_e32 v47, v46
	s_nop 0
	v_fma_f32 v48, -v46, v47, 1.0
	v_fmac_f32_e32 v47, v48, v47
	v_div_scale_f32 v48, vcc, v42, v45, v42
	v_mul_f32_e32 v49, v48, v47
	v_fma_f32 v50, -v46, v49, v48
	v_fmac_f32_e32 v49, v50, v47
	v_fma_f32 v46, -v46, v49, v48
	v_div_fmas_f32 v46, v46, v47, v49
	v_div_fixup_f32 v42, v46, v45, v42
	v_mul_f32_e32 v45, 0xbfb8aa3b, v43
	v_fma_f32 v46, v43, s34, -v45
	v_rndne_f32_e32 v47, v45
	v_fmac_f32_e32 v46, 0xb2a5705f, v43
	v_sub_f32_e32 v45, v45, v47
	v_add_f32_e32 v45, v45, v46
	v_exp_f32_e32 v45, v45
	v_cvt_i32_f32_e32 v46, v47
	v_cmp_nlt_f32_e32 vcc, s55, v43
	v_ldexp_f32 v45, v45, v46
	s_nop 0
	v_cndmask_b32_e32 v45, 0, v45, vcc
	v_cmp_ngt_f32_e32 vcc, s56, v43
	s_nop 1
	v_cndmask_b32_e32 v45, v219, v45, vcc
	v_add_f32_e32 v45, 1.0, v45
	v_div_scale_f32 v46, s[0:1], v45, v45, v43
	v_rcp_f32_e32 v47, v46
	s_add_i32 s0, s8, s7
	s_ashr_i32 s1, s0, 31
	s_lshl_b64 s[0:1], s[0:1], 11
	v_fma_f32 v48, -v46, v47, 1.0
	v_fmac_f32_e32 v47, v48, v47
	v_div_scale_f32 v48, vcc, v43, v45, v43
	v_mul_f32_e32 v49, v48, v47
	v_fma_f32 v50, -v46, v49, v48
	v_fmac_f32_e32 v49, v50, v47
	v_fma_f32 v46, -v46, v49, v48
	v_div_fmas_f32 v46, v46, v47, v49
	v_div_fixup_f32 v43, v46, v45, v43
	s_add_u32 s0, s4, s0
	s_addc_u32 s1, s5, s1
	v_cvt_pk_bf16_f32 v45, v42, v43
	v_lshl_add_u64 v[42:43], s[0:1], 0, v[0:1]
	v_add_co_u32_e32 v42, vcc, 0x10f60000, v42
	v_readlane_b32 s0, v255, 26
	s_nop 0
	v_addc_co_u32_e32 v43, vcc, 0, v43, vcc
	global_store_dwordx2 v[42:43], v[44:45], off offset:1536
	s_waitcnt lgkmcnt(0)
	s_barrier
	s_add_i32 s0, s6, s0
	s_mul_i32 s2, s0, 30
	s_ashr_i32 s3, s2, 31
	s_and_saveexec_b64 s[8:9], s[36:37]
	s_cbranch_execnz .LBB0_469
	s_or_b64 exec, exec, s[8:9]
	s_and_saveexec_b64 s[8:9], s[38:39]
	s_cbranch_execnz .LBB0_474

.LBB0_489:
	s_or_b64 exec, exec, s[8:9]
	s_waitcnt lgkmcnt(0)
	s_barrier
	ds_read2st64_b32 v[56:57], v127 offset1:4
	ds_read2st64_b32 v[58:59], v127 offset0:8 offset1:12
	ds_read2st64_b32 v[50:51], v127 offset0:16 offset1:20
	ds_read2st64_b32 v[48:49], v127 offset0:24 offset1:28
	ds_read2st64_b32 v[46:47], v127 offset0:32 offset1:36
	ds_read2st64_b32 v[44:45], v127 offset0:40 offset1:44
	ds_read2st64_b32 v[42:43], v127 offset0:48 offset1:52
	ds_read2st64_b32 v[40:41], v127 offset0:56 offset1:60
	ds_read2st64_b32 v[38:39], v127 offset0:64 offset1:68
	ds_read2st64_b32 v[36:37], v127 offset0:72 offset1:76
	ds_read2st64_b32 v[34:35], v127 offset0:80 offset1:84
	ds_read2st64_b32 v[32:33], v127 offset0:88 offset1:92
	ds_read2st64_b32 v[30:31], v127 offset0:96 offset1:100
	ds_read2st64_b32 v[28:29], v127 offset0:104 offset1:108
	ds_read2st64_b32 v[26:27], v127 offset0:112 offset1:116
	ds_read2st64_b32 v[24:25], v127 offset0:120 offset1:124
	ds_read2st64_b32 v[22:23], v127 offset0:128 offset1:132
	ds_read2st64_b32 v[20:21], v127 offset0:136 offset1:140
	ds_read2st64_b32 v[18:19], v127 offset0:144 offset1:148
	ds_read2st64_b32 v[16:17], v127 offset0:152 offset1:156
	ds_read2st64_b32 v[14:15], v127 offset0:160 offset1:164
	ds_read2st64_b32 v[12:13], v127 offset0:168 offset1:172
	ds_read2st64_b32 v[10:11], v127 offset0:176 offset1:180
	s_waitcnt lgkmcnt(14)
	v_fma_f32 v56, v89, v56, v117
	v_fmac_f32_e32 v56, v88, v57
	v_fma_f32 v57, v89, v57, v117
	v_fmac_f32_e32 v57, v88, v58
	v_fmac_f32_e32 v56, v87, v58
	v_fmac_f32_e32 v57, v87, v59
	v_fmac_f32_e32 v56, v86, v59
	v_fmac_f32_e32 v57, v86, v50
	v_fmac_f32_e32 v56, v93, v50
	v_fmac_f32_e32 v57, v93, v51
	v_fmac_f32_e32 v56, v92, v51
	v_fmac_f32_e32 v57, v92, v48
	v_fmac_f32_e32 v56, v91, v48
	v_fmac_f32_e32 v57, v91, v49
	v_fmac_f32_e32 v56, v90, v49
	v_fmac_f32_e32 v57, v90, v46
	v_fmac_f32_e32 v56, v97, v46
	v_fmac_f32_e32 v57, v97, v47
	v_fmac_f32_e32 v56, v96, v47
	v_fmac_f32_e32 v57, v96, v44
	v_fmac_f32_e32 v56, v95, v44
	v_fmac_f32_e32 v57, v95, v45
	v_fmac_f32_e32 v56, v94, v45
	v_fmac_f32_e32 v57, v94, v42
	v_fmac_f32_e32 v56, v105, v42
	v_fmac_f32_e32 v57, v105, v43
	v_fmac_f32_e32 v56, v104, v43
	v_fmac_f32_e32 v57, v104, v40
	v_fmac_f32_e32 v56, v103, v40
	v_fmac_f32_e32 v57, v103, v41
	v_fmac_f32_e32 v56, v102, v41
	v_fmac_f32_e32 v57, v102, v38
	v_fmac_f32_e32 v56, v101, v38
	v_fmac_f32_e32 v57, v101, v39
	v_fmac_f32_e32 v56, v100, v39
	s_waitcnt lgkmcnt(13)
	v_fmac_f32_e32 v57, v100, v36
	v_fmac_f32_e32 v56, v99, v36
	v_fmac_f32_e32 v57, v99, v37
	v_fmac_f32_e32 v56, v98, v37
	s_waitcnt lgkmcnt(12)
	v_fmac_f32_e32 v57, v98, v34
	v_fmac_f32_e32 v56, v106, v34
	v_fmac_f32_e32 v57, v106, v35
	v_fmac_f32_e32 v56, v109, v35
	s_waitcnt lgkmcnt(11)
	v_fmac_f32_e32 v57, v109, v32
	v_fmac_f32_e32 v56, v108, v32
	v_fmac_f32_e32 v57, v108, v33
	v_fmac_f32_e32 v56, v107, v33
	s_waitcnt lgkmcnt(10)
	v_fmac_f32_e32 v57, v107, v30
	v_fmac_f32_e32 v56, v113, v30
	v_fmac_f32_e32 v57, v113, v31
	v_fmac_f32_e32 v56, v112, v31
	s_waitcnt lgkmcnt(9)
	v_fmac_f32_e32 v57, v112, v28
	v_fmac_f32_e32 v56, v111, v28
	v_fmac_f32_e32 v57, v111, v29
	v_fmac_f32_e32 v56, v110, v29
	s_waitcnt lgkmcnt(8)
	v_fmac_f32_e32 v57, v110, v26
	v_fmac_f32_e32 v56, v116, v26
	v_fmac_f32_e32 v57, v116, v27
	v_fmac_f32_e32 v56, v115, v27
	s_waitcnt lgkmcnt(7)
	v_fmac_f32_e32 v57, v115, v24
	v_fmac_f32_e32 v56, v114, v24
	v_fmac_f32_e32 v57, v114, v25
	ds_write2st64_b32 v127, v56, v57 offset0:248 offset1:252
	v_fma_f32 v56, v89, v58, v117
	v_fmac_f32_e32 v56, v88, v59
	v_fma_f32 v57, v89, v59, v117
	v_fmac_f32_e32 v56, v87, v50
	v_fmac_f32_e32 v57, v88, v50
	v_fma_f32 v50, v89, v50, v117
	v_fmac_f32_e32 v56, v86, v51
	v_fmac_f32_e32 v57, v87, v51
	v_fmac_f32_e32 v50, v88, v51
	v_fma_f32 v51, v89, v51, v117
	v_fmac_f32_e32 v56, v93, v48
	v_fmac_f32_e32 v57, v86, v48
	v_fmac_f32_e32 v50, v87, v48
	v_fmac_f32_e32 v51, v88, v48
	v_fma_f32 v48, v89, v48, v117
	v_fmac_f32_e32 v56, v92, v49
	v_fmac_f32_e32 v57, v93, v49
	v_fmac_f32_e32 v50, v86, v49
	v_fmac_f32_e32 v51, v87, v49
	v_fmac_f32_e32 v48, v88, v49
	v_fma_f32 v49, v89, v49, v117
	v_fmac_f32_e32 v56, v91, v46
	v_fmac_f32_e32 v57, v92, v46
	v_fmac_f32_e32 v50, v93, v46
	v_fmac_f32_e32 v51, v86, v46
	v_fmac_f32_e32 v48, v87, v46
	v_fmac_f32_e32 v49, v88, v46
	v_fma_f32 v46, v89, v46, v117
	v_fmac_f32_e32 v56, v90, v47
	v_fmac_f32_e32 v57, v91, v47
	v_fmac_f32_e32 v50, v92, v47
	v_fmac_f32_e32 v51, v93, v47
	v_fmac_f32_e32 v48, v86, v47
	v_fmac_f32_e32 v49, v87, v47
	v_fmac_f32_e32 v46, v88, v47
	v_fma_f32 v47, v89, v47, v117
	v_fmac_f32_e32 v56, v97, v44
	v_fmac_f32_e32 v57, v90, v44
	v_fmac_f32_e32 v50, v91, v44
	v_fmac_f32_e32 v51, v92, v44
	v_fmac_f32_e32 v48, v93, v44
	v_fmac_f32_e32 v49, v86, v44
	v_fmac_f32_e32 v46, v87, v44
	v_fmac_f32_e32 v47, v88, v44
	v_fma_f32 v44, v89, v44, v117
	v_fmac_f32_e32 v56, v96, v45
	v_fmac_f32_e32 v57, v97, v45
	v_fmac_f32_e32 v50, v90, v45
	v_fmac_f32_e32 v51, v91, v45
	v_fmac_f32_e32 v48, v92, v45
	v_fmac_f32_e32 v49, v93, v45
	v_fmac_f32_e32 v46, v86, v45
	v_fmac_f32_e32 v47, v87, v45
	v_fmac_f32_e32 v44, v88, v45
	v_fma_f32 v45, v89, v45, v117
	v_fmac_f32_e32 v56, v95, v42
	v_fmac_f32_e32 v57, v96, v42
	v_fmac_f32_e32 v50, v97, v42
	v_fmac_f32_e32 v51, v90, v42
	v_fmac_f32_e32 v48, v91, v42
	v_fmac_f32_e32 v49, v92, v42
	v_fmac_f32_e32 v46, v93, v42
	v_fmac_f32_e32 v47, v86, v42
	v_fmac_f32_e32 v44, v87, v42
	v_fmac_f32_e32 v45, v88, v42
	v_fma_f32 v42, v89, v42, v117
	v_fmac_f32_e32 v56, v94, v43
	v_fmac_f32_e32 v57, v95, v43
	v_fmac_f32_e32 v50, v96, v43
	v_fmac_f32_e32 v51, v97, v43
	v_fmac_f32_e32 v48, v90, v43
	v_fmac_f32_e32 v49, v91, v43
	v_fmac_f32_e32 v46, v92, v43
	v_fmac_f32_e32 v47, v93, v43
	v_fmac_f32_e32 v44, v86, v43
	v_fmac_f32_e32 v45, v87, v43
	v_fmac_f32_e32 v42, v88, v43
	v_fma_f32 v43, v89, v43, v117
	v_fmac_f32_e32 v56, v105, v40
	v_fmac_f32_e32 v57, v94, v40
	v_fmac_f32_e32 v50, v95, v40
	v_fmac_f32_e32 v51, v96, v40
	v_fmac_f32_e32 v48, v97, v40
	v_fmac_f32_e32 v49, v90, v40
	v_fmac_f32_e32 v46, v91, v40
	v_fmac_f32_e32 v47, v92, v40
	v_fmac_f32_e32 v44, v93, v40
	v_fmac_f32_e32 v45, v86, v40
	v_fmac_f32_e32 v42, v87, v40
	v_fmac_f32_e32 v43, v88, v40
	v_fma_f32 v40, v89, v40, v117
	v_fmac_f32_e32 v117, v89, v41
	v_fmac_f32_e32 v40, v88, v41
	v_fmac_f32_e32 v117, v88, v38
	v_fmac_f32_e32 v43, v87, v41
	v_fmac_f32_e32 v40, v87, v38
	v_fmac_f32_e32 v117, v87, v39
	v_fmac_f32_e32 v42, v86, v41
	v_fmac_f32_e32 v43, v86, v38
	v_fmac_f32_e32 v40, v86, v39
	v_fmac_f32_e32 v117, v86, v36
	v_fmac_f32_e32 v45, v93, v41
	v_fmac_f32_e32 v42, v93, v38
	v_fmac_f32_e32 v43, v93, v39
	v_fmac_f32_e32 v40, v93, v36
	v_fmac_f32_e32 v117, v93, v37
	v_fmac_f32_e32 v44, v92, v41
	v_fmac_f32_e32 v45, v92, v38
	v_fmac_f32_e32 v42, v92, v39
	v_fmac_f32_e32 v43, v92, v36
	v_fmac_f32_e32 v40, v92, v37
	v_fmac_f32_e32 v117, v92, v34
	v_fmac_f32_e32 v47, v91, v41
	v_fmac_f32_e32 v44, v91, v38
	v_fmac_f32_e32 v45, v91, v39
	v_fmac_f32_e32 v42, v91, v36
	v_fmac_f32_e32 v43, v91, v37
	v_fmac_f32_e32 v40, v91, v34
	v_fmac_f32_e32 v117, v91, v35
	v_fmac_f32_e32 v46, v90, v41
	v_fmac_f32_e32 v47, v90, v38
	v_fmac_f32_e32 v44, v90, v39
	v_fmac_f32_e32 v45, v90, v36
	v_fmac_f32_e32 v42, v90, v37
	v_fmac_f32_e32 v43, v90, v34
	v_fmac_f32_e32 v40, v90, v35
	v_fmac_f32_e32 v117, v90, v32
	v_fmac_f32_e32 v49, v97, v41
	v_fmac_f32_e32 v46, v97, v38
	v_fmac_f32_e32 v47, v97, v39
	v_fmac_f32_e32 v44, v97, v36
	v_fmac_f32_e32 v45, v97, v37
	v_fmac_f32_e32 v42, v97, v34
	v_fmac_f32_e32 v43, v97, v35
	v_fmac_f32_e32 v40, v97, v32
	v_fmac_f32_e32 v117, v97, v33
	v_fmac_f32_e32 v48, v96, v41
	v_fmac_f32_e32 v49, v96, v38
	v_fmac_f32_e32 v46, v96, v39
	v_fmac_f32_e32 v47, v96, v36
	v_fmac_f32_e32 v44, v96, v37
	v_fmac_f32_e32 v45, v96, v34
	v_fmac_f32_e32 v42, v96, v35
	v_fmac_f32_e32 v43, v96, v32
	v_fmac_f32_e32 v40, v96, v33
	v_fmac_f32_e32 v117, v96, v30
	v_fmac_f32_e32 v51, v95, v41
	v_fmac_f32_e32 v48, v95, v38
	v_fmac_f32_e32 v49, v95, v39
	v_fmac_f32_e32 v46, v95, v36
	v_fmac_f32_e32 v47, v95, v37
	v_fmac_f32_e32 v44, v95, v34
	v_fmac_f32_e32 v45, v95, v35
	v_fmac_f32_e32 v42, v95, v32
	v_fmac_f32_e32 v43, v95, v33
	v_fmac_f32_e32 v40, v95, v30
	v_fmac_f32_e32 v117, v95, v31
	v_fmac_f32_e32 v50, v94, v41
	v_fmac_f32_e32 v51, v94, v38
	v_fmac_f32_e32 v48, v94, v39
	v_fmac_f32_e32 v49, v94, v36
	v_fmac_f32_e32 v46, v94, v37
	v_fmac_f32_e32 v47, v94, v34
	v_fmac_f32_e32 v44, v94, v35
	v_fmac_f32_e32 v45, v94, v32
	v_fmac_f32_e32 v42, v94, v33
	v_fmac_f32_e32 v43, v94, v30
	v_fmac_f32_e32 v40, v94, v31
	v_fmac_f32_e32 v117, v94, v28
	v_fmac_f32_e32 v57, v105, v41
	v_fmac_f32_e32 v50, v105, v38
	v_fmac_f32_e32 v51, v105, v39
	v_fmac_f32_e32 v48, v105, v36
	v_fmac_f32_e32 v49, v105, v37
	v_fmac_f32_e32 v46, v105, v34
	v_fmac_f32_e32 v47, v105, v35
	v_fmac_f32_e32 v44, v105, v32
	v_fmac_f32_e32 v45, v105, v33
	v_fmac_f32_e32 v42, v105, v30
	v_fmac_f32_e32 v43, v105, v31
	v_fmac_f32_e32 v40, v105, v28
	v_fmac_f32_e32 v117, v105, v29
	v_fmac_f32_e32 v56, v104, v41
	v_fmac_f32_e32 v57, v104, v38
	v_fmac_f32_e32 v50, v104, v39
	v_fmac_f32_e32 v51, v104, v36
	v_fmac_f32_e32 v48, v104, v37
	v_fmac_f32_e32 v49, v104, v34
	v_fmac_f32_e32 v46, v104, v35
	v_fmac_f32_e32 v47, v104, v32
	v_fmac_f32_e32 v44, v104, v33
	v_fmac_f32_e32 v45, v104, v30
	v_fmac_f32_e32 v42, v104, v31
	v_fmac_f32_e32 v43, v104, v28
	v_fmac_f32_e32 v40, v104, v29
	v_fmac_f32_e32 v117, v104, v26
	v_fmac_f32_e32 v56, v103, v38
	v_fmac_f32_e32 v57, v103, v39
	v_fmac_f32_e32 v50, v103, v36
	v_fmac_f32_e32 v51, v103, v37
	v_fmac_f32_e32 v48, v103, v34
	v_fmac_f32_e32 v49, v103, v35
	v_fmac_f32_e32 v46, v103, v32
	v_fmac_f32_e32 v47, v103, v33
	v_fmac_f32_e32 v44, v103, v30
	v_fmac_f32_e32 v45, v103, v31
	v_fmac_f32_e32 v42, v103, v28
	v_fmac_f32_e32 v43, v103, v29
	v_fmac_f32_e32 v40, v103, v26
	v_fmac_f32_e32 v117, v103, v27
	v_fmac_f32_e32 v56, v102, v39
	v_fmac_f32_e32 v57, v102, v36
	v_fmac_f32_e32 v50, v102, v37
	v_fmac_f32_e32 v51, v102, v34
	v_fmac_f32_e32 v48, v102, v35
	v_fmac_f32_e32 v49, v102, v32
	v_fmac_f32_e32 v46, v102, v33
	v_fmac_f32_e32 v47, v102, v30
	v_fmac_f32_e32 v44, v102, v31
	v_fmac_f32_e32 v45, v102, v28
	v_fmac_f32_e32 v42, v102, v29
	v_fmac_f32_e32 v43, v102, v26
	v_fmac_f32_e32 v40, v102, v27
	v_fmac_f32_e32 v117, v102, v24
	v_fmac_f32_e32 v56, v101, v36
	v_fmac_f32_e32 v57, v101, v37
	v_fmac_f32_e32 v50, v101, v34
	v_fmac_f32_e32 v51, v101, v35
	v_fmac_f32_e32 v48, v101, v32
	v_fmac_f32_e32 v49, v101, v33
	v_fmac_f32_e32 v46, v101, v30
	v_fmac_f32_e32 v47, v101, v31
	v_fmac_f32_e32 v44, v101, v28
	v_fmac_f32_e32 v45, v101, v29
	v_fmac_f32_e32 v42, v101, v26
	v_fmac_f32_e32 v43, v101, v27
	v_fmac_f32_e32 v40, v101, v24
	v_fmac_f32_e32 v117, v101, v25
	v_fmac_f32_e32 v56, v100, v37
	v_fmac_f32_e32 v57, v100, v34
	v_fmac_f32_e32 v50, v100, v35
	v_fmac_f32_e32 v51, v100, v32
	v_fmac_f32_e32 v48, v100, v33
	v_fmac_f32_e32 v49, v100, v30
	v_fmac_f32_e32 v46, v100, v31
	v_fmac_f32_e32 v47, v100, v28
	v_fmac_f32_e32 v44, v100, v29
	v_fmac_f32_e32 v45, v100, v26
	v_fmac_f32_e32 v42, v100, v27
	v_fmac_f32_e32 v43, v100, v24
	v_fmac_f32_e32 v40, v100, v25
	s_waitcnt lgkmcnt(7)
	v_fmac_f32_e32 v117, v100, v22
	v_fmac_f32_e32 v56, v99, v34
	v_fmac_f32_e32 v57, v99, v35
	v_fmac_f32_e32 v50, v99, v32
	v_fmac_f32_e32 v51, v99, v33
	v_fmac_f32_e32 v48, v99, v30
	v_fmac_f32_e32 v49, v99, v31
	v_fmac_f32_e32 v46, v99, v28
	v_fmac_f32_e32 v47, v99, v29
	v_fmac_f32_e32 v44, v99, v26
	v_fmac_f32_e32 v45, v99, v27
	v_fmac_f32_e32 v42, v99, v24
	v_fmac_f32_e32 v43, v99, v25
	v_fmac_f32_e32 v40, v99, v22
	v_fmac_f32_e32 v117, v99, v23
	v_fmac_f32_e32 v56, v98, v35
	v_fmac_f32_e32 v57, v98, v32
	v_fmac_f32_e32 v50, v98, v33
	v_fmac_f32_e32 v51, v98, v30
	v_fmac_f32_e32 v48, v98, v31
	v_fmac_f32_e32 v49, v98, v28
	v_fmac_f32_e32 v46, v98, v29
	v_fmac_f32_e32 v47, v98, v26
	v_fmac_f32_e32 v44, v98, v27
	v_fmac_f32_e32 v45, v98, v24
	v_fmac_f32_e32 v42, v98, v25
	v_fmac_f32_e32 v43, v98, v22
	v_fmac_f32_e32 v40, v98, v23
	s_waitcnt lgkmcnt(6)
	v_fmac_f32_e32 v117, v98, v20
	v_fmac_f32_e32 v56, v106, v32
	v_fmac_f32_e32 v57, v106, v33
	v_fmac_f32_e32 v50, v106, v30
	v_fmac_f32_e32 v51, v106, v31
	v_fmac_f32_e32 v48, v106, v28
	v_fmac_f32_e32 v49, v106, v29
	v_fmac_f32_e32 v46, v106, v26
	v_fmac_f32_e32 v47, v106, v27
	v_fmac_f32_e32 v44, v106, v24
	v_fmac_f32_e32 v45, v106, v25
	v_fmac_f32_e32 v42, v106, v22
	v_fmac_f32_e32 v43, v106, v23
	v_fmac_f32_e32 v40, v106, v20
	v_fmac_f32_e32 v117, v106, v21
	v_fmac_f32_e32 v56, v109, v33
	v_fmac_f32_e32 v57, v109, v30
	v_fmac_f32_e32 v50, v109, v31
	v_fmac_f32_e32 v51, v109, v28
	v_fmac_f32_e32 v48, v109, v29
	v_fmac_f32_e32 v49, v109, v26
	v_fmac_f32_e32 v46, v109, v27
	v_fmac_f32_e32 v47, v109, v24
	v_fmac_f32_e32 v44, v109, v25
	v_fmac_f32_e32 v45, v109, v22
	v_fmac_f32_e32 v42, v109, v23
	v_fmac_f32_e32 v43, v109, v20
	v_fmac_f32_e32 v40, v109, v21
	s_waitcnt lgkmcnt(5)
	v_fmac_f32_e32 v117, v109, v18
	v_fmac_f32_e32 v56, v108, v30
	v_fmac_f32_e32 v57, v108, v31
	v_fmac_f32_e32 v50, v108, v28
	v_fmac_f32_e32 v51, v108, v29
	v_fmac_f32_e32 v48, v108, v26
	v_fmac_f32_e32 v49, v108, v27
	v_fmac_f32_e32 v46, v108, v24
	v_fmac_f32_e32 v47, v108, v25
	v_fmac_f32_e32 v44, v108, v22
	v_fmac_f32_e32 v45, v108, v23
	v_fmac_f32_e32 v42, v108, v20
	v_fmac_f32_e32 v43, v108, v21
	v_fmac_f32_e32 v40, v108, v18
	v_fmac_f32_e32 v117, v108, v19
	v_fmac_f32_e32 v56, v107, v31
	v_fmac_f32_e32 v57, v107, v28
	v_fmac_f32_e32 v50, v107, v29
	v_fmac_f32_e32 v51, v107, v26
	v_fmac_f32_e32 v48, v107, v27
	v_fmac_f32_e32 v49, v107, v24
	v_fmac_f32_e32 v46, v107, v25
	v_fmac_f32_e32 v47, v107, v22
	v_fmac_f32_e32 v44, v107, v23
	v_fmac_f32_e32 v45, v107, v20
	v_fmac_f32_e32 v42, v107, v21
	v_fmac_f32_e32 v43, v107, v18
	v_fmac_f32_e32 v40, v107, v19
	s_waitcnt lgkmcnt(4)
	v_fmac_f32_e32 v117, v107, v16
	v_fmac_f32_e32 v56, v113, v28
	v_fmac_f32_e32 v57, v113, v29
	v_fmac_f32_e32 v50, v113, v26
	v_fmac_f32_e32 v51, v113, v27
	v_fmac_f32_e32 v48, v113, v24
	v_fmac_f32_e32 v49, v113, v25
	v_fmac_f32_e32 v46, v113, v22
	v_fmac_f32_e32 v47, v113, v23
	v_fmac_f32_e32 v44, v113, v20
	v_fmac_f32_e32 v45, v113, v21
	v_fmac_f32_e32 v42, v113, v18
	v_fmac_f32_e32 v43, v113, v19
	v_fmac_f32_e32 v40, v113, v16
	v_fmac_f32_e32 v117, v113, v17
	v_fmac_f32_e32 v56, v112, v29
	v_fmac_f32_e32 v57, v112, v26
	v_fmac_f32_e32 v50, v112, v27
	v_fmac_f32_e32 v51, v112, v24
	v_fmac_f32_e32 v48, v112, v25
	v_fmac_f32_e32 v49, v112, v22
	v_fmac_f32_e32 v46, v112, v23
	v_fmac_f32_e32 v47, v112, v20
	v_fmac_f32_e32 v44, v112, v21
	v_fmac_f32_e32 v45, v112, v18
	v_fmac_f32_e32 v42, v112, v19
	v_fmac_f32_e32 v43, v112, v16
	v_fmac_f32_e32 v40, v112, v17
	s_waitcnt lgkmcnt(3)
	v_fmac_f32_e32 v117, v112, v14
	v_fmac_f32_e32 v56, v111, v26
	v_fmac_f32_e32 v57, v111, v27
	v_fmac_f32_e32 v50, v111, v24
	v_fmac_f32_e32 v51, v111, v25
	v_fmac_f32_e32 v48, v111, v22
	v_fmac_f32_e32 v49, v111, v23
	v_fmac_f32_e32 v46, v111, v20
	v_fmac_f32_e32 v47, v111, v21
	v_fmac_f32_e32 v44, v111, v18
	v_fmac_f32_e32 v45, v111, v19
	v_fmac_f32_e32 v42, v111, v16
	v_fmac_f32_e32 v43, v111, v17
	v_fmac_f32_e32 v40, v111, v14
	v_fmac_f32_e32 v117, v111, v15
	v_fmac_f32_e32 v56, v110, v27
	v_fmac_f32_e32 v57, v110, v24
	v_fmac_f32_e32 v50, v110, v25
	v_fmac_f32_e32 v51, v110, v22
	v_fmac_f32_e32 v48, v110, v23
	v_fmac_f32_e32 v49, v110, v20
	v_fmac_f32_e32 v46, v110, v21
	v_fmac_f32_e32 v47, v110, v18
	v_fmac_f32_e32 v44, v110, v19
	v_fmac_f32_e32 v45, v110, v16
	v_fmac_f32_e32 v42, v110, v17
	v_fmac_f32_e32 v43, v110, v14
	v_fmac_f32_e32 v40, v110, v15
	s_waitcnt lgkmcnt(2)
	v_fmac_f32_e32 v117, v110, v12
	v_fmac_f32_e32 v56, v116, v24
	v_fmac_f32_e32 v57, v116, v25
	v_fmac_f32_e32 v50, v116, v22
	v_fmac_f32_e32 v51, v116, v23
	v_fmac_f32_e32 v48, v116, v20
	v_fmac_f32_e32 v49, v116, v21
	v_fmac_f32_e32 v46, v116, v18
	v_fmac_f32_e32 v47, v116, v19
	v_fmac_f32_e32 v44, v116, v16
	v_fmac_f32_e32 v45, v116, v17
	v_fmac_f32_e32 v42, v116, v14
	v_fmac_f32_e32 v43, v116, v15
	v_fmac_f32_e32 v40, v116, v12
	v_fmac_f32_e32 v117, v116, v13
	v_fmac_f32_e32 v56, v115, v25
	v_fmac_f32_e32 v57, v115, v22
	v_fmac_f32_e32 v50, v115, v23
	v_fmac_f32_e32 v51, v115, v20
	v_fmac_f32_e32 v48, v115, v21
	v_fmac_f32_e32 v49, v115, v18
	v_fmac_f32_e32 v46, v115, v19
	v_fmac_f32_e32 v47, v115, v16
	v_fmac_f32_e32 v44, v115, v17
	v_fmac_f32_e32 v45, v115, v14
	v_fmac_f32_e32 v42, v115, v15
	v_fmac_f32_e32 v43, v115, v12
	v_fmac_f32_e32 v40, v115, v13
	s_waitcnt lgkmcnt(1)
	v_fmac_f32_e32 v117, v115, v10
	v_fmac_f32_e32 v56, v114, v22
	v_fmac_f32_e32 v57, v114, v23
	v_fmac_f32_e32 v50, v114, v20
	v_fmac_f32_e32 v51, v114, v21
	v_fmac_f32_e32 v48, v114, v18
	v_fmac_f32_e32 v49, v114, v19
	v_fmac_f32_e32 v46, v114, v16
	v_fmac_f32_e32 v47, v114, v17
	v_fmac_f32_e32 v44, v114, v14
	v_fmac_f32_e32 v45, v114, v15
	v_fmac_f32_e32 v42, v114, v12
	v_fmac_f32_e32 v43, v114, v13
	v_fmac_f32_e32 v40, v114, v10
	v_fmac_f32_e32 v117, v114, v11
	ds_write2st64_b32 v123, v56, v57 offset0:8 offset1:12
	ds_write2st64_b32 v123, v50, v51 offset0:16 offset1:20
	ds_write2st64_b32 v123, v48, v49 offset0:24 offset1:28
	ds_write2st64_b32 v123, v46, v47 offset0:32 offset1:36
	ds_write2st64_b32 v123, v44, v45 offset0:40 offset1:44
	ds_write2st64_b32 v123, v42, v43 offset0:48 offset1:52
	ds_write2st64_b32 v123, v40, v117 offset0:56 offset1:60
	s_waitcnt lgkmcnt(0)
	s_barrier
	ds_read_b128 v[10:13], v55 offset:63488
	s_lshl_b32 s0, s6, 11
	s_or_b32 s6, s0, s15
	s_mov_b32 s8, 0x10f60000
	s_waitcnt lgkmcnt(0)
	v_mov_b32_e32 v14, v11
	v_mov_b32_e32 v15, v12
	v_mov_b32_e32 v16, v10
	v_mov_b32_e32 v17, v13
	v_pk_add_f32 v[14:15], v[14:15], v[16:17]
	s_nop 0
	v_add_f32_e32 v14, v14, v15
	s_nop 1
	v_add_f32_dpp v14, v14, v14 quad_perm:[1,0,3,2] row_mask:0xf bank_mask:0xf bound_ctrl:1
	s_nop 1
	v_add_f32_dpp v14, v14, v14 quad_perm:[2,3,0,1] row_mask:0xf bank_mask:0xf bound_ctrl:1
	s_nop 1
	v_add_f32_dpp v14, v14, v14 row_half_mirror row_mask:0xf bank_mask:0xf bound_ctrl:1
	s_nop 1
	v_add_f32_dpp v14, v14, v14 row_mirror row_mask:0xf bank_mask:0xf bound_ctrl:1
	v_fmamk_f32 v11, v14, 0xbc800000, v11
	v_fmamk_f32 v10, v14, 0xbc800000, v10
	v_fmamk_f32 v13, v14, 0xbc800000, v13
	v_fmac_f32_e32 v12, 0xbc800000, v14
	v_pk_mul_f32 v[14:15], v[12:13], v[12:13]
	v_pk_mul_f32 v[16:17], v[10:11], v[10:11]
	s_nop 0
	v_pk_mov_b32 v[18:19], v[16:17], v[14:15] op_sel:[1,0]
	v_mov_b32_e32 v17, v15
	v_pk_add_f32 v[14:15], v[18:19], v[16:17]
	s_nop 0
	v_add_f32_e32 v14, v14, v15
	s_nop 1
	v_add_f32_dpp v14, v14, v14 quad_perm:[1,0,3,2] row_mask:0xf bank_mask:0xf bound_ctrl:1
	s_nop 1
	v_add_f32_dpp v14, v14, v14 quad_perm:[2,3,0,1] row_mask:0xf bank_mask:0xf bound_ctrl:1
	s_nop 1
	v_add_f32_dpp v14, v14, v14 row_half_mirror row_mask:0xf bank_mask:0xf bound_ctrl:1
	s_nop 1
	v_add_f32_dpp v14, v14, v14 row_mirror row_mask:0xf bank_mask:0xf bound_ctrl:1
	v_fmamk_f32 v14, v14, 0x3c800000, v216
	v_cmp_gt_f32_e32 vcc, s60, v14
	v_mul_f32_e32 v15, 0x4f800000, v14
	s_nop 0
	v_cndmask_b32_e32 v14, v14, v15, vcc
	v_sqrt_f32_e32 v15, v14
	s_nop 0
	v_add_u32_e32 v16, -1, v15
	v_fma_f32 v17, -v16, v15, v14
	v_cmp_ge_f32_e64 s[2:3], 0, v17
	v_add_u32_e32 v17, 1, v15
	s_nop 0
	v_cndmask_b32_e64 v16, v15, v16, s[2:3]
	v_fma_f32 v15, -v17, v15, v14
	v_cmp_lt_f32_e64 s[2:3], 0, v15
	s_nop 1
	v_cndmask_b32_e64 v15, v16, v17, s[2:3]
	v_mul_f32_e32 v16, 0x37800000, v15
	v_cndmask_b32_e32 v15, v15, v16, vcc
	v_cmp_class_f32_e32 vcc, v14, v217
	s_nop 1
	v_cndmask_b32_e32 v14, v15, v14, vcc
	v_div_scale_f32 v15, s[0:1], v14, v14, 1.0
	v_rcp_f32_e32 v16, v15
	s_nop 0
	v_fma_f32 v17, -v15, v16, 1.0
	v_fmac_f32_e32 v16, v17, v16
	v_div_scale_f32 v17, vcc, 1.0, v14, 1.0
	v_mul_f32_e32 v18, v17, v16
	v_fma_f32 v19, -v15, v18, v17
	v_fmac_f32_e32 v18, v19, v16
	v_fma_f32 v15, -v15, v18, v17
	v_div_fmas_f32 v15, v15, v16, v18
	v_div_fixup_f32 v14, v15, v14, 1.0
	v_pk_mul_f32 v[10:11], v[10:11], v[14:15] op_sel_hi:[1,0]
	v_pk_mul_f32 v[12:13], v[12:13], v[14:15] op_sel_hi:[1,0]
	v_pk_fma_f32 v[10:11], v[2:3], v[10:11], v[6:7]
	v_pk_fma_f32 v[12:13], v[4:5], v[12:13], v[8:9]
	v_mul_f32_e32 v14, 0xbfb8aa3b, v10
	v_fma_f32 v15, v10, s34, -v14
	v_rndne_f32_e32 v16, v14
	v_fmac_f32_e32 v15, 0xb2a5705f, v10
	v_sub_f32_e32 v14, v14, v16
	v_add_f32_e32 v14, v14, v15
	v_exp_f32_e32 v14, v14
	v_cvt_i32_f32_e32 v15, v16
	v_cmp_nlt_f32_e32 vcc, s55, v10
	v_ldexp_f32 v14, v14, v15
	s_nop 0
	v_cndmask_b32_e32 v14, 0, v14, vcc
	v_cmp_ngt_f32_e32 vcc, s56, v10
	s_nop 1
	v_cndmask_b32_e32 v14, v219, v14, vcc
	v_add_f32_e32 v14, 1.0, v14
	v_div_scale_f32 v15, s[0:1], v14, v14, v10
	v_rcp_f32_e32 v16, v15
	s_nop 0
	v_fma_f32 v17, -v15, v16, 1.0
	v_fmac_f32_e32 v16, v17, v16
	v_div_scale_f32 v17, vcc, v10, v14, v10
	v_mul_f32_e32 v18, v17, v16
	v_fma_f32 v19, -v15, v18, v17
	v_fmac_f32_e32 v18, v19, v16
	v_fma_f32 v15, -v15, v18, v17
	v_div_fmas_f32 v15, v15, v16, v18
	v_div_fixup_f32 v10, v15, v14, v10
	v_mul_f32_e32 v14, 0xbfb8aa3b, v11
	v_fma_f32 v15, v11, s34, -v14
	v_rndne_f32_e32 v16, v14
	v_fmac_f32_e32 v15, 0xb2a5705f, v11
	v_sub_f32_e32 v14, v14, v16
	v_add_f32_e32 v14, v14, v15
	v_exp_f32_e32 v14, v14
	v_cvt_i32_f32_e32 v15, v16
	v_cmp_nlt_f32_e32 vcc, s55, v11
	v_ldexp_f32 v14, v14, v15
	s_nop 0
	v_cndmask_b32_e32 v14, 0, v14, vcc
	v_cmp_ngt_f32_e32 vcc, s56, v11
	s_nop 1
	v_cndmask_b32_e32 v14, v219, v14, vcc
	v_add_f32_e32 v14, 1.0, v14
	v_div_scale_f32 v15, s[0:1], v14, v14, v11
	v_rcp_f32_e32 v16, v15
	s_nop 0
	v_fma_f32 v17, -v15, v16, 1.0
	v_fmac_f32_e32 v16, v17, v16
	v_div_scale_f32 v17, vcc, v11, v14, v11
	v_mul_f32_e32 v18, v17, v16
	v_fma_f32 v19, -v15, v18, v17
	v_fmac_f32_e32 v18, v19, v16
	v_fma_f32 v15, -v15, v18, v17
	v_div_fmas_f32 v15, v15, v16, v18
	v_div_fixup_f32 v11, v15, v14, v11
	v_cvt_pk_bf16_f32 v10, v10, v11
	v_mul_f32_e32 v11, 0xbfb8aa3b, v12
	v_fma_f32 v14, v12, s34, -v11
	v_rndne_f32_e32 v15, v11
	v_fmac_f32_e32 v14, 0xb2a5705f, v12
	v_sub_f32_e32 v11, v11, v15
	v_add_f32_e32 v11, v11, v14
	v_exp_f32_e32 v11, v11
	v_cvt_i32_f32_e32 v14, v15
	v_cmp_nlt_f32_e32 vcc, s55, v12
	v_ldexp_f32 v11, v11, v14
	s_nop 0
	v_cndmask_b32_e32 v11, 0, v11, vcc
	v_cmp_ngt_f32_e32 vcc, s56, v12
	s_nop 1
	v_cndmask_b32_e32 v11, v219, v11, vcc
	v_add_f32_e32 v11, 1.0, v11
	v_div_scale_f32 v14, s[0:1], v11, v11, v12
	v_rcp_f32_e32 v15, v14
	s_nop 0
	v_fma_f32 v16, -v14, v15, 1.0
	v_fmac_f32_e32 v15, v16, v15
	v_div_scale_f32 v16, vcc, v12, v11, v12
	v_mul_f32_e32 v17, v16, v15
	v_fma_f32 v18, -v14, v17, v16
	v_fmac_f32_e32 v17, v18, v15
	v_fma_f32 v14, -v14, v17, v16
	v_div_fmas_f32 v14, v14, v15, v17
	v_div_fixup_f32 v11, v14, v11, v12
	v_mul_f32_e32 v12, 0xbfb8aa3b, v13
	v_fma_f32 v14, v13, s34, -v12
	v_rndne_f32_e32 v15, v12
	v_fmac_f32_e32 v14, 0xb2a5705f, v13
	v_sub_f32_e32 v12, v12, v15
	v_add_f32_e32 v12, v12, v14
	v_exp_f32_e32 v12, v12
	v_cvt_i32_f32_e32 v14, v15
	v_cmp_nlt_f32_e32 vcc, s55, v13
	v_ldexp_f32 v12, v12, v14
	s_nop 0
	v_cndmask_b32_e32 v12, 0, v12, vcc
	v_cmp_ngt_f32_e32 vcc, s56, v13
	s_nop 1
	v_cndmask_b32_e32 v12, v219, v12, vcc
	v_add_f32_e32 v12, 1.0, v12
	v_div_scale_f32 v14, s[0:1], v12, v12, v13
	v_rcp_f32_e32 v15, v14
	s_add_i32 s0, s6, s21
	s_ashr_i32 s1, s0, 31
	s_lshl_b64 s[0:1], s[0:1], 11
	v_fma_f32 v16, -v14, v15, 1.0
	v_fmac_f32_e32 v15, v16, v15
	v_div_scale_f32 v16, vcc, v13, v12, v13
	v_mul_f32_e32 v17, v16, v15
	v_fma_f32 v18, -v14, v17, v16
	v_fmac_f32_e32 v17, v18, v15
	v_fma_f32 v14, -v14, v17, v16
	v_div_fmas_f32 v14, v14, v15, v17
	v_div_fixup_f32 v12, v14, v12, v13
	s_add_u32 s0, s4, s0
	s_addc_u32 s1, s5, s1
	v_cvt_pk_bf16_f32 v11, v11, v12
	v_lshl_add_u64 v[12:13], s[0:1], 0, v[0:1]
	v_add_co_u32_e32 v12, vcc, s8, v12
	s_nop 1
	v_addc_co_u32_e32 v13, vcc, 0, v13, vcc
	global_store_dwordx2 v[12:13], v[10:11], off offset:1536
	ds_read_b128 v[10:13], v54 offset:63488
	s_waitcnt lgkmcnt(0)
	v_mov_b32_e32 v14, v11
	v_mov_b32_e32 v15, v12
	v_mov_b32_e32 v16, v10
	v_mov_b32_e32 v17, v13
	v_pk_add_f32 v[14:15], v[14:15], v[16:17]
	s_nop 0
	v_add_f32_e32 v14, v14, v15
	s_nop 1
	v_add_f32_dpp v14, v14, v14 quad_perm:[1,0,3,2] row_mask:0xf bank_mask:0xf bound_ctrl:1
	s_nop 1
	v_add_f32_dpp v14, v14, v14 quad_perm:[2,3,0,1] row_mask:0xf bank_mask:0xf bound_ctrl:1
	s_nop 1
	v_add_f32_dpp v14, v14, v14 row_half_mirror row_mask:0xf bank_mask:0xf bound_ctrl:1
	s_nop 1
	v_add_f32_dpp v14, v14, v14 row_mirror row_mask:0xf bank_mask:0xf bound_ctrl:1
	v_fmamk_f32 v11, v14, 0xbc800000, v11
	v_fmamk_f32 v10, v14, 0xbc800000, v10
	v_fmamk_f32 v13, v14, 0xbc800000, v13
	v_fmac_f32_e32 v12, 0xbc800000, v14
	v_pk_mul_f32 v[14:15], v[12:13], v[12:13]
	v_pk_mul_f32 v[16:17], v[10:11], v[10:11]
	s_nop 0
	v_pk_mov_b32 v[18:19], v[16:17], v[14:15] op_sel:[1,0]
	v_mov_b32_e32 v17, v15
	v_pk_add_f32 v[14:15], v[18:19], v[16:17]
	s_nop 0
	v_add_f32_e32 v14, v14, v15
	s_nop 1
	v_add_f32_dpp v14, v14, v14 quad_perm:[1,0,3,2] row_mask:0xf bank_mask:0xf bound_ctrl:1
	s_nop 1
	v_add_f32_dpp v14, v14, v14 quad_perm:[2,3,0,1] row_mask:0xf bank_mask:0xf bound_ctrl:1
	s_nop 1
	v_add_f32_dpp v14, v14, v14 row_half_mirror row_mask:0xf bank_mask:0xf bound_ctrl:1
	s_nop 1
	v_add_f32_dpp v14, v14, v14 row_mirror row_mask:0xf bank_mask:0xf bound_ctrl:1
	v_fmamk_f32 v14, v14, 0x3c800000, v216
	v_cmp_gt_f32_e32 vcc, s60, v14
	v_mul_f32_e32 v15, 0x4f800000, v14
	s_nop 0
	v_cndmask_b32_e32 v14, v14, v15, vcc
	v_sqrt_f32_e32 v15, v14
	s_nop 0
	v_add_u32_e32 v16, -1, v15
	v_fma_f32 v17, -v16, v15, v14
	v_cmp_ge_f32_e64 s[2:3], 0, v17
	v_add_u32_e32 v17, 1, v15
	s_nop 0
	v_cndmask_b32_e64 v16, v15, v16, s[2:3]
	v_fma_f32 v15, -v17, v15, v14
	v_cmp_lt_f32_e64 s[2:3], 0, v15
	s_nop 1
	v_cndmask_b32_e64 v15, v16, v17, s[2:3]
	v_mul_f32_e32 v16, 0x37800000, v15
	v_cndmask_b32_e32 v15, v15, v16, vcc
	v_cmp_class_f32_e32 vcc, v14, v217
	s_nop 1
	v_cndmask_b32_e32 v14, v15, v14, vcc
	v_div_scale_f32 v15, s[0:1], v14, v14, 1.0
	v_rcp_f32_e32 v16, v15
	s_nop 0
	v_fma_f32 v17, -v15, v16, 1.0
	v_fmac_f32_e32 v16, v17, v16
	v_div_scale_f32 v17, vcc, 1.0, v14, 1.0
	v_mul_f32_e32 v18, v17, v16
	v_fma_f32 v19, -v15, v18, v17
	v_fmac_f32_e32 v18, v19, v16
	v_fma_f32 v15, -v15, v18, v17
	v_div_fmas_f32 v15, v15, v16, v18
	v_div_fixup_f32 v14, v15, v14, 1.0
	v_pk_mul_f32 v[16:17], v[10:11], v[14:15] op_sel_hi:[1,0]
	v_pk_mul_f32 v[10:11], v[12:13], v[14:15] op_sel_hi:[1,0]
	v_pk_fma_f32 v[12:13], v[2:3], v[16:17], v[6:7]
	v_pk_fma_f32 v[10:11], v[4:5], v[10:11], v[8:9]
	v_mul_f32_e32 v14, 0xbfb8aa3b, v12
	v_fma_f32 v15, v12, s34, -v14
	v_rndne_f32_e32 v16, v14
	v_fmac_f32_e32 v15, 0xb2a5705f, v12
	v_sub_f32_e32 v14, v14, v16
	v_add_f32_e32 v14, v14, v15
	v_exp_f32_e32 v14, v14
	v_cvt_i32_f32_e32 v15, v16
	v_cmp_nlt_f32_e32 vcc, s55, v12
	v_ldexp_f32 v14, v14, v15
	s_nop 0
	v_cndmask_b32_e32 v14, 0, v14, vcc
	v_cmp_ngt_f32_e32 vcc, s56, v12
	s_nop 1
	v_cndmask_b32_e32 v14, v219, v14, vcc
	v_add_f32_e32 v14, 1.0, v14
	v_div_scale_f32 v15, s[0:1], v14, v14, v12
	v_rcp_f32_e32 v16, v15
	s_nop 0
	v_fma_f32 v17, -v15, v16, 1.0
	v_fmac_f32_e32 v16, v17, v16
	v_div_scale_f32 v17, vcc, v12, v14, v12
	v_mul_f32_e32 v18, v17, v16
	v_fma_f32 v19, -v15, v18, v17
	v_fmac_f32_e32 v18, v19, v16
	v_fma_f32 v15, -v15, v18, v17
	v_div_fmas_f32 v15, v15, v16, v18
	v_div_fixup_f32 v12, v15, v14, v12
	v_mul_f32_e32 v14, 0xbfb8aa3b, v13
	v_fma_f32 v15, v13, s34, -v14
	v_rndne_f32_e32 v16, v14
	v_fmac_f32_e32 v15, 0xb2a5705f, v13
	v_sub_f32_e32 v14, v14, v16
	v_add_f32_e32 v14, v14, v15
	v_exp_f32_e32 v14, v14
	v_cvt_i32_f32_e32 v15, v16
	v_cmp_nlt_f32_e32 vcc, s55, v13
	v_ldexp_f32 v14, v14, v15
	s_nop 0
	v_cndmask_b32_e32 v14, 0, v14, vcc
	v_cmp_ngt_f32_e32 vcc, s56, v13
	s_nop 1
	v_cndmask_b32_e32 v14, v219, v14, vcc
	v_add_f32_e32 v14, 1.0, v14
	v_div_scale_f32 v15, s[0:1], v14, v14, v13
	v_rcp_f32_e32 v16, v15
	s_nop 0
	v_fma_f32 v17, -v15, v16, 1.0
	v_fmac_f32_e32 v16, v17, v16
	v_div_scale_f32 v17, vcc, v13, v14, v13
	v_mul_f32_e32 v18, v17, v16
	v_fma_f32 v19, -v15, v18, v17
	v_fmac_f32_e32 v18, v19, v16
	v_fma_f32 v15, -v15, v18, v17
	v_div_fmas_f32 v15, v15, v16, v18
	v_div_fixup_f32 v13, v15, v14, v13
	v_cvt_pk_bf16_f32 v12, v12, v13
	v_mul_f32_e32 v13, 0xbfb8aa3b, v10
	v_fma_f32 v14, v10, s34, -v13
	v_rndne_f32_e32 v15, v13
	v_fmac_f32_e32 v14, 0xb2a5705f, v10
	v_sub_f32_e32 v13, v13, v15
	v_add_f32_e32 v13, v13, v14
	v_exp_f32_e32 v13, v13
	v_cvt_i32_f32_e32 v14, v15
	v_cmp_nlt_f32_e32 vcc, s55, v10
	v_ldexp_f32 v13, v13, v14
	s_nop 0
	v_cndmask_b32_e32 v13, 0, v13, vcc
	v_cmp_ngt_f32_e32 vcc, s56, v10
	s_nop 1
	v_cndmask_b32_e32 v13, v219, v13, vcc
	v_add_f32_e32 v13, 1.0, v13
	v_div_scale_f32 v14, s[0:1], v13, v13, v10
	v_rcp_f32_e32 v15, v14
	s_nop 0
	v_fma_f32 v16, -v14, v15, 1.0
	v_fmac_f32_e32 v15, v16, v15
	v_div_scale_f32 v16, vcc, v10, v13, v10
	v_mul_f32_e32 v17, v16, v15
	v_fma_f32 v18, -v14, v17, v16
	v_fmac_f32_e32 v17, v18, v15
	v_fma_f32 v14, -v14, v17, v16
	v_div_fmas_f32 v14, v14, v15, v17
	v_div_fixup_f32 v10, v14, v13, v10
	v_mul_f32_e32 v13, 0xbfb8aa3b, v11
	v_fma_f32 v14, v11, s34, -v13
	v_rndne_f32_e32 v15, v13
	v_fmac_f32_e32 v14, 0xb2a5705f, v11
	v_sub_f32_e32 v13, v13, v15
	v_add_f32_e32 v13, v13, v14
	v_exp_f32_e32 v13, v13
	v_cvt_i32_f32_e32 v14, v15
	v_cmp_nlt_f32_e32 vcc, s55, v11
	v_ldexp_f32 v13, v13, v14
	s_nop 0
	v_cndmask_b32_e32 v13, 0, v13, vcc
	v_cmp_ngt_f32_e32 vcc, s56, v11
	s_nop 1
	v_cndmask_b32_e32 v13, v219, v13, vcc
	v_add_f32_e32 v13, 1.0, v13
	v_div_scale_f32 v14, s[0:1], v13, v13, v11
	v_rcp_f32_e32 v15, v14
	s_add_i32 s0, s6, s19
	s_ashr_i32 s1, s0, 31
	s_lshl_b64 s[0:1], s[0:1], 11
	v_fma_f32 v16, -v14, v15, 1.0
	v_fmac_f32_e32 v15, v16, v15
	v_div_scale_f32 v16, vcc, v11, v13, v11
	v_mul_f32_e32 v17, v16, v15
	v_fma_f32 v18, -v14, v17, v16
	v_fmac_f32_e32 v17, v18, v15
	v_fma_f32 v14, -v14, v17, v16
	v_div_fmas_f32 v14, v14, v15, v17
	v_div_fixup_f32 v11, v14, v13, v11
	s_add_u32 s0, s4, s0
	s_addc_u32 s1, s5, s1
	v_cvt_pk_bf16_f32 v13, v10, v11
	v_lshl_add_u64 v[10:11], s[0:1], 0, v[0:1]
	v_add_co_u32_e32 v10, vcc, s8, v10
	s_nop 1
	v_addc_co_u32_e32 v11, vcc, 0, v11, vcc
	global_store_dwordx2 v[10:11], v[12:13], off offset:1536
	ds_read_b128 v[10:13], v53 offset:63488
	s_waitcnt lgkmcnt(0)
	v_mov_b32_e32 v14, v11
	v_mov_b32_e32 v15, v12
	v_mov_b32_e32 v16, v10
	v_mov_b32_e32 v17, v13
	v_pk_add_f32 v[14:15], v[14:15], v[16:17]
	s_nop 0
	v_add_f32_e32 v14, v14, v15
	s_nop 1
	v_add_f32_dpp v14, v14, v14 quad_perm:[1,0,3,2] row_mask:0xf bank_mask:0xf bound_ctrl:1
	s_nop 1
	v_add_f32_dpp v14, v14, v14 quad_perm:[2,3,0,1] row_mask:0xf bank_mask:0xf bound_ctrl:1
	s_nop 1
	v_add_f32_dpp v14, v14, v14 row_half_mirror row_mask:0xf bank_mask:0xf bound_ctrl:1
	s_nop 1
	v_add_f32_dpp v14, v14, v14 row_mirror row_mask:0xf bank_mask:0xf bound_ctrl:1
	v_fmamk_f32 v11, v14, 0xbc800000, v11
	v_fmamk_f32 v10, v14, 0xbc800000, v10
	v_fmamk_f32 v13, v14, 0xbc800000, v13
	v_fmac_f32_e32 v12, 0xbc800000, v14
	v_pk_mul_f32 v[14:15], v[12:13], v[12:13]
	v_pk_mul_f32 v[16:17], v[10:11], v[10:11]
	s_nop 0
	v_pk_mov_b32 v[18:19], v[16:17], v[14:15] op_sel:[1,0]
	v_mov_b32_e32 v17, v15
	v_pk_add_f32 v[14:15], v[18:19], v[16:17]
	s_nop 0
	v_add_f32_e32 v14, v14, v15
	s_nop 1
	v_add_f32_dpp v14, v14, v14 quad_perm:[1,0,3,2] row_mask:0xf bank_mask:0xf bound_ctrl:1
	s_nop 1
	v_add_f32_dpp v14, v14, v14 quad_perm:[2,3,0,1] row_mask:0xf bank_mask:0xf bound_ctrl:1
	s_nop 1
	v_add_f32_dpp v14, v14, v14 row_half_mirror row_mask:0xf bank_mask:0xf bound_ctrl:1
	s_nop 1
	v_add_f32_dpp v14, v14, v14 row_mirror row_mask:0xf bank_mask:0xf bound_ctrl:1
	v_fmamk_f32 v14, v14, 0x3c800000, v216
	v_cmp_gt_f32_e32 vcc, s60, v14
	v_mul_f32_e32 v15, 0x4f800000, v14
	s_nop 0
	v_cndmask_b32_e32 v14, v14, v15, vcc
	v_sqrt_f32_e32 v15, v14
	s_nop 0
	v_add_u32_e32 v16, -1, v15
	v_fma_f32 v17, -v16, v15, v14
	v_cmp_ge_f32_e64 s[2:3], 0, v17
	v_add_u32_e32 v17, 1, v15
	s_nop 0
	v_cndmask_b32_e64 v16, v15, v16, s[2:3]
	v_fma_f32 v15, -v17, v15, v14
	v_cmp_lt_f32_e64 s[2:3], 0, v15
	s_nop 1
	v_cndmask_b32_e64 v15, v16, v17, s[2:3]
	v_mul_f32_e32 v16, 0x37800000, v15
	v_cndmask_b32_e32 v15, v15, v16, vcc
	v_cmp_class_f32_e32 vcc, v14, v217
	s_nop 1
	v_cndmask_b32_e32 v14, v15, v14, vcc
	v_div_scale_f32 v15, s[0:1], v14, v14, 1.0
	v_rcp_f32_e32 v16, v15
	s_nop 0
	v_fma_f32 v17, -v15, v16, 1.0
	v_fmac_f32_e32 v16, v17, v16
	v_div_scale_f32 v17, vcc, 1.0, v14, 1.0
	v_mul_f32_e32 v18, v17, v16
	v_fma_f32 v19, -v15, v18, v17
	v_fmac_f32_e32 v18, v19, v16
	v_fma_f32 v15, -v15, v18, v17
	v_div_fmas_f32 v15, v15, v16, v18
	v_div_fixup_f32 v14, v15, v14, 1.0
	v_pk_mul_f32 v[10:11], v[10:11], v[14:15] op_sel_hi:[1,0]
	v_pk_mul_f32 v[12:13], v[12:13], v[14:15] op_sel_hi:[1,0]
	v_pk_fma_f32 v[10:11], v[2:3], v[10:11], v[6:7]
	v_pk_fma_f32 v[12:13], v[4:5], v[12:13], v[8:9]
	v_mul_f32_e32 v14, 0xbfb8aa3b, v10
	v_fma_f32 v15, v10, s34, -v14
	v_rndne_f32_e32 v16, v14
	v_fmac_f32_e32 v15, 0xb2a5705f, v10
	v_sub_f32_e32 v14, v14, v16
	v_add_f32_e32 v14, v14, v15
	v_exp_f32_e32 v14, v14
	v_cvt_i32_f32_e32 v15, v16
	v_cmp_nlt_f32_e32 vcc, s55, v10
	v_ldexp_f32 v14, v14, v15
	s_nop 0
	v_cndmask_b32_e32 v14, 0, v14, vcc
	v_cmp_ngt_f32_e32 vcc, s56, v10
	s_nop 1
	v_cndmask_b32_e32 v14, v219, v14, vcc
	v_add_f32_e32 v14, 1.0, v14
	v_div_scale_f32 v15, s[0:1], v14, v14, v10
	v_rcp_f32_e32 v16, v15
	s_nop 0
	v_fma_f32 v17, -v15, v16, 1.0
	v_fmac_f32_e32 v16, v17, v16
	v_div_scale_f32 v17, vcc, v10, v14, v10
	v_mul_f32_e32 v18, v17, v16
	v_fma_f32 v19, -v15, v18, v17
	v_fmac_f32_e32 v18, v19, v16
	v_fma_f32 v15, -v15, v18, v17
	v_div_fmas_f32 v15, v15, v16, v18
	v_div_fixup_f32 v10, v15, v14, v10
	v_mul_f32_e32 v14, 0xbfb8aa3b, v11
	v_fma_f32 v15, v11, s34, -v14
	v_rndne_f32_e32 v16, v14
	v_fmac_f32_e32 v15, 0xb2a5705f, v11
	v_sub_f32_e32 v14, v14, v16
	v_add_f32_e32 v14, v14, v15
	v_exp_f32_e32 v14, v14
	v_cvt_i32_f32_e32 v15, v16
	v_cmp_nlt_f32_e32 vcc, s55, v11
	v_ldexp_f32 v14, v14, v15
	s_nop 0
	v_cndmask_b32_e32 v14, 0, v14, vcc
	v_cmp_ngt_f32_e32 vcc, s56, v11
	s_nop 1
	v_cndmask_b32_e32 v14, v219, v14, vcc
	v_add_f32_e32 v14, 1.0, v14
	v_div_scale_f32 v15, s[0:1], v14, v14, v11
	v_rcp_f32_e32 v16, v15
	s_nop 0
	v_fma_f32 v17, -v15, v16, 1.0
	v_fmac_f32_e32 v16, v17, v16
	v_div_scale_f32 v17, vcc, v11, v14, v11
	v_mul_f32_e32 v18, v17, v16
	v_fma_f32 v19, -v15, v18, v17
	v_fmac_f32_e32 v18, v19, v16
	v_fma_f32 v15, -v15, v18, v17
	v_div_fmas_f32 v15, v15, v16, v18
	v_div_fixup_f32 v11, v15, v14, v11
	v_cvt_pk_bf16_f32 v10, v10, v11
	v_mul_f32_e32 v11, 0xbfb8aa3b, v12
	v_fma_f32 v14, v12, s34, -v11
	v_rndne_f32_e32 v15, v11
	v_fmac_f32_e32 v14, 0xb2a5705f, v12
	v_sub_f32_e32 v11, v11, v15
	v_add_f32_e32 v11, v11, v14
	v_exp_f32_e32 v11, v11
	v_cvt_i32_f32_e32 v14, v15
	v_cmp_nlt_f32_e32 vcc, s55, v12
	v_ldexp_f32 v11, v11, v14
	s_nop 0
	v_cndmask_b32_e32 v11, 0, v11, vcc
	v_cmp_ngt_f32_e32 vcc, s56, v12
	s_nop 1
	v_cndmask_b32_e32 v11, v219, v11, vcc
	v_add_f32_e32 v11, 1.0, v11
	v_div_scale_f32 v14, s[0:1], v11, v11, v12
	v_rcp_f32_e32 v15, v14
	s_nop 0
	v_fma_f32 v16, -v14, v15, 1.0
	v_fmac_f32_e32 v15, v16, v15
	v_div_scale_f32 v16, vcc, v12, v11, v12
	v_mul_f32_e32 v17, v16, v15
	v_fma_f32 v18, -v14, v17, v16
	v_fmac_f32_e32 v17, v18, v15
	v_fma_f32 v14, -v14, v17, v16
	v_div_fmas_f32 v14, v14, v15, v17
	v_div_fixup_f32 v11, v14, v11, v12
	v_mul_f32_e32 v12, 0xbfb8aa3b, v13
	v_fma_f32 v14, v13, s34, -v12
	v_rndne_f32_e32 v15, v12
	v_fmac_f32_e32 v14, 0xb2a5705f, v13
	v_sub_f32_e32 v12, v12, v15
	v_add_f32_e32 v12, v12, v14
	v_exp_f32_e32 v12, v12
	v_cvt_i32_f32_e32 v14, v15
	v_cmp_nlt_f32_e32 vcc, s55, v13
	v_ldexp_f32 v12, v12, v14
	s_nop 0
	v_cndmask_b32_e32 v12, 0, v12, vcc
	v_cmp_ngt_f32_e32 vcc, s56, v13
	s_nop 1
	v_cndmask_b32_e32 v12, v219, v12, vcc
	v_add_f32_e32 v12, 1.0, v12
	v_div_scale_f32 v14, s[0:1], v12, v12, v13
	v_rcp_f32_e32 v15, v14
	s_add_i32 s0, s6, s20
	s_ashr_i32 s1, s0, 31
	s_lshl_b64 s[0:1], s[0:1], 11
	v_fma_f32 v16, -v14, v15, 1.0
	v_fmac_f32_e32 v15, v16, v15
	v_div_scale_f32 v16, vcc, v13, v12, v13
	v_mul_f32_e32 v17, v16, v15
	v_fma_f32 v18, -v14, v17, v16
	v_fmac_f32_e32 v17, v18, v15
	v_fma_f32 v14, -v14, v17, v16
	v_div_fmas_f32 v14, v14, v15, v17
	v_div_fixup_f32 v12, v14, v12, v13
	s_add_u32 s0, s4, s0
	s_addc_u32 s1, s5, s1
	v_cvt_pk_bf16_f32 v11, v11, v12
	v_lshl_add_u64 v[12:13], s[0:1], 0, v[0:1]
	v_add_co_u32_e32 v12, vcc, s8, v12
	s_nop 1
	v_addc_co_u32_e32 v13, vcc, 0, v13, vcc
	global_store_dwordx2 v[12:13], v[10:11], off offset:1536
	ds_read_b128 v[10:13], v52 offset:63488
	s_waitcnt lgkmcnt(0)
	v_mov_b32_e32 v14, v11
	v_mov_b32_e32 v15, v12
	v_mov_b32_e32 v16, v10
	v_mov_b32_e32 v17, v13
	v_pk_add_f32 v[14:15], v[14:15], v[16:17]
	s_nop 0
	v_add_f32_e32 v14, v14, v15
	s_nop 1
	v_add_f32_dpp v14, v14, v14 quad_perm:[1,0,3,2] row_mask:0xf bank_mask:0xf bound_ctrl:1
	s_nop 1
	v_add_f32_dpp v14, v14, v14 quad_perm:[2,3,0,1] row_mask:0xf bank_mask:0xf bound_ctrl:1
	s_nop 1
	v_add_f32_dpp v14, v14, v14 row_half_mirror row_mask:0xf bank_mask:0xf bound_ctrl:1
	s_nop 1
	v_add_f32_dpp v14, v14, v14 row_mirror row_mask:0xf bank_mask:0xf bound_ctrl:1
	v_fmamk_f32 v11, v14, 0xbc800000, v11
	v_fmamk_f32 v10, v14, 0xbc800000, v10
	v_fmamk_f32 v13, v14, 0xbc800000, v13
	v_fmac_f32_e32 v12, 0xbc800000, v14
	v_pk_mul_f32 v[14:15], v[12:13], v[12:13]
	v_pk_mul_f32 v[16:17], v[10:11], v[10:11]
	s_nop 0
	v_pk_mov_b32 v[18:19], v[16:17], v[14:15] op_sel:[1,0]
	v_mov_b32_e32 v17, v15
	v_pk_add_f32 v[14:15], v[18:19], v[16:17]
	s_nop 0
	v_add_f32_e32 v14, v14, v15
	s_nop 1
	v_add_f32_dpp v14, v14, v14 quad_perm:[1,0,3,2] row_mask:0xf bank_mask:0xf bound_ctrl:1
	s_nop 1
	v_add_f32_dpp v14, v14, v14 quad_perm:[2,3,0,1] row_mask:0xf bank_mask:0xf bound_ctrl:1
	s_nop 1
	v_add_f32_dpp v14, v14, v14 row_half_mirror row_mask:0xf bank_mask:0xf bound_ctrl:1
	s_nop 1
	v_add_f32_dpp v14, v14, v14 row_mirror row_mask:0xf bank_mask:0xf bound_ctrl:1
	v_fmamk_f32 v14, v14, 0x3c800000, v216
	v_cmp_gt_f32_e32 vcc, s60, v14
	v_mul_f32_e32 v15, 0x4f800000, v14
	s_nop 0
	v_cndmask_b32_e32 v14, v14, v15, vcc
	v_sqrt_f32_e32 v15, v14
	s_nop 0
	v_add_u32_e32 v16, -1, v15
	v_fma_f32 v17, -v16, v15, v14
	v_cmp_ge_f32_e64 s[2:3], 0, v17
	v_add_u32_e32 v17, 1, v15
	s_nop 0
	v_cndmask_b32_e64 v16, v15, v16, s[2:3]
	v_fma_f32 v15, -v17, v15, v14
	v_cmp_lt_f32_e64 s[2:3], 0, v15
	s_nop 1
	v_cndmask_b32_e64 v15, v16, v17, s[2:3]
	v_mul_f32_e32 v16, 0x37800000, v15
	v_cndmask_b32_e32 v15, v15, v16, vcc
	v_cmp_class_f32_e32 vcc, v14, v217
	s_nop 1
	v_cndmask_b32_e32 v14, v15, v14, vcc
	v_div_scale_f32 v15, s[0:1], v14, v14, 1.0
	v_rcp_f32_e32 v16, v15
	s_nop 0
	v_fma_f32 v17, -v15, v16, 1.0
	v_fmac_f32_e32 v16, v17, v16
	v_div_scale_f32 v17, vcc, 1.0, v14, 1.0
	v_mul_f32_e32 v18, v17, v16
	v_fma_f32 v19, -v15, v18, v17
	v_fmac_f32_e32 v18, v19, v16
	v_fma_f32 v15, -v15, v18, v17
	v_div_fmas_f32 v15, v15, v16, v18
	v_div_fixup_f32 v14, v15, v14, 1.0
	v_pk_mul_f32 v[10:11], v[10:11], v[14:15] op_sel_hi:[1,0]
	v_pk_mul_f32 v[12:13], v[12:13], v[14:15] op_sel_hi:[1,0]
	v_pk_fma_f32 v[2:3], v[2:3], v[10:11], v[6:7]
	v_pk_fma_f32 v[4:5], v[4:5], v[12:13], v[8:9]
	v_mul_f32_e32 v6, 0xbfb8aa3b, v2
	v_fma_f32 v7, v2, s34, -v6
	v_rndne_f32_e32 v8, v6
	v_fmac_f32_e32 v7, 0xb2a5705f, v2
	v_sub_f32_e32 v6, v6, v8
	v_add_f32_e32 v6, v6, v7
	v_exp_f32_e32 v6, v6
	v_cvt_i32_f32_e32 v7, v8
	v_cmp_nlt_f32_e32 vcc, s55, v2
	v_ldexp_f32 v6, v6, v7
	s_nop 0
	v_cndmask_b32_e32 v6, 0, v6, vcc
	v_cmp_ngt_f32_e32 vcc, s56, v2
	s_nop 1
	v_cndmask_b32_e32 v6, v219, v6, vcc
	v_add_f32_e32 v6, 1.0, v6
	v_div_scale_f32 v7, s[0:1], v6, v6, v2
	v_rcp_f32_e32 v8, v7
	s_nop 0
	v_fma_f32 v9, -v7, v8, 1.0
	v_fmac_f32_e32 v8, v9, v8
	v_div_scale_f32 v9, vcc, v2, v6, v2
	v_mul_f32_e32 v10, v9, v8
	v_fma_f32 v11, -v7, v10, v9
	v_fmac_f32_e32 v10, v11, v8
	v_fma_f32 v7, -v7, v10, v9
	v_div_fmas_f32 v7, v7, v8, v10
	v_div_fixup_f32 v2, v7, v6, v2
	v_mul_f32_e32 v6, 0xbfb8aa3b, v3
	v_fma_f32 v7, v3, s34, -v6
	v_rndne_f32_e32 v8, v6
	v_fmac_f32_e32 v7, 0xb2a5705f, v3
	v_sub_f32_e32 v6, v6, v8
	v_add_f32_e32 v6, v6, v7
	v_exp_f32_e32 v6, v6
	v_cvt_i32_f32_e32 v7, v8
	v_cmp_nlt_f32_e32 vcc, s55, v3
	v_ldexp_f32 v6, v6, v7
	s_nop 0
	v_cndmask_b32_e32 v6, 0, v6, vcc
	v_cmp_ngt_f32_e32 vcc, s56, v3
	s_nop 1
	v_cndmask_b32_e32 v6, v219, v6, vcc
	v_add_f32_e32 v6, 1.0, v6
	v_div_scale_f32 v7, s[0:1], v6, v6, v3
	v_rcp_f32_e32 v8, v7
	s_nop 0
	v_fma_f32 v9, -v7, v8, 1.0
	v_fmac_f32_e32 v8, v9, v8
	v_div_scale_f32 v9, vcc, v3, v6, v3
	v_mul_f32_e32 v10, v9, v8
	v_fma_f32 v11, -v7, v10, v9
	v_fmac_f32_e32 v10, v11, v8
	v_fma_f32 v7, -v7, v10, v9
	v_div_fmas_f32 v7, v7, v8, v10
	v_div_fixup_f32 v3, v7, v6, v3
	v_cvt_pk_bf16_f32 v2, v2, v3
	v_mul_f32_e32 v3, 0xbfb8aa3b, v4
	v_fma_f32 v6, v4, s34, -v3
	v_rndne_f32_e32 v7, v3
	v_fmac_f32_e32 v6, 0xb2a5705f, v4
	v_sub_f32_e32 v3, v3, v7
	v_add_f32_e32 v3, v3, v6
	v_exp_f32_e32 v3, v3
	v_cvt_i32_f32_e32 v6, v7
	v_cmp_nlt_f32_e32 vcc, s55, v4
	v_ldexp_f32 v3, v3, v6
	s_nop 0
	v_cndmask_b32_e32 v3, 0, v3, vcc
	v_cmp_ngt_f32_e32 vcc, s56, v4
	s_nop 1
	v_cndmask_b32_e32 v3, v219, v3, vcc
	v_add_f32_e32 v3, 1.0, v3
	v_div_scale_f32 v6, s[0:1], v3, v3, v4
	v_rcp_f32_e32 v7, v6
	s_nop 0
	v_fma_f32 v8, -v6, v7, 1.0
	v_fmac_f32_e32 v7, v8, v7
	v_div_scale_f32 v8, vcc, v4, v3, v4
	v_mul_f32_e32 v9, v8, v7
	v_fma_f32 v10, -v6, v9, v8
	v_fmac_f32_e32 v9, v10, v7
	v_fma_f32 v6, -v6, v9, v8
	v_div_fmas_f32 v6, v6, v7, v9
	v_div_fixup_f32 v3, v6, v3, v4
	v_mul_f32_e32 v4, 0xbfb8aa3b, v5
	v_fma_f32 v6, v5, s34, -v4
	v_rndne_f32_e32 v7, v4
	v_fmac_f32_e32 v6, 0xb2a5705f, v5
	v_sub_f32_e32 v4, v4, v7
	v_add_f32_e32 v4, v4, v6
	v_exp_f32_e32 v4, v4
	v_cvt_i32_f32_e32 v6, v7
	v_cmp_nlt_f32_e32 vcc, s55, v5
	v_ldexp_f32 v4, v4, v6
	s_nop 0
	v_cndmask_b32_e32 v4, 0, v4, vcc
	v_cmp_ngt_f32_e32 vcc, s56, v5
	s_nop 1
	v_cndmask_b32_e32 v4, v219, v4, vcc
	v_add_f32_e32 v4, 1.0, v4
	v_div_scale_f32 v6, s[0:1], v4, v4, v5
	v_rcp_f32_e32 v7, v6
	s_add_i32 s0, s6, s7
	s_ashr_i32 s1, s0, 31
	s_lshl_b64 s[0:1], s[0:1], 11
	v_fma_f32 v8, -v6, v7, 1.0
	v_fmac_f32_e32 v7, v8, v7
	v_div_scale_f32 v8, vcc, v5, v4, v5
	v_mul_f32_e32 v9, v8, v7
	v_fma_f32 v10, -v6, v9, v8
	v_fmac_f32_e32 v9, v10, v7
	v_fma_f32 v6, -v6, v9, v8
	v_div_fmas_f32 v6, v6, v7, v9
	v_div_fixup_f32 v4, v6, v4, v5
	s_add_u32 s0, s4, s0
	s_addc_u32 s1, s5, s1
	v_cvt_pk_bf16_f32 v3, v3, v4
	v_lshl_add_u64 v[4:5], s[0:1], 0, v[0:1]
	v_add_co_u32_e32 v4, vcc, 0x10f60000, v4
	s_nop 1
	v_addc_co_u32_e32 v5, vcc, 0, v5, vcc
	global_store_dwordx2 v[4:5], v[2:3], off offset:1536

.LBB0_640:
	s_or_b64 exec, exec, s[2:3]
	s_lshl_b32 s0, s81, 3
	s_or_b32 s82, s0, s15
	s_cmpk_gt_i32 s82, 0x1ff
	s_mov_b64 s[2:3], -1
	s_cbranch_scc0 .LBB0_760
	s_cmpk_gt_u32 s0, 0x21f
	s_cbranch_scc0 .LBB0_750
	s_cmpk_gt_u32 s0, 0x23f
	s_cbranch_scc0 .LBB0_741
	s_cmpk_gt_u32 s0, 0x25f
	s_cbranch_scc0 .LBB0_736
	s_lshl_b32 s0, s82, 3
	s_add_i32 s0, s25, s0
	s_cmp_ge_i32 s0, s19
	s_cbranch_scc1 .LBB0_735
	s_mul_hi_i32 s1, s0, 0x2c0b02c1
	s_lshr_b32 s2, s1, 31
	s_ashr_i32 s1, s1, 10
	s_add_i32 s2, s1, s2
	s_mul_i32 s1, s2, 0x1740
	s_sub_i32 s16, s0, s1
	v_mov_b32_e32 v4, v73
	s_cmpk_gt_i32 s16, 0x57f
	s_mov_b64 s[10:11], -1
	s_cbranch_scc0 .LBB0_655
	s_cmpk_gt_u32 s16, 0x77f
	s_cbranch_scc0 .LBB0_652
	v_and_b32_e32 v6, 31, v4
	s_cmpk_gt_u32 s16, 0x11ff
	s_mul_hi_i32 s0, s2, 0xa80000
	s_mul_i32 s1, s2, 0xa80000
	v_lshlrev_b32_e32 v5, 2, v6
	s_cbranch_scc0 .LBB0_649
	s_load_dwordx2 s[10:11], s[4:5], 0xe0
	s_load_dwordx2 s[12:13], s[4:5], 0x100
	s_add_i32 s3, s16, 0xffffee00
	v_ashrrev_i32_e32 v7, 5, v4
	s_waitcnt lgkmcnt(0)
	s_add_u32 s20, s10, s1
	s_addc_u32 s21, s11, s0
	s_mul_i32 s10, s2, 0x540000
	s_mul_hi_i32 s11, s2, 0x540000
	s_add_u32 s10, s12, s10
	s_addc_u32 s11, s13, s11
	s_lshl_b32 s12, s3, 1
	s_lshl_b32 s3, s3, 5
	s_and_b32 s12, s12, 0xfc0
	s_and_b32 s3, s3, 0x3e0
	v_or_b32_e32 v0, s3, v6
	v_add_u32_e32 v2, s12, v7
	v_lshlrev_b32_e32 v0, 2, v0
	v_ashrrev_i32_e32 v3, 31, v2
	v_lshl_add_u64 v[8:9], s[20:21], 0, v[0:1]
	v_lshlrev_b64 v[2:3], 12, v[2:3]
	v_lshl_add_u64 v[2:3], v[8:9], 0, v[2:3]
	s_movk_i32 s13, 0x2000
	v_add_co_u32_e32 v8, vcc, s13, v2
	s_movk_i32 s13, 0x4000
	s_nop 0
	v_addc_co_u32_e32 v9, vcc, 0, v3, vcc
	global_load_dword v0, v[2:3], off nt
	global_load_dword v10, v[8:9], off nt
	v_add_co_u32_e32 v8, vcc, s13, v2
	s_movk_i32 s13, 0x6000
	s_nop 0
	v_addc_co_u32_e32 v9, vcc, 0, v3, vcc
	global_load_dword v11, v[8:9], off nt
	v_add_co_u32_e32 v8, vcc, s13, v2
	s_mov_b32 s13, 0x8000
	s_nop 0
	v_addc_co_u32_e32 v9, vcc, 0, v3, vcc
	global_load_dword v12, v[8:9], off nt
	v_add_co_u32_e32 v8, vcc, s13, v2
	s_mov_b32 s13, 0xa000
	s_nop 0
	v_addc_co_u32_e32 v9, vcc, 0, v3, vcc
	global_load_dword v13, v[8:9], off nt
	v_add_co_u32_e32 v8, vcc, s13, v2
	s_mov_b32 s13, 0xc000
	s_nop 0
	v_addc_co_u32_e32 v9, vcc, 0, v3, vcc
	global_load_dword v14, v[8:9], off nt
	v_add_co_u32_e32 v8, vcc, s13, v2
	s_mov_b32 s13, 0xe000
	s_nop 0
	v_addc_co_u32_e32 v9, vcc, 0, v3, vcc
	global_load_dword v15, v[8:9], off nt
	v_add_co_u32_e32 v8, vcc, s13, v2
	s_mov_b32 s13, 0x10000
	s_nop 0
	v_addc_co_u32_e32 v9, vcc, 0, v3, vcc
	global_load_dword v16, v[8:9], off nt
	v_add_co_u32_e32 v8, vcc, s13, v2
	s_mov_b32 s13, 0x12000
	s_nop 0
	v_addc_co_u32_e32 v9, vcc, 0, v3, vcc
	global_load_dword v17, v[8:9], off nt
	v_add_co_u32_e32 v8, vcc, s13, v2
	s_mov_b32 s13, 0x14000
	s_nop 0
	v_addc_co_u32_e32 v9, vcc, 0, v3, vcc
	global_load_dword v18, v[8:9], off nt
	v_add_co_u32_e32 v8, vcc, s13, v2
	s_mov_b32 s13, 0x16000
	s_nop 0
	v_addc_co_u32_e32 v9, vcc, 0, v3, vcc
	global_load_dword v19, v[8:9], off nt
	v_add_co_u32_e32 v8, vcc, s13, v2
	s_mov_b32 s13, 0x18000
	s_nop 0
	v_addc_co_u32_e32 v9, vcc, 0, v3, vcc
	global_load_dword v20, v[8:9], off nt
	v_add_co_u32_e32 v8, vcc, s13, v2
	s_mov_b32 s13, 0x1a000
	s_nop 0
	v_addc_co_u32_e32 v9, vcc, 0, v3, vcc
	global_load_dword v21, v[8:9], off nt
	v_add_co_u32_e32 v8, vcc, s13, v2
	s_mov_b32 s13, 0x1c000
	s_nop 0
	v_addc_co_u32_e32 v9, vcc, 0, v3, vcc
	global_load_dword v22, v[8:9], off nt
	v_add_co_u32_e32 v8, vcc, s13, v2
	s_mov_b32 s13, 0x1e000
	s_nop 0
	v_addc_co_u32_e32 v9, vcc, 0, v3, vcc
	global_load_dword v23, v[8:9], off nt
	v_add_co_u32_e32 v8, vcc, s13, v2
	s_mov_b32 s13, 0x22000
	s_nop 0
	v_addc_co_u32_e32 v9, vcc, 0, v3, vcc
	global_load_dword v24, v[8:9], off nt
	v_add_co_u32_e32 v8, vcc, s14, v2
	s_lshl_b32 s12, s12, 1
	s_nop 0
	v_addc_co_u32_e32 v9, vcc, 0, v3, vcc
	global_load_dword v25, v[8:9], off nt
	v_add_co_u32_e32 v8, vcc, s13, v2
	s_mov_b32 s13, 0x24000
	s_nop 0
	v_addc_co_u32_e32 v9, vcc, 0, v3, vcc
	global_load_dword v26, v[8:9], off nt
	v_add_co_u32_e32 v8, vcc, s13, v2
	s_mov_b32 s13, 0x26000
	s_nop 0
	v_addc_co_u32_e32 v9, vcc, 0, v3, vcc
	global_load_dword v27, v[8:9], off nt
	v_add_co_u32_e32 v8, vcc, s13, v2
	s_mov_b32 s13, 0x28000
	s_nop 0
	v_addc_co_u32_e32 v9, vcc, 0, v3, vcc
	global_load_dword v28, v[8:9], off nt
	v_add_co_u32_e32 v8, vcc, s13, v2
	s_mov_b32 s13, 0x2a000
	s_nop 0
	v_addc_co_u32_e32 v9, vcc, 0, v3, vcc
	global_load_dword v29, v[8:9], off nt
	v_add_co_u32_e32 v8, vcc, s13, v2
	s_mov_b32 s13, 0x2c000
	s_nop 0
	v_addc_co_u32_e32 v9, vcc, 0, v3, vcc
	global_load_dword v30, v[8:9], off nt
	v_add_co_u32_e32 v8, vcc, s13, v2
	s_mov_b32 s13, 0x2e000
	s_nop 0
	v_addc_co_u32_e32 v9, vcc, 0, v3, vcc
	global_load_dword v31, v[8:9], off nt
	v_add_co_u32_e32 v8, vcc, s13, v2
	s_mov_b32 s13, 0x30000
	s_nop 0
	v_addc_co_u32_e32 v9, vcc, 0, v3, vcc
	global_load_dword v32, v[8:9], off nt
	v_add_co_u32_e32 v8, vcc, s13, v2
	s_mov_b32 s13, 0x32000
	s_nop 0
	v_addc_co_u32_e32 v9, vcc, 0, v3, vcc
	global_load_dword v33, v[8:9], off nt
	v_add_co_u32_e32 v8, vcc, s13, v2
	s_mov_b32 s13, 0x34000
	s_nop 0
	v_addc_co_u32_e32 v9, vcc, 0, v3, vcc
	global_load_dword v34, v[8:9], off nt
	v_add_co_u32_e32 v8, vcc, s13, v2
	s_mov_b32 s13, 0x36000
	s_nop 0
	v_addc_co_u32_e32 v9, vcc, 0, v3, vcc
	global_load_dword v35, v[8:9], off nt
	v_add_co_u32_e32 v8, vcc, s13, v2
	s_mov_b32 s13, 0x38000
	s_nop 0
	v_addc_co_u32_e32 v9, vcc, 0, v3, vcc
	global_load_dword v36, v[8:9], off nt
	v_add_co_u32_e32 v8, vcc, s13, v2
	s_mov_b32 s13, 0x3a000
	s_nop 0
	v_addc_co_u32_e32 v9, vcc, 0, v3, vcc
	global_load_dword v37, v[8:9], off nt
	v_add_co_u32_e32 v8, vcc, s13, v2
	s_mov_b32 s13, 0x3c000
	s_nop 0
	v_addc_co_u32_e32 v9, vcc, 0, v3, vcc
	global_load_dword v38, v[8:9], off nt
	v_add_co_u32_e32 v8, vcc, s13, v2
	s_mov_b32 s13, 0x3e000
	s_nop 0
	v_addc_co_u32_e32 v9, vcc, 0, v3, vcc
	v_add_co_u32_e32 v2, vcc, s13, v2
	global_load_dword v8, v[8:9], off nt
	s_nop 0
	v_addc_co_u32_e32 v3, vcc, 0, v3, vcc
	global_load_dword v2, v[2:3], off nt
	s_movk_i32 s13, 0x84
	v_mul_lo_u32 v3, v7, s13
	v_add3_u32 v3, s28, v5, v3
	s_waitcnt vmcnt(30)
	ds_write2_b32 v3, v0, v10 offset1:66
	s_waitcnt vmcnt(28)
	ds_write2_b32 v3, v11, v12 offset0:132 offset1:198
	v_add_u32_e32 v0, 0x400, v3
	s_waitcnt vmcnt(26)
	ds_write2_b32 v0, v13, v14 offset0:8 offset1:74
	s_waitcnt vmcnt(24)
	ds_write2_b32 v0, v15, v16 offset0:140 offset1:206
	v_add_u32_e32 v0, 0x800, v3
	s_waitcnt vmcnt(22)
	ds_write2_b32 v0, v17, v18 offset0:16 offset1:82
	s_waitcnt vmcnt(20)
	ds_write2_b32 v0, v19, v20 offset0:148 offset1:214
	v_add_u32_e32 v0, 0xc00, v3
	s_waitcnt vmcnt(18)
	ds_write2_b32 v0, v21, v22 offset0:24 offset1:90
	s_waitcnt vmcnt(16)
	ds_write2_b32 v0, v23, v24 offset0:156 offset1:222
	v_add_u32_e32 v0, 0x1000, v3
	s_waitcnt vmcnt(14)
	ds_write2_b32 v0, v25, v26 offset0:32 offset1:98
	s_waitcnt vmcnt(12)
	ds_write2_b32 v0, v27, v28 offset0:164 offset1:230
	v_add_u32_e32 v0, 0x1400, v3
	s_waitcnt vmcnt(10)
	ds_write2_b32 v0, v29, v30 offset0:40 offset1:106
	s_waitcnt vmcnt(8)
	ds_write2_b32 v0, v31, v32 offset0:172 offset1:238
	v_add_u32_e32 v0, 0x1800, v3
	s_waitcnt vmcnt(6)
	ds_write2_b32 v0, v33, v34 offset0:48 offset1:114
	s_waitcnt vmcnt(4)
	ds_write2_b32 v0, v35, v36 offset0:180 offset1:246
	v_add_u32_e32 v0, 0x1c00, v3
	s_waitcnt vmcnt(2)
	ds_write2_b32 v0, v37, v38 offset0:56 offset1:122
	s_waitcnt vmcnt(0)
	ds_write2_b32 v0, v8, v2 offset0:188 offset1:254
	v_lshlrev_b32_e32 v0, 3, v4
	v_and_b32_e32 v0, 56, v0
	s_add_u32 s10, s10, s12
	v_ashrrev_i32_e32 v7, 3, v4
	v_mul_u32_u24_e32 v8, 0x84, v0
	s_addc_u32 s11, s11, 0
	v_lshlrev_b32_e32 v0, 1, v0
	s_waitcnt lgkmcnt(0)
	v_lshl_add_u64 v[2:3], s[10:11], 0, v[0:1]
	v_lshlrev_b32_e32 v0, 2, v7
	v_add3_u32 v0, s28, v8, v0
	ds_read2_b32 v[12:13], v0 offset0:33 offset1:41
	ds_read2_b32 v[14:15], v0 offset1:8
	ds_read2_b32 v[16:17], v0 offset0:66 offset1:74
	ds_read2_b32 v[18:19], v0 offset0:99 offset1:107
	ds_read2_b32 v[20:21], v0 offset0:132 offset1:140
	ds_read2_b32 v[22:23], v0 offset0:165 offset1:173
	ds_read2_b32 v[24:25], v0 offset0:198 offset1:206
	ds_read2_b32 v[26:27], v0 offset0:231 offset1:239
	s_waitcnt lgkmcnt(7)
	s_waitcnt lgkmcnt(6)
	v_cvt_pk_bf16_f32 v8, v14, v12
	s_waitcnt lgkmcnt(5)
	s_waitcnt lgkmcnt(4)
	v_cvt_pk_bf16_f32 v9, v16, v18
	s_waitcnt lgkmcnt(3)
	s_waitcnt lgkmcnt(2)
	v_cvt_pk_bf16_f32 v10, v20, v22
	s_waitcnt lgkmcnt(1)
	s_mov_b64 s[10:11], 0x2600000
	s_waitcnt lgkmcnt(0)
	v_lshl_add_u64 v[2:3], v[2:3], 0, s[10:11]
	v_add_u32_e32 v7, s3, v7
	s_movk_i32 s3, 0x1500
	v_cvt_pk_bf16_f32 v11, v24, v26
	v_mad_i64_i32 v[28:29], s[10:11], v7, s3, v[2:3]
	global_store_dwordx4 v[28:29], v[8:11], off
	s_nop 1
	v_cvt_pk_bf16_f32 v8, v15, v13
	v_cvt_pk_bf16_f32 v9, v17, v19
	v_cvt_pk_bf16_f32 v10, v21, v23
	v_cvt_pk_bf16_f32 v11, v25, v27
	v_add_u32_e32 v12, 8, v7
	v_mad_i64_i32 v[12:13], s[10:11], v12, s3, v[2:3]
	global_store_dwordx4 v[12:13], v[8:11], off
	ds_read2_b32 v[12:13], v0 offset0:49 offset1:57
	ds_read2_b32 v[14:15], v0 offset0:16 offset1:24
	ds_read2_b32 v[16:17], v0 offset0:82 offset1:90
	ds_read2_b32 v[18:19], v0 offset0:115 offset1:123
	ds_read2_b32 v[20:21], v0 offset0:148 offset1:156
	ds_read2_b32 v[22:23], v0 offset0:181 offset1:189
	ds_read2_b32 v[24:25], v0 offset0:214 offset1:222
	ds_read2_b32 v[26:27], v0 offset0:247 offset1:255
	s_waitcnt lgkmcnt(7)
	s_waitcnt lgkmcnt(6)
	v_cvt_pk_bf16_f32 v8, v14, v12
	s_waitcnt lgkmcnt(5)
	s_waitcnt lgkmcnt(4)
	v_cvt_pk_bf16_f32 v9, v16, v18
	s_waitcnt lgkmcnt(3)
	s_waitcnt lgkmcnt(2)
	s_waitcnt lgkmcnt(1)
	v_cvt_pk_bf16_f32 v10, v20, v22
	s_waitcnt lgkmcnt(0)
	v_cvt_pk_bf16_f32 v11, v24, v26
	v_add_u32_e32 v0, 16, v7
	v_mad_i64_i32 v[28:29], s[10:11], v0, s3, v[2:3]
	global_store_dwordx4 v[28:29], v[8:11], off
	s_nop 1
	v_cvt_pk_bf16_f32 v8, v15, v13
	v_cvt_pk_bf16_f32 v9, v17, v19
	v_cvt_pk_bf16_f32 v10, v21, v23
	v_cvt_pk_bf16_f32 v11, v25, v27
	v_add_u32_e32 v0, 24, v7
	v_mad_i64_i32 v[2:3], s[10:11], v0, s3, v[2:3]
	global_store_dwordx4 v[2:3], v[8:11], off
	s_waitcnt lgkmcnt(0)
	s_mov_b64 s[10:11], 0
.LBB0_649:
	s_andn2_b64 vcc, exec, s[10:11]
	s_cbranch_vccnz .LBB0_651
	s_load_dwordx2 s[10:11], s[4:5], 0xc8
	s_load_dwordx2 s[12:13], s[4:5], 0x100
	s_mul_i32 s17, s2, 0x1500000
	s_mul_hi_i32 s3, s2, 0x1500000
	v_ashrrev_i32_e32 v8, 5, v4
	s_waitcnt lgkmcnt(0)
	s_add_u32 s20, s10, s17
	s_addc_u32 s21, s11, s3
	s_add_u32 s1, s12, s1
	s_addc_u32 s3, s13, s0
	s_add_i32 s0, s16, 0xf880
	s_bfe_u32 s10, s0, 0xd0003
	s_mulk_i32 s10, 0xc31
	s_lshr_b32 s10, s10, 16
	s_mul_i32 s11, s10, 0xa8
	s_sub_i32 s11, s0, s11
	s_and_b32 s12, s11, 0xffff
	s_lshl_b32 s0, s12, 5
	s_lshl_b32 s12, s12, 4
	s_and_b32 s12, s12, 0xf80
	s_and_b32 s11, s11, 4
	s_add_i32 s13, s12, 0xa80
	s_cmp_eq_u32 s11, 0
	s_cselect_b32 s11, s12, s13
	s_and_b32 s12, s0, 0x60
	s_or_b32 s11, s11, s12
	v_or_b32_e32 v0, s11, v6
	v_lshlrev_b32_e32 v0, 2, v0
	v_lshl_add_u32 v9, s10, 6, v8
	v_lshl_add_u64 v[2:3], s[20:21], 0, v[0:1]
	s_movk_i32 s11, 0x5400
	v_mad_i64_i32 v[6:7], s[12:13], v9, s11, v[2:3]
	global_load_dword v0, v[6:7], off nt
	v_add_u32_e32 v6, 2, v9
	v_mad_i64_i32 v[6:7], s[12:13], v6, s11, v[2:3]
	global_load_dword v10, v[6:7], off nt
	v_add_u32_e32 v6, 4, v9
	v_mad_i64_i32 v[6:7], s[12:13], v6, s11, v[2:3]
	global_load_dword v11, v[6:7], off nt
	v_add_u32_e32 v6, 6, v9
	v_mad_i64_i32 v[6:7], s[12:13], v6, s11, v[2:3]
	global_load_dword v12, v[6:7], off nt
	v_add_u32_e32 v6, 8, v9
	v_mad_i64_i32 v[6:7], s[12:13], v6, s11, v[2:3]
	global_load_dword v13, v[6:7], off nt
	v_add_u32_e32 v6, 10, v9
	v_mad_i64_i32 v[6:7], s[12:13], v6, s11, v[2:3]
	global_load_dword v14, v[6:7], off nt
	v_add_u32_e32 v6, 12, v9
	v_mad_i64_i32 v[6:7], s[12:13], v6, s11, v[2:3]
	global_load_dword v15, v[6:7], off nt
	v_add_u32_e32 v6, 14, v9
	v_mad_i64_i32 v[6:7], s[12:13], v6, s11, v[2:3]
	global_load_dword v16, v[6:7], off nt
	v_add_u32_e32 v6, 16, v9
	v_mad_i64_i32 v[6:7], s[12:13], v6, s11, v[2:3]
	global_load_dword v17, v[6:7], off nt
	v_add_u32_e32 v6, 18, v9
	v_mad_i64_i32 v[6:7], s[12:13], v6, s11, v[2:3]
	global_load_dword v18, v[6:7], off nt
	v_add_u32_e32 v6, 20, v9
	v_mad_i64_i32 v[6:7], s[12:13], v6, s11, v[2:3]
	global_load_dword v19, v[6:7], off nt
	v_add_u32_e32 v6, 22, v9
	v_mad_i64_i32 v[6:7], s[12:13], v6, s11, v[2:3]
	global_load_dword v20, v[6:7], off nt
	v_add_u32_e32 v6, 24, v9
	v_mad_i64_i32 v[6:7], s[12:13], v6, s11, v[2:3]
	global_load_dword v21, v[6:7], off nt
	v_add_u32_e32 v6, 26, v9
	v_mad_i64_i32 v[6:7], s[12:13], v6, s11, v[2:3]
	global_load_dword v22, v[6:7], off nt
	v_add_u32_e32 v6, 28, v9
	v_mad_i64_i32 v[6:7], s[12:13], v6, s11, v[2:3]
	global_load_dword v23, v[6:7], off nt
	v_add_u32_e32 v6, 30, v9
	v_mad_i64_i32 v[6:7], s[12:13], v6, s11, v[2:3]
	global_load_dword v24, v[6:7], off nt
	v_add_u32_e32 v6, 32, v9
	v_mad_i64_i32 v[6:7], s[12:13], v6, s11, v[2:3]
	global_load_dword v25, v[6:7], off nt
	v_add_u32_e32 v6, 34, v9
	v_mad_i64_i32 v[6:7], s[12:13], v6, s11, v[2:3]
	global_load_dword v26, v[6:7], off nt
	v_add_u32_e32 v6, 36, v9
	v_mad_i64_i32 v[6:7], s[12:13], v6, s11, v[2:3]
	global_load_dword v27, v[6:7], off nt
	v_add_u32_e32 v6, 38, v9
	v_mad_i64_i32 v[6:7], s[12:13], v6, s11, v[2:3]
	global_load_dword v28, v[6:7], off nt
	v_add_u32_e32 v6, 40, v9
	v_mad_i64_i32 v[6:7], s[12:13], v6, s11, v[2:3]
	global_load_dword v29, v[6:7], off nt
	v_add_u32_e32 v6, 42, v9
	v_mad_i64_i32 v[6:7], s[12:13], v6, s11, v[2:3]
	global_load_dword v30, v[6:7], off nt
	v_add_u32_e32 v6, 44, v9
	v_mad_i64_i32 v[6:7], s[12:13], v6, s11, v[2:3]
	global_load_dword v31, v[6:7], off nt
	v_add_u32_e32 v6, 46, v9
	v_mad_i64_i32 v[6:7], s[12:13], v6, s11, v[2:3]
	global_load_dword v32, v[6:7], off nt
	v_add_u32_e32 v6, 48, v9
	v_mad_i64_i32 v[6:7], s[12:13], v6, s11, v[2:3]
	global_load_dword v33, v[6:7], off nt
	v_add_u32_e32 v6, 50, v9
	v_mad_i64_i32 v[6:7], s[12:13], v6, s11, v[2:3]
	global_load_dword v34, v[6:7], off nt
	v_add_u32_e32 v6, 52, v9
	v_mad_i64_i32 v[6:7], s[12:13], v6, s11, v[2:3]
	global_load_dword v35, v[6:7], off nt
	v_add_u32_e32 v6, 54, v9
	v_mad_i64_i32 v[6:7], s[12:13], v6, s11, v[2:3]
	global_load_dword v36, v[6:7], off nt
	v_add_u32_e32 v6, 56, v9
	v_mad_i64_i32 v[6:7], s[12:13], v6, s11, v[2:3]
	global_load_dword v37, v[6:7], off nt
	v_add_u32_e32 v6, 58, v9
	v_mad_i64_i32 v[6:7], s[12:13], v6, s11, v[2:3]
	global_load_dword v38, v[6:7], off nt
	v_add_u32_e32 v6, 60, v9
	v_mad_i64_i32 v[6:7], s[12:13], v6, s11, v[2:3]
	global_load_dword v6, v[6:7], off nt
	v_add_u32_e32 v7, 62, v9
	v_mad_i64_i32 v[2:3], s[12:13], v7, s11, v[2:3]
	global_load_dword v2, v[2:3], off nt
	s_movk_i32 s11, 0x84
	v_mul_lo_u32 v3, v8, s11
	v_add3_u32 v3, s28, v5, v3
	s_waitcnt vmcnt(30)
	ds_write2_b32 v3, v0, v10 offset1:66
	s_waitcnt vmcnt(28)
	ds_write2_b32 v3, v11, v12 offset0:132 offset1:198
	v_add_u32_e32 v0, 0x400, v3
	s_waitcnt vmcnt(26)
	ds_write2_b32 v0, v13, v14 offset0:8 offset1:74
	s_waitcnt vmcnt(24)
	ds_write2_b32 v0, v15, v16 offset0:140 offset1:206
	v_add_u32_e32 v0, 0x800, v3
	s_waitcnt vmcnt(22)
	ds_write2_b32 v0, v17, v18 offset0:16 offset1:82
	s_waitcnt vmcnt(20)
	ds_write2_b32 v0, v19, v20 offset0:148 offset1:214
	v_add_u32_e32 v0, 0xc00, v3
	s_waitcnt vmcnt(18)
	ds_write2_b32 v0, v21, v22 offset0:24 offset1:90
	s_waitcnt vmcnt(16)
	ds_write2_b32 v0, v23, v24 offset0:156 offset1:222
	v_add_u32_e32 v0, 0x1000, v3
	s_waitcnt vmcnt(14)
	ds_write2_b32 v0, v25, v26 offset0:32 offset1:98
	s_waitcnt vmcnt(12)
	ds_write2_b32 v0, v27, v28 offset0:164 offset1:230
	v_add_u32_e32 v0, 0x1400, v3
	s_waitcnt vmcnt(10)
	ds_write2_b32 v0, v29, v30 offset0:40 offset1:106
	s_waitcnt vmcnt(8)
	ds_write2_b32 v0, v31, v32 offset0:172 offset1:238
	v_add_u32_e32 v0, 0x1800, v3
	s_waitcnt vmcnt(6)
	ds_write2_b32 v0, v33, v34 offset0:48 offset1:114
	s_waitcnt vmcnt(4)
	ds_write2_b32 v0, v35, v36 offset0:180 offset1:246
	v_add_u32_e32 v0, 0x1c00, v3
	s_waitcnt vmcnt(2)
	ds_write2_b32 v0, v37, v38 offset0:56 offset1:122
	s_waitcnt vmcnt(0)
	ds_write2_b32 v0, v6, v2 offset0:188 offset1:254
	v_lshlrev_b32_e32 v0, 3, v4
	s_lshl_b32 s10, s10, 7
	v_and_b32_e32 v0, 56, v0
	s_add_u32 s10, s1, s10
	v_ashrrev_i32_e32 v5, 3, v4
	v_mul_u32_u24_e32 v6, 0x84, v0
	s_addc_u32 s11, s3, 0
	v_lshlrev_b32_e32 v0, 1, v0
	s_waitcnt lgkmcnt(0)
	v_lshl_add_u64 v[2:3], s[10:11], 0, v[0:1]
	v_lshlrev_b32_e32 v0, 2, v5
	v_add3_u32 v0, s28, v6, v0
	ds_read2_b32 v[10:11], v0 offset0:33 offset1:41
	ds_read2_b32 v[12:13], v0 offset1:8
	ds_read2_b32 v[14:15], v0 offset0:66 offset1:74
	ds_read2_b32 v[16:17], v0 offset0:99 offset1:107
	ds_read2_b32 v[18:19], v0 offset0:132 offset1:140
	ds_read2_b32 v[20:21], v0 offset0:165 offset1:173
	ds_read2_b32 v[22:23], v0 offset0:198 offset1:206
	ds_read2_b32 v[24:25], v0 offset0:231 offset1:239
	s_waitcnt lgkmcnt(7)
	s_waitcnt lgkmcnt(6)
	v_cvt_pk_bf16_f32 v6, v12, v10
	s_waitcnt lgkmcnt(5)
	s_waitcnt lgkmcnt(4)
	v_cvt_pk_bf16_f32 v7, v14, v16
	s_waitcnt lgkmcnt(3)
	s_waitcnt lgkmcnt(2)
	v_cvt_pk_bf16_f32 v8, v18, v20
	s_waitcnt lgkmcnt(1)
	v_add_u32_e32 v26, s0, v5
	s_mov_b64 s[10:11], 0x1100000
	s_waitcnt lgkmcnt(0)
	v_ashrrev_i32_e32 v27, 31, v26
	v_lshl_add_u64 v[2:3], v[2:3], 0, s[10:11]
	v_lshlrev_b64 v[28:29], 11, v[26:27]
	v_cvt_pk_bf16_f32 v9, v22, v24
	v_lshl_add_u64 v[28:29], v[2:3], 0, v[28:29]
	global_store_dwordx4 v[28:29], v[6:9], off
	s_nop 1
	v_cvt_pk_bf16_f32 v6, v13, v11
	v_cvt_pk_bf16_f32 v7, v15, v17
	v_cvt_pk_bf16_f32 v8, v19, v21
	v_add_u32_e32 v10, 8, v26
	v_ashrrev_i32_e32 v11, 31, v10
	v_lshlrev_b64 v[10:11], 11, v[10:11]
	v_cvt_pk_bf16_f32 v9, v23, v25
	v_lshl_add_u64 v[10:11], v[2:3], 0, v[10:11]
	global_store_dwordx4 v[10:11], v[6:9], off
	ds_read2_b32 v[10:11], v0 offset0:49 offset1:57
	ds_read2_b32 v[12:13], v0 offset0:16 offset1:24
	ds_read2_b32 v[14:15], v0 offset0:82 offset1:90
	ds_read2_b32 v[16:17], v0 offset0:115 offset1:123
	ds_read2_b32 v[18:19], v0 offset0:148 offset1:156
	ds_read2_b32 v[20:21], v0 offset0:181 offset1:189
	ds_read2_b32 v[22:23], v0 offset0:214 offset1:222
	ds_read2_b32 v[24:25], v0 offset0:247 offset1:255
	s_waitcnt lgkmcnt(7)
	s_waitcnt lgkmcnt(6)
	v_cvt_pk_bf16_f32 v6, v12, v10
	s_waitcnt lgkmcnt(5)
	s_waitcnt lgkmcnt(4)
	v_cvt_pk_bf16_f32 v7, v14, v16
	s_waitcnt lgkmcnt(3)
	s_waitcnt lgkmcnt(2)
	s_waitcnt lgkmcnt(1)
	v_cvt_pk_bf16_f32 v8, v18, v20
	s_waitcnt lgkmcnt(0)
	v_add_u32_e32 v28, 16, v26
	v_cvt_pk_bf16_f32 v9, v22, v24
	v_ashrrev_i32_e32 v29, 31, v28
	v_bfe_u32 v0, v13, 16, 1
	v_lshlrev_b64 v[28:29], 11, v[28:29]
	v_add3_u32 v0, v13, v0, s33
	v_bfe_u32 v5, v11, 16, 1
	v_lshl_add_u64 v[28:29], v[2:3], 0, v[28:29]
	v_lshrrev_b32_e32 v0, 16, v0
	v_add3_u32 v5, v11, v5, s33
	global_store_dwordx4 v[28:29], v[6:9], off
	v_add_u32_e32 v10, 24, v26
	v_ashrrev_i32_e32 v11, 31, v10
	v_and_or_b32 v6, v5, s26, v0
	v_cvt_pk_bf16_f32 v7, v15, v17
	v_cvt_pk_bf16_f32 v8, v19, v21
	v_lshlrev_b64 v[10:11], 11, v[10:11]
	v_cvt_pk_bf16_f32 v9, v23, v25
	v_lshl_add_u64 v[2:3], v[2:3], 0, v[10:11]
	global_store_dwordx4 v[2:3], v[6:9], off
	s_waitcnt lgkmcnt(0)

.LBB0_652:
	s_andn2_b64 vcc, exec, s[10:11]
	s_cbranch_vccnz .LBB0_654
	s_load_dwordx2 s[0:1], s[4:5], 0xb0
	s_ashr_i32 s3, s2, 31
	s_add_i32 s17, s16, 0xfffffa80
	s_lshl_b64 s[10:11], s[2:3], 22
	v_and_b32_e32 v5, 31, v4
	s_waitcnt lgkmcnt(0)
	s_add_u32 s12, s0, s10
	s_addc_u32 s13, s1, s11
	s_load_dwordx2 s[10:11], s[4:5], 0x100
	s_lshl_b64 s[20:21], s[2:3], 21
	v_ashrrev_i32_e32 v8, 5, v4
	s_waitcnt lgkmcnt(0)
	s_add_u32 s1, s10, s20
	s_addc_u32 s3, s11, s21
	s_lshl_b32 s0, s17, 1
	s_and_b32 s10, s0, 0xfc0
	s_lshl_b32 s0, s17, 5
	s_and_b32 s0, s0, 0x3e0
	v_or_b32_e32 v0, s0, v5
	v_add_u32_e32 v2, s10, v8
	v_lshlrev_b32_e32 v0, 2, v0
	v_ashrrev_i32_e32 v3, 31, v2
	v_lshl_add_u64 v[6:7], s[12:13], 0, v[0:1]
	v_lshlrev_b64 v[2:3], 12, v[2:3]
	v_lshl_add_u64 v[2:3], v[6:7], 0, v[2:3]
	s_movk_i32 s11, 0x2000
	v_add_co_u32_e32 v6, vcc, s11, v2
	s_movk_i32 s11, 0x4000
	s_nop 0
	v_addc_co_u32_e32 v7, vcc, 0, v3, vcc
	global_load_dword v0, v[2:3], off nt
	global_load_dword v9, v[6:7], off nt
	v_add_co_u32_e32 v6, vcc, s11, v2
	s_movk_i32 s11, 0x6000
	s_nop 0
	v_addc_co_u32_e32 v7, vcc, 0, v3, vcc
	global_load_dword v10, v[6:7], off nt
	v_add_co_u32_e32 v6, vcc, s11, v2
	s_mov_b32 s11, 0x8000
	s_nop 0
	v_addc_co_u32_e32 v7, vcc, 0, v3, vcc
	global_load_dword v11, v[6:7], off nt
	v_add_co_u32_e32 v6, vcc, s11, v2
	s_mov_b32 s11, 0xa000
	s_nop 0
	v_addc_co_u32_e32 v7, vcc, 0, v3, vcc
	global_load_dword v12, v[6:7], off nt
	v_add_co_u32_e32 v6, vcc, s11, v2
	s_mov_b32 s11, 0xc000
	s_nop 0
	v_addc_co_u32_e32 v7, vcc, 0, v3, vcc
	global_load_dword v13, v[6:7], off nt
	v_add_co_u32_e32 v6, vcc, s11, v2
	s_mov_b32 s11, 0xe000
	s_nop 0
	v_addc_co_u32_e32 v7, vcc, 0, v3, vcc
	global_load_dword v14, v[6:7], off nt
	v_add_co_u32_e32 v6, vcc, s11, v2
	s_mov_b32 s11, 0x10000
	s_nop 0
	v_addc_co_u32_e32 v7, vcc, 0, v3, vcc
	global_load_dword v15, v[6:7], off nt
	v_add_co_u32_e32 v6, vcc, s11, v2
	s_mov_b32 s11, 0x12000
	s_nop 0
	v_addc_co_u32_e32 v7, vcc, 0, v3, vcc
	global_load_dword v16, v[6:7], off nt
	v_add_co_u32_e32 v6, vcc, s11, v2
	s_mov_b32 s11, 0x14000
	s_nop 0
	v_addc_co_u32_e32 v7, vcc, 0, v3, vcc
	global_load_dword v17, v[6:7], off nt
	v_add_co_u32_e32 v6, vcc, s11, v2
	s_mov_b32 s11, 0x16000
	s_nop 0
	v_addc_co_u32_e32 v7, vcc, 0, v3, vcc
	global_load_dword v18, v[6:7], off nt
	v_add_co_u32_e32 v6, vcc, s11, v2
	s_mov_b32 s11, 0x18000
	s_nop 0
	v_addc_co_u32_e32 v7, vcc, 0, v3, vcc
	global_load_dword v19, v[6:7], off nt
	v_add_co_u32_e32 v6, vcc, s11, v2
	s_mov_b32 s11, 0x1a000
	s_nop 0
	v_addc_co_u32_e32 v7, vcc, 0, v3, vcc
	global_load_dword v20, v[6:7], off nt
	v_add_co_u32_e32 v6, vcc, s11, v2
	s_mov_b32 s11, 0x1c000
	s_nop 0
	v_addc_co_u32_e32 v7, vcc, 0, v3, vcc
	global_load_dword v21, v[6:7], off nt
	v_add_co_u32_e32 v6, vcc, s11, v2
	s_mov_b32 s11, 0x1e000
	s_nop 0
	v_addc_co_u32_e32 v7, vcc, 0, v3, vcc
	global_load_dword v22, v[6:7], off nt
	v_add_co_u32_e32 v6, vcc, s11, v2
	s_mov_b32 s11, 0x22000
	s_nop 0
	v_addc_co_u32_e32 v7, vcc, 0, v3, vcc
	global_load_dword v23, v[6:7], off nt
	v_add_co_u32_e32 v6, vcc, s14, v2
	s_lshl_b32 s10, s10, 1
	s_nop 0
	v_addc_co_u32_e32 v7, vcc, 0, v3, vcc
	global_load_dword v24, v[6:7], off nt
	v_add_co_u32_e32 v6, vcc, s11, v2
	s_mov_b32 s11, 0x24000
	s_nop 0
	v_addc_co_u32_e32 v7, vcc, 0, v3, vcc
	global_load_dword v25, v[6:7], off nt
	v_add_co_u32_e32 v6, vcc, s11, v2
	s_mov_b32 s11, 0x26000
	s_nop 0
	v_addc_co_u32_e32 v7, vcc, 0, v3, vcc
	global_load_dword v26, v[6:7], off nt
	v_add_co_u32_e32 v6, vcc, s11, v2
	s_mov_b32 s11, 0x28000
	s_nop 0
	v_addc_co_u32_e32 v7, vcc, 0, v3, vcc
	global_load_dword v27, v[6:7], off nt
	v_add_co_u32_e32 v6, vcc, s11, v2
	s_mov_b32 s11, 0x2a000
	s_nop 0
	v_addc_co_u32_e32 v7, vcc, 0, v3, vcc
	global_load_dword v28, v[6:7], off nt
	v_add_co_u32_e32 v6, vcc, s11, v2
	s_mov_b32 s11, 0x2c000
	s_nop 0
	v_addc_co_u32_e32 v7, vcc, 0, v3, vcc
	global_load_dword v29, v[6:7], off nt
	v_add_co_u32_e32 v6, vcc, s11, v2
	s_mov_b32 s11, 0x2e000
	s_nop 0
	v_addc_co_u32_e32 v7, vcc, 0, v3, vcc
	global_load_dword v30, v[6:7], off nt
	v_add_co_u32_e32 v6, vcc, s11, v2
	s_mov_b32 s11, 0x30000
	s_nop 0
	v_addc_co_u32_e32 v7, vcc, 0, v3, vcc
	global_load_dword v31, v[6:7], off nt
	v_add_co_u32_e32 v6, vcc, s11, v2
	s_mov_b32 s11, 0x32000
	s_nop 0
	v_addc_co_u32_e32 v7, vcc, 0, v3, vcc
	global_load_dword v32, v[6:7], off nt
	v_add_co_u32_e32 v6, vcc, s11, v2
	s_mov_b32 s11, 0x34000
	s_nop 0
	v_addc_co_u32_e32 v7, vcc, 0, v3, vcc
	global_load_dword v33, v[6:7], off nt
	v_add_co_u32_e32 v6, vcc, s11, v2
	s_mov_b32 s11, 0x36000
	s_nop 0
	v_addc_co_u32_e32 v7, vcc, 0, v3, vcc
	global_load_dword v34, v[6:7], off nt
	v_add_co_u32_e32 v6, vcc, s11, v2
	s_mov_b32 s11, 0x38000
	s_nop 0
	v_addc_co_u32_e32 v7, vcc, 0, v3, vcc
	global_load_dword v35, v[6:7], off nt
	v_add_co_u32_e32 v6, vcc, s11, v2
	s_mov_b32 s11, 0x3a000
	s_nop 0
	v_addc_co_u32_e32 v7, vcc, 0, v3, vcc
	global_load_dword v36, v[6:7], off nt
	v_add_co_u32_e32 v6, vcc, s11, v2
	s_mov_b32 s11, 0x3c000
	s_nop 0
	v_addc_co_u32_e32 v7, vcc, 0, v3, vcc
	global_load_dword v37, v[6:7], off nt
	v_add_co_u32_e32 v6, vcc, s11, v2
	s_mov_b32 s11, 0x3e000
	s_nop 0
	v_addc_co_u32_e32 v7, vcc, 0, v3, vcc
	v_add_co_u32_e32 v2, vcc, s11, v2
	global_load_dword v6, v[6:7], off nt
	s_nop 0
	v_addc_co_u32_e32 v3, vcc, 0, v3, vcc
	global_load_dword v2, v[2:3], off nt
	s_movk_i32 s11, 0x84
	v_lshlrev_b32_e32 v3, 2, v5
	v_mul_lo_u32 v5, v8, s11
	v_add3_u32 v3, s28, v3, v5
	s_waitcnt vmcnt(30)
	ds_write2_b32 v3, v0, v9 offset1:66
	s_waitcnt vmcnt(28)
	ds_write2_b32 v3, v10, v11 offset0:132 offset1:198
	v_add_u32_e32 v0, 0x400, v3
	s_waitcnt vmcnt(26)
	ds_write2_b32 v0, v12, v13 offset0:8 offset1:74
	s_waitcnt vmcnt(24)
	ds_write2_b32 v0, v14, v15 offset0:140 offset1:206
	v_add_u32_e32 v0, 0x800, v3
	s_waitcnt vmcnt(22)
	ds_write2_b32 v0, v16, v17 offset0:16 offset1:82
	s_waitcnt vmcnt(20)
	ds_write2_b32 v0, v18, v19 offset0:148 offset1:214
	v_add_u32_e32 v0, 0xc00, v3
	s_waitcnt vmcnt(18)
	ds_write2_b32 v0, v20, v21 offset0:24 offset1:90
	s_waitcnt vmcnt(16)
	ds_write2_b32 v0, v22, v23 offset0:156 offset1:222
	v_add_u32_e32 v0, 0x1000, v3
	s_waitcnt vmcnt(14)
	ds_write2_b32 v0, v24, v25 offset0:32 offset1:98
	s_waitcnt vmcnt(12)
	ds_write2_b32 v0, v26, v27 offset0:164 offset1:230
	v_add_u32_e32 v0, 0x1400, v3
	s_waitcnt vmcnt(10)
	ds_write2_b32 v0, v28, v29 offset0:40 offset1:106
	s_waitcnt vmcnt(8)
	ds_write2_b32 v0, v30, v31 offset0:172 offset1:238
	v_add_u32_e32 v0, 0x1800, v3
	s_waitcnt vmcnt(6)
	ds_write2_b32 v0, v32, v33 offset0:48 offset1:114
	s_waitcnt vmcnt(4)
	ds_write2_b32 v0, v34, v35 offset0:180 offset1:246
	v_add_u32_e32 v0, 0x1c00, v3
	s_waitcnt vmcnt(2)
	ds_write2_b32 v0, v36, v37 offset0:56 offset1:122
	s_waitcnt vmcnt(0)
	ds_write2_b32 v0, v6, v2 offset0:188 offset1:254
	v_lshlrev_b32_e32 v0, 3, v4
	v_and_b32_e32 v0, 56, v0
	s_add_u32 s10, s1, s10
	v_ashrrev_i32_e32 v5, 3, v4
	v_mul_u32_u24_e32 v6, 0x84, v0
	s_addc_u32 s11, s3, 0
	v_lshlrev_b32_e32 v0, 1, v0
	s_waitcnt lgkmcnt(0)
	v_lshl_add_u64 v[2:3], s[10:11], 0, v[0:1]
	v_lshlrev_b32_e32 v0, 2, v5
	v_add3_u32 v0, s28, v6, v0
	ds_read2_b32 v[10:11], v0 offset0:33 offset1:41
	ds_read2_b32 v[12:13], v0 offset1:8
	ds_read2_b32 v[14:15], v0 offset0:66 offset1:74
	ds_read2_b32 v[16:17], v0 offset0:99 offset1:107
	ds_read2_b32 v[18:19], v0 offset0:132 offset1:140
	ds_read2_b32 v[20:21], v0 offset0:165 offset1:173
	ds_read2_b32 v[22:23], v0 offset0:198 offset1:206
	ds_read2_b32 v[24:25], v0 offset0:231 offset1:239
	s_waitcnt lgkmcnt(7)
	s_waitcnt lgkmcnt(6)
	v_cvt_pk_bf16_f32 v6, v12, v10
	s_waitcnt lgkmcnt(5)
	s_waitcnt lgkmcnt(4)
	v_cvt_pk_bf16_f32 v7, v14, v16
	s_waitcnt lgkmcnt(3)
	s_waitcnt lgkmcnt(2)
	v_cvt_pk_bf16_f32 v8, v18, v20
	s_waitcnt lgkmcnt(1)
	v_add_u32_e32 v26, s0, v5
	s_mov_b64 s[10:11], 0xd00000
	s_waitcnt lgkmcnt(0)
	v_ashrrev_i32_e32 v27, 31, v26
	v_lshl_add_u64 v[2:3], v[2:3], 0, s[10:11]
	v_lshlrev_b64 v[28:29], 11, v[26:27]
	v_cvt_pk_bf16_f32 v9, v22, v24
	v_lshl_add_u64 v[28:29], v[2:3], 0, v[28:29]
	global_store_dwordx4 v[28:29], v[6:9], off
	s_nop 1
	v_cvt_pk_bf16_f32 v6, v13, v11
	v_cvt_pk_bf16_f32 v7, v15, v17
	v_cvt_pk_bf16_f32 v8, v19, v21
	v_add_u32_e32 v10, 8, v26
	v_ashrrev_i32_e32 v11, 31, v10
	v_lshlrev_b64 v[10:11], 11, v[10:11]
	v_cvt_pk_bf16_f32 v9, v23, v25
	v_lshl_add_u64 v[10:11], v[2:3], 0, v[10:11]
	global_store_dwordx4 v[10:11], v[6:9], off
	ds_read2_b32 v[10:11], v0 offset0:49 offset1:57
	ds_read2_b32 v[12:13], v0 offset0:16 offset1:24
	ds_read2_b32 v[14:15], v0 offset0:82 offset1:90
	ds_read2_b32 v[16:17], v0 offset0:115 offset1:123
	ds_read2_b32 v[18:19], v0 offset0:148 offset1:156
	ds_read2_b32 v[20:21], v0 offset0:181 offset1:189
	ds_read2_b32 v[22:23], v0 offset0:214 offset1:222
	ds_read2_b32 v[24:25], v0 offset0:247 offset1:255
	s_waitcnt lgkmcnt(7)
	s_waitcnt lgkmcnt(6)
	v_cvt_pk_bf16_f32 v6, v12, v10
	s_waitcnt lgkmcnt(5)
	s_waitcnt lgkmcnt(4)
	v_cvt_pk_bf16_f32 v7, v14, v16
	s_waitcnt lgkmcnt(3)
	s_waitcnt lgkmcnt(2)
	s_waitcnt lgkmcnt(1)
	v_cvt_pk_bf16_f32 v8, v18, v20
	s_waitcnt lgkmcnt(0)
	v_add_u32_e32 v28, 16, v26
	v_cvt_pk_bf16_f32 v9, v22, v24
	v_ashrrev_i32_e32 v29, 31, v28
	v_bfe_u32 v0, v13, 16, 1
	v_lshlrev_b64 v[28:29], 11, v[28:29]
	v_add3_u32 v0, v13, v0, s33
	v_bfe_u32 v5, v11, 16, 1
	v_lshl_add_u64 v[28:29], v[2:3], 0, v[28:29]
	v_lshrrev_b32_e32 v0, 16, v0
	v_add3_u32 v5, v11, v5, s33
	global_store_dwordx4 v[28:29], v[6:9], off
	v_add_u32_e32 v10, 24, v26
	v_ashrrev_i32_e32 v11, 31, v10
	v_and_or_b32 v6, v5, s26, v0
	v_cvt_pk_bf16_f32 v7, v15, v17
	v_cvt_pk_bf16_f32 v8, v19, v21
	v_lshlrev_b64 v[10:11], 11, v[10:11]
	v_cvt_pk_bf16_f32 v9, v23, v25
	v_lshl_add_u64 v[2:3], v[2:3], 0, v[10:11]
	global_store_dwordx4 v[2:3], v[6:9], off
	s_waitcnt lgkmcnt(0)

.LBB0_734:
	s_or_b64 exec, exec, s[16:17]
	s_mul_hi_i32 s1, s2, 0x580000
	s_mul_i32 s2, s2, 0x580000
	s_add_u32 s10, s10, s2
	s_movk_i32 s2, 0x84
	v_lshlrev_b32_e32 v2, 2, v5
	v_mul_lo_u32 v3, v6, s2
	v_add3_u32 v2, s28, v2, v3
	s_waitcnt vmcnt(0)
	ds_write2_b32 v2, v0, v7 offset1:66
	ds_write2_b32 v2, v10, v9 offset0:132 offset1:198
	v_add_u32_e32 v0, 0x400, v2
	ds_write2_b32 v0, v12, v11 offset0:8 offset1:74
	ds_write2_b32 v0, v14, v13 offset0:140 offset1:206
	v_add_u32_e32 v0, 0x800, v2
	ds_write2_b32 v0, v16, v15 offset0:16 offset1:82
	ds_write2_b32 v0, v18, v17 offset0:148 offset1:214
	v_add_u32_e32 v0, 0xc00, v2
	ds_write2_b32 v0, v20, v19 offset0:24 offset1:90
	ds_write2_b32 v0, v22, v21 offset0:156 offset1:222
	v_add_u32_e32 v0, 0x1000, v2
	ds_write2_b32 v0, v24, v23 offset0:32 offset1:98
	ds_write2_b32 v0, v26, v25 offset0:164 offset1:230
	v_add_u32_e32 v0, 0x1400, v2
	ds_write2_b32 v0, v28, v27 offset0:40 offset1:106
	ds_write2_b32 v0, v30, v29 offset0:172 offset1:238
	v_add_u32_e32 v0, 0x1800, v2
	ds_write2_b32 v0, v32, v31 offset0:48 offset1:114
	ds_write2_b32 v0, v34, v33 offset0:180 offset1:246
	v_add_u32_e32 v0, 0x1c00, v2
	ds_write2_b32 v0, v36, v35 offset0:56 offset1:122
	ds_write2_b32 v0, v38, v37 offset0:188 offset1:254
	v_lshlrev_b32_e32 v0, 3, v4
	v_ashrrev_i32_e32 v24, 3, v4
	v_and_b32_e32 v0, 56, v0
	s_waitcnt lgkmcnt(0)
	v_mul_u32_u24_e32 v2, 0x84, v0
	v_lshlrev_b32_e32 v3, 2, v24
	v_add3_u32 v28, s28, v2, v3
	ds_read2_b32 v[6:7], v28 offset1:8
	s_addc_u32 s1, s11, s1
	s_ashr_i32 s13, s12, 31
	ds_read2_b32 v[10:11], v28 offset0:33 offset1:41
	s_lshl_b64 s[2:3], s[12:13], 1
	s_add_u32 s2, s10, s2
	ds_read2_b32 v[12:13], v28 offset0:66 offset1:74
	s_addc_u32 s3, s1, s3
	v_lshlrev_b32_e32 v0, 1, v0
	ds_read2_b32 v[14:15], v28 offset0:99 offset1:107
	v_lshl_add_u64 v[2:3], s[2:3], 0, v[0:1]
	s_mov_b64 s[2:3], 0x200000
	s_waitcnt lgkmcnt(3)
	v_lshl_add_u64 v[8:9], v[2:3], 0, s[2:3]
	s_waitcnt lgkmcnt(2)
	ds_read2_b32 v[16:17], v28 offset0:132 offset1:140
	ds_read2_b32 v[18:19], v28 offset0:165 offset1:173
	v_cvt_pk_bf16_f32 v2, v6, v10
	s_waitcnt lgkmcnt(3)
	s_waitcnt lgkmcnt(2)
	ds_read2_b32 v[20:21], v28 offset0:198 offset1:206
	ds_read2_b32 v[22:23], v28 offset0:231 offset1:239
	v_cvt_pk_bf16_f32 v3, v12, v14
	s_waitcnt lgkmcnt(3)
	s_waitcnt lgkmcnt(2)
	v_cvt_pk_bf16_f32 v4, v16, v18
	s_waitcnt lgkmcnt(1)
	v_add_u32_e32 v24, s0, v24
	s_waitcnt lgkmcnt(0)
	v_ashrrev_i32_e32 v25, 31, v24
	v_lshlrev_b64 v[26:27], 11, v[24:25]
	v_cvt_pk_bf16_f32 v5, v20, v22
	v_lshl_add_u64 v[26:27], v[8:9], 0, v[26:27]
	global_store_dwordx4 v[26:27], v[2:5], off
	s_nop 1
	v_cvt_pk_bf16_f32 v2, v7, v11
	v_cvt_pk_bf16_f32 v3, v13, v15
	v_cvt_pk_bf16_f32 v4, v17, v19
	v_add_u32_e32 v6, 8, v24
	v_ashrrev_i32_e32 v7, 31, v6
	v_lshlrev_b64 v[6:7], 11, v[6:7]
	v_cvt_pk_bf16_f32 v5, v21, v23
	ds_read2_b32 v[10:11], v28 offset0:16 offset1:24
	v_lshl_add_u64 v[6:7], v[8:9], 0, v[6:7]
	global_store_dwordx4 v[6:7], v[2:5], off
	ds_read2_b32 v[6:7], v28 offset0:49 offset1:57
	ds_read2_b32 v[12:13], v28 offset0:82 offset1:90
	ds_read2_b32 v[14:15], v28 offset0:115 offset1:123
	s_waitcnt lgkmcnt(3)
	s_waitcnt lgkmcnt(2)
	ds_read2_b32 v[16:17], v28 offset0:148 offset1:156
	ds_read2_b32 v[18:19], v28 offset0:181 offset1:189
	v_cvt_pk_bf16_f32 v2, v10, v6
	s_waitcnt lgkmcnt(3)
	s_waitcnt lgkmcnt(2)
	ds_read2_b32 v[20:21], v28 offset0:214 offset1:222
	ds_read2_b32 v[22:23], v28 offset0:247 offset1:255
	v_cvt_pk_bf16_f32 v3, v12, v14
	s_waitcnt lgkmcnt(3)
	s_waitcnt lgkmcnt(2)
	v_cvt_pk_bf16_f32 v4, v16, v18
	s_waitcnt lgkmcnt(1)
	v_add_u32_e32 v26, 16, v24
	s_waitcnt lgkmcnt(0)
	v_ashrrev_i32_e32 v27, 31, v26
	v_lshlrev_b64 v[26:27], 11, v[26:27]
	v_cvt_pk_bf16_f32 v5, v20, v22
	v_lshl_add_u64 v[26:27], v[8:9], 0, v[26:27]
	global_store_dwordx4 v[26:27], v[2:5], off
	s_nop 1
	v_cvt_pk_bf16_f32 v2, v11, v7
	v_cvt_pk_bf16_f32 v3, v13, v15
	v_cvt_pk_bf16_f32 v4, v17, v19
	v_add_u32_e32 v6, 24, v24
	v_ashrrev_i32_e32 v7, 31, v6
	v_lshlrev_b64 v[6:7], 11, v[6:7]
	v_cvt_pk_bf16_f32 v5, v21, v23
	v_lshl_add_u64 v[6:7], v[8:9], 0, v[6:7]
	global_store_dwordx4 v[6:7], v[2:5], off
	s_waitcnt lgkmcnt(0)

.LBB0_765:
	s_waitcnt vmcnt(11)
	v_mul_f32_e32 v36, 0x3fb8aa3b, v26
	v_rndne_f32_e32 v37, v36
	s_mov_b32 s10, 0x3fb8aa3b
	v_sub_f32_e32 v38, v36, v37
	v_fma_f32 v36, v26, s10, -v36
	v_fmac_f32_e32 v36, 0x32a5705f, v26
	v_add_f32_e32 v36, v38, v36
	v_exp_f32_e32 v36, v36
	v_cvt_i32_f32_e32 v37, v37
	v_bfe_u32 v30, v110, 16, 1
	v_add3_u32 v30, v110, v30, s33
	ds_write_b16_d16_hi v205, v30 offset:28672
	v_ldexp_f32 v36, v36, v37
	v_mul_f32_e32 v37, 0xbfb8aa3b, v26
	v_bfe_u32 v30, v111, 16, 1
	v_rndne_f32_e32 v40, v37
	v_add3_u32 v30, v111, v30, s33
	v_sub_f32_e32 v41, v37, v40
	v_fma_f32 v37, v26, s34, -v37
	ds_write_b16_d16_hi v205, v30 offset:28752
	v_bfe_u32 v30, v112, 16, 1
	v_fmac_f32_e32 v37, 0xb2a5705f, v26
	v_add3_u32 v30, v112, v30, s33
	v_add_f32_e32 v37, v41, v37
	ds_write_b16_d16_hi v205, v30 offset:28832
	v_bfe_u32 v30, v113, 16, 1
	s_mov_b32 s11, 0xc2ce8ed0
	v_exp_f32_e32 v37, v37
	v_cvt_i32_f32_e32 v40, v40
	v_add3_u32 v30, v113, v30, s33
	v_cmp_ngt_f32_e32 vcc, s11, v26
	s_mov_b32 s12, 0x42b17218
	ds_write_b16_d16_hi v205, v30 offset:28912
	s_waitcnt vmcnt(10)
	v_lshlrev_b32_e32 v30, 16, v116
	v_cndmask_b32_e32 v36, 0, v36, vcc
	v_cmp_nlt_f32_e32 vcc, s12, v26
	v_mul_f32_e32 v30, 0x3e3504f3, v30
	s_mov_b32 s0, 0x42ce8ed0
	v_cndmask_b32_e32 v36, v219, v36, vcc
	v_mul_f32_e32 v30, v36, v30
	v_ldexp_f32 v36, v37, v40
	v_mul_f32_e32 v37, 0x3fb8aa3b, v27
	v_rndne_f32_e32 v40, v37
	v_sub_f32_e32 v41, v37, v40
	v_fma_f32 v37, v27, s10, -v37
	v_fmac_f32_e32 v37, 0x32a5705f, v27
	v_add_f32_e32 v37, v41, v37
	v_exp_f32_e32 v37, v37
	v_cvt_i32_f32_e32 v40, v40
	v_cmp_nlt_f32_e32 vcc, s0, v26
	s_mov_b32 s1, 0xc2b17218
	v_and_b32_e32 v31, 0xffff0000, v116
	v_cndmask_b32_e32 v36, 0, v36, vcc
	v_cmp_ngt_f32_e32 vcc, s1, v26
	s_waitcnt vmcnt(9)
	v_lshlrev_b32_e32 v34, 16, v114
	v_and_b32_e32 v35, 0xffff0000, v114
	v_cndmask_b32_e32 v26, v219, v36, vcc
	v_mul_f32_e32 v36, 0xbfb8aa3b, v27
	v_mul_f32_e32 v34, v26, v34
	v_mul_f32_e32 v26, 0x3e3504f3, v31
	v_ldexp_f32 v31, v37, v40
	v_rndne_f32_e32 v37, v36
	v_sub_f32_e32 v40, v36, v37
	v_fma_f32 v36, v27, s34, -v36
	v_fmac_f32_e32 v36, 0xb2a5705f, v27
	v_add_f32_e32 v36, v40, v36
	v_exp_f32_e32 v36, v36
	v_cvt_i32_f32_e32 v37, v37
	v_cmp_ngt_f32_e32 vcc, s11, v27
	v_lshlrev_b32_e32 v32, 16, v117
	v_and_b32_e32 v33, 0xffff0000, v117
	v_cndmask_b32_e32 v31, 0, v31, vcc
	v_cmp_nlt_f32_e32 vcc, s12, v27
	v_lshlrev_b32_e32 v38, 16, v115
	v_and_b32_e32 v39, 0xffff0000, v115
	v_cndmask_b32_e32 v31, v219, v31, vcc
	v_mul_f32_e32 v26, v31, v26
	v_ldexp_f32 v31, v36, v37
	v_mul_f32_e32 v36, 0x3fb8aa3b, v28
	v_rndne_f32_e32 v37, v36
	v_sub_f32_e32 v40, v36, v37
	v_fma_f32 v36, v28, s10, -v36
	v_fmac_f32_e32 v36, 0x32a5705f, v28
	v_add_f32_e32 v36, v40, v36
	v_cmp_nlt_f32_e32 vcc, s0, v27
	v_exp_f32_e32 v36, v36
	v_cvt_i32_f32_e32 v37, v37
	v_cndmask_b32_e32 v31, 0, v31, vcc
	v_cmp_ngt_f32_e32 vcc, s1, v27
	v_add_u32_e32 v40, v175, v173
	s_nop 0
	v_cndmask_b32_e32 v27, v219, v31, vcc
	v_mul_f32_e32 v31, v27, v35
	v_mul_f32_e32 v35, 0xbfb8aa3b, v28
	v_mul_f32_e32 v27, 0x3e3504f3, v32
	v_ldexp_f32 v32, v36, v37
	v_rndne_f32_e32 v36, v35
	v_sub_f32_e32 v37, v35, v36
	v_fma_f32 v35, v28, s34, -v35
	v_fmac_f32_e32 v35, 0xb2a5705f, v28
	v_add_f32_e32 v35, v37, v35
	v_exp_f32_e32 v35, v35
	v_cvt_i32_f32_e32 v36, v36
	v_cmp_ngt_f32_e32 vcc, s11, v28
	s_nop 1
	v_cndmask_b32_e32 v32, 0, v32, vcc
	v_cmp_nlt_f32_e32 vcc, s12, v28
	s_nop 1
	v_cndmask_b32_e32 v32, v219, v32, vcc
	v_mul_f32_e32 v27, v32, v27
	v_ldexp_f32 v32, v35, v36
	v_mul_f32_e32 v35, 0x3fb8aa3b, v29
	v_rndne_f32_e32 v36, v35
	v_sub_f32_e32 v37, v35, v36
	v_fma_f32 v35, v29, s10, -v35
	v_fmac_f32_e32 v35, 0x32a5705f, v29
	v_add_f32_e32 v35, v37, v35
	v_exp_f32_e32 v35, v35
	v_cvt_i32_f32_e32 v36, v36
	v_cmp_nlt_f32_e32 vcc, s0, v28
	s_nop 1
	v_cndmask_b32_e32 v32, 0, v32, vcc
	v_cmp_ngt_f32_e32 vcc, s1, v28
	s_nop 1
	v_cndmask_b32_e32 v28, v219, v32, vcc
	v_mul_f32_e32 v32, 0x3e3504f3, v33
	v_ldexp_f32 v33, v35, v36
	v_mul_f32_e32 v35, 0xbfb8aa3b, v29
	v_rndne_f32_e32 v36, v35
	v_sub_f32_e32 v37, v35, v36
	v_fma_f32 v35, v29, s34, -v35
	v_fmac_f32_e32 v35, 0xb2a5705f, v29
	v_add_f32_e32 v35, v37, v35
	v_exp_f32_e32 v35, v35
	v_cvt_i32_f32_e32 v36, v36
	v_cmp_ngt_f32_e32 vcc, s11, v29
	v_mul_f32_e32 v28, v28, v38
	v_add_u32_e32 v38, v170, v171
	v_cndmask_b32_e32 v33, 0, v33, vcc
	v_cmp_nlt_f32_e32 vcc, s12, v29
	s_nop 1
	v_cndmask_b32_e32 v33, v219, v33, vcc
	v_mul_f32_e32 v32, v33, v32
	v_ldexp_f32 v33, v35, v36
	v_cmp_nlt_f32_e32 vcc, s0, v29
	v_add_u32_e32 v36, v174, v173
	v_add_u32_e32 v35, s79, v177
	v_cndmask_b32_e32 v33, 0, v33, vcc
	v_cmp_ngt_f32_e32 vcc, s1, v29
	s_nop 1
	v_cndmask_b32_e32 v29, v219, v33, vcc
	v_cvt_pk_bf16_f32 v26, v30, v26
	v_cvt_pk_bf16_f32 v27, v27, v32
	ds_write_b64 v38, v[26:27]
	v_mul_f32_e32 v29, v29, v39
	v_cvt_pk_bf16_f32 v26, v34, v31
	v_cvt_pk_bf16_f32 v27, v28, v29
	v_add_u32_e32 v39, v172, v84
	ds_write_b64 v39, v[26:27] offset:5120
	s_waitcnt vmcnt(8)
	ds_write_b16 v206, v18 offset:19456
	ds_write_b16_d16_hi v206, v18 offset:19600
	ds_write_b16 v206, v19 offset:19744
	ds_write_b16_d16_hi v206, v19 offset:19888
	ds_write_b16 v206, v20 offset:20032
	ds_write_b16_d16_hi v206, v20 offset:20176
	ds_write_b16 v206, v21 offset:20320
	ds_write_b16_d16_hi v206, v21 offset:20464
	s_waitcnt vmcnt(7)
	ds_write_b128 v207, v[22:25] offset:33792
	s_waitcnt lgkmcnt(0)
	s_barrier
	ds_read_b128 v[18:21], v208
	ds_read_b128 v[22:25], v209 offset:5120
	s_waitcnt lgkmcnt(0)
	v_mfma_f32_16x16x32_bf16 v[22:25], v[18:21], v[22:25], 0
	s_nop 7
	v_cndmask_b32_e64 v22, v22, 0, s[50:51]
	v_bfe_u32 v26, v22, 16, 1
	v_add3_u32 v22, v22, v26, s33
	ds_write_b16_d16_hi v210, v22 offset:10240
	v_cndmask_b32_e64 v22, v23, 0, s[52:53]
	v_bfe_u32 v23, v22, 16, 1
	v_add3_u32 v22, v22, v23, s33
	ds_write_b16_d16_hi v210, v22 offset:10384
	v_cndmask_b32_e64 v22, v24, 0, s[54:55]
	v_bfe_u32 v23, v22, 16, 1
	v_add3_u32 v22, v22, v23, s33
	ds_write_b16_d16_hi v210, v22 offset:10528
	v_cndmask_b32_e64 v22, v25, 0, s[56:57]
	v_bfe_u32 v23, v22, 16, 1
	v_add3_u32 v22, v22, v23, s33
	ds_write_b16_d16_hi v210, v22 offset:10672
	ds_read_b128 v[22:25], v209 offset:6400
	s_waitcnt lgkmcnt(0)
	v_mfma_f32_16x16x32_bf16 v[18:21], v[18:21], v[22:25], 0
	s_nop 7
	v_cndmask_b32_e64 v18, v18, 0, s[58:59]
	v_bfe_u32 v22, v18, 16, 1
	v_add3_u32 v18, v18, v22, s33
	ds_write_b16_d16_hi v211, v18 offset:10240
	v_cndmask_b32_e64 v18, v19, 0, s[60:61]
	v_bfe_u32 v19, v18, 16, 1
	v_add3_u32 v18, v18, v19, s33
	ds_write_b16_d16_hi v211, v18 offset:10384
	v_cndmask_b32_e64 v18, v20, 0, s[62:63]
	v_bfe_u32 v19, v18, 16, 1
	v_add3_u32 v18, v18, v19, s33
	ds_write_b16_d16_hi v211, v18 offset:10528
	v_cndmask_b32_e64 v18, v21, 0, s[64:65]
	v_bfe_u32 v19, v18, 16, 1
	v_add3_u32 v18, v18, v19, s33
	ds_write_b16_d16_hi v211, v18 offset:10672
	s_waitcnt lgkmcnt(0)
	s_barrier
	ds_read_b128 v[18:21], v36 offset:10240
	ds_read_b128 v[22:25], v40 offset:19456
	ds_read_b128 v[26:29], v36 offset:10304
	ds_read_b128 v[30:33], v40 offset:19520
	s_waitcnt lgkmcnt(2)
	v_mfma_f32_16x16x32_bf16 v[22:25], v[18:21], v[22:25], 0
	ds_read_b128 v[42:45], v212
	s_waitcnt lgkmcnt(1)
	v_mfma_f32_16x16x32_bf16 v[22:25], v[26:29], v[30:33], v[22:25]
	ds_read_b128 v[30:33], v213 offset:28672
	s_waitcnt lgkmcnt(0)
	v_mfma_f32_16x16x32_bf16 v[22:25], v[42:45], v[30:33], v[22:25]
	ds_read_b128 v[30:33], v226 offset:19456
	s_waitcnt lgkmcnt(0)
	v_mfma_f32_16x16x32_bf16 v[18:21], v[18:21], v[30:33], 0
	ds_read_b128 v[30:33], v226 offset:19520
	s_waitcnt lgkmcnt(0)
	v_mfma_f32_16x16x32_bf16 v[18:21], v[26:29], v[30:33], v[18:21]
	ds_read_b128 v[26:29], v213 offset:29952
	s_waitcnt lgkmcnt(0)
	v_mfma_f32_16x16x32_bf16 v[18:21], v[42:45], v[26:29], v[18:21]
	s_nop 7
	v_mul_f32_e32 v26, v18, v18
	v_fmac_f32_e32 v26, v22, v22
	s_nop 1
	v_add_f32_dpp v26, v26, v26 quad_perm:[1,0,3,2] row_mask:0xf bank_mask:0xf bound_ctrl:1
	s_nop 1
	v_add_f32_dpp v26, v26, v26 quad_perm:[2,3,0,1] row_mask:0xf bank_mask:0xf bound_ctrl:1
	s_nop 1
	v_add_f32_dpp v26, v26, v26 row_half_mirror row_mask:0xf bank_mask:0xf bound_ctrl:1
	s_nop 1
	v_mov_b32_dpp v27, v26 row_mirror row_mask:0xf bank_mask:0xf bound_ctrl:1
	s_and_saveexec_b64 s[10:11], s[66:67]
	v_add_f32_e32 v26, v26, v27
	ds_write_b32 v35, v26 offset:43008
	s_or_b64 exec, exec, s[10:11]
	v_mul_f32_e32 v26, v19, v19
	v_fmac_f32_e32 v26, v23, v23
	s_nop 1
	v_add_f32_dpp v26, v26, v26 quad_perm:[1,0,3,2] row_mask:0xf bank_mask:0xf bound_ctrl:1
	s_nop 1
	v_add_f32_dpp v26, v26, v26 quad_perm:[2,3,0,1] row_mask:0xf bank_mask:0xf bound_ctrl:1
	s_nop 1
	v_add_f32_dpp v26, v26, v26 row_half_mirror row_mask:0xf bank_mask:0xf bound_ctrl:1
	s_nop 1
	v_mov_b32_dpp v27, v26 row_mirror row_mask:0xf bank_mask:0xf bound_ctrl:1
	s_and_saveexec_b64 s[10:11], s[66:67]
	v_add_f32_e32 v26, v26, v27
	ds_write_b32 v35, v26 offset:43016
	s_or_b64 exec, exec, s[10:11]
	v_mul_f32_e32 v26, v20, v20
	v_fmac_f32_e32 v26, v24, v24
	s_nop 1
	v_add_f32_dpp v26, v26, v26 quad_perm:[1,0,3,2] row_mask:0xf bank_mask:0xf bound_ctrl:1
	s_nop 1
	v_add_f32_dpp v26, v26, v26 quad_perm:[2,3,0,1] row_mask:0xf bank_mask:0xf bound_ctrl:1
	s_nop 1
	v_add_f32_dpp v26, v26, v26 row_half_mirror row_mask:0xf bank_mask:0xf bound_ctrl:1
	s_nop 1
	v_mov_b32_dpp v27, v26 row_mirror row_mask:0xf bank_mask:0xf bound_ctrl:1
	s_and_saveexec_b64 s[10:11], s[66:67]
	v_add_f32_e32 v26, v26, v27
	ds_write_b32 v35, v26 offset:43024
	s_or_b64 exec, exec, s[10:11]
	v_mul_f32_e32 v26, v21, v21
	v_fmac_f32_e32 v26, v25, v25
	v_add_u32_e32 v37, s79, v179
	s_nop 0
	v_add_f32_dpp v26, v26, v26 quad_perm:[1,0,3,2] row_mask:0xf bank_mask:0xf bound_ctrl:1
	s_nop 1
	v_add_f32_dpp v26, v26, v26 quad_perm:[2,3,0,1] row_mask:0xf bank_mask:0xf bound_ctrl:1
	s_nop 1
	v_add_f32_dpp v26, v26, v26 row_half_mirror row_mask:0xf bank_mask:0xf bound_ctrl:1
	s_nop 1
	v_mov_b32_dpp v27, v26 row_mirror row_mask:0xf bank_mask:0xf bound_ctrl:1
	s_and_saveexec_b64 s[10:11], s[66:67]
	v_add_f32_e32 v26, v26, v27
	ds_write_b32 v37, v26 offset:43008
	s_or_b64 exec, exec, s[10:11]
	s_waitcnt lgkmcnt(0)
	s_barrier
	ds_read_b128 v[26:29], v181 offset:43008
	s_or_b32 s0, s22, s97
	s_lshl_b32 s1, s22, 1
	s_mov_b32 s22, 0xf800000
	s_add_u32 s1, s2, s1
	s_waitcnt lgkmcnt(0)
	v_add_f32_e32 v26, v26, v27
	v_fmamk_f32 v26, v26, 0x3c800000, v216
	v_cmp_gt_f32_e32 vcc, s22, v26
	v_mul_f32_e32 v27, 0x4f800000, v26
	s_addc_u32 s2, s3, 0
	v_cndmask_b32_e32 v26, v26, v27, vcc
	v_sqrt_f32_e32 v27, v26
	s_add_u32 s10, s1, 0x10f60000
	s_addc_u32 s11, s2, 0
	s_load_dwordx2 s[12:13], s[4:5], 0x60
	v_add_u32_e32 v30, -1, v27
	v_fma_f32 v31, -v30, v27, v26
	v_cmp_ge_f32_e64 s[2:3], 0, v31
	v_add_u32_e32 v31, 1, v27
	v_add_u32_e32 v34, v182, v180
	v_cndmask_b32_e64 v30, v27, v30, s[2:3]
	v_fma_f32 v27, -v31, v27, v26
	v_cmp_lt_f32_e64 s[2:3], 0, v27
	s_waitcnt vmcnt(0)
	v_pk_fma_f32 v[16:17], v[108:109], v[112:113], v[16:17] op_sel_hi:[0,1,1]
	v_pk_fma_f32 v[14:15], v[108:109], v[110:111], v[14:15] op_sel_hi:[0,1,1]
	v_cndmask_b32_e64 v27, v30, v31, s[2:3]
	v_mul_f32_e32 v30, 0x37800000, v27
	v_cndmask_b32_e32 v27, v27, v30, vcc
	v_cmp_class_f32_e32 vcc, v26, v217
	s_cmp_lg_u32 s21, 30
	s_nop 0
	v_cndmask_b32_e32 v26, v27, v26, vcc
	v_div_scale_f32 v27, s[2:3], v26, v26, 1.0
	v_rcp_f32_e32 v30, v27
	s_nop 0
	v_fma_f32 v31, -v27, v30, 1.0
	v_fmac_f32_e32 v30, v31, v30
	v_div_scale_f32 v31, vcc, 1.0, v26, 1.0
	v_mul_f32_e32 v32, v31, v30
	v_fma_f32 v33, -v27, v32, v31
	v_fmac_f32_e32 v32, v33, v30
	v_fma_f32 v27, -v27, v32, v31
	v_div_fmas_f32 v27, v27, v30, v32
	v_add_u32_e32 v32, s0, v90
	v_ashrrev_i32_e32 v33, 31, v32
	s_waitcnt lgkmcnt(0)
	v_lshl_add_u64 v[44:45], v[32:33], 2, s[12:13]
	global_load_dword v43, v[44:45], off
	ds_read_u16 v30, v34 offset:33792
	s_mov_b32 s12, 0x42ce8ed0
	s_mov_b32 s13, 0xc2b17218
	v_div_fixup_f32 v41, v27, v26, 1.0
	v_mul_f32_e32 v22, v22, v41
	s_waitcnt lgkmcnt(0)
	v_lshlrev_b32_e32 v30, 16, v30
	v_mul_f32_e32 v31, 0xbfb8aa3b, v30
	v_fma_f32 v42, v30, s34, -v31
	v_rndne_f32_e32 v46, v31
	v_fmac_f32_e32 v42, 0xb2a5705f, v30
	v_sub_f32_e32 v31, v31, v46
	v_add_f32_e32 v31, v31, v42
	v_exp_f32_e32 v31, v31
	v_cvt_i32_f32_e32 v42, v46
	v_cmp_nlt_f32_e32 vcc, s12, v30
	v_or_b32_e32 v26, s16, v176
	v_ashrrev_i32_e32 v27, 31, v26
	v_ldexp_f32 v31, v31, v42
	v_cndmask_b32_e32 v31, 0, v31, vcc
	v_cmp_ngt_f32_e32 vcc, s13, v30
	v_lshlrev_b64 v[26:27], 11, v[26:27]
	v_lshl_add_u64 v[26:27], s[10:11], 0, v[26:27]
	v_cndmask_b32_e32 v31, v219, v31, vcc
	v_add_f32_e32 v31, 1.0, v31
	v_div_scale_f32 v42, s[0:1], v31, v31, v30
	v_rcp_f32_e32 v46, v42
	v_mul_f32_e32 v18, v18, v41
	v_fma_f32 v47, -v42, v46, 1.0
	v_fmac_f32_e32 v46, v47, v46
	v_div_scale_f32 v47, vcc, v30, v31, v30
	v_mul_f32_e32 v48, v47, v46
	v_fma_f32 v49, -v42, v48, v47
	v_fmac_f32_e32 v48, v49, v46
	v_fma_f32 v42, -v42, v48, v47
	v_div_fmas_f32 v42, v42, v46, v48
	v_div_fixup_f32 v30, v42, v31, v30
	s_waitcnt vmcnt(0)
	v_mul_f32_e32 v22, v43, v22
	v_mul_f32_e32 v22, v22, v30
	v_bfe_u32 v30, v22, 16, 1
	v_add3_u32 v22, v22, v30, s33
	v_lshlrev_b64 v[30:31], 1, v[90:91]
	v_lshl_add_u64 v[26:27], v[26:27], 0, v[30:31]
	global_store_short_d16_hi v[26:27], v22, off
	v_add_u32_e32 v22, v182, v183
	ds_read_u16 v42, v22 offset:33792
	s_waitcnt lgkmcnt(0)
	v_lshlrev_b32_e32 v46, 16, v42
	global_load_dword v42, v[44:45], off offset:64
	v_mul_f32_e32 v41, 0xbfb8aa3b, v46
	v_fma_f32 v44, v46, s34, -v41
	v_rndne_f32_e32 v45, v41
	v_fmac_f32_e32 v44, 0xb2a5705f, v46
	v_sub_f32_e32 v41, v41, v45
	v_add_f32_e32 v41, v41, v44
	v_exp_f32_e32 v41, v41
	v_cvt_i32_f32_e32 v44, v45
	v_cmp_nlt_f32_e32 vcc, s12, v46
	v_ldexp_f32 v41, v41, v44
	s_nop 0
	v_cndmask_b32_e32 v41, 0, v41, vcc
	v_cmp_ngt_f32_e32 vcc, s13, v46
	s_waitcnt vmcnt(0)
	v_mul_f32_e32 v18, v42, v18
	v_cndmask_b32_e32 v41, v219, v41, vcc
	v_add_f32_e32 v41, 1.0, v41
	v_div_scale_f32 v44, s[0:1], v41, v41, v46
	v_rcp_f32_e32 v45, v44
	s_nop 0
	v_fma_f32 v47, -v44, v45, 1.0
	v_fmac_f32_e32 v45, v47, v45
	v_div_scale_f32 v47, vcc, v46, v41, v46
	v_mul_f32_e32 v48, v47, v45
	v_fma_f32 v49, -v44, v48, v47
	v_fmac_f32_e32 v48, v49, v45
	v_fma_f32 v44, -v44, v48, v47
	v_div_fmas_f32 v44, v44, v45, v48
	v_div_fixup_f32 v41, v44, v41, v46
	v_mul_f32_e32 v18, v18, v41
	v_bfe_u32 v41, v18, 16, 1
	v_add3_u32 v18, v18, v41, s33
	global_store_short_d16_hi v[26:27], v18, off offset:32
	v_add_f32_e32 v18, v28, v29
	v_fmamk_f32 v18, v18, 0x3c800000, v216
	v_cmp_gt_f32_e32 vcc, s22, v18
	v_mul_f32_e32 v26, 0x4f800000, v18
	s_nop 0
	v_cndmask_b32_e32 v18, v18, v26, vcc
	v_sqrt_f32_e32 v26, v18
	s_nop 0
	v_add_u32_e32 v27, -1, v26
	v_fma_f32 v28, -v27, v26, v18
	v_cmp_ge_f32_e64 s[2:3], 0, v28
	v_add_u32_e32 v28, 1, v26
	s_nop 0
	v_cndmask_b32_e64 v27, v26, v27, s[2:3]
	v_fma_f32 v26, -v28, v26, v18
	v_cmp_lt_f32_e64 s[2:3], 0, v26
	s_nop 1
	v_cndmask_b32_e64 v26, v27, v28, s[2:3]
	v_mul_f32_e32 v27, 0x37800000, v26
	v_cndmask_b32_e32 v26, v26, v27, vcc
	v_cmp_class_f32_e32 vcc, v18, v217
	s_nop 1
	v_cndmask_b32_e32 v18, v26, v18, vcc
	v_div_scale_f32 v26, s[0:1], v18, v18, 1.0
	v_rcp_f32_e32 v27, v26
	s_nop 0
	v_fma_f32 v28, -v26, v27, 1.0
	v_fmac_f32_e32 v27, v28, v27
	v_div_scale_f32 v28, vcc, 1.0, v18, 1.0
	v_mul_f32_e32 v29, v28, v27
	v_fma_f32 v41, -v26, v29, v28
	v_fmac_f32_e32 v29, v41, v27
	v_add_u32_e32 v41, v185, v180
	v_fma_f32 v26, -v26, v29, v28
	ds_read_u16 v28, v41 offset:33792
	v_div_fmas_f32 v26, v26, v27, v29
	v_div_fixup_f32 v18, v26, v18, 1.0
	v_or_b32_e32 v26, s16, v184
	v_mul_f32_e32 v23, v23, v18
	s_waitcnt lgkmcnt(0)
	v_lshlrev_b32_e32 v28, 16, v28
	v_mul_f32_e32 v29, 0xbfb8aa3b, v28
	v_fma_f32 v44, v28, s34, -v29
	v_rndne_f32_e32 v45, v29
	v_fmac_f32_e32 v44, 0xb2a5705f, v28
	v_sub_f32_e32 v29, v29, v45
	v_add_f32_e32 v29, v29, v44
	v_exp_f32_e32 v29, v29
	v_cvt_i32_f32_e32 v44, v45
	v_cmp_nlt_f32_e32 vcc, s12, v28
	v_ashrrev_i32_e32 v27, 31, v26
	v_mul_f32_e32 v23, v43, v23
	v_ldexp_f32 v29, v29, v44
	v_cndmask_b32_e32 v29, 0, v29, vcc
	v_cmp_ngt_f32_e32 vcc, s13, v28
	v_lshlrev_b64 v[26:27], 11, v[26:27]
	v_lshl_add_u64 v[26:27], s[10:11], 0, v[26:27]
	v_cndmask_b32_e32 v29, v219, v29, vcc
	v_add_f32_e32 v29, 1.0, v29
	v_div_scale_f32 v44, s[0:1], v29, v29, v28
	v_rcp_f32_e32 v45, v44
	v_lshl_add_u64 v[26:27], v[26:27], 0, v[30:31]
	v_mul_f32_e32 v18, v19, v18
	v_mul_f32_e32 v18, v42, v18
	v_fma_f32 v46, -v44, v45, 1.0
	v_fmac_f32_e32 v45, v46, v45
	v_div_scale_f32 v46, vcc, v28, v29, v28
	v_mul_f32_e32 v47, v46, v45
	v_fma_f32 v48, -v44, v47, v46
	v_fmac_f32_e32 v47, v48, v45
	v_fma_f32 v44, -v44, v47, v46
	v_div_fmas_f32 v44, v44, v45, v47
	v_div_fixup_f32 v28, v44, v29, v28
	v_mul_f32_e32 v23, v23, v28
	v_bfe_u32 v28, v23, 16, 1
	v_add3_u32 v23, v23, v28, s33
	global_store_short_d16_hi v[26:27], v23, off
	v_add_u32_e32 v23, v185, v183
	ds_read_u16 v28, v23 offset:33792
	s_waitcnt lgkmcnt(0)
	v_lshlrev_b32_e32 v28, 16, v28
	v_mul_f32_e32 v19, 0xbfb8aa3b, v28
	v_fma_f32 v29, v28, s34, -v19
	v_rndne_f32_e32 v44, v19
	v_fmac_f32_e32 v29, 0xb2a5705f, v28
	v_sub_f32_e32 v19, v19, v44
	v_add_f32_e32 v19, v19, v29
	v_exp_f32_e32 v19, v19
	v_cvt_i32_f32_e32 v29, v44
	v_cmp_nlt_f32_e32 vcc, s12, v28
	v_ldexp_f32 v19, v19, v29
	s_nop 0
	v_cndmask_b32_e32 v19, 0, v19, vcc
	v_cmp_ngt_f32_e32 vcc, s13, v28
	s_nop 1
	v_cndmask_b32_e32 v19, v219, v19, vcc
	v_add_f32_e32 v19, 1.0, v19
	v_div_scale_f32 v29, s[0:1], v19, v19, v28
	v_rcp_f32_e32 v44, v29
	s_nop 0
	v_fma_f32 v45, -v29, v44, 1.0
	v_fmac_f32_e32 v44, v45, v44
	v_div_scale_f32 v45, vcc, v28, v19, v28
	v_mul_f32_e32 v46, v45, v44
	v_fma_f32 v47, -v29, v46, v45
	v_fmac_f32_e32 v46, v47, v44
	v_fma_f32 v29, -v29, v46, v45
	v_div_fmas_f32 v29, v29, v44, v46
	v_div_fixup_f32 v19, v29, v19, v28
	v_mul_f32_e32 v18, v18, v19
	v_bfe_u32 v19, v18, 16, 1
	v_add3_u32 v18, v18, v19, s33
	global_store_short_d16_hi v[26:27], v18, off offset:32
	ds_read_b128 v[26:29], v187 offset:43008
	s_waitcnt lgkmcnt(0)
	v_add_f32_e32 v18, v26, v27
	v_fmamk_f32 v18, v18, 0x3c800000, v216
	v_cmp_gt_f32_e32 vcc, s22, v18
	v_mul_f32_e32 v19, 0x4f800000, v18
	s_nop 0
	v_cndmask_b32_e32 v18, v18, v19, vcc
	v_sqrt_f32_e32 v19, v18
	s_nop 0
	v_add_u32_e32 v26, -1, v19
	v_fma_f32 v27, -v26, v19, v18
	v_cmp_ge_f32_e64 s[2:3], 0, v27
	v_add_u32_e32 v27, 1, v19
	s_nop 0
	v_cndmask_b32_e64 v26, v19, v26, s[2:3]
	v_fma_f32 v19, -v27, v19, v18
	v_cmp_lt_f32_e64 s[2:3], 0, v19
	s_nop 1
	v_cndmask_b32_e64 v19, v26, v27, s[2:3]
	v_mul_f32_e32 v26, 0x37800000, v19
	v_cndmask_b32_e32 v19, v19, v26, vcc
	v_cmp_class_f32_e32 vcc, v18, v217
	s_nop 1
	v_cndmask_b32_e32 v18, v19, v18, vcc
	v_div_scale_f32 v19, s[0:1], v18, v18, 1.0
	v_rcp_f32_e32 v26, v19
	s_nop 0
	v_fma_f32 v27, -v19, v26, 1.0
	v_fmac_f32_e32 v26, v27, v26
	v_div_scale_f32 v27, vcc, 1.0, v18, 1.0
	v_mul_f32_e32 v44, v27, v26
	v_fma_f32 v45, -v19, v44, v27
	v_fmac_f32_e32 v44, v45, v26
	v_fma_f32 v19, -v19, v44, v27
	v_div_fmas_f32 v19, v19, v26, v44
	v_add_u32_e32 v26, v202, v180
	ds_read_u16 v44, v26 offset:33792
	v_div_fixup_f32 v27, v19, v18, 1.0
	v_or_b32_e32 v18, s16, v186
	v_mul_f32_e32 v24, v24, v27
	v_ashrrev_i32_e32 v19, 31, v18
	s_waitcnt lgkmcnt(0)
	v_lshlrev_b32_e32 v44, 16, v44
	v_mul_f32_e32 v45, 0xbfb8aa3b, v44
	v_fma_f32 v46, v44, s34, -v45
	v_rndne_f32_e32 v47, v45
	v_fmac_f32_e32 v46, 0xb2a5705f, v44
	v_sub_f32_e32 v45, v45, v47
	v_add_f32_e32 v45, v45, v46
	v_exp_f32_e32 v45, v45
	v_cvt_i32_f32_e32 v46, v47
	v_cmp_nlt_f32_e32 vcc, s12, v44
	v_mul_f32_e32 v24, v43, v24
	v_lshlrev_b64 v[18:19], 11, v[18:19]
	v_ldexp_f32 v45, v45, v46
	v_cndmask_b32_e32 v45, 0, v45, vcc
	v_cmp_ngt_f32_e32 vcc, s13, v44
	v_lshl_add_u64 v[18:19], s[10:11], 0, v[18:19]
	v_lshl_add_u64 v[18:19], v[18:19], 0, v[30:31]
	v_cndmask_b32_e32 v45, v219, v45, vcc
	v_add_f32_e32 v45, 1.0, v45
	v_div_scale_f32 v46, s[0:1], v45, v45, v44
	v_rcp_f32_e32 v47, v46
	v_mul_f32_e32 v20, v20, v27
	v_mul_f32_e32 v20, v42, v20
	v_fma_f32 v48, -v46, v47, 1.0
	v_fmac_f32_e32 v47, v48, v47
	v_div_scale_f32 v48, vcc, v44, v45, v44
	v_mul_f32_e32 v49, v48, v47
	v_fma_f32 v50, -v46, v49, v48
	v_fmac_f32_e32 v49, v50, v47
	v_fma_f32 v46, -v46, v49, v48
	v_div_fmas_f32 v46, v46, v47, v49
	v_div_fixup_f32 v44, v46, v45, v44
	v_mul_f32_e32 v24, v24, v44
	v_bfe_u32 v44, v24, 16, 1
	v_add3_u32 v24, v24, v44, s33
	global_store_short_d16_hi v[18:19], v24, off
	v_add_u32_e32 v24, v202, v183
	ds_read_u16 v44, v24 offset:33792
	s_waitcnt lgkmcnt(0)
	v_lshlrev_b32_e32 v44, 16, v44
	v_mul_f32_e32 v27, 0xbfb8aa3b, v44
	v_fma_f32 v45, v44, s34, -v27
	v_rndne_f32_e32 v46, v27
	v_fmac_f32_e32 v45, 0xb2a5705f, v44
	v_sub_f32_e32 v27, v27, v46
	v_add_f32_e32 v27, v27, v45
	v_exp_f32_e32 v27, v27
	v_cvt_i32_f32_e32 v45, v46
	v_cmp_nlt_f32_e32 vcc, s12, v44
	v_ldexp_f32 v27, v27, v45
	s_nop 0
	v_cndmask_b32_e32 v27, 0, v27, vcc
	v_cmp_ngt_f32_e32 vcc, s13, v44
	s_nop 1
	v_cndmask_b32_e32 v27, v219, v27, vcc
	v_add_f32_e32 v27, 1.0, v27
	v_div_scale_f32 v45, s[0:1], v27, v27, v44
	v_rcp_f32_e32 v46, v45
	s_nop 0
	v_fma_f32 v47, -v45, v46, 1.0
	v_fmac_f32_e32 v46, v47, v46
	v_div_scale_f32 v47, vcc, v44, v27, v44
	v_mul_f32_e32 v48, v47, v46
	v_fma_f32 v49, -v45, v48, v47
	v_fmac_f32_e32 v48, v49, v46
	v_fma_f32 v45, -v45, v48, v47
	v_div_fmas_f32 v45, v45, v46, v48
	v_div_fixup_f32 v27, v45, v27, v44
	v_mul_f32_e32 v20, v20, v27
	v_bfe_u32 v27, v20, 16, 1
	v_add3_u32 v20, v20, v27, s33
	global_store_short_d16_hi v[18:19], v20, off offset:32
	v_add_f32_e32 v18, v28, v29
	v_fmamk_f32 v18, v18, 0x3c800000, v216
	v_cmp_gt_f32_e32 vcc, s22, v18
	v_mul_f32_e32 v19, 0x4f800000, v18
	s_nop 0
	v_cndmask_b32_e32 v18, v18, v19, vcc
	v_sqrt_f32_e32 v19, v18
	s_nop 0
	v_add_u32_e32 v20, -1, v19
	v_fma_f32 v27, -v20, v19, v18
	v_cmp_ge_f32_e64 s[2:3], 0, v27
	v_add_u32_e32 v27, 1, v19
	s_nop 0
	v_cndmask_b32_e64 v20, v19, v20, s[2:3]
	v_fma_f32 v19, -v27, v19, v18
	v_cmp_lt_f32_e64 s[2:3], 0, v19
	s_nop 1
	v_cndmask_b32_e64 v19, v20, v27, s[2:3]
	v_mul_f32_e32 v20, 0x37800000, v19
	v_cndmask_b32_e32 v19, v19, v20, vcc
	v_cmp_class_f32_e32 vcc, v18, v217
	s_nop 1
	v_cndmask_b32_e32 v18, v19, v18, vcc
	v_div_scale_f32 v19, s[0:1], v18, v18, 1.0
	v_rcp_f32_e32 v20, v19
	s_nop 0
	v_fma_f32 v27, -v19, v20, 1.0
	v_fmac_f32_e32 v20, v27, v20
	v_div_scale_f32 v27, vcc, 1.0, v18, 1.0
	v_mul_f32_e32 v28, v27, v20
	v_fma_f32 v29, -v19, v28, v27
	v_fmac_f32_e32 v28, v29, v20
	v_fma_f32 v19, -v19, v28, v27
	v_add_u32_e32 v27, v203, v180
	v_div_fmas_f32 v19, v19, v20, v28
	ds_read_u16 v28, v27 offset:33792
	v_div_fixup_f32 v20, v19, v18, 1.0
	v_mul_f32_e32 v25, v25, v20
	v_mul_f32_e32 v25, v43, v25
	v_or_b32_e32 v18, s16, v178
	s_waitcnt lgkmcnt(0)
	v_lshlrev_b32_e32 v28, 16, v28
	v_mul_f32_e32 v29, 0xbfb8aa3b, v28
	v_fma_f32 v43, v28, s34, -v29
	v_rndne_f32_e32 v44, v29
	v_fmac_f32_e32 v43, 0xb2a5705f, v28
	v_sub_f32_e32 v29, v29, v44
	v_add_f32_e32 v29, v29, v43
	v_exp_f32_e32 v29, v29
	v_cvt_i32_f32_e32 v43, v44
	v_cmp_nlt_f32_e32 vcc, s12, v28
	v_ashrrev_i32_e32 v19, 31, v18
	v_lshlrev_b64 v[18:19], 11, v[18:19]
	v_ldexp_f32 v29, v29, v43
	v_cndmask_b32_e32 v29, 0, v29, vcc
	v_cmp_ngt_f32_e32 vcc, s13, v28
	v_lshl_add_u64 v[18:19], s[10:11], 0, v[18:19]
	v_lshl_add_u64 v[18:19], v[18:19], 0, v[30:31]
	v_cndmask_b32_e32 v29, v219, v29, vcc
	v_add_f32_e32 v29, 1.0, v29
	v_div_scale_f32 v43, s[0:1], v29, v29, v28
	v_rcp_f32_e32 v44, v43
	v_mul_f32_e32 v20, v21, v20
	v_mul_f32_e32 v20, v42, v20
	v_fma_f32 v45, -v43, v44, 1.0
	v_fmac_f32_e32 v44, v45, v44
	v_div_scale_f32 v45, vcc, v28, v29, v28
	v_mul_f32_e32 v46, v45, v44
	v_fma_f32 v47, -v43, v46, v45
	v_fmac_f32_e32 v46, v47, v44
	v_fma_f32 v43, -v43, v46, v45
	v_div_fmas_f32 v43, v43, v44, v46
	v_div_fixup_f32 v28, v43, v29, v28
	v_mul_f32_e32 v25, v25, v28
	v_bfe_u32 v28, v25, 16, 1
	v_add3_u32 v25, v25, v28, s33
	global_store_short_d16_hi v[18:19], v25, off
	v_add_u32_e32 v25, v203, v183
	ds_read_u16 v28, v25 offset:33792
	s_waitcnt lgkmcnt(0)
	v_lshlrev_b32_e32 v28, 16, v28
	v_mul_f32_e32 v21, 0xbfb8aa3b, v28
	v_fma_f32 v29, v28, s34, -v21
	v_rndne_f32_e32 v42, v21
	v_fmac_f32_e32 v29, 0xb2a5705f, v28
	v_sub_f32_e32 v21, v21, v42
	v_add_f32_e32 v21, v21, v29
	v_exp_f32_e32 v21, v21
	v_cvt_i32_f32_e32 v29, v42
	v_cmp_nlt_f32_e32 vcc, s12, v28
	v_ldexp_f32 v21, v21, v29
	s_nop 0
	v_cndmask_b32_e32 v21, 0, v21, vcc
	v_cmp_ngt_f32_e32 vcc, s13, v28
	s_nop 1
	v_cndmask_b32_e32 v21, v219, v21, vcc
	v_add_f32_e32 v21, 1.0, v21
	v_div_scale_f32 v29, s[0:1], v21, v21, v28
	v_rcp_f32_e32 v42, v29
	s_nop 0
	v_fma_f32 v43, -v29, v42, 1.0
	v_fmac_f32_e32 v42, v43, v42
	v_div_scale_f32 v43, vcc, v28, v21, v28
	v_mul_f32_e32 v44, v43, v42
	v_fma_f32 v45, -v29, v44, v43
	v_fmac_f32_e32 v44, v45, v42
	v_fma_f32 v29, -v29, v44, v43
	v_div_fmas_f32 v29, v29, v42, v44
	v_div_fixup_f32 v21, v29, v21, v28
	v_mul_f32_e32 v20, v20, v21
	v_bfe_u32 v21, v20, 16, 1
	v_add3_u32 v20, v20, v21, s33
	global_store_short_d16_hi v[18:19], v20, off offset:32
	s_waitcnt lgkmcnt(0)
	s_barrier
	s_cbranch_scc1 .LBB0_775
	v_add_co_u32_e32 v18, vcc, 0x3e000, v104
	global_load_dword v28, v[106:107], off offset:3968
	s_nop 0
	v_addc_co_u32_e32 v19, vcc, 0, v105, vcc
	global_load_dwordx4 v[18:21], v[18:19], off
	s_load_dwordx2 s[2:3], s[4:5], 0xf8
	v_readlane_b32 s0, v255, 26
	s_add_i32 s0, s20, s0
	s_ashr_i32 s1, s0, 31
	s_lshl_b64 s[0:1], s[0:1], 15
	s_waitcnt lgkmcnt(0)
	s_add_u32 s0, s2, s0
	s_addc_u32 s1, s3, s1
	s_lshl_b32 s2, s17, 13
	s_add_u32 s0, s0, s2
	s_addc_u32 s1, s1, 0
	s_waitcnt vmcnt(0)
	v_pk_fma_f32 v[20:21], v[16:17], v[28:29], v[20:21] op_sel_hi:[1,0,1]
	v_pk_fma_f32 v[18:19], v[14:15], v[28:29], v[18:19] op_sel_hi:[1,0,1]
	v_lshl_add_u64 v[28:29], v[80:81], 2, s[0:1]
	v_lshl_add_u64 v[28:29], v[28:29], 0, v[0:1]
	v_add_co_u32_e32 v28, vcc, 0x8100000, v28
	s_nop 1
	v_addc_co_u32_e32 v29, vcc, 0, v29, vcc
	global_store_dwordx4 v[28:29], v[18:21], off
.LBB0_775:
	s_nop 1
	v_mul_f32_e32 v19, 0x3fb8aa3b, v10
	v_rndne_f32_e32 v20, v19
	s_mov_b32 s2, 0x3fb8aa3b
	v_sub_f32_e32 v21, v19, v20
	v_fma_f32 v19, v10, s2, -v19
	v_fmac_f32_e32 v19, 0x32a5705f, v10
	v_add_f32_e32 v19, v21, v19
	v_exp_f32_e32 v19, v19
	v_cvt_i32_f32_e32 v20, v20
	v_bfe_u32 v0, v14, 16, 1
	v_add3_u32 v0, v14, v0, s33
	ds_write_b16_d16_hi v205, v0 offset:28672
	v_ldexp_f32 v19, v19, v20
	v_mul_f32_e32 v20, 0xbfb8aa3b, v10
	v_bfe_u32 v0, v15, 16, 1
	v_rndne_f32_e32 v29, v20
	v_add3_u32 v0, v15, v0, s33
	v_sub_f32_e32 v42, v20, v29
	v_fma_f32 v20, v10, s34, -v20
	ds_write_b16_d16_hi v205, v0 offset:28752
	v_bfe_u32 v0, v16, 16, 1
	v_fmac_f32_e32 v20, 0xb2a5705f, v10
	v_add3_u32 v0, v16, v0, s33
	v_add_f32_e32 v20, v42, v20
	ds_write_b16_d16_hi v205, v0 offset:28832
	v_bfe_u32 v0, v17, 16, 1
	s_mov_b32 s3, 0xc2ce8ed0
	v_exp_f32_e32 v20, v20
	v_cvt_i32_f32_e32 v29, v29
	v_add3_u32 v0, v17, v0, s33
	v_cmp_ngt_f32_e32 vcc, s3, v10
	s_mov_b32 s12, 0x42b17218
	ds_write_b16_d16_hi v205, v0 offset:28912
	v_lshlrev_b32_e32 v0, 16, v64
	v_cndmask_b32_e32 v19, 0, v19, vcc
	v_cmp_nlt_f32_e32 vcc, s12, v10
	v_mul_f32_e32 v0, 0x3e3504f3, v0
	s_mov_b32 s0, 0x42ce8ed0
	v_cndmask_b32_e32 v19, v219, v19, vcc
	v_mul_f32_e32 v0, v19, v0
	v_ldexp_f32 v19, v20, v29
	v_mul_f32_e32 v20, 0x3fb8aa3b, v11
	v_rndne_f32_e32 v29, v20
	v_sub_f32_e32 v42, v20, v29
	v_fma_f32 v20, v11, s2, -v20
	v_fmac_f32_e32 v20, 0x32a5705f, v11
	v_add_f32_e32 v20, v42, v20
	v_exp_f32_e32 v20, v20
	v_cvt_i32_f32_e32 v29, v29
	v_cmp_nlt_f32_e32 vcc, s0, v10
	s_mov_b32 s1, 0xc2b17218
	v_and_b32_e32 v14, 0xffff0000, v64
	v_cndmask_b32_e32 v19, 0, v19, vcc
	v_cmp_ngt_f32_e32 vcc, s1, v10
	v_lshlrev_b32_e32 v17, 16, v62
	v_and_b32_e32 v18, 0xffff0000, v62
	v_cndmask_b32_e32 v10, v219, v19, vcc
	v_mul_f32_e32 v19, 0xbfb8aa3b, v11
	v_mul_f32_e32 v17, v10, v17
	v_mul_f32_e32 v10, 0x3e3504f3, v14
	v_ldexp_f32 v14, v20, v29
	v_rndne_f32_e32 v20, v19
	v_sub_f32_e32 v29, v19, v20
	v_fma_f32 v19, v11, s34, -v19
	v_fmac_f32_e32 v19, 0xb2a5705f, v11
	v_add_f32_e32 v19, v29, v19
	v_exp_f32_e32 v19, v19
	v_cvt_i32_f32_e32 v20, v20
	v_cmp_ngt_f32_e32 vcc, s3, v11
	v_lshlrev_b32_e32 v15, 16, v65
	v_and_b32_e32 v16, 0xffff0000, v65
	v_cndmask_b32_e32 v14, 0, v14, vcc
	v_cmp_nlt_f32_e32 vcc, s12, v11
	v_lshlrev_b32_e32 v21, 16, v63
	v_and_b32_e32 v28, 0xffff0000, v63
	v_cndmask_b32_e32 v14, v219, v14, vcc
	v_mul_f32_e32 v10, v14, v10
	v_ldexp_f32 v14, v19, v20
	v_mul_f32_e32 v19, 0x3fb8aa3b, v12
	v_rndne_f32_e32 v20, v19
	v_sub_f32_e32 v29, v19, v20
	v_fma_f32 v19, v12, s2, -v19
	v_fmac_f32_e32 v19, 0x32a5705f, v12
	v_add_f32_e32 v19, v29, v19
	v_cmp_nlt_f32_e32 vcc, s0, v11
	v_exp_f32_e32 v19, v19
	v_cvt_i32_f32_e32 v20, v20
	v_cndmask_b32_e32 v14, 0, v14, vcc
	v_cmp_ngt_f32_e32 vcc, s1, v11
	s_nop 1
	v_cndmask_b32_e32 v11, v219, v14, vcc
	v_mul_f32_e32 v14, v11, v18
	v_mul_f32_e32 v18, 0xbfb8aa3b, v12
	v_mul_f32_e32 v11, 0x3e3504f3, v15
	v_ldexp_f32 v15, v19, v20
	v_rndne_f32_e32 v19, v18
	v_sub_f32_e32 v20, v18, v19
	v_fma_f32 v18, v12, s34, -v18
	v_fmac_f32_e32 v18, 0xb2a5705f, v12
	v_add_f32_e32 v18, v20, v18
	v_exp_f32_e32 v18, v18
	v_cvt_i32_f32_e32 v19, v19
	v_cmp_ngt_f32_e32 vcc, s3, v12
	s_nop 1
	v_cndmask_b32_e32 v15, 0, v15, vcc
	v_cmp_nlt_f32_e32 vcc, s12, v12
	s_nop 1
	v_cndmask_b32_e32 v15, v219, v15, vcc
	v_mul_f32_e32 v11, v15, v11
	v_ldexp_f32 v15, v18, v19
	v_mul_f32_e32 v18, 0x3fb8aa3b, v13
	v_rndne_f32_e32 v19, v18
	v_sub_f32_e32 v20, v18, v19
	v_fma_f32 v18, v13, s2, -v18
	v_fmac_f32_e32 v18, 0x32a5705f, v13
	v_add_f32_e32 v18, v20, v18
	v_exp_f32_e32 v18, v18
	v_cvt_i32_f32_e32 v19, v19
	v_cmp_nlt_f32_e32 vcc, s0, v12
	s_nop 1
	v_cndmask_b32_e32 v15, 0, v15, vcc
	v_cmp_ngt_f32_e32 vcc, s1, v12
	s_nop 1
	v_cndmask_b32_e32 v12, v219, v15, vcc
	v_mul_f32_e32 v15, 0x3e3504f3, v16
	v_ldexp_f32 v16, v18, v19
	v_mul_f32_e32 v18, 0xbfb8aa3b, v13
	v_rndne_f32_e32 v19, v18
	v_sub_f32_e32 v20, v18, v19
	v_fma_f32 v18, v13, s34, -v18
	v_fmac_f32_e32 v18, 0xb2a5705f, v13
	v_add_f32_e32 v18, v20, v18
	v_exp_f32_e32 v18, v18
	v_cvt_i32_f32_e32 v19, v19
	v_cmp_ngt_f32_e32 vcc, s3, v13
	v_mul_f32_e32 v12, v12, v21
	s_nop 0
	v_cndmask_b32_e32 v16, 0, v16, vcc
	v_cmp_nlt_f32_e32 vcc, s12, v13
	s_nop 1
	v_cndmask_b32_e32 v16, v219, v16, vcc
	v_mul_f32_e32 v15, v16, v15
	v_ldexp_f32 v16, v18, v19
	v_cmp_nlt_f32_e32 vcc, s0, v13
	s_nop 1
	v_cndmask_b32_e32 v16, 0, v16, vcc
	v_cmp_ngt_f32_e32 vcc, s1, v13
	s_nop 1
	v_cndmask_b32_e32 v13, v219, v16, vcc
	v_cvt_pk_bf16_f32 v10, v0, v10
	v_cvt_pk_bf16_f32 v11, v11, v15
	ds_write_b64 v38, v[10:11]
	v_mul_f32_e32 v13, v13, v28
	v_cvt_pk_bf16_f32 v10, v17, v14
	v_cvt_pk_bf16_f32 v11, v12, v13
	ds_write_b64 v39, v[10:11] offset:5120
	ds_write_b16 v206, v2 offset:19456
	ds_write_b16_d16_hi v206, v2 offset:19600
	ds_write_b16 v206, v3 offset:19744
	ds_write_b16_d16_hi v206, v3 offset:19888
	ds_write_b16 v206, v4 offset:20032
	ds_write_b16_d16_hi v206, v4 offset:20176
	ds_write_b16 v206, v5 offset:20320
	ds_write_b16_d16_hi v206, v5 offset:20464
	ds_write_b128 v207, v[6:9] offset:33792
	s_waitcnt lgkmcnt(0)
	s_barrier
	ds_read_b128 v[2:5], v208
	ds_read_b128 v[6:9], v209 offset:5120
	s_waitcnt lgkmcnt(0)
	v_mfma_f32_16x16x32_bf16 v[6:9], v[2:5], v[6:9], 0
	s_nop 7
	v_cndmask_b32_e64 v0, v6, 0, s[50:51]
	v_bfe_u32 v6, v0, 16, 1
	v_add3_u32 v0, v0, v6, s33
	ds_write_b16_d16_hi v210, v0 offset:10240
	v_cndmask_b32_e64 v0, v7, 0, s[52:53]
	v_bfe_u32 v6, v0, 16, 1
	v_add3_u32 v0, v0, v6, s33
	ds_write_b16_d16_hi v210, v0 offset:10384
	v_cndmask_b32_e64 v0, v8, 0, s[54:55]
	v_bfe_u32 v6, v0, 16, 1
	v_add3_u32 v0, v0, v6, s33
	ds_write_b16_d16_hi v210, v0 offset:10528
	v_cndmask_b32_e64 v0, v9, 0, s[56:57]
	v_bfe_u32 v6, v0, 16, 1
	v_add3_u32 v0, v0, v6, s33
	ds_write_b16_d16_hi v210, v0 offset:10672
	ds_read_b128 v[6:9], v209 offset:6400
	s_waitcnt lgkmcnt(0)
	v_mfma_f32_16x16x32_bf16 v[2:5], v[2:5], v[6:9], 0
	s_nop 7
	v_cndmask_b32_e64 v0, v2, 0, s[58:59]
	v_bfe_u32 v2, v0, 16, 1
	v_add3_u32 v0, v0, v2, s33
	ds_write_b16_d16_hi v211, v0 offset:10240
	v_cndmask_b32_e64 v0, v3, 0, s[60:61]
	v_bfe_u32 v2, v0, 16, 1
	v_add3_u32 v0, v0, v2, s33
	ds_write_b16_d16_hi v211, v0 offset:10384
	v_cndmask_b32_e64 v0, v4, 0, s[62:63]
	v_bfe_u32 v2, v0, 16, 1
	v_add3_u32 v0, v0, v2, s33
	ds_write_b16_d16_hi v211, v0 offset:10528
	v_cndmask_b32_e64 v0, v5, 0, s[64:65]
	v_bfe_u32 v2, v0, 16, 1
	v_add3_u32 v0, v0, v2, s33
	ds_write_b16_d16_hi v211, v0 offset:10672
	s_waitcnt lgkmcnt(0)
	s_barrier
	ds_read_b128 v[2:5], v36 offset:10240
	ds_read_b128 v[6:9], v40 offset:19456
	ds_read_b128 v[10:13], v36 offset:10304
	ds_read_b128 v[14:17], v40 offset:19520
	s_waitcnt lgkmcnt(2)
	v_mfma_f32_16x16x32_bf16 v[6:9], v[2:5], v[6:9], 0
	ds_read_b128 v[18:21], v212
	s_waitcnt lgkmcnt(1)
	v_mfma_f32_16x16x32_bf16 v[6:9], v[10:13], v[14:17], v[6:9]
	ds_read_b128 v[14:17], v213 offset:28672
	s_waitcnt lgkmcnt(0)
	v_mfma_f32_16x16x32_bf16 v[6:9], v[18:21], v[14:17], v[6:9]
	ds_read_b128 v[14:17], v226 offset:19456
	s_waitcnt lgkmcnt(0)
	v_mfma_f32_16x16x32_bf16 v[2:5], v[2:5], v[14:17], 0
	ds_read_b128 v[14:17], v226 offset:19520
	s_waitcnt lgkmcnt(0)
	v_mfma_f32_16x16x32_bf16 v[2:5], v[10:13], v[14:17], v[2:5]
	ds_read_b128 v[10:13], v213 offset:29952
	s_waitcnt lgkmcnt(0)
	v_mfma_f32_16x16x32_bf16 v[2:5], v[18:21], v[10:13], v[2:5]
	s_nop 7
	v_mul_f32_e32 v0, v2, v2
	v_fmac_f32_e32 v0, v6, v6
	s_nop 1
	v_add_f32_dpp v0, v0, v0 quad_perm:[1,0,3,2] row_mask:0xf bank_mask:0xf bound_ctrl:1
	s_nop 1
	v_add_f32_dpp v0, v0, v0 quad_perm:[2,3,0,1] row_mask:0xf bank_mask:0xf bound_ctrl:1
	s_nop 1
	v_add_f32_dpp v0, v0, v0 row_half_mirror row_mask:0xf bank_mask:0xf bound_ctrl:1
	s_nop 1
	v_mov_b32_dpp v10, v0 row_mirror row_mask:0xf bank_mask:0xf bound_ctrl:1
	s_and_saveexec_b64 s[2:3], s[66:67]
	v_add_f32_e32 v0, v0, v10
	ds_write_b32 v35, v0 offset:43008
	s_or_b64 exec, exec, s[2:3]
	v_mul_f32_e32 v0, v3, v3
	v_fmac_f32_e32 v0, v7, v7
	s_nop 1
	v_add_f32_dpp v0, v0, v0 quad_perm:[1,0,3,2] row_mask:0xf bank_mask:0xf bound_ctrl:1
	s_nop 1
	v_add_f32_dpp v0, v0, v0 quad_perm:[2,3,0,1] row_mask:0xf bank_mask:0xf bound_ctrl:1
	s_nop 1
	v_add_f32_dpp v0, v0, v0 row_half_mirror row_mask:0xf bank_mask:0xf bound_ctrl:1
	s_nop 1
	v_mov_b32_dpp v10, v0 row_mirror row_mask:0xf bank_mask:0xf bound_ctrl:1
	s_and_saveexec_b64 s[2:3], s[66:67]
	v_add_f32_e32 v0, v0, v10
	ds_write_b32 v35, v0 offset:43016
	s_or_b64 exec, exec, s[2:3]
	v_mul_f32_e32 v0, v4, v4
	v_fmac_f32_e32 v0, v8, v8
	s_nop 1
	v_add_f32_dpp v0, v0, v0 quad_perm:[1,0,3,2] row_mask:0xf bank_mask:0xf bound_ctrl:1
	s_nop 1
	v_add_f32_dpp v0, v0, v0 quad_perm:[2,3,0,1] row_mask:0xf bank_mask:0xf bound_ctrl:1
	s_nop 1
	v_add_f32_dpp v0, v0, v0 row_half_mirror row_mask:0xf bank_mask:0xf bound_ctrl:1
	s_nop 1
	v_mov_b32_dpp v10, v0 row_mirror row_mask:0xf bank_mask:0xf bound_ctrl:1
	s_and_saveexec_b64 s[2:3], s[66:67]
	v_add_f32_e32 v0, v0, v10
	ds_write_b32 v35, v0 offset:43024
	s_or_b64 exec, exec, s[2:3]
	v_mul_f32_e32 v0, v5, v5
	v_fmac_f32_e32 v0, v9, v9
	s_nop 1
	v_add_f32_dpp v0, v0, v0 quad_perm:[1,0,3,2] row_mask:0xf bank_mask:0xf bound_ctrl:1
	s_nop 1
	v_add_f32_dpp v0, v0, v0 quad_perm:[2,3,0,1] row_mask:0xf bank_mask:0xf bound_ctrl:1
	s_nop 1
	v_add_f32_dpp v0, v0, v0 row_half_mirror row_mask:0xf bank_mask:0xf bound_ctrl:1
	s_nop 1
	v_mov_b32_dpp v10, v0 row_mirror row_mask:0xf bank_mask:0xf bound_ctrl:1
	s_and_saveexec_b64 s[2:3], s[66:67]
	v_add_f32_e32 v0, v0, v10
	ds_write_b32 v37, v0 offset:43008
	s_or_b64 exec, exec, s[2:3]
	s_waitcnt lgkmcnt(0)
	s_barrier
	s_load_dwordx2 s[2:3], s[4:5], 0x60
	s_mov_b32 s1, 0xf800000
	s_or_b32 s0, s16, 64
	s_mov_b32 s16, 0x42ce8ed0
	s_mov_b32 s17, 0xc2b17218
	s_waitcnt lgkmcnt(0)
	v_lshl_add_u64 v[20:21], v[32:33], 2, s[2:3]
	global_load_dword v0, v[20:21], off
	ds_read_b128 v[14:17], v181 offset:43008
	ds_read_b128 v[10:13], v187 offset:43008
	ds_read_u16 v28, v34 offset:33792
	ds_read_u16 v22, v22 offset:33792
	ds_read_u16 v29, v41 offset:33792
	ds_read_u16 v23, v23 offset:33792
	ds_read_u16 v26, v26 offset:33792
	ds_read_u16 v24, v24 offset:33792
	ds_read_u16 v27, v27 offset:33792
	ds_read_u16 v25, v25 offset:33792
	global_load_dword v20, v[20:21], off offset:64
	s_waitcnt lgkmcnt(9)
	v_add_f32_e32 v14, v14, v15
	v_fmamk_f32 v14, v14, 0x3c800000, v216
	s_waitcnt lgkmcnt(7)
	v_lshlrev_b32_e32 v15, 16, v28
	v_mul_f32_e32 v32, 0x4f800000, v14
	v_cmp_gt_f32_e32 vcc, s1, v14
	v_mul_f32_e32 v28, 0xbfb8aa3b, v15
	v_fma_f32 v33, v15, s34, -v28
	v_cndmask_b32_e32 v14, v14, v32, vcc
	v_rndne_f32_e32 v34, v28
	v_sqrt_f32_e32 v32, v14
	v_fmac_f32_e32 v33, 0xb2a5705f, v15
	v_sub_f32_e32 v28, v28, v34
	v_add_f32_e32 v28, v28, v33
	v_cvt_i32_f32_e32 v34, v34
	v_exp_f32_e32 v28, v28
	v_add_u32_e32 v33, -1, v32
	v_fma_f32 v37, -v33, v32, v14
	v_add_u32_e32 v36, 1, v32
	v_cmp_ge_f32_e64 s[2:3], 0, v37
	v_fma_f32 v38, -v36, v32, v14
	v_ldexp_f32 v28, v28, v34
	v_cndmask_b32_e64 v32, v32, v33, s[2:3]
	v_cmp_nlt_f32_e64 s[2:3], s16, v15
	s_waitcnt lgkmcnt(6)
	v_lshlrev_b32_e32 v22, 16, v22
	v_mul_f32_e32 v21, 0xbfb8aa3b, v22
	v_cndmask_b32_e64 v28, 0, v28, s[2:3]
	v_cmp_lt_f32_e64 s[2:3], 0, v38
	v_fma_f32 v35, v22, s34, -v21
	v_fmac_f32_e32 v35, 0xb2a5705f, v22
	v_cndmask_b32_e64 v32, v32, v36, s[2:3]
	v_cmp_ngt_f32_e64 s[2:3], s17, v15
	v_mul_f32_e32 v33, 0x37800000, v32
	v_cndmask_b32_e32 v32, v32, v33, vcc
	v_cndmask_b32_e64 v28, v219, v28, s[2:3]
	v_add_f32_e32 v28, 1.0, v28
	v_cmp_class_f32_e32 vcc, v14, v217
	v_div_scale_f32 v33, s[2:3], v28, v28, v15
	s_nop 0
	v_cndmask_b32_e32 v14, v32, v14, vcc
	v_rcp_f32_e32 v32, v33
	v_div_scale_f32 v36, s[12:13], v14, v14, 1.0
	v_rcp_f32_e32 v37, v36
	v_fma_f32 v39, -v33, v32, 1.0
	v_div_scale_f32 v34, s[2:3], v15, v28, v15
	v_fmac_f32_e32 v32, v39, v32
	v_fma_f32 v39, -v36, v37, 1.0
	v_div_scale_f32 v38, vcc, 1.0, v14, 1.0
	v_mul_f32_e32 v40, v34, v32
	v_fmac_f32_e32 v37, v39, v37
	v_fma_f32 v39, -v33, v40, v34
	v_mul_f32_e32 v41, v38, v37
	v_fmac_f32_e32 v40, v39, v32
	v_fma_f32 v39, -v36, v41, v38
	v_fmac_f32_e32 v41, v39, v37
	v_fma_f32 v33, -v33, v40, v34
	v_fma_f32 v34, -v36, v41, v38
	v_div_fmas_f32 v34, v34, v37, v41
	v_div_fixup_f32 v34, v34, v14, 1.0
	s_mov_b64 vcc, s[2:3]
	v_div_fmas_f32 v14, v33, v32, v40
	v_mul_f32_e32 v6, v6, v34
	v_div_fixup_f32 v14, v14, v28, v15
	v_or_b32_e32 v18, s0, v176
	v_ashrrev_i32_e32 v19, 31, v18
	v_lshlrev_b64 v[18:19], 11, v[18:19]
	v_lshl_add_u64 v[18:19], s[10:11], 0, v[18:19]
	v_cmp_nlt_f32_e32 vcc, s16, v22
	v_add_f32_e32 v16, v16, v17
	v_fmamk_f32 v16, v16, 0x3c800000, v216
	v_mul_f32_e32 v17, 0x4f800000, v16
	v_mul_f32_e32 v2, v2, v34
	v_add_f32_e32 v10, v10, v11
	v_fmamk_f32 v10, v10, 0x3c800000, v216
	v_mul_f32_e32 v11, 0x4f800000, v10
	s_waitcnt vmcnt(1)
	v_mul_f32_e32 v6, v0, v6
	v_mul_f32_e32 v6, v6, v14
	v_rndne_f32_e32 v14, v21
	v_sub_f32_e32 v15, v21, v14
	v_add_f32_e32 v15, v15, v35
	v_exp_f32_e32 v21, v15
	v_cvt_i32_f32_e32 v28, v14
	v_bfe_u32 v14, v6, 16, 1
	v_add3_u32 v6, v6, v14, s33
	v_lshl_add_u64 v[14:15], v[18:19], 0, v[30:31]
	v_ldexp_f32 v18, v21, v28
	v_cndmask_b32_e32 v18, 0, v18, vcc
	v_cmp_ngt_f32_e32 vcc, s17, v22
	global_store_short_d16_hi v[14:15], v6, off
	s_waitcnt vmcnt(1)
	v_mul_f32_e32 v2, v20, v2
	v_cndmask_b32_e32 v18, v219, v18, vcc
	v_add_f32_e32 v18, 1.0, v18
	v_div_scale_f32 v19, s[2:3], v18, v18, v22
	v_rcp_f32_e32 v21, v19
	v_cmp_gt_f32_e64 s[2:3], s1, v16
	s_mov_b32 s71, 0x42ce8ed0
	s_mov_b32 s83, 0xc2b17218
	v_fma_f32 v6, -v19, v21, 1.0
	v_fmac_f32_e32 v21, v6, v21
	v_div_scale_f32 v6, vcc, v22, v18, v22
	v_mul_f32_e32 v28, v6, v21
	v_fma_f32 v32, -v19, v28, v6
	v_cndmask_b32_e64 v16, v16, v17, s[2:3]
	v_fmac_f32_e32 v28, v32, v21
	v_sqrt_f32_e32 v17, v16
	v_fma_f32 v6, -v19, v28, v6
	v_div_fmas_f32 v6, v6, v21, v28
	v_div_fixup_f32 v6, v6, v18, v22
	v_mul_f32_e32 v2, v2, v6
	v_add_u32_e32 v6, -1, v17
	v_fma_f32 v18, -v6, v17, v16
	v_cmp_ge_f32_e32 vcc, 0, v18
	v_add_u32_e32 v18, 1, v17
	s_nop 0
	v_cndmask_b32_e32 v6, v17, v6, vcc
	v_fma_f32 v17, -v18, v17, v16
	v_cmp_lt_f32_e32 vcc, 0, v17
	s_nop 1
	v_cndmask_b32_e32 v6, v6, v18, vcc
	v_mul_f32_e32 v17, 0x37800000, v6
	v_cndmask_b32_e64 v6, v6, v17, s[2:3]
	v_cmp_class_f32_e32 vcc, v16, v217
	v_bfe_u32 v18, v2, 16, 1
	v_add3_u32 v2, v2, v18, s33
	v_cndmask_b32_e32 v6, v6, v16, vcc
	v_div_scale_f32 v16, s[2:3], v6, v6, 1.0
	v_rcp_f32_e32 v17, v16
	global_store_short_d16_hi v[14:15], v2, off offset:32
	v_fma_f32 v2, -v16, v17, 1.0
	v_fmac_f32_e32 v17, v2, v17
	v_div_scale_f32 v2, vcc, 1.0, v6, 1.0
	v_mul_f32_e32 v14, v2, v17
	v_fma_f32 v15, -v16, v14, v2
	v_fmac_f32_e32 v14, v15, v17
	v_fma_f32 v2, -v16, v14, v2
	v_div_fmas_f32 v2, v2, v17, v14
	v_div_fixup_f32 v2, v2, v6, 1.0
	s_waitcnt lgkmcnt(5)
	v_lshlrev_b32_e32 v6, 16, v29
	v_mul_f32_e32 v14, 0xbfb8aa3b, v6
	v_fma_f32 v15, v6, s34, -v14
	v_rndne_f32_e32 v16, v14
	v_fmac_f32_e32 v15, 0xb2a5705f, v6
	v_sub_f32_e32 v14, v14, v16
	v_add_f32_e32 v14, v14, v15
	v_exp_f32_e32 v17, v14
	v_cvt_i32_f32_e32 v16, v16
	v_cmp_nlt_f32_e32 vcc, s16, v6
	v_mul_f32_e32 v7, v7, v2
	v_mul_f32_e32 v7, v0, v7
	v_ldexp_f32 v16, v17, v16
	v_cndmask_b32_e32 v16, 0, v16, vcc
	v_cmp_ngt_f32_e32 vcc, s17, v6
	v_or_b32_e32 v14, s0, v184
	v_ashrrev_i32_e32 v15, 31, v14
	v_cndmask_b32_e32 v16, v219, v16, vcc
	v_add_f32_e32 v16, 1.0, v16
	v_div_scale_f32 v17, s[2:3], v16, v16, v6
	v_rcp_f32_e32 v18, v17
	v_lshlrev_b64 v[14:15], 11, v[14:15]
	v_lshl_add_u64 v[14:15], s[10:11], 0, v[14:15]
	v_mul_f32_e32 v2, v3, v2
	v_fma_f32 v19, -v17, v18, 1.0
	v_fmac_f32_e32 v18, v19, v18
	v_div_scale_f32 v19, vcc, v6, v16, v6
	v_mul_f32_e32 v21, v19, v18
	v_fma_f32 v22, -v17, v21, v19
	v_fmac_f32_e32 v21, v22, v18
	v_fma_f32 v17, -v17, v21, v19
	v_div_fmas_f32 v17, v17, v18, v21
	v_div_fixup_f32 v6, v17, v16, v6
	s_waitcnt lgkmcnt(4)
	v_lshlrev_b32_e32 v16, 16, v23
	v_mul_f32_e32 v6, v7, v6
	v_mul_f32_e32 v7, 0xbfb8aa3b, v16
	v_fma_f32 v17, v16, s34, -v7
	v_rndne_f32_e32 v18, v7
	v_fmac_f32_e32 v17, 0xb2a5705f, v16
	v_sub_f32_e32 v7, v7, v18
	v_add_f32_e32 v7, v7, v17
	v_exp_f32_e32 v17, v7
	v_cvt_i32_f32_e32 v18, v18
	v_bfe_u32 v7, v6, 16, 1
	v_add3_u32 v19, v6, v7, s33
	v_lshl_add_u64 v[6:7], v[14:15], 0, v[30:31]
	v_ldexp_f32 v14, v17, v18
	v_cmp_nlt_f32_e32 vcc, s16, v16
	global_store_short_d16_hi v[6:7], v19, off
	v_mul_f32_e32 v2, v20, v2
	v_cndmask_b32_e32 v14, 0, v14, vcc
	v_cmp_ngt_f32_e32 vcc, s17, v16
	s_nop 1
	v_cndmask_b32_e32 v14, v219, v14, vcc
	v_add_f32_e32 v14, 1.0, v14
	v_div_scale_f32 v15, s[2:3], v14, v14, v16
	v_rcp_f32_e32 v17, v15
	v_cmp_gt_f32_e64 s[2:3], s1, v10
	v_fma_f32 v3, -v15, v17, 1.0
	v_fmac_f32_e32 v17, v3, v17
	v_div_scale_f32 v3, vcc, v16, v14, v16
	v_mul_f32_e32 v18, v3, v17
	v_fma_f32 v19, -v15, v18, v3
	v_cndmask_b32_e64 v10, v10, v11, s[2:3]
	v_fmac_f32_e32 v18, v19, v17
	v_sqrt_f32_e32 v11, v10
	v_fma_f32 v3, -v15, v18, v3
	v_div_fmas_f32 v3, v3, v17, v18
	v_div_fixup_f32 v3, v3, v14, v16
	v_mul_f32_e32 v2, v2, v3
	v_add_u32_e32 v3, -1, v11
	v_fma_f32 v14, -v3, v11, v10
	v_cmp_ge_f32_e32 vcc, 0, v14
	v_add_u32_e32 v14, 1, v11
	s_nop 0
	v_cndmask_b32_e32 v3, v11, v3, vcc
	v_fma_f32 v11, -v14, v11, v10
	v_cmp_lt_f32_e32 vcc, 0, v11
	s_nop 1
	v_cndmask_b32_e32 v3, v3, v14, vcc
	v_mul_f32_e32 v11, 0x37800000, v3
	v_cndmask_b32_e64 v3, v3, v11, s[2:3]
	v_cmp_class_f32_e32 vcc, v10, v217
	v_bfe_u32 v14, v2, 16, 1
	v_add3_u32 v2, v2, v14, s33
	v_cndmask_b32_e32 v3, v3, v10, vcc
	v_div_scale_f32 v10, s[2:3], v3, v3, 1.0
	v_rcp_f32_e32 v11, v10
	global_store_short_d16_hi v[6:7], v2, off offset:32
	v_fma_f32 v2, -v10, v11, 1.0
	v_fmac_f32_e32 v11, v2, v11
	v_div_scale_f32 v2, vcc, 1.0, v3, 1.0
	v_mul_f32_e32 v6, v2, v11
	v_fma_f32 v7, -v10, v6, v2
	v_fmac_f32_e32 v6, v7, v11
	v_fma_f32 v2, -v10, v6, v2
	v_div_fmas_f32 v2, v2, v11, v6
	s_waitcnt lgkmcnt(3)
	v_lshlrev_b32_e32 v7, 16, v26
	v_div_fixup_f32 v6, v2, v3, 1.0
	v_mul_f32_e32 v2, 0xbfb8aa3b, v7
	v_fma_f32 v3, v7, s34, -v2
	v_rndne_f32_e32 v10, v2
	v_fmac_f32_e32 v3, 0xb2a5705f, v7
	v_sub_f32_e32 v2, v2, v10
	v_add_f32_e32 v2, v2, v3
	v_exp_f32_e32 v11, v2
	v_cvt_i32_f32_e32 v10, v10
	v_cmp_nlt_f32_e32 vcc, s16, v7
	v_mul_f32_e32 v8, v8, v6
	v_mul_f32_e32 v8, v0, v8
	v_ldexp_f32 v10, v11, v10
	v_cndmask_b32_e32 v10, 0, v10, vcc
	v_cmp_ngt_f32_e32 vcc, s17, v7
	v_or_b32_e32 v2, s0, v186
	v_ashrrev_i32_e32 v3, 31, v2
	v_cndmask_b32_e32 v10, v219, v10, vcc
	v_add_f32_e32 v10, 1.0, v10
	v_div_scale_f32 v11, s[2:3], v10, v10, v7
	v_rcp_f32_e32 v14, v11
	v_lshlrev_b64 v[2:3], 11, v[2:3]
	v_lshl_add_u64 v[2:3], s[10:11], 0, v[2:3]
	v_mul_f32_e32 v4, v4, v6
	v_fma_f32 v15, -v11, v14, 1.0
	v_fmac_f32_e32 v14, v15, v14
	v_div_scale_f32 v15, vcc, v7, v10, v7
	v_mul_f32_e32 v16, v15, v14
	v_fma_f32 v17, -v11, v16, v15
	v_fmac_f32_e32 v16, v17, v14
	v_fma_f32 v11, -v11, v16, v15
	v_div_fmas_f32 v11, v11, v14, v16
	v_div_fixup_f32 v7, v11, v10, v7
	v_mul_f32_e32 v7, v8, v7
	s_waitcnt lgkmcnt(2)
	v_lshlrev_b32_e32 v8, 16, v24
	v_mul_f32_e32 v10, 0xbfb8aa3b, v8
	v_fma_f32 v11, v8, s34, -v10
	v_rndne_f32_e32 v14, v10
	v_fmac_f32_e32 v11, 0xb2a5705f, v8
	v_sub_f32_e32 v10, v10, v14
	v_add_f32_e32 v10, v10, v11
	v_exp_f32_e32 v10, v10
	v_cvt_i32_f32_e32 v11, v14
	v_cmp_nlt_f32_e32 vcc, s16, v8
	v_bfe_u32 v14, v7, 16, 1
	v_add3_u32 v7, v7, v14, s33
	v_ldexp_f32 v10, v10, v11
	v_cndmask_b32_e32 v10, 0, v10, vcc
	v_cmp_ngt_f32_e32 vcc, s17, v8
	v_lshl_add_u64 v[2:3], v[2:3], 0, v[30:31]
	global_store_short_d16_hi v[2:3], v7, off
	v_cndmask_b32_e32 v10, v219, v10, vcc
	v_add_f32_e32 v10, 1.0, v10
	v_div_scale_f32 v11, s[2:3], v10, v10, v8
	v_rcp_f32_e32 v14, v11
	v_mul_f32_e32 v4, v20, v4
	v_fma_f32 v6, -v11, v14, 1.0
	v_fmac_f32_e32 v14, v6, v14
	v_div_scale_f32 v6, vcc, v8, v10, v8
	v_mul_f32_e32 v7, v6, v14
	v_fma_f32 v15, -v11, v7, v6
	v_fmac_f32_e32 v7, v15, v14
	v_fma_f32 v6, -v11, v7, v6
	v_add_f32_e32 v11, v12, v13
	v_fmamk_f32 v11, v11, 0x3c800000, v216
	v_mul_f32_e32 v12, 0x4f800000, v11
	v_cmp_gt_f32_e64 s[2:3], s1, v11
	v_div_fmas_f32 v6, v6, v14, v7
	v_div_fixup_f32 v6, v6, v10, v8
	v_cndmask_b32_e64 v11, v11, v12, s[2:3]
	v_sqrt_f32_e32 v12, v11
	v_mul_f32_e32 v4, v4, v6
	v_bfe_u32 v10, v4, 16, 1
	v_add3_u32 v4, v4, v10, s33
	v_add_u32_e32 v6, -1, v12
	v_fma_f32 v7, -v6, v12, v11
	v_cmp_ge_f32_e32 vcc, 0, v7
	v_add_u32_e32 v7, 1, v12
	v_fma_f32 v8, -v7, v12, v11
	v_cndmask_b32_e32 v6, v12, v6, vcc
	v_cmp_lt_f32_e32 vcc, 0, v8
	global_store_short_d16_hi v[2:3], v4, off offset:32
	s_nop 0
	v_cndmask_b32_e32 v6, v6, v7, vcc
	v_mul_f32_e32 v7, 0x37800000, v6
	v_cndmask_b32_e64 v6, v6, v7, s[2:3]
	v_cmp_class_f32_e32 vcc, v11, v217
	s_nop 1
	v_cndmask_b32_e32 v6, v6, v11, vcc
	v_div_scale_f32 v7, s[2:3], v6, v6, 1.0
	v_rcp_f32_e32 v8, v7
	s_nop 0
	v_fma_f32 v2, -v7, v8, 1.0
	v_fmac_f32_e32 v8, v2, v8
	v_div_scale_f32 v2, vcc, 1.0, v6, 1.0
	v_mul_f32_e32 v3, v2, v8
	v_fma_f32 v4, -v7, v3, v2
	v_fmac_f32_e32 v3, v4, v8
	v_fma_f32 v2, -v7, v3, v2
	v_div_fmas_f32 v2, v2, v8, v3
	v_div_fixup_f32 v4, v2, v6, 1.0
	s_waitcnt lgkmcnt(1)
	v_lshlrev_b32_e32 v6, 16, v27
	v_mul_f32_e32 v2, 0xbfb8aa3b, v6
	v_fma_f32 v3, v6, s34, -v2
	v_rndne_f32_e32 v7, v2
	v_fmac_f32_e32 v3, 0xb2a5705f, v6
	v_sub_f32_e32 v2, v2, v7
	v_add_f32_e32 v2, v2, v3
	v_exp_f32_e32 v8, v2
	v_cvt_i32_f32_e32 v7, v7
	v_cmp_nlt_f32_e32 vcc, s16, v6
	v_or_b32_e32 v2, s0, v178
	v_mul_f32_e32 v9, v9, v4
	v_ldexp_f32 v7, v8, v7
	v_cndmask_b32_e32 v7, 0, v7, vcc
	v_cmp_ngt_f32_e32 vcc, s17, v6
	v_mul_f32_e32 v0, v0, v9
	v_ashrrev_i32_e32 v3, 31, v2
	v_cndmask_b32_e32 v7, v219, v7, vcc
	v_add_f32_e32 v7, 1.0, v7
	v_div_scale_f32 v8, s[0:1], v7, v7, v6
	v_rcp_f32_e32 v10, v8
	v_lshlrev_b64 v[2:3], 11, v[2:3]
	v_lshl_add_u64 v[2:3], s[10:11], 0, v[2:3]
	v_lshl_add_u64 v[2:3], v[2:3], 0, v[30:31]
	v_fma_f32 v9, -v8, v10, 1.0
	v_fmac_f32_e32 v10, v9, v10
	v_div_scale_f32 v9, vcc, v6, v7, v6
	v_mul_f32_e32 v11, v9, v10
	v_fma_f32 v12, -v8, v11, v9
	v_fmac_f32_e32 v11, v12, v10
	v_fma_f32 v8, -v8, v11, v9
	v_div_fmas_f32 v8, v8, v10, v11
	v_div_fixup_f32 v6, v8, v7, v6
	v_mul_f32_e32 v0, v0, v6
	s_waitcnt lgkmcnt(0)
	v_lshlrev_b32_e32 v6, 16, v25
	v_mul_f32_e32 v7, 0xbfb8aa3b, v6
	v_fma_f32 v8, v6, s34, -v7
	v_rndne_f32_e32 v9, v7
	v_fmac_f32_e32 v8, 0xb2a5705f, v6
	v_sub_f32_e32 v7, v7, v9
	v_add_f32_e32 v7, v7, v8
	v_exp_f32_e32 v7, v7
	v_cvt_i32_f32_e32 v8, v9
	v_cmp_nlt_f32_e32 vcc, s16, v6
	v_bfe_u32 v9, v0, 16, 1
	v_add3_u32 v0, v0, v9, s33
	v_ldexp_f32 v7, v7, v8
	v_cndmask_b32_e32 v7, 0, v7, vcc
	v_cmp_ngt_f32_e32 vcc, s17, v6
	global_store_short_d16_hi v[2:3], v0, off
	v_mul_f32_e32 v0, v5, v4
	v_cndmask_b32_e32 v7, v219, v7, vcc
	v_add_f32_e32 v7, 1.0, v7
	v_div_scale_f32 v8, s[0:1], v7, v7, v6
	v_rcp_f32_e32 v9, v8
	v_mul_f32_e32 v0, v20, v0
	v_fma_f32 v4, -v8, v9, 1.0
	v_fmac_f32_e32 v9, v4, v9
	v_div_scale_f32 v4, vcc, v6, v7, v6
	v_mul_f32_e32 v5, v4, v9
	v_fma_f32 v10, -v8, v5, v4
	v_fmac_f32_e32 v5, v10, v9
	v_fma_f32 v4, -v8, v5, v4
	v_div_fmas_f32 v4, v4, v9, v5
	v_div_fixup_f32 v4, v4, v7, v6
	v_mul_f32_e32 v0, v0, v4
	v_bfe_u32 v4, v0, 16, 1
	v_add3_u32 v0, v0, v4, s33
	global_store_short_d16_hi v[2:3], v0, off offset:32

.LBB0_1313:
	s_or_b64 exec, exec, s[12:13]
	s_mul_hi_i32 s1, s4, 0x580000
	s_mul_i32 s4, s4, 0x580000
	s_add_u32 s6, s6, s4
	s_movk_i32 s4, 0x84
	v_lshlrev_b32_e32 v2, 2, v6
	v_mul_lo_u32 v3, v7, s4
	v_add3_u32 v2, s19, v2, v3
	s_waitcnt vmcnt(0)
	ds_write2_b32 v2, v0, v8 offset1:66
	ds_write2_b32 v2, v11, v10 offset0:132 offset1:198
	v_add_u32_e32 v0, 0x400, v2
	ds_write2_b32 v0, v13, v12 offset0:8 offset1:74
	ds_write2_b32 v0, v15, v14 offset0:140 offset1:206
	v_add_u32_e32 v0, 0x800, v2
	ds_write2_b32 v0, v17, v16 offset0:16 offset1:82
	ds_write2_b32 v0, v19, v18 offset0:148 offset1:214
	v_add_u32_e32 v0, 0xc00, v2
	ds_write2_b32 v0, v21, v20 offset0:24 offset1:90
	ds_write2_b32 v0, v23, v22 offset0:156 offset1:222
	v_add_u32_e32 v0, 0x1000, v2
	ds_write2_b32 v0, v25, v24 offset0:32 offset1:98
	ds_write2_b32 v0, v27, v26 offset0:164 offset1:230
	v_add_u32_e32 v0, 0x1400, v2
	ds_write2_b32 v0, v29, v28 offset0:40 offset1:106
	ds_write2_b32 v0, v31, v30 offset0:172 offset1:238
	v_add_u32_e32 v0, 0x1800, v2
	ds_write2_b32 v0, v33, v32 offset0:48 offset1:114
	ds_write2_b32 v0, v35, v34 offset0:180 offset1:246
	v_add_u32_e32 v0, 0x1c00, v2
	ds_write2_b32 v0, v37, v36 offset0:56 offset1:122
	ds_write2_b32 v0, v39, v38 offset0:188 offset1:254
	v_lshlrev_b32_e32 v0, 3, v5
	v_ashrrev_i32_e32 v26, 3, v5
	v_and_b32_e32 v0, 56, v0
	s_waitcnt lgkmcnt(0)
	v_mul_u32_u24_e32 v2, 0x84, v0
	v_lshlrev_b32_e32 v3, 2, v26
	v_add3_u32 v5, s19, v2, v3
	ds_read2_b32 v[2:3], v5 offset1:8
	s_addc_u32 s1, s7, s1
	s_ashr_i32 s11, s10, 31
	ds_read2_b32 v[12:13], v5 offset0:33 offset1:41
	s_lshl_b64 s[4:5], s[10:11], 1
	s_add_u32 s4, s6, s4
	ds_read2_b32 v[14:15], v5 offset0:66 offset1:74
	s_addc_u32 s5, s1, s5
	v_lshlrev_b32_e32 v0, 1, v0
	ds_read2_b32 v[16:17], v5 offset0:99 offset1:107
	v_lshl_add_u64 v[6:7], s[4:5], 0, v[0:1]
	s_waitcnt lgkmcnt(3)
	s_waitcnt lgkmcnt(2)
	ds_read2_b32 v[18:19], v5 offset0:132 offset1:140
	s_mov_b64 s[4:5], 0x200000
	ds_read2_b32 v[20:21], v5 offset0:165 offset1:173
	v_lshl_add_u64 v[10:11], v[6:7], 0, s[4:5]
	v_cvt_pk_bf16_f32 v6, v2, v12
	s_waitcnt lgkmcnt(3)
	s_waitcnt lgkmcnt(2)
	ds_read2_b32 v[22:23], v5 offset0:198 offset1:206
	ds_read2_b32 v[24:25], v5 offset0:231 offset1:239
	v_cvt_pk_bf16_f32 v7, v14, v16
	s_waitcnt lgkmcnt(3)
	s_waitcnt lgkmcnt(2)
	v_cvt_pk_bf16_f32 v8, v18, v20
	s_waitcnt lgkmcnt(1)
	s_waitcnt lgkmcnt(0)
	v_add_u32_e32 v26, s0, v26
	v_cvt_pk_bf16_f32 v9, v22, v24
	v_ashrrev_i32_e32 v27, 31, v26
	v_bfe_u32 v0, v3, 16, 1
	v_lshlrev_b64 v[28:29], 11, v[26:27]
	v_add3_u32 v0, v3, v0, s33
	v_bfe_u32 v2, v13, 16, 1
	v_lshl_add_u64 v[28:29], v[10:11], 0, v[28:29]
	v_lshrrev_b32_e32 v0, 16, v0
	v_add3_u32 v2, v13, v2, s33
	global_store_dwordx4 v[28:29], v[6:9], off
	ds_read2_b32 v[12:13], v5 offset0:16 offset1:24
	v_add_u32_e32 v28, 16, v26
	v_and_or_b32 v6, v2, s26, v0
	v_cvt_pk_bf16_f32 v7, v15, v17
	v_cvt_pk_bf16_f32 v8, v19, v21
	v_cvt_pk_bf16_f32 v9, v23, v25
	v_add_u32_e32 v2, 8, v26
	v_ashrrev_i32_e32 v3, 31, v2
	v_lshlrev_b64 v[2:3], 11, v[2:3]
	v_lshl_add_u64 v[2:3], v[10:11], 0, v[2:3]
	global_store_dwordx4 v[2:3], v[6:9], off
	ds_read2_b32 v[2:3], v5 offset0:49 offset1:57
	ds_read2_b32 v[14:15], v5 offset0:82 offset1:90
	ds_read2_b32 v[16:17], v5 offset0:115 offset1:123
	s_waitcnt lgkmcnt(3)
	s_waitcnt lgkmcnt(2)
	ds_read2_b32 v[18:19], v5 offset0:148 offset1:156
	ds_read2_b32 v[20:21], v5 offset0:181 offset1:189
	v_cvt_pk_bf16_f32 v6, v12, v2
	s_waitcnt lgkmcnt(3)
	s_waitcnt lgkmcnt(2)
	ds_read2_b32 v[22:23], v5 offset0:214 offset1:222
	ds_read2_b32 v[24:25], v5 offset0:247 offset1:255
	v_cvt_pk_bf16_f32 v7, v14, v16
	s_waitcnt lgkmcnt(3)
	s_waitcnt lgkmcnt(2)
	v_cvt_pk_bf16_f32 v8, v18, v20
	s_waitcnt lgkmcnt(1)
	s_waitcnt lgkmcnt(0)
	v_cvt_pk_bf16_f32 v9, v22, v24
	v_ashrrev_i32_e32 v29, 31, v28
	v_lshlrev_b64 v[28:29], 11, v[28:29]
	v_lshl_add_u64 v[28:29], v[10:11], 0, v[28:29]
	global_store_dwordx4 v[28:29], v[6:9], off
	s_nop 1
	v_cvt_pk_bf16_f32 v6, v13, v3
	v_cvt_pk_bf16_f32 v7, v15, v17
	v_cvt_pk_bf16_f32 v8, v19, v21
	v_cvt_pk_bf16_f32 v9, v23, v25
	v_add_u32_e32 v2, 24, v26
	v_ashrrev_i32_e32 v3, 31, v2
	v_lshlrev_b64 v[2:3], 11, v[2:3]
	v_lshl_add_u64 v[2:3], v[10:11], 0, v[2:3]
	global_store_dwordx4 v[2:3], v[6:9], off
	s_waitcnt lgkmcnt(0)

.LBB0_1315:
	s_mul_hi_i32 s0, s15, 0x2c0b02c1
	s_lshr_b32 s1, s0, 31
	s_ashr_i32 s0, s0, 10
	s_add_i32 s4, s0, s1
	s_mul_i32 s0, s4, 0xffffe8c0
	s_add_i32 s12, s15, s0
	v_mov_b32_e32 v5, v4
	s_cmpk_gt_i32 s12, 0x57f
	s_mov_b64 s[6:7], -1
	s_cbranch_scc0 .LBB0_1325
	s_cmpk_gt_u32 s12, 0x77f
	s_cbranch_scc0 .LBB0_1322
	v_and_b32_e32 v7, 31, v5
	s_cmpk_gt_u32 s12, 0x11ff
	s_mul_hi_i32 s0, s4, 0xa80000
	s_mul_i32 s1, s4, 0xa80000
	v_lshlrev_b32_e32 v6, 2, v7
	s_cbranch_scc0 .LBB0_1319
	s_load_dwordx2 s[6:7], s[2:3], 0xe0
	s_load_dwordx2 s[10:11], s[2:3], 0x100
	s_mul_hi_i32 s5, s4, 0x540000
	v_ashrrev_i32_e32 v10, 5, v5
	s_waitcnt lgkmcnt(0)
	s_add_u32 s16, s6, s1
	s_addc_u32 s17, s7, s0
	s_mul_i32 s6, s4, 0x540000
	s_add_u32 s6, s10, s6
	s_addc_u32 s7, s11, s5
	s_mul_i32 s5, s4, 0xffffd180
	s_add_i32 s5, s21, s5
	s_addk_i32 s5, 0xe700
	s_and_b32 s10, s5, 0xfc0
	s_add_i32 s5, s20, 0xfffe7000
	s_and_b32 s5, s5, 0x3e0
	v_or_b32_e32 v0, s5, v7
	v_add_u32_e32 v2, s10, v10
	v_lshlrev_b32_e32 v0, 2, v0
	v_ashrrev_i32_e32 v3, 31, v2
	v_lshl_add_u64 v[8:9], s[16:17], 0, v[0:1]
	v_lshlrev_b64 v[2:3], 12, v[2:3]
	v_lshl_add_u64 v[2:3], v[8:9], 0, v[2:3]
	s_movk_i32 s11, 0x2000
	v_add_co_u32_e32 v8, vcc, s11, v2
	s_movk_i32 s11, 0x4000
	s_nop 0
	v_addc_co_u32_e32 v9, vcc, 0, v3, vcc
	global_load_dword v0, v[2:3], off nt
	global_load_dword v11, v[8:9], off nt
	v_add_co_u32_e32 v8, vcc, s11, v2
	s_movk_i32 s11, 0x6000
	s_nop 0
	v_addc_co_u32_e32 v9, vcc, 0, v3, vcc
	global_load_dword v12, v[8:9], off nt
	v_add_co_u32_e32 v8, vcc, s11, v2
	s_mov_b32 s11, 0x8000
	s_nop 0
	v_addc_co_u32_e32 v9, vcc, 0, v3, vcc
	global_load_dword v13, v[8:9], off nt
	v_add_co_u32_e32 v8, vcc, s11, v2
	s_mov_b32 s11, 0xa000
	s_nop 0
	v_addc_co_u32_e32 v9, vcc, 0, v3, vcc
	global_load_dword v14, v[8:9], off nt
	v_add_co_u32_e32 v8, vcc, s11, v2
	s_mov_b32 s11, 0xc000
	s_nop 0
	v_addc_co_u32_e32 v9, vcc, 0, v3, vcc
	global_load_dword v15, v[8:9], off nt
	v_add_co_u32_e32 v8, vcc, s11, v2
	s_mov_b32 s11, 0xe000
	s_nop 0
	v_addc_co_u32_e32 v9, vcc, 0, v3, vcc
	global_load_dword v16, v[8:9], off nt
	v_add_co_u32_e32 v8, vcc, s11, v2
	s_mov_b32 s11, 0x10000
	s_nop 0
	v_addc_co_u32_e32 v9, vcc, 0, v3, vcc
	global_load_dword v17, v[8:9], off nt
	v_add_co_u32_e32 v8, vcc, s11, v2
	s_mov_b32 s11, 0x12000
	s_nop 0
	v_addc_co_u32_e32 v9, vcc, 0, v3, vcc
	global_load_dword v18, v[8:9], off nt
	v_add_co_u32_e32 v8, vcc, s11, v2
	s_mov_b32 s11, 0x14000
	s_nop 0
	v_addc_co_u32_e32 v9, vcc, 0, v3, vcc
	global_load_dword v19, v[8:9], off nt
	v_add_co_u32_e32 v8, vcc, s11, v2
	s_mov_b32 s11, 0x16000
	s_nop 0
	v_addc_co_u32_e32 v9, vcc, 0, v3, vcc
	global_load_dword v20, v[8:9], off nt
	v_add_co_u32_e32 v8, vcc, s11, v2
	s_mov_b32 s11, 0x18000
	s_nop 0
	v_addc_co_u32_e32 v9, vcc, 0, v3, vcc
	global_load_dword v21, v[8:9], off nt
	v_add_co_u32_e32 v8, vcc, s11, v2
	s_mov_b32 s11, 0x1a000
	s_nop 0
	v_addc_co_u32_e32 v9, vcc, 0, v3, vcc
	global_load_dword v22, v[8:9], off nt
	v_add_co_u32_e32 v8, vcc, s11, v2
	s_mov_b32 s11, 0x1c000
	s_nop 0
	v_addc_co_u32_e32 v9, vcc, 0, v3, vcc
	global_load_dword v23, v[8:9], off nt
	v_add_co_u32_e32 v8, vcc, s11, v2
	s_mov_b32 s11, 0x1e000
	s_nop 0
	v_addc_co_u32_e32 v9, vcc, 0, v3, vcc
	global_load_dword v24, v[8:9], off nt
	v_add_co_u32_e32 v8, vcc, s11, v2
	s_mov_b32 s11, 0x22000
	s_nop 0
	v_addc_co_u32_e32 v9, vcc, 0, v3, vcc
	global_load_dword v25, v[8:9], off nt
	v_add_co_u32_e32 v8, vcc, s14, v2
	s_lshl_b32 s10, s10, 1
	s_nop 0
	v_addc_co_u32_e32 v9, vcc, 0, v3, vcc
	global_load_dword v26, v[8:9], off nt
	v_add_co_u32_e32 v8, vcc, s11, v2
	s_mov_b32 s11, 0x24000
	s_nop 0
	v_addc_co_u32_e32 v9, vcc, 0, v3, vcc
	global_load_dword v27, v[8:9], off nt
	v_add_co_u32_e32 v8, vcc, s11, v2
	s_mov_b32 s11, 0x26000
	s_nop 0
	v_addc_co_u32_e32 v9, vcc, 0, v3, vcc
	global_load_dword v28, v[8:9], off nt
	v_add_co_u32_e32 v8, vcc, s11, v2
	s_mov_b32 s11, 0x28000
	s_nop 0
	v_addc_co_u32_e32 v9, vcc, 0, v3, vcc
	global_load_dword v29, v[8:9], off nt
	v_add_co_u32_e32 v8, vcc, s11, v2
	s_mov_b32 s11, 0x2a000
	s_nop 0
	v_addc_co_u32_e32 v9, vcc, 0, v3, vcc
	global_load_dword v30, v[8:9], off nt
	v_add_co_u32_e32 v8, vcc, s11, v2
	s_mov_b32 s11, 0x2c000
	s_nop 0
	v_addc_co_u32_e32 v9, vcc, 0, v3, vcc
	global_load_dword v31, v[8:9], off nt
	v_add_co_u32_e32 v8, vcc, s11, v2
	s_mov_b32 s11, 0x2e000
	s_nop 0
	v_addc_co_u32_e32 v9, vcc, 0, v3, vcc
	global_load_dword v32, v[8:9], off nt
	v_add_co_u32_e32 v8, vcc, s11, v2
	s_mov_b32 s11, 0x30000
	s_nop 0
	v_addc_co_u32_e32 v9, vcc, 0, v3, vcc
	global_load_dword v33, v[8:9], off nt
	v_add_co_u32_e32 v8, vcc, s11, v2
	s_mov_b32 s11, 0x32000
	s_nop 0
	v_addc_co_u32_e32 v9, vcc, 0, v3, vcc
	global_load_dword v34, v[8:9], off nt
	v_add_co_u32_e32 v8, vcc, s11, v2
	s_mov_b32 s11, 0x34000
	s_nop 0
	v_addc_co_u32_e32 v9, vcc, 0, v3, vcc
	global_load_dword v35, v[8:9], off nt
	v_add_co_u32_e32 v8, vcc, s11, v2
	s_mov_b32 s11, 0x36000
	s_nop 0
	v_addc_co_u32_e32 v9, vcc, 0, v3, vcc
	global_load_dword v36, v[8:9], off nt
	v_add_co_u32_e32 v8, vcc, s11, v2
	s_mov_b32 s11, 0x38000
	s_nop 0
	v_addc_co_u32_e32 v9, vcc, 0, v3, vcc
	global_load_dword v37, v[8:9], off nt
	v_add_co_u32_e32 v8, vcc, s11, v2
	s_mov_b32 s11, 0x3a000
	s_nop 0
	v_addc_co_u32_e32 v9, vcc, 0, v3, vcc
	global_load_dword v38, v[8:9], off nt
	v_add_co_u32_e32 v8, vcc, s11, v2
	s_mov_b32 s11, 0x3c000
	s_nop 0
	v_addc_co_u32_e32 v9, vcc, 0, v3, vcc
	global_load_dword v39, v[8:9], off nt
	v_add_co_u32_e32 v8, vcc, s11, v2
	s_mov_b32 s11, 0x3e000
	s_nop 0
	v_addc_co_u32_e32 v9, vcc, 0, v3, vcc
	v_add_co_u32_e32 v2, vcc, s11, v2
	global_load_dword v8, v[8:9], off nt
	s_nop 0
	v_addc_co_u32_e32 v3, vcc, 0, v3, vcc
	global_load_dword v2, v[2:3], off nt
	s_movk_i32 s11, 0x84
	v_mul_lo_u32 v3, v10, s11
	v_add3_u32 v3, s19, v6, v3
	s_waitcnt vmcnt(30)
	ds_write2_b32 v3, v0, v11 offset1:66
	s_waitcnt vmcnt(28)
	ds_write2_b32 v3, v12, v13 offset0:132 offset1:198
	v_add_u32_e32 v0, 0x400, v3
	s_waitcnt vmcnt(26)
	ds_write2_b32 v0, v14, v15 offset0:8 offset1:74
	s_waitcnt vmcnt(24)
	ds_write2_b32 v0, v16, v17 offset0:140 offset1:206
	v_add_u32_e32 v0, 0x800, v3
	s_waitcnt vmcnt(22)
	ds_write2_b32 v0, v18, v19 offset0:16 offset1:82
	s_waitcnt vmcnt(20)
	ds_write2_b32 v0, v20, v21 offset0:148 offset1:214
	v_add_u32_e32 v0, 0xc00, v3
	s_waitcnt vmcnt(18)
	ds_write2_b32 v0, v22, v23 offset0:24 offset1:90
	s_waitcnt vmcnt(16)
	ds_write2_b32 v0, v24, v25 offset0:156 offset1:222
	v_add_u32_e32 v0, 0x1000, v3
	s_waitcnt vmcnt(14)
	ds_write2_b32 v0, v26, v27 offset0:32 offset1:98
	s_waitcnt vmcnt(12)
	ds_write2_b32 v0, v28, v29 offset0:164 offset1:230
	v_add_u32_e32 v0, 0x1400, v3
	s_waitcnt vmcnt(10)
	ds_write2_b32 v0, v30, v31 offset0:40 offset1:106
	s_waitcnt vmcnt(8)
	ds_write2_b32 v0, v32, v33 offset0:172 offset1:238
	v_add_u32_e32 v0, 0x1800, v3
	s_waitcnt vmcnt(6)
	ds_write2_b32 v0, v34, v35 offset0:48 offset1:114
	s_waitcnt vmcnt(4)
	ds_write2_b32 v0, v36, v37 offset0:180 offset1:246
	v_add_u32_e32 v0, 0x1c00, v3
	s_waitcnt vmcnt(2)
	ds_write2_b32 v0, v38, v39 offset0:56 offset1:122
	s_waitcnt vmcnt(0)
	ds_write2_b32 v0, v8, v2 offset0:188 offset1:254
	v_lshlrev_b32_e32 v0, 3, v5
	v_and_b32_e32 v0, 56, v0
	s_add_u32 s6, s6, s10
	v_ashrrev_i32_e32 v28, 3, v5
	v_mul_u32_u24_e32 v8, 0x84, v0
	s_addc_u32 s7, s7, 0
	v_lshlrev_b32_e32 v0, 1, v0
	s_waitcnt lgkmcnt(0)
	v_lshl_add_u64 v[2:3], s[6:7], 0, v[0:1]
	v_lshlrev_b32_e32 v0, 2, v28
	v_add3_u32 v0, s19, v8, v0
	ds_read2_b32 v[12:13], v0 offset0:33 offset1:41
	ds_read2_b32 v[14:15], v0 offset1:8
	ds_read2_b32 v[16:17], v0 offset0:66 offset1:74
	ds_read2_b32 v[18:19], v0 offset0:99 offset1:107
	ds_read2_b32 v[20:21], v0 offset0:132 offset1:140
	ds_read2_b32 v[22:23], v0 offset0:165 offset1:173
	ds_read2_b32 v[24:25], v0 offset0:198 offset1:206
	ds_read2_b32 v[26:27], v0 offset0:231 offset1:239
	s_waitcnt lgkmcnt(7)
	s_waitcnt lgkmcnt(6)
	v_cvt_pk_bf16_f32 v8, v14, v12
	s_waitcnt lgkmcnt(5)
	s_waitcnt lgkmcnt(4)
	v_cvt_pk_bf16_f32 v9, v16, v18
	s_waitcnt lgkmcnt(3)
	s_waitcnt lgkmcnt(2)
	v_cvt_pk_bf16_f32 v10, v20, v22
	s_waitcnt lgkmcnt(1)
	s_mov_b64 s[6:7], 0x2600000
	s_waitcnt lgkmcnt(0)
	v_lshl_add_u64 v[2:3], v[2:3], 0, s[6:7]
	v_add_u32_e32 v30, s5, v28
	s_movk_i32 s5, 0x1500
	v_cvt_pk_bf16_f32 v11, v24, v26
	v_mad_i64_i32 v[28:29], s[6:7], v30, s5, v[2:3]
	global_store_dwordx4 v[28:29], v[8:11], off
	s_nop 1
	v_cvt_pk_bf16_f32 v8, v15, v13
	v_cvt_pk_bf16_f32 v9, v17, v19
	v_cvt_pk_bf16_f32 v10, v21, v23
	v_cvt_pk_bf16_f32 v11, v25, v27
	v_add_u32_e32 v12, 8, v30
	v_mad_i64_i32 v[12:13], s[6:7], v12, s5, v[2:3]
	global_store_dwordx4 v[12:13], v[8:11], off
	ds_read2_b32 v[12:13], v0 offset0:49 offset1:57
	ds_read2_b32 v[14:15], v0 offset0:16 offset1:24
	ds_read2_b32 v[16:17], v0 offset0:82 offset1:90
	ds_read2_b32 v[18:19], v0 offset0:115 offset1:123
	ds_read2_b32 v[20:21], v0 offset0:148 offset1:156
	ds_read2_b32 v[22:23], v0 offset0:181 offset1:189
	ds_read2_b32 v[24:25], v0 offset0:214 offset1:222
	ds_read2_b32 v[26:27], v0 offset0:247 offset1:255
	s_waitcnt lgkmcnt(7)
	s_waitcnt lgkmcnt(6)
	v_cvt_pk_bf16_f32 v8, v14, v12
	s_waitcnt lgkmcnt(5)
	s_waitcnt lgkmcnt(4)
	v_cvt_pk_bf16_f32 v9, v16, v18
	s_waitcnt lgkmcnt(3)
	s_waitcnt lgkmcnt(2)
	s_waitcnt lgkmcnt(1)
	v_cvt_pk_bf16_f32 v10, v20, v22
	s_waitcnt lgkmcnt(0)
	v_cvt_pk_bf16_f32 v11, v24, v26
	v_add_u32_e32 v0, 16, v30
	v_mad_i64_i32 v[28:29], s[6:7], v0, s5, v[2:3]
	global_store_dwordx4 v[28:29], v[8:11], off
	s_nop 1
	v_cvt_pk_bf16_f32 v8, v15, v13
	v_cvt_pk_bf16_f32 v9, v17, v19
	v_cvt_pk_bf16_f32 v10, v21, v23
	v_cvt_pk_bf16_f32 v11, v25, v27
	v_add_u32_e32 v0, 24, v30
	v_mad_i64_i32 v[2:3], s[6:7], v0, s5, v[2:3]
	global_store_dwordx4 v[2:3], v[8:11], off
	s_waitcnt lgkmcnt(0)
	s_mov_b64 s[6:7], 0
.LBB0_1319:
	s_andn2_b64 vcc, exec, s[6:7]
	s_cbranch_vccnz .LBB0_1321
	s_load_dwordx2 s[6:7], s[2:3], 0xc8
	s_load_dwordx2 s[10:11], s[2:3], 0x100
	s_mul_i32 s13, s4, 0x1500000
	s_mul_hi_i32 s5, s4, 0x1500000
	s_waitcnt lgkmcnt(0)
	s_add_u32 s16, s6, s13
	s_addc_u32 s17, s7, s5
	s_add_u32 s1, s10, s1
	s_addc_u32 s5, s11, s0
	s_add_i32 s0, s12, 0xf880
	s_bfe_u32 s6, s0, 0xd0003
	s_mulk_i32 s6, 0xc31
	s_lshr_b32 s6, s6, 16
	s_mul_i32 s7, s6, 0xa8
	s_sub_i32 s7, s0, s7
	s_and_b32 s10, s7, 0xffff
	s_lshl_b32 s0, s10, 5
	s_lshl_b32 s10, s10, 4
	s_and_b32 s10, s10, 0xf80
	s_and_b32 s7, s7, 4
	s_add_i32 s11, s10, 0xa80
	s_cmp_eq_u32 s7, 0
	s_cselect_b32 s7, s10, s11
	s_and_b32 s10, s0, 0x60
	s_or_b32 s7, s7, s10
	v_or_b32_e32 v0, s7, v7
	v_ashrrev_i32_e32 v7, 5, v5
	v_lshlrev_b32_e32 v0, 2, v0
	v_lshl_add_u32 v10, s6, 6, v7
	v_lshl_add_u64 v[2:3], s[16:17], 0, v[0:1]
	s_movk_i32 s7, 0x5400
	v_mad_i64_i32 v[8:9], s[10:11], v10, s7, v[2:3]
	global_load_dword v0, v[8:9], off nt
	v_add_u32_e32 v8, 2, v10
	v_mad_i64_i32 v[8:9], s[10:11], v8, s7, v[2:3]
	global_load_dword v11, v[8:9], off nt
	v_add_u32_e32 v8, 4, v10
	v_mad_i64_i32 v[8:9], s[10:11], v8, s7, v[2:3]
	global_load_dword v12, v[8:9], off nt
	v_add_u32_e32 v8, 6, v10
	v_mad_i64_i32 v[8:9], s[10:11], v8, s7, v[2:3]
	global_load_dword v13, v[8:9], off nt
	v_add_u32_e32 v8, 8, v10
	v_mad_i64_i32 v[8:9], s[10:11], v8, s7, v[2:3]
	global_load_dword v14, v[8:9], off nt
	v_add_u32_e32 v8, 10, v10
	v_mad_i64_i32 v[8:9], s[10:11], v8, s7, v[2:3]
	global_load_dword v15, v[8:9], off nt
	v_add_u32_e32 v8, 12, v10
	v_mad_i64_i32 v[8:9], s[10:11], v8, s7, v[2:3]
	global_load_dword v16, v[8:9], off nt
	v_add_u32_e32 v8, 14, v10
	v_mad_i64_i32 v[8:9], s[10:11], v8, s7, v[2:3]
	global_load_dword v17, v[8:9], off nt
	v_add_u32_e32 v8, 16, v10
	v_mad_i64_i32 v[8:9], s[10:11], v8, s7, v[2:3]
	global_load_dword v18, v[8:9], off nt
	v_add_u32_e32 v8, 18, v10
	v_mad_i64_i32 v[8:9], s[10:11], v8, s7, v[2:3]
	global_load_dword v19, v[8:9], off nt
	v_add_u32_e32 v8, 20, v10
	v_mad_i64_i32 v[8:9], s[10:11], v8, s7, v[2:3]
	global_load_dword v20, v[8:9], off nt
	v_add_u32_e32 v8, 22, v10
	v_mad_i64_i32 v[8:9], s[10:11], v8, s7, v[2:3]
	global_load_dword v21, v[8:9], off nt
	v_add_u32_e32 v8, 24, v10
	v_mad_i64_i32 v[8:9], s[10:11], v8, s7, v[2:3]
	global_load_dword v22, v[8:9], off nt
	v_add_u32_e32 v8, 26, v10
	v_mad_i64_i32 v[8:9], s[10:11], v8, s7, v[2:3]
	global_load_dword v23, v[8:9], off nt
	v_add_u32_e32 v8, 28, v10
	v_mad_i64_i32 v[8:9], s[10:11], v8, s7, v[2:3]
	global_load_dword v24, v[8:9], off nt
	v_add_u32_e32 v8, 30, v10
	v_mad_i64_i32 v[8:9], s[10:11], v8, s7, v[2:3]
	global_load_dword v25, v[8:9], off nt
	v_add_u32_e32 v8, 32, v10
	v_mad_i64_i32 v[8:9], s[10:11], v8, s7, v[2:3]
	global_load_dword v26, v[8:9], off nt
	v_add_u32_e32 v8, 34, v10
	v_mad_i64_i32 v[8:9], s[10:11], v8, s7, v[2:3]
	global_load_dword v27, v[8:9], off nt
	v_add_u32_e32 v8, 36, v10
	v_mad_i64_i32 v[8:9], s[10:11], v8, s7, v[2:3]
	global_load_dword v28, v[8:9], off nt
	v_add_u32_e32 v8, 38, v10
	v_mad_i64_i32 v[8:9], s[10:11], v8, s7, v[2:3]
	global_load_dword v29, v[8:9], off nt
	v_add_u32_e32 v8, 40, v10
	v_mad_i64_i32 v[8:9], s[10:11], v8, s7, v[2:3]
	global_load_dword v30, v[8:9], off nt
	v_add_u32_e32 v8, 42, v10
	v_mad_i64_i32 v[8:9], s[10:11], v8, s7, v[2:3]
	global_load_dword v31, v[8:9], off nt
	v_add_u32_e32 v8, 44, v10
	v_mad_i64_i32 v[8:9], s[10:11], v8, s7, v[2:3]
	global_load_dword v32, v[8:9], off nt
	v_add_u32_e32 v8, 46, v10
	v_mad_i64_i32 v[8:9], s[10:11], v8, s7, v[2:3]
	global_load_dword v33, v[8:9], off nt
	v_add_u32_e32 v8, 48, v10
	v_mad_i64_i32 v[8:9], s[10:11], v8, s7, v[2:3]
	global_load_dword v34, v[8:9], off nt
	v_add_u32_e32 v8, 50, v10
	v_mad_i64_i32 v[8:9], s[10:11], v8, s7, v[2:3]
	global_load_dword v35, v[8:9], off nt
	v_add_u32_e32 v8, 52, v10
	v_mad_i64_i32 v[8:9], s[10:11], v8, s7, v[2:3]
	global_load_dword v36, v[8:9], off nt
	v_add_u32_e32 v8, 54, v10
	v_mad_i64_i32 v[8:9], s[10:11], v8, s7, v[2:3]
	global_load_dword v37, v[8:9], off nt
	v_add_u32_e32 v8, 56, v10
	v_mad_i64_i32 v[8:9], s[10:11], v8, s7, v[2:3]
	global_load_dword v38, v[8:9], off nt
	v_add_u32_e32 v8, 58, v10
	v_mad_i64_i32 v[8:9], s[10:11], v8, s7, v[2:3]
	global_load_dword v39, v[8:9], off nt
	v_add_u32_e32 v8, 60, v10
	v_mad_i64_i32 v[8:9], s[10:11], v8, s7, v[2:3]
	global_load_dword v8, v[8:9], off nt
	v_add_u32_e32 v9, 62, v10
	v_mad_i64_i32 v[2:3], s[10:11], v9, s7, v[2:3]
	global_load_dword v2, v[2:3], off nt
	s_movk_i32 s7, 0x84
	v_mul_lo_u32 v3, v7, s7
	v_add3_u32 v3, s19, v6, v3
	s_waitcnt vmcnt(30)
	ds_write2_b32 v3, v0, v11 offset1:66
	s_waitcnt vmcnt(28)
	ds_write2_b32 v3, v12, v13 offset0:132 offset1:198
	v_add_u32_e32 v0, 0x400, v3
	s_waitcnt vmcnt(26)
	ds_write2_b32 v0, v14, v15 offset0:8 offset1:74
	s_waitcnt vmcnt(24)
	ds_write2_b32 v0, v16, v17 offset0:140 offset1:206
	v_add_u32_e32 v0, 0x800, v3
	s_waitcnt vmcnt(22)
	ds_write2_b32 v0, v18, v19 offset0:16 offset1:82
	s_waitcnt vmcnt(20)
	ds_write2_b32 v0, v20, v21 offset0:148 offset1:214
	v_add_u32_e32 v0, 0xc00, v3
	s_waitcnt vmcnt(18)
	ds_write2_b32 v0, v22, v23 offset0:24 offset1:90
	s_waitcnt vmcnt(16)
	ds_write2_b32 v0, v24, v25 offset0:156 offset1:222
	v_add_u32_e32 v0, 0x1000, v3
	s_waitcnt vmcnt(14)
	ds_write2_b32 v0, v26, v27 offset0:32 offset1:98
	s_waitcnt vmcnt(12)
	ds_write2_b32 v0, v28, v29 offset0:164 offset1:230
	v_add_u32_e32 v0, 0x1400, v3
	s_waitcnt vmcnt(10)
	ds_write2_b32 v0, v30, v31 offset0:40 offset1:106
	s_waitcnt vmcnt(8)
	ds_write2_b32 v0, v32, v33 offset0:172 offset1:238
	v_add_u32_e32 v0, 0x1800, v3
	s_waitcnt vmcnt(6)
	ds_write2_b32 v0, v34, v35 offset0:48 offset1:114
	s_waitcnt vmcnt(4)
	ds_write2_b32 v0, v36, v37 offset0:180 offset1:246
	v_add_u32_e32 v0, 0x1c00, v3
	s_waitcnt vmcnt(2)
	ds_write2_b32 v0, v38, v39 offset0:56 offset1:122
	s_waitcnt vmcnt(0)
	ds_write2_b32 v0, v8, v2 offset0:188 offset1:254
	v_lshlrev_b32_e32 v0, 3, v5
	s_lshl_b32 s6, s6, 7
	v_and_b32_e32 v0, 56, v0
	s_add_u32 s6, s1, s6
	v_ashrrev_i32_e32 v26, 3, v5
	v_mul_u32_u24_e32 v6, 0x84, v0
	s_addc_u32 s7, s5, 0
	v_lshlrev_b32_e32 v0, 1, v0
	s_waitcnt lgkmcnt(0)
	v_lshl_add_u64 v[2:3], s[6:7], 0, v[0:1]
	v_lshlrev_b32_e32 v0, 2, v26
	v_add3_u32 v0, s19, v6, v0
	ds_read2_b32 v[10:11], v0 offset0:33 offset1:41
	ds_read2_b32 v[12:13], v0 offset1:8
	ds_read2_b32 v[14:15], v0 offset0:66 offset1:74
	ds_read2_b32 v[16:17], v0 offset0:99 offset1:107
	ds_read2_b32 v[18:19], v0 offset0:132 offset1:140
	ds_read2_b32 v[20:21], v0 offset0:165 offset1:173
	ds_read2_b32 v[22:23], v0 offset0:198 offset1:206
	ds_read2_b32 v[24:25], v0 offset0:231 offset1:239
	s_waitcnt lgkmcnt(7)
	s_waitcnt lgkmcnt(6)
	v_cvt_pk_bf16_f32 v6, v12, v10
	s_waitcnt lgkmcnt(5)
	s_waitcnt lgkmcnt(4)
	v_cvt_pk_bf16_f32 v7, v14, v16
	s_waitcnt lgkmcnt(3)
	s_waitcnt lgkmcnt(2)
	v_cvt_pk_bf16_f32 v8, v18, v20
	s_waitcnt lgkmcnt(1)
	v_add_u32_e32 v26, s0, v26
	s_mov_b64 s[6:7], 0x1100000
	s_waitcnt lgkmcnt(0)
	v_ashrrev_i32_e32 v27, 31, v26
	v_lshl_add_u64 v[2:3], v[2:3], 0, s[6:7]
	v_lshlrev_b64 v[28:29], 11, v[26:27]
	v_cvt_pk_bf16_f32 v9, v22, v24
	v_lshl_add_u64 v[28:29], v[2:3], 0, v[28:29]
	global_store_dwordx4 v[28:29], v[6:9], off
	s_nop 1
	v_cvt_pk_bf16_f32 v6, v13, v11
	v_cvt_pk_bf16_f32 v7, v15, v17
	v_cvt_pk_bf16_f32 v8, v19, v21
	v_cvt_pk_bf16_f32 v9, v23, v25
	v_add_u32_e32 v10, 8, v26
	v_ashrrev_i32_e32 v11, 31, v10
	v_lshlrev_b64 v[10:11], 11, v[10:11]
	v_lshl_add_u64 v[10:11], v[2:3], 0, v[10:11]
	global_store_dwordx4 v[10:11], v[6:9], off
	ds_read2_b32 v[10:11], v0 offset0:49 offset1:57
	ds_read2_b32 v[12:13], v0 offset0:16 offset1:24
	ds_read2_b32 v[14:15], v0 offset0:82 offset1:90
	ds_read2_b32 v[16:17], v0 offset0:115 offset1:123
	ds_read2_b32 v[18:19], v0 offset0:148 offset1:156
	ds_read2_b32 v[20:21], v0 offset0:181 offset1:189
	ds_read2_b32 v[22:23], v0 offset0:214 offset1:222
	ds_read2_b32 v[24:25], v0 offset0:247 offset1:255
	s_waitcnt lgkmcnt(7)
	s_waitcnt lgkmcnt(6)
	v_cvt_pk_bf16_f32 v6, v12, v10
	s_waitcnt lgkmcnt(5)
	s_waitcnt lgkmcnt(4)
	v_cvt_pk_bf16_f32 v7, v14, v16
	s_waitcnt lgkmcnt(3)
	s_waitcnt lgkmcnt(2)
	s_waitcnt lgkmcnt(1)
	v_add_u32_e32 v28, 16, v26
	v_cvt_pk_bf16_f32 v8, v18, v20
	s_waitcnt lgkmcnt(0)
	v_ashrrev_i32_e32 v29, 31, v28
	v_lshlrev_b64 v[28:29], 11, v[28:29]
	v_cvt_pk_bf16_f32 v9, v22, v24
	v_lshl_add_u64 v[28:29], v[2:3], 0, v[28:29]
	global_store_dwordx4 v[28:29], v[6:9], off
	s_nop 1
	v_cvt_pk_bf16_f32 v6, v13, v11
	v_cvt_pk_bf16_f32 v7, v15, v17
	v_cvt_pk_bf16_f32 v8, v19, v21
	v_add_u32_e32 v10, 24, v26
	v_ashrrev_i32_e32 v11, 31, v10
	v_lshlrev_b64 v[10:11], 11, v[10:11]
	v_cvt_pk_bf16_f32 v9, v23, v25
	v_lshl_add_u64 v[2:3], v[2:3], 0, v[10:11]
	global_store_dwordx4 v[2:3], v[6:9], off
	s_waitcnt lgkmcnt(0)

.LBB0_1322:
	s_andn2_b64 vcc, exec, s[6:7]
	s_cbranch_vccnz .LBB0_1324
	s_load_dwordx2 s[0:1], s[2:3], 0xb0
	s_ashr_i32 s5, s4, 31
	s_lshl_b64 s[6:7], s[4:5], 22
	v_and_b32_e32 v8, 31, v5
	v_ashrrev_i32_e32 v9, 5, v5
	s_waitcnt lgkmcnt(0)
	s_add_u32 s10, s0, s6
	s_addc_u32 s11, s1, s7
	s_load_dwordx2 s[6:7], s[2:3], 0x100
	s_lshl_b64 s[16:17], s[4:5], 21
	s_mul_i32 s0, s4, 0xffffd180
	s_waitcnt lgkmcnt(0)
	s_add_u32 s1, s6, s16
	s_addc_u32 s5, s7, s17
	s_add_i32 s0, s21, s0
	s_and_b32 s6, s0, 0xfc0
	s_and_b32 s0, s20, 0x3e0
	v_or_b32_e32 v0, s0, v8
	v_add_u32_e32 v2, s6, v9
	v_lshlrev_b32_e32 v0, 2, v0
	v_ashrrev_i32_e32 v3, 31, v2
	v_lshl_add_u64 v[6:7], s[10:11], 0, v[0:1]
	v_lshlrev_b64 v[2:3], 12, v[2:3]
	v_lshl_add_u64 v[2:3], v[6:7], 0, v[2:3]
	s_movk_i32 s7, 0x2000
	v_add_co_u32_e32 v6, vcc, s7, v2
	s_movk_i32 s7, 0x4000
	s_nop 0
	v_addc_co_u32_e32 v7, vcc, 0, v3, vcc
	global_load_dword v0, v[2:3], off nt
	global_load_dword v10, v[6:7], off nt
	v_add_co_u32_e32 v6, vcc, s7, v2
	s_movk_i32 s7, 0x6000
	s_nop 0
	v_addc_co_u32_e32 v7, vcc, 0, v3, vcc
	global_load_dword v11, v[6:7], off nt
	v_add_co_u32_e32 v6, vcc, s7, v2
	s_mov_b32 s7, 0x8000
	s_nop 0
	v_addc_co_u32_e32 v7, vcc, 0, v3, vcc
	global_load_dword v12, v[6:7], off nt
	v_add_co_u32_e32 v6, vcc, s7, v2
	s_mov_b32 s7, 0xa000
	s_nop 0
	v_addc_co_u32_e32 v7, vcc, 0, v3, vcc
	global_load_dword v13, v[6:7], off nt
	v_add_co_u32_e32 v6, vcc, s7, v2
	s_mov_b32 s7, 0xc000
	s_nop 0
	v_addc_co_u32_e32 v7, vcc, 0, v3, vcc
	global_load_dword v14, v[6:7], off nt
	v_add_co_u32_e32 v6, vcc, s7, v2
	s_mov_b32 s7, 0xe000
	s_nop 0
	v_addc_co_u32_e32 v7, vcc, 0, v3, vcc
	global_load_dword v15, v[6:7], off nt
	v_add_co_u32_e32 v6, vcc, s7, v2
	s_mov_b32 s7, 0x10000
	s_nop 0
	v_addc_co_u32_e32 v7, vcc, 0, v3, vcc
	global_load_dword v16, v[6:7], off nt
	v_add_co_u32_e32 v6, vcc, s7, v2
	s_mov_b32 s7, 0x12000
	s_nop 0
	v_addc_co_u32_e32 v7, vcc, 0, v3, vcc
	global_load_dword v17, v[6:7], off nt
	v_add_co_u32_e32 v6, vcc, s7, v2
	s_mov_b32 s7, 0x14000
	s_nop 0
	v_addc_co_u32_e32 v7, vcc, 0, v3, vcc
	global_load_dword v18, v[6:7], off nt
	v_add_co_u32_e32 v6, vcc, s7, v2
	s_mov_b32 s7, 0x16000
	s_nop 0
	v_addc_co_u32_e32 v7, vcc, 0, v3, vcc
	global_load_dword v19, v[6:7], off nt
	v_add_co_u32_e32 v6, vcc, s7, v2
	s_mov_b32 s7, 0x18000
	s_nop 0
	v_addc_co_u32_e32 v7, vcc, 0, v3, vcc
	global_load_dword v20, v[6:7], off nt
	v_add_co_u32_e32 v6, vcc, s7, v2
	s_mov_b32 s7, 0x1a000
	s_nop 0
	v_addc_co_u32_e32 v7, vcc, 0, v3, vcc
	global_load_dword v21, v[6:7], off nt
	v_add_co_u32_e32 v6, vcc, s7, v2
	s_mov_b32 s7, 0x1c000
	s_nop 0
	v_addc_co_u32_e32 v7, vcc, 0, v3, vcc
	global_load_dword v22, v[6:7], off nt
	v_add_co_u32_e32 v6, vcc, s7, v2
	s_mov_b32 s7, 0x1e000
	s_nop 0
	v_addc_co_u32_e32 v7, vcc, 0, v3, vcc
	global_load_dword v23, v[6:7], off nt
	v_add_co_u32_e32 v6, vcc, s7, v2
	s_mov_b32 s7, 0x22000
	s_nop 0
	v_addc_co_u32_e32 v7, vcc, 0, v3, vcc
	global_load_dword v24, v[6:7], off nt
	v_add_co_u32_e32 v6, vcc, s14, v2
	s_lshl_b32 s6, s6, 1
	s_nop 0
	v_addc_co_u32_e32 v7, vcc, 0, v3, vcc
	global_load_dword v25, v[6:7], off nt
	v_add_co_u32_e32 v6, vcc, s7, v2
	s_mov_b32 s7, 0x24000
	s_nop 0
	v_addc_co_u32_e32 v7, vcc, 0, v3, vcc
	global_load_dword v26, v[6:7], off nt
	v_add_co_u32_e32 v6, vcc, s7, v2
	s_mov_b32 s7, 0x26000
	s_nop 0
	v_addc_co_u32_e32 v7, vcc, 0, v3, vcc
	global_load_dword v27, v[6:7], off nt
	v_add_co_u32_e32 v6, vcc, s7, v2
	s_mov_b32 s7, 0x28000
	s_nop 0
	v_addc_co_u32_e32 v7, vcc, 0, v3, vcc
	global_load_dword v28, v[6:7], off nt
	v_add_co_u32_e32 v6, vcc, s7, v2
	s_mov_b32 s7, 0x2a000
	s_nop 0
	v_addc_co_u32_e32 v7, vcc, 0, v3, vcc
	global_load_dword v29, v[6:7], off nt
	v_add_co_u32_e32 v6, vcc, s7, v2
	s_mov_b32 s7, 0x2c000
	s_nop 0
	v_addc_co_u32_e32 v7, vcc, 0, v3, vcc
	global_load_dword v30, v[6:7], off nt
	v_add_co_u32_e32 v6, vcc, s7, v2
	s_mov_b32 s7, 0x2e000
	s_nop 0
	v_addc_co_u32_e32 v7, vcc, 0, v3, vcc
	global_load_dword v31, v[6:7], off nt
	v_add_co_u32_e32 v6, vcc, s7, v2
	s_mov_b32 s7, 0x30000
	s_nop 0
	v_addc_co_u32_e32 v7, vcc, 0, v3, vcc
	global_load_dword v32, v[6:7], off nt
	v_add_co_u32_e32 v6, vcc, s7, v2
	s_mov_b32 s7, 0x32000
	s_nop 0
	v_addc_co_u32_e32 v7, vcc, 0, v3, vcc
	global_load_dword v33, v[6:7], off nt
	v_add_co_u32_e32 v6, vcc, s7, v2
	s_mov_b32 s7, 0x34000
	s_nop 0
	v_addc_co_u32_e32 v7, vcc, 0, v3, vcc
	global_load_dword v34, v[6:7], off nt
	v_add_co_u32_e32 v6, vcc, s7, v2
	s_mov_b32 s7, 0x36000
	s_nop 0
	v_addc_co_u32_e32 v7, vcc, 0, v3, vcc
	global_load_dword v35, v[6:7], off nt
	v_add_co_u32_e32 v6, vcc, s7, v2
	s_mov_b32 s7, 0x38000
	s_nop 0
	v_addc_co_u32_e32 v7, vcc, 0, v3, vcc
	global_load_dword v36, v[6:7], off nt
	v_add_co_u32_e32 v6, vcc, s7, v2
	s_mov_b32 s7, 0x3a000
	s_nop 0
	v_addc_co_u32_e32 v7, vcc, 0, v3, vcc
	global_load_dword v37, v[6:7], off nt
	v_add_co_u32_e32 v6, vcc, s7, v2
	s_mov_b32 s7, 0x3c000
	s_nop 0
	v_addc_co_u32_e32 v7, vcc, 0, v3, vcc
	global_load_dword v38, v[6:7], off nt
	v_add_co_u32_e32 v6, vcc, s7, v2
	s_mov_b32 s7, 0x3e000
	s_nop 0
	v_addc_co_u32_e32 v7, vcc, 0, v3, vcc
	v_add_co_u32_e32 v2, vcc, s7, v2
	global_load_dword v6, v[6:7], off nt
	s_nop 0
	v_addc_co_u32_e32 v3, vcc, 0, v3, vcc
	global_load_dword v2, v[2:3], off nt
	s_movk_i32 s7, 0x84
	v_lshlrev_b32_e32 v3, 2, v8
	v_mul_lo_u32 v7, v9, s7
	v_add3_u32 v3, s19, v3, v7
	s_waitcnt vmcnt(30)
	ds_write2_b32 v3, v0, v10 offset1:66
	s_waitcnt vmcnt(28)
	ds_write2_b32 v3, v11, v12 offset0:132 offset1:198
	v_add_u32_e32 v0, 0x400, v3
	s_waitcnt vmcnt(26)
	ds_write2_b32 v0, v13, v14 offset0:8 offset1:74
	s_waitcnt vmcnt(24)
	ds_write2_b32 v0, v15, v16 offset0:140 offset1:206
	v_add_u32_e32 v0, 0x800, v3
	s_waitcnt vmcnt(22)
	ds_write2_b32 v0, v17, v18 offset0:16 offset1:82
	s_waitcnt vmcnt(20)
	ds_write2_b32 v0, v19, v20 offset0:148 offset1:214
	v_add_u32_e32 v0, 0xc00, v3
	s_waitcnt vmcnt(18)
	ds_write2_b32 v0, v21, v22 offset0:24 offset1:90
	s_waitcnt vmcnt(16)
	ds_write2_b32 v0, v23, v24 offset0:156 offset1:222
	v_add_u32_e32 v0, 0x1000, v3
	s_waitcnt vmcnt(14)
	ds_write2_b32 v0, v25, v26 offset0:32 offset1:98
	s_waitcnt vmcnt(12)
	ds_write2_b32 v0, v27, v28 offset0:164 offset1:230
	v_add_u32_e32 v0, 0x1400, v3
	s_waitcnt vmcnt(10)
	ds_write2_b32 v0, v29, v30 offset0:40 offset1:106
	s_waitcnt vmcnt(8)
	ds_write2_b32 v0, v31, v32 offset0:172 offset1:238
	v_add_u32_e32 v0, 0x1800, v3
	s_waitcnt vmcnt(6)
	ds_write2_b32 v0, v33, v34 offset0:48 offset1:114
	s_waitcnt vmcnt(4)
	ds_write2_b32 v0, v35, v36 offset0:180 offset1:246
	v_add_u32_e32 v0, 0x1c00, v3
	s_waitcnt vmcnt(2)
	ds_write2_b32 v0, v37, v38 offset0:56 offset1:122
	s_waitcnt vmcnt(0)
	ds_write2_b32 v0, v6, v2 offset0:188 offset1:254
	v_lshlrev_b32_e32 v0, 3, v5
	v_and_b32_e32 v0, 56, v0
	s_add_u32 s6, s1, s6
	v_ashrrev_i32_e32 v26, 3, v5
	v_mul_u32_u24_e32 v6, 0x84, v0
	s_addc_u32 s7, s5, 0
	v_lshlrev_b32_e32 v0, 1, v0
	s_waitcnt lgkmcnt(0)
	v_lshl_add_u64 v[2:3], s[6:7], 0, v[0:1]
	v_lshlrev_b32_e32 v0, 2, v26
	v_add3_u32 v0, s19, v6, v0
	ds_read2_b32 v[10:11], v0 offset0:33 offset1:41
	ds_read2_b32 v[12:13], v0 offset1:8
	ds_read2_b32 v[14:15], v0 offset0:66 offset1:74
	ds_read2_b32 v[16:17], v0 offset0:99 offset1:107
	ds_read2_b32 v[18:19], v0 offset0:132 offset1:140
	ds_read2_b32 v[20:21], v0 offset0:165 offset1:173
	ds_read2_b32 v[22:23], v0 offset0:198 offset1:206
	ds_read2_b32 v[24:25], v0 offset0:231 offset1:239
	s_waitcnt lgkmcnt(7)
	s_waitcnt lgkmcnt(6)
	v_cvt_pk_bf16_f32 v6, v12, v10
	s_waitcnt lgkmcnt(5)
	s_waitcnt lgkmcnt(4)
	v_cvt_pk_bf16_f32 v7, v14, v16
	s_waitcnt lgkmcnt(3)
	s_waitcnt lgkmcnt(2)
	v_cvt_pk_bf16_f32 v8, v18, v20
	s_waitcnt lgkmcnt(1)
	v_add_u32_e32 v26, s0, v26
	s_mov_b64 s[6:7], 0xd00000
	s_waitcnt lgkmcnt(0)
	v_ashrrev_i32_e32 v27, 31, v26
	v_lshl_add_u64 v[2:3], v[2:3], 0, s[6:7]
	v_lshlrev_b64 v[28:29], 11, v[26:27]
	v_cvt_pk_bf16_f32 v9, v22, v24
	v_lshl_add_u64 v[28:29], v[2:3], 0, v[28:29]
	global_store_dwordx4 v[28:29], v[6:9], off
	s_nop 1
	v_cvt_pk_bf16_f32 v6, v13, v11
	v_cvt_pk_bf16_f32 v7, v15, v17
	v_cvt_pk_bf16_f32 v8, v19, v21
	v_cvt_pk_bf16_f32 v9, v23, v25
	v_add_u32_e32 v10, 8, v26
	v_ashrrev_i32_e32 v11, 31, v10
	v_lshlrev_b64 v[10:11], 11, v[10:11]
	v_lshl_add_u64 v[10:11], v[2:3], 0, v[10:11]
	global_store_dwordx4 v[10:11], v[6:9], off
	ds_read2_b32 v[10:11], v0 offset0:49 offset1:57
	ds_read2_b32 v[12:13], v0 offset0:16 offset1:24
	ds_read2_b32 v[14:15], v0 offset0:82 offset1:90
	ds_read2_b32 v[16:17], v0 offset0:115 offset1:123
	ds_read2_b32 v[18:19], v0 offset0:148 offset1:156
	ds_read2_b32 v[20:21], v0 offset0:181 offset1:189
	ds_read2_b32 v[22:23], v0 offset0:214 offset1:222
	ds_read2_b32 v[24:25], v0 offset0:247 offset1:255
	s_waitcnt lgkmcnt(7)
	s_waitcnt lgkmcnt(6)
	v_cvt_pk_bf16_f32 v6, v12, v10
	s_waitcnt lgkmcnt(5)
	s_waitcnt lgkmcnt(4)
	v_cvt_pk_bf16_f32 v7, v14, v16
	s_waitcnt lgkmcnt(3)
	s_waitcnt lgkmcnt(2)
	s_waitcnt lgkmcnt(1)
	v_add_u32_e32 v28, 16, v26
	v_cvt_pk_bf16_f32 v8, v18, v20
	s_waitcnt lgkmcnt(0)
	v_ashrrev_i32_e32 v29, 31, v28
	v_lshlrev_b64 v[28:29], 11, v[28:29]
	v_cvt_pk_bf16_f32 v9, v22, v24
	v_lshl_add_u64 v[28:29], v[2:3], 0, v[28:29]
	global_store_dwordx4 v[28:29], v[6:9], off
	s_nop 1
	v_cvt_pk_bf16_f32 v6, v13, v11
	v_cvt_pk_bf16_f32 v7, v15, v17
	v_cvt_pk_bf16_f32 v8, v19, v21
	v_add_u32_e32 v10, 24, v26
	v_ashrrev_i32_e32 v11, 31, v10
	v_lshlrev_b64 v[10:11], 11, v[10:11]
	v_cvt_pk_bf16_f32 v9, v23, v25
	v_lshl_add_u64 v[2:3], v[2:3], 0, v[10:11]
	global_store_dwordx4 v[2:3], v[6:9], off
	s_waitcnt lgkmcnt(0)

.LBB0_1469:
	s_cmp_gt_i32 s22, 63
	s_cselect_b64 s[0:1], -1, 0
	s_and_b32 s19, s22, 7
	s_cmp_eq_u32 s19, 0
	s_cselect_b64 s[20:21], -1, 0
	s_or_b64 s[0:1], s[0:1], s[20:21]
	s_and_b64 vcc, exec, s[0:1]
	s_cbranch_vccnz .LBB0_1460
	s_and_saveexec_b64 s[38:39], s[36:37]
	s_cbranch_execz .LBB0_1459
	s_load_dwordx4 s[40:43], s[2:3], 0xd0
	s_load_dwordx2 s[20:21], s[2:3], 0x100
	s_lshl_b32 s19, s22, 1
	s_mov_b32 s25, s22
	s_mulk_i32 s22, 0x5400
	s_add_i32 s0, s19, -2
	s_add_i32 s1, s22, 0xffffac00
	s_mul_hi_i32 s24, s0, 0x2a00
	s_waitcnt lgkmcnt(0)
	s_add_u32 s0, s20, s1
	s_addc_u32 s1, s21, s24
	v_lshlrev_b64 v[2:3], 2, v[82:83]
	v_lshl_add_u64 v[4:5], s[0:1], 0, v[2:3]
	s_mov_b64 s[0:1], 0x1d260000
	v_lshl_add_u64 v[6:7], v[4:5], 0, s[0:1]
	s_mul_hi_i32 s1, s19, 0x2a00
	s_add_u32 s0, s20, s22
	s_addc_u32 s1, s21, s1
	v_lshl_add_u64 v[18:19], s[0:1], 0, v[2:3]
	s_mov_b64 s[0:1], 0x1d460000
	v_lshl_add_u64 v[10:11], v[18:19], 0, s[0:1]
	s_mov_b64 s[0:1], 0x1d660000
	v_lshl_add_u64 v[20:21], v[18:19], 0, s[0:1]
	s_add_u32 s0, s40, s6
	s_addc_u32 s1, s41, s7
	v_lshl_add_u64 v[26:27], s[0:1], 0, v[2:3]
	s_add_u32 s0, s42, s10
	s_addc_u32 s1, s43, s11
	v_lshl_add_u64 v[66:67], s[0:1], 0, v[2:3]
	s_mov_b64 s[0:1], 0x1d262a00
	v_lshl_add_u64 v[2:3], v[4:5], 0, s[0:1]
	s_mov_b64 s[0:1], 0x1d462a00
	v_lshl_add_u64 v[12:13], v[18:19], 0, s[0:1]
	s_mov_b64 s[0:1], 0x1d662a00
	v_lshl_add_u64 v[28:29], v[18:19], 0, s[0:1]
	s_mov_b64 s[0:1], 0x2a00
	v_lshl_add_u64 v[30:31], v[26:27], 0, s[0:1]
	s_mov_b64 s[0:1], 0x5400
	v_lshl_add_u64 v[32:33], v[26:27], 0, s[0:1]
	s_mov_b32 s0, 0x1d260000
	v_add_co_u32_e32 v8, vcc, s0, v4
	s_mov_b32 s0, 0x1d262000
	s_nop 0
	v_addc_co_u32_e32 v9, vcc, 0, v5, vcc
	v_add_co_u32_e32 v4, vcc, s0, v4
	s_mov_b32 s0, 0x1d460000
	s_nop 0
	v_addc_co_u32_e32 v5, vcc, 0, v5, vcc
	global_load_dwordx4 v[78:81], v[8:9], off
	global_load_dwordx4 v[70:73], v[6:7], off offset:16
	global_load_dwordx4 v[38:41], v[4:5], off offset:2560
	s_nop 0
	global_load_dwordx4 v[6:9], v[2:3], off offset:16
	v_add_co_u32_e32 v2, vcc, s0, v18
	s_mov_b32 s0, 0x1d462000
	s_nop 0
	v_addc_co_u32_e32 v3, vcc, 0, v19, vcc
	global_load_dwordx4 v[46:49], v[2:3], off
	global_load_dwordx4 v[14:17], v[10:11], off offset:16
	v_add_co_u32_e32 v2, vcc, s0, v18
	s_mov_b32 s0, 0x1d660000
	s_nop 0
	v_addc_co_u32_e32 v3, vcc, 0, v19, vcc
	global_load_dwordx4 v[42:45], v[2:3], off offset:2560
	s_nop 0
	global_load_dwordx4 v[10:13], v[12:13], off offset:16
	v_add_co_u32_e32 v2, vcc, s0, v18
	s_mov_b32 s0, 0x1d662000
	s_nop 0
	v_addc_co_u32_e32 v3, vcc, 0, v19, vcc
	global_load_dwordx4 v[74:77], v[2:3], off
	global_load_dwordx4 v[50:53], v[20:21], off offset:16
	v_add_co_u32_e32 v2, vcc, s0, v18
	s_movk_i32 s0, 0x2000
	s_nop 0
	v_addc_co_u32_e32 v3, vcc, 0, v19, vcc
	global_load_dwordx4 v[22:25], v[2:3], off offset:2560
	s_nop 0
	global_load_dwordx4 v[2:5], v[28:29], off offset:16
	global_load_dwordx4 v[18:21], v[26:27], off offset:16
	global_load_dwordx4 v[54:57], v[26:27], off
	v_add_co_u32_e32 v28, vcc, s0, v26
	s_movk_i32 s0, 0x5000
	s_nop 0
	v_addc_co_u32_e32 v29, vcc, 0, v27, vcc
	global_load_dwordx4 v[62:65], v[28:29], off offset:2560
	global_load_dwordx4 v[34:37], v[30:31], off offset:16
	v_add_co_u32_e32 v26, vcc, s0, v26
	s_add_u32 s19, s20, 0x1d860000
	s_nop 0
	v_addc_co_u32_e32 v27, vcc, 0, v27, vcc
	global_load_dwordx4 v[58:61], v[26:27], off offset:1024
	s_nop 0
	global_load_dwordx4 v[30:33], v[32:33], off offset:16
	s_nop 0
	global_load_dwordx4 v[26:29], v[66:67], off offset:16
	s_nop 0
	global_load_dwordx4 v[66:69], v[66:67], off
	s_addc_u32 s20, s21, 0
	s_mov_b32 s22, s25
	s_waitcnt vmcnt(5)
	v_pk_mul_f32 v[84:85], v[40:41], v[64:65]
	v_pk_mul_f32 v[86:87], v[38:39], v[62:63]
	v_pk_fma_f32 v[80:81], v[80:81], v[56:57], v[84:85]
	v_pk_fma_f32 v[78:79], v[78:79], v[54:55], v[86:87]
	s_waitcnt vmcnt(3)
	v_pk_fma_f32 v[80:81], v[48:49], v[60:61], v[80:81]
	v_pk_fma_f32 v[78:79], v[46:47], v[58:59], v[78:79]
	v_pk_mul_f32 v[48:49], v[48:49], v[64:65]
	s_waitcnt vmcnt(0)
	v_pk_add_f32 v[84:85], v[68:69], v[80:81]
	v_pk_add_f32 v[80:81], v[66:67], v[78:79]
	v_pk_mul_f32 v[46:47], v[46:47], v[62:63]
	v_mul_f32_e32 v0, 0xbfb8aa3b, v80
	v_fma_f32 v78, v80, s34, -v0
	v_rndne_f32_e32 v79, v0
	v_fmac_f32_e32 v78, 0xb2a5705f, v80
	v_sub_f32_e32 v0, v0, v79
	v_add_f32_e32 v0, v0, v78
	v_exp_f32_e32 v0, v0
	v_cvt_i32_f32_e32 v78, v79
	v_cmp_nlt_f32_e32 vcc, s55, v80
	v_pk_fma_f32 v[40:41], v[40:41], v[56:57], v[48:49]
	v_pk_fma_f32 v[38:39], v[38:39], v[54:55], v[46:47]
	v_ldexp_f32 v0, v0, v78
	v_cndmask_b32_e32 v0, 0, v0, vcc
	v_cmp_ngt_f32_e32 vcc, s56, v80
	v_pk_fma_f32 v[40:41], v[44:45], v[60:61], v[40:41]
	v_pk_fma_f32 v[38:39], v[42:43], v[58:59], v[38:39]
	v_cndmask_b32_e32 v78, v219, v0, vcc
	v_mul_f32_e32 v0, 0xbfb8aa3b, v81
	v_fma_f32 v79, v81, s34, -v0
	v_rndne_f32_e32 v86, v0
	v_fmac_f32_e32 v79, 0xb2a5705f, v81
	v_sub_f32_e32 v0, v0, v86
	v_add_f32_e32 v0, v0, v79
	v_exp_f32_e32 v0, v0
	v_cvt_i32_f32_e32 v79, v86
	v_cmp_nlt_f32_e32 vcc, s55, v81
	v_pk_add_f32 v[42:43], v[68:69], v[40:41]
	v_pk_add_f32 v[40:41], v[66:67], v[38:39]
	v_ldexp_f32 v0, v0, v79
	v_cndmask_b32_e32 v0, 0, v0, vcc
	v_cmp_ngt_f32_e32 vcc, s56, v81
	s_nop 1
	v_cndmask_b32_e32 v86, v219, v0, vcc
	v_mul_f32_e32 v0, 0xbfb8aa3b, v84
	v_fma_f32 v79, v84, s34, -v0
	v_rndne_f32_e32 v87, v0
	v_fmac_f32_e32 v79, 0xb2a5705f, v84
	v_sub_f32_e32 v0, v0, v87
	v_add_f32_e32 v0, v0, v79
	v_exp_f32_e32 v0, v0
	v_cvt_i32_f32_e32 v79, v87
	v_cmp_nlt_f32_e32 vcc, s55, v84
	v_ldexp_f32 v0, v0, v79
	s_nop 0
	v_cndmask_b32_e32 v0, 0, v0, vcc
	v_cmp_ngt_f32_e32 vcc, s56, v84
	s_nop 1
	v_cndmask_b32_e32 v79, v219, v0, vcc
	v_pk_add_f32 v[78:79], v[78:79], 1.0 op_sel_hi:[1,0]
	s_nop 0
	v_div_scale_f32 v0, s[0:1], v79, v79, v84
	v_rcp_f32_e32 v87, v0
	s_nop 0
	v_fma_f32 v88, -v0, v87, 1.0
	v_fmac_f32_e32 v87, v88, v87
	v_div_scale_f32 v88, vcc, v84, v79, v84
	v_mul_f32_e32 v89, v88, v87
	v_fma_f32 v90, -v0, v89, v88
	v_fmac_f32_e32 v89, v90, v87
	v_fma_f32 v0, -v0, v89, v88
	v_div_fmas_f32 v0, v0, v87, v89
	v_div_fixup_f32 v79, v0, v79, v84
	v_div_scale_f32 v0, s[0:1], v78, v78, v80
	v_rcp_f32_e32 v84, v0
	s_nop 0
	v_fma_f32 v87, -v0, v84, 1.0
	v_fmac_f32_e32 v84, v87, v84
	v_div_scale_f32 v87, vcc, v80, v78, v80
	v_mul_f32_e32 v88, v87, v84
	v_fma_f32 v89, -v0, v88, v87
	v_fmac_f32_e32 v88, v89, v84
	v_fma_f32 v0, -v0, v88, v87
	v_div_fmas_f32 v0, v0, v84, v88
	v_div_fixup_f32 v78, v0, v78, v80
	v_mul_f32_e32 v0, 0xbfb8aa3b, v85
	v_mov_b32_e32 v88, v74
	v_mov_b32_e32 v89, v76
	v_fma_f32 v74, v85, s34, -v0
	v_rndne_f32_e32 v76, v0
	v_fmac_f32_e32 v74, 0xb2a5705f, v85
	v_sub_f32_e32 v0, v0, v76
	v_add_f32_e32 v0, v0, v74
	v_exp_f32_e32 v0, v0
	v_cvt_i32_f32_e32 v74, v76
	v_cmp_nlt_f32_e32 vcc, s55, v85
	v_pk_mul_f32 v[78:79], v[88:89], v[78:79]
	v_ldexp_f32 v0, v0, v74
	v_cndmask_b32_e32 v0, 0, v0, vcc
	v_cmp_ngt_f32_e32 vcc, s56, v85
	s_nop 1
	v_cndmask_b32_e32 v87, v219, v0, vcc
	v_pk_add_f32 v[86:87], v[86:87], 1.0 op_sel_hi:[1,0]
	s_nop 0
	v_div_scale_f32 v0, s[0:1], v87, v87, v85
	v_rcp_f32_e32 v74, v0
	s_nop 0
	v_fma_f32 v76, -v0, v74, 1.0
	v_fmac_f32_e32 v74, v76, v74
	v_div_scale_f32 v76, vcc, v85, v87, v85
	v_mul_f32_e32 v80, v76, v74
	v_fma_f32 v84, -v0, v80, v76
	v_fmac_f32_e32 v80, v84, v74
	v_fma_f32 v0, -v0, v80, v76
	v_div_fmas_f32 v0, v0, v74, v80
	v_div_fixup_f32 v85, v0, v87, v85
	v_div_scale_f32 v0, s[0:1], v86, v86, v81
	v_rcp_f32_e32 v74, v0
	s_nop 0
	v_fma_f32 v76, -v0, v74, 1.0
	v_fmac_f32_e32 v74, v76, v74
	v_div_scale_f32 v76, vcc, v81, v86, v81
	v_mul_f32_e32 v80, v76, v74
	v_fma_f32 v84, -v0, v80, v76
	v_fmac_f32_e32 v80, v84, v74
	v_fma_f32 v0, -v0, v80, v76
	v_div_fmas_f32 v0, v0, v74, v80
	v_div_fixup_f32 v84, v0, v86, v81
	v_pk_mul_f32 v[80:81], v[6:7], v[34:35]
	v_mov_b32_e32 v76, v75
	v_pk_fma_f32 v[70:71], v[70:71], v[18:19], v[80:81]
	v_pk_mul_f32 v[74:75], v[76:77], v[84:85]
	v_pk_fma_f32 v[70:71], v[14:15], v[30:31], v[70:71]
	v_pk_mul_f32 v[76:77], v[8:9], v[36:37]
	v_pk_add_f32 v[70:71], v[26:27], v[70:71]
	v_pk_fma_f32 v[72:73], v[72:73], v[20:21], v[76:77]
	v_mul_f32_e32 v0, 0xbfb8aa3b, v70
	v_fma_f32 v76, v70, s34, -v0
	v_rndne_f32_e32 v77, v0
	v_fmac_f32_e32 v76, 0xb2a5705f, v70
	v_sub_f32_e32 v0, v0, v77
	v_add_f32_e32 v0, v0, v76
	v_exp_f32_e32 v0, v0
	v_cvt_i32_f32_e32 v76, v77
	v_cmp_nlt_f32_e32 vcc, s55, v70
	v_pk_fma_f32 v[72:73], v[16:17], v[32:33], v[72:73]
	v_pk_mul_f32 v[14:15], v[14:15], v[34:35]
	v_ldexp_f32 v0, v0, v76
	v_cndmask_b32_e32 v0, 0, v0, vcc
	v_cmp_ngt_f32_e32 vcc, s56, v70
	v_pk_add_f32 v[72:73], v[28:29], v[72:73]
	v_pk_fma_f32 v[6:7], v[6:7], v[18:19], v[14:15]
	v_cndmask_b32_e32 v76, v219, v0, vcc
	v_mul_f32_e32 v0, 0xbfb8aa3b, v71
	v_fma_f32 v77, v71, s34, -v0
	v_rndne_f32_e32 v80, v0
	v_fmac_f32_e32 v77, 0xb2a5705f, v71
	v_sub_f32_e32 v0, v0, v80
	v_add_f32_e32 v0, v0, v77
	v_exp_f32_e32 v0, v0
	v_cvt_i32_f32_e32 v77, v80
	v_cmp_nlt_f32_e32 vcc, s55, v71
	v_pk_fma_f32 v[6:7], v[10:11], v[30:31], v[6:7]
	v_pk_mul_f32 v[16:17], v[16:17], v[36:37]
	v_ldexp_f32 v0, v0, v77
	v_cndmask_b32_e32 v0, 0, v0, vcc
	v_cmp_ngt_f32_e32 vcc, s56, v71
	v_pk_add_f32 v[6:7], v[26:27], v[6:7]
	v_pk_fma_f32 v[8:9], v[8:9], v[20:21], v[16:17]
	v_cndmask_b32_e32 v80, v219, v0, vcc
	v_mul_f32_e32 v0, 0xbfb8aa3b, v72
	v_fma_f32 v77, v72, s34, -v0
	v_rndne_f32_e32 v81, v0
	v_fmac_f32_e32 v77, 0xb2a5705f, v72
	v_sub_f32_e32 v0, v0, v81
	v_add_f32_e32 v0, v0, v77
	v_exp_f32_e32 v0, v0
	v_cvt_i32_f32_e32 v77, v81
	v_cmp_nlt_f32_e32 vcc, s55, v72
	v_pk_fma_f32 v[8:9], v[12:13], v[32:33], v[8:9]
	v_ldexp_f32 v0, v0, v77
	v_cndmask_b32_e32 v0, 0, v0, vcc
	v_cmp_ngt_f32_e32 vcc, s56, v72
	v_pk_add_f32 v[8:9], v[28:29], v[8:9]
	s_nop 0
	v_cndmask_b32_e32 v77, v219, v0, vcc
	v_pk_add_f32 v[76:77], v[76:77], 1.0 op_sel_hi:[1,0]
	s_nop 0
	v_div_scale_f32 v0, s[0:1], v77, v77, v72
	v_rcp_f32_e32 v81, v0
	s_nop 0
	v_fma_f32 v84, -v0, v81, 1.0
	v_fmac_f32_e32 v81, v84, v81
	v_div_scale_f32 v84, vcc, v72, v77, v72
	v_mul_f32_e32 v85, v84, v81
	v_fma_f32 v86, -v0, v85, v84
	v_fmac_f32_e32 v85, v86, v81
	v_fma_f32 v0, -v0, v85, v84
	v_div_fmas_f32 v0, v0, v81, v85
	v_div_fixup_f32 v77, v0, v77, v72
	v_div_scale_f32 v0, s[0:1], v76, v76, v70
	v_rcp_f32_e32 v72, v0
	s_nop 0
	v_fma_f32 v81, -v0, v72, 1.0
	v_fmac_f32_e32 v72, v81, v72
	v_div_scale_f32 v81, vcc, v70, v76, v70
	v_mul_f32_e32 v84, v81, v72
	v_fma_f32 v85, -v0, v84, v81
	v_fmac_f32_e32 v84, v85, v72
	v_fma_f32 v0, -v0, v84, v81
	v_div_fmas_f32 v0, v0, v72, v84
	v_div_fixup_f32 v76, v0, v76, v70
	v_mul_f32_e32 v0, 0xbfb8aa3b, v73
	v_mov_b32_e32 v84, v50
	v_mov_b32_e32 v85, v52
	v_fma_f32 v50, v73, s34, -v0
	v_rndne_f32_e32 v52, v0
	v_fmac_f32_e32 v50, 0xb2a5705f, v73
	v_sub_f32_e32 v0, v0, v52
	v_add_f32_e32 v0, v0, v50
	v_exp_f32_e32 v0, v0
	v_cvt_i32_f32_e32 v50, v52
	v_cmp_nlt_f32_e32 vcc, s55, v73
	v_pk_mul_f32 v[76:77], v[84:85], v[76:77]
	v_ldexp_f32 v0, v0, v50
	v_cndmask_b32_e32 v0, 0, v0, vcc
	v_cmp_ngt_f32_e32 vcc, s56, v73
	s_nop 1
	v_cndmask_b32_e32 v81, v219, v0, vcc
	v_pk_add_f32 v[80:81], v[80:81], 1.0 op_sel_hi:[1,0]
	s_nop 0
	v_div_scale_f32 v0, s[0:1], v81, v81, v73
	v_rcp_f32_e32 v50, v0
	s_nop 0
	v_fma_f32 v52, -v0, v50, 1.0
	v_fmac_f32_e32 v50, v52, v50
	v_div_scale_f32 v52, vcc, v73, v81, v73
	v_mul_f32_e32 v70, v52, v50
	v_fma_f32 v72, -v0, v70, v52
	v_fmac_f32_e32 v70, v72, v50
	v_fma_f32 v0, -v0, v70, v52
	v_div_fmas_f32 v0, v0, v50, v70
	v_div_fixup_f32 v73, v0, v81, v73
	v_div_scale_f32 v0, s[0:1], v80, v80, v71
	v_rcp_f32_e32 v50, v0
	s_lshl_b32 s0, s25, 8
	s_mul_i32 s1, s25, 0x150000
	s_mul_hi_i32 s21, s0, 0x1500
	v_fma_f32 v52, -v0, v50, 1.0
	v_fmac_f32_e32 v50, v52, v50
	v_div_scale_f32 v52, vcc, v71, v80, v71
	v_mul_f32_e32 v70, v52, v50
	v_fma_f32 v72, -v0, v70, v52
	v_fmac_f32_e32 v70, v72, v50
	v_fma_f32 v0, -v0, v70, v52
	v_div_fmas_f32 v0, v0, v50, v70
	v_div_fixup_f32 v72, v0, v80, v71
	v_mov_b32_e32 v52, v51
	v_pk_mul_f32 v[50:51], v[52:53], v[72:73]
	v_bfe_u32 v52, v74, 16, 1
	v_add3_u32 v52, v74, v52, s33
	v_cvt_pk_bf16_f32 v71, v79, v75
	v_mul_f32_e32 v0, 0xbfb8aa3b, v40
	v_fma_f32 v38, v40, s34, -v0
	v_rndne_f32_e32 v39, v0
	v_fmac_f32_e32 v38, 0xb2a5705f, v40
	v_sub_f32_e32 v0, v0, v39
	v_add_f32_e32 v0, v0, v38
	v_exp_f32_e32 v0, v0
	v_cvt_i32_f32_e32 v38, v39
	v_cmp_nlt_f32_e32 vcc, s55, v40
	v_ldexp_f32 v0, v0, v38
	s_nop 0
	v_cndmask_b32_e32 v0, 0, v0, vcc
	v_cmp_ngt_f32_e32 vcc, s56, v40
	v_bfe_u32 v53, v78, 16, 1
	s_nop 0
	v_cndmask_b32_e32 v38, v219, v0, vcc
	v_mul_f32_e32 v0, 0xbfb8aa3b, v41
	v_fma_f32 v39, v41, s34, -v0
	v_rndne_f32_e32 v44, v0
	v_fmac_f32_e32 v39, 0xb2a5705f, v41
	v_sub_f32_e32 v0, v0, v44
	v_add_f32_e32 v0, v0, v39
	v_exp_f32_e32 v0, v0
	v_cvt_i32_f32_e32 v39, v44
	v_cmp_nlt_f32_e32 vcc, s55, v41
	v_add3_u32 v53, v78, v53, s33
	v_ldexp_f32 v0, v0, v39
	v_cndmask_b32_e32 v0, 0, v0, vcc
	v_cmp_ngt_f32_e32 vcc, s56, v41
	s_add_u32 s24, s19, s1
	s_nop 0
	v_cndmask_b32_e32 v44, v219, v0, vcc
	v_mul_f32_e32 v0, 0xbfb8aa3b, v42
	v_fma_f32 v39, v42, s34, -v0
	v_rndne_f32_e32 v45, v0
	v_fmac_f32_e32 v39, 0xb2a5705f, v42
	v_sub_f32_e32 v0, v0, v45
	v_add_f32_e32 v0, v0, v39
	v_exp_f32_e32 v0, v0
	v_cvt_i32_f32_e32 v39, v45
	v_cmp_nlt_f32_e32 vcc, s55, v42
	v_lshrrev_b32_e32 v53, 16, v53
	v_cvt_pk_bf16_f32 v73, v77, v51
	v_ldexp_f32 v0, v0, v39
	v_cndmask_b32_e32 v0, 0, v0, vcc
	v_cmp_ngt_f32_e32 vcc, s56, v42
	v_cvt_pk_bf16_f32 v72, v76, v50
	s_addc_u32 s25, s20, s21
	v_cndmask_b32_e32 v39, v219, v0, vcc
	v_lshlrev_b64 v[50:51], 1, v[82:83]
	v_pk_add_f32 v[38:39], v[38:39], 1.0 op_sel_hi:[1,0]
	v_and_or_b32 v70, v52, s26, v53
	v_lshl_add_u64 v[52:53], s[24:25], 0, v[50:51]
	v_div_scale_f32 v0, s[24:25], v39, v39, v42
	v_rcp_f32_e32 v45, v0
	s_or_b32 s0, s0, 1
	s_mul_hi_i32 s1, s0, 0x1500
	s_mulk_i32 s0, 0x1500
	v_fma_f32 v46, -v0, v45, 1.0
	v_fmac_f32_e32 v45, v46, v45
	v_div_scale_f32 v46, vcc, v42, v39, v42
	v_mul_f32_e32 v47, v46, v45
	v_fma_f32 v48, -v0, v47, v46
	v_fmac_f32_e32 v47, v48, v45
	v_fma_f32 v0, -v0, v47, v46
	v_div_fmas_f32 v0, v0, v45, v47
	v_div_fixup_f32 v39, v0, v39, v42
	v_div_scale_f32 v0, s[24:25], v38, v38, v40
	v_rcp_f32_e32 v42, v0
	s_add_u32 s0, s19, s0
	s_addc_u32 s1, s20, s1
	global_store_dwordx4 v[52:53], v[70:73], off
	v_fma_f32 v45, -v0, v42, 1.0
	v_fmac_f32_e32 v42, v45, v42
	v_div_scale_f32 v45, vcc, v40, v38, v40
	v_mul_f32_e32 v46, v45, v42
	v_fma_f32 v47, -v0, v46, v45
	v_fmac_f32_e32 v46, v47, v42
	v_fma_f32 v0, -v0, v46, v45
	v_div_fmas_f32 v0, v0, v42, v46
	v_div_fixup_f32 v38, v0, v38, v40
	v_mul_f32_e32 v0, 0xbfb8aa3b, v43
	v_mov_b32_e32 v46, v22
	v_mov_b32_e32 v47, v24
	v_fma_f32 v22, v43, s34, -v0
	v_rndne_f32_e32 v24, v0
	v_fmac_f32_e32 v22, 0xb2a5705f, v43
	v_sub_f32_e32 v0, v0, v24
	v_add_f32_e32 v0, v0, v22
	v_exp_f32_e32 v0, v0
	v_cvt_i32_f32_e32 v22, v24
	v_cmp_nlt_f32_e32 vcc, s55, v43
	v_pk_mul_f32 v[38:39], v[46:47], v[38:39]
	v_ldexp_f32 v0, v0, v22
	v_cndmask_b32_e32 v0, 0, v0, vcc
	v_cmp_ngt_f32_e32 vcc, s56, v43
	s_nop 1
	v_cndmask_b32_e32 v45, v219, v0, vcc
	v_pk_add_f32 v[44:45], v[44:45], 1.0 op_sel_hi:[1,0]
	s_nop 0
	v_div_scale_f32 v0, s[24:25], v45, v45, v43
	v_rcp_f32_e32 v22, v0
	s_nop 0
	v_fma_f32 v24, -v0, v22, 1.0
	v_fmac_f32_e32 v22, v24, v22
	v_div_scale_f32 v24, vcc, v43, v45, v43
	v_mul_f32_e32 v40, v24, v22
	v_fma_f32 v42, -v0, v40, v24
	v_fmac_f32_e32 v40, v42, v22
	v_fma_f32 v0, -v0, v40, v24
	v_div_fmas_f32 v0, v0, v22, v40
	v_div_fixup_f32 v43, v0, v45, v43
	v_div_scale_f32 v0, s[24:25], v44, v44, v41
	v_rcp_f32_e32 v22, v0
	s_nop 0
	v_fma_f32 v24, -v0, v22, 1.0
	v_fmac_f32_e32 v22, v24, v22
	v_div_scale_f32 v24, vcc, v41, v44, v41
	v_mul_f32_e32 v40, v24, v22
	v_fma_f32 v42, -v0, v40, v24
	v_fmac_f32_e32 v40, v42, v22
	v_fma_f32 v0, -v0, v40, v24
	v_div_fmas_f32 v0, v0, v22, v40
	v_div_fixup_f32 v42, v0, v44, v41
	v_mul_f32_e32 v0, 0xbfb8aa3b, v6
	v_fma_f32 v10, v6, s34, -v0
	v_rndne_f32_e32 v11, v0
	v_fmac_f32_e32 v10, 0xb2a5705f, v6
	v_sub_f32_e32 v0, v0, v11
	v_add_f32_e32 v0, v0, v10
	v_exp_f32_e32 v0, v0
	v_cvt_i32_f32_e32 v10, v11
	v_cmp_nlt_f32_e32 vcc, s55, v6
	v_mov_b32_e32 v24, v23
	v_pk_mul_f32 v[22:23], v[24:25], v[42:43]
	v_ldexp_f32 v0, v0, v10
	v_cndmask_b32_e32 v0, 0, v0, vcc
	v_cmp_ngt_f32_e32 vcc, s56, v6
	s_nop 1
	v_cndmask_b32_e32 v10, v219, v0, vcc
	v_mul_f32_e32 v0, 0xbfb8aa3b, v7
	v_fma_f32 v11, v7, s34, -v0
	v_rndne_f32_e32 v12, v0
	v_fmac_f32_e32 v11, 0xb2a5705f, v7
	v_sub_f32_e32 v0, v0, v12
	v_add_f32_e32 v0, v0, v11
	v_exp_f32_e32 v0, v0
	v_cvt_i32_f32_e32 v11, v12
	v_cmp_nlt_f32_e32 vcc, s55, v7
	v_ldexp_f32 v0, v0, v11
	s_nop 0
	v_cndmask_b32_e32 v0, 0, v0, vcc
	v_cmp_ngt_f32_e32 vcc, s56, v7
	s_nop 1
	v_cndmask_b32_e32 v12, v219, v0, vcc
	v_mul_f32_e32 v0, 0xbfb8aa3b, v8
	v_fma_f32 v11, v8, s34, -v0
	v_rndne_f32_e32 v13, v0
	v_fmac_f32_e32 v11, 0xb2a5705f, v8
	v_sub_f32_e32 v0, v0, v13
	v_add_f32_e32 v0, v0, v11
	v_exp_f32_e32 v0, v0
	v_cvt_i32_f32_e32 v11, v13
	v_cmp_nlt_f32_e32 vcc, s55, v8
	v_ldexp_f32 v0, v0, v11
	s_nop 0
	v_cndmask_b32_e32 v0, 0, v0, vcc
	v_cmp_ngt_f32_e32 vcc, s56, v8
	s_nop 1
	v_cndmask_b32_e32 v11, v219, v0, vcc
	v_pk_add_f32 v[10:11], v[10:11], 1.0 op_sel_hi:[1,0]
	s_nop 0
	v_div_scale_f32 v0, s[24:25], v11, v11, v8
	v_rcp_f32_e32 v13, v0
	s_nop 0
	v_fma_f32 v14, -v0, v13, 1.0
	v_fmac_f32_e32 v13, v14, v13
	v_div_scale_f32 v14, vcc, v8, v11, v8
	v_mul_f32_e32 v15, v14, v13
	v_fma_f32 v16, -v0, v15, v14
	v_fmac_f32_e32 v15, v16, v13
	v_fma_f32 v0, -v0, v15, v14
	v_div_fmas_f32 v0, v0, v13, v15
	v_div_fixup_f32 v11, v0, v11, v8
	v_div_scale_f32 v0, s[24:25], v10, v10, v6
	v_rcp_f32_e32 v8, v0
	s_nop 0
	v_fma_f32 v13, -v0, v8, 1.0
	v_fmac_f32_e32 v8, v13, v8
	v_div_scale_f32 v13, vcc, v6, v10, v6
	v_mul_f32_e32 v14, v13, v8
	v_fma_f32 v15, -v0, v14, v13
	v_fmac_f32_e32 v14, v15, v8
	v_fma_f32 v0, -v0, v14, v13
	v_div_fmas_f32 v0, v0, v8, v14
	v_div_fixup_f32 v10, v0, v10, v6
	v_mul_f32_e32 v0, 0xbfb8aa3b, v9
	v_mov_b32_e32 v14, v2
	v_mov_b32_e32 v15, v4
	v_fma_f32 v2, v9, s34, -v0
	v_rndne_f32_e32 v4, v0
	v_fmac_f32_e32 v2, 0xb2a5705f, v9
	v_sub_f32_e32 v0, v0, v4
	v_add_f32_e32 v0, v0, v2
	v_exp_f32_e32 v0, v0
	v_cvt_i32_f32_e32 v2, v4
	v_cmp_nlt_f32_e32 vcc, s55, v9
	v_pk_mul_f32 v[10:11], v[14:15], v[10:11]
	v_ldexp_f32 v0, v0, v2
	v_cndmask_b32_e32 v0, 0, v0, vcc
	v_cmp_ngt_f32_e32 vcc, s56, v9
	s_nop 1
	v_cndmask_b32_e32 v13, v219, v0, vcc
	v_pk_add_f32 v[12:13], v[12:13], 1.0 op_sel_hi:[1,0]
	s_nop 0
	v_div_scale_f32 v0, s[24:25], v13, v13, v9
	v_rcp_f32_e32 v2, v0
	s_nop 0
	v_fma_f32 v4, -v0, v2, 1.0
	v_fmac_f32_e32 v2, v4, v2
	v_div_scale_f32 v4, vcc, v9, v13, v9
	v_mul_f32_e32 v6, v4, v2
	v_fma_f32 v8, -v0, v6, v4
	v_fmac_f32_e32 v6, v8, v2
	v_fma_f32 v0, -v0, v6, v4
	v_div_fmas_f32 v0, v0, v2, v6
	v_div_fixup_f32 v9, v0, v13, v9
	v_div_scale_f32 v0, s[24:25], v12, v12, v7
	v_rcp_f32_e32 v2, v0
	s_nop 0
	v_fma_f32 v4, -v0, v2, 1.0
	v_fmac_f32_e32 v2, v4, v2
	v_div_scale_f32 v4, vcc, v7, v12, v7
	v_mul_f32_e32 v6, v4, v2
	v_fma_f32 v8, -v0, v6, v4
	v_fmac_f32_e32 v6, v8, v2
	v_fma_f32 v0, -v0, v6, v4
	v_div_fmas_f32 v0, v0, v2, v6
	v_div_fixup_f32 v8, v0, v12, v7
	v_mov_b32_e32 v4, v3
	v_pk_mul_f32 v[2:3], v[4:5], v[8:9]
	s_nop 0
	v_cvt_pk_bf16_f32 v5, v11, v3
	v_cvt_pk_bf16_f32 v3, v39, v23
	v_cvt_pk_bf16_f32 v4, v10, v2
	v_cvt_pk_bf16_f32 v2, v38, v22
	v_lshl_add_u64 v[6:7], s[0:1], 0, v[50:51]
	global_store_dwordx4 v[6:7], v[2:5], off
	s_branch .LBB0_1459
